# no grid barrier between gate GEMM (C1) and up-projection (C2): per-row-panel G arrival counters + RWKV-output-stage counter, write-through G and ys stores
# speedup vs baseline: 1.0147x; 1.0017x over previous
.LBB0_809:
	v_cmp_gt_i32_e32 vcc, s37, v6
	s_mov_b32 s0, 0xd0a3000
	v_ashrrev_i32_e32 v15, 31, v14
	v_cndmask_b32_e32 v2, v213, v214, vcc
	v_and_b32_e32 v16, v2, v6
	v_ashrrev_i32_e32 v17, 31, v16
	v_lshlrev_b64 v[22:23], 2, v[16:17]
	v_lshl_add_u64 v[16:17], s[18:19], 0, v[12:13]
	v_add_co_u32_e64 v36, s[0:1], s0, v16
	v_cndmask_b32_e32 v7, v215, v216, vcc
	s_nop 0
	v_addc_co_u32_e64 v37, s[0:1], 0, v17, s[0:1]
	s_mov_b32 s0, 0xd8a3000
	v_and_or_b32 v22, v7, v6, v22
	v_add_co_u32_e64 v40, s[0:1], s0, v16
	v_lshl_add_u64 v[2:3], v[14:15], 2, s[52:53]
	s_nop 0
	v_addc_co_u32_e64 v41, s[0:1], 0, v17, s[0:1]
	v_mad_u64_u32 v[16:17], s[0:1], v22, s66, v[8:9]
	v_mad_i32_i24 v17, v23, s66, v17
	global_load_dwordx4 v[2:5], v[2:3], off
	s_mov_b32 s0, 0x78a3000
	global_load_dword v39, v[36:37], off offset:1792 nt
	global_load_dword v43, v[40:41], off offset:1792 nt
	global_load_dword v48, v[16:17], off
	v_lshl_add_u64 v[16:17], s[18:19], 0, v[10:11]
	v_add_co_u32_e64 v44, s[0:1], s0, v16
	v_add_u32_e32 v6, s10, v6
	s_nop 0
	v_addc_co_u32_e64 v45, s[0:1], 0, v17, s[0:1]
	global_load_ushort v49, v[44:45], off offset:2304
	global_load_dword v38, v[36:37], off offset:2048 nt
	global_load_dword v42, v[40:41], off offset:2048 nt
	v_lshl_add_u64 v[10:11], v[10:11], 0, s[62:63]
	v_lshl_add_u64 v[12:13], v[12:13], 0, s[12:13]
	v_add_u32_e32 v14, s11, v14
	v_cndmask_b32_e64 v52, 10, 8, vcc
	v_lshlrev_b64 v[18:19], v52, 1
	v_lshl_add_u64 v[18:19], v[22:23], 0, v[18:19]
	v_mad_u64_u32 v[20:21], s[0:1], v18, s66, v[8:9]
	v_mad_i32_i24 v21, v19, s66, v21
	global_load_dword v50, v[20:21], off
	global_load_ushort v51, v[44:45], off offset:2432
	v_lshlrev_b64 v[34:35], v52, 2
	v_lshl_add_u64 v[34:35], v[22:23], 0, v[34:35]
	v_mad_u64_u32 v[46:47], s[0:1], v34, s66, v[8:9]
	v_mad_i32_i24 v47, v35, s66, v47
	global_load_dword v19, v[36:37], off offset:2304 nt
	global_load_dword v21, v[40:41], off offset:2304 nt
	global_load_dword v33, v[46:47], off
	global_load_ushort v34, v[44:45], off offset:2560
	global_load_dword v18, v[36:37], off offset:2560 nt
	global_load_dword v20, v[40:41], off offset:2560 nt
	v_lshlrev_b64 v[36:37], v52, 3
	v_lshl_add_u64 v[22:23], v[22:23], 0, v[36:37]
	v_mad_u64_u32 v[36:37], s[0:1], v22, s66, v[8:9]
	v_mad_i32_i24 v37, v23, s66, v37
	s_mov_b32 s0, 0x3a27c5ac
	global_load_dword v7, v[36:37], off
	global_load_ushort v15, v[44:45], off offset:2688
	v_mov_b32_e32 v37, v131
	v_mov_b32_e32 v36, v131
	s_waitcnt vmcnt(0)
	v_lshlrev_b32_e32 v15, 16, v15
	v_lshlrev_b32_e32 v49, 16, v49
	v_lshlrev_b32_e32 v51, 16, v51
	v_lshlrev_b32_e32 v34, 16, v34
	v_pk_add_f32 v[22:23], v[38:39], v[42:43]
	v_mov_b32_e32 v39, v131
	v_mov_b32_e32 v38, v131
	v_mov_b32_dpp v37, v23 row_ror:8 row_mask:0xf bank_mask:0xf
	v_mov_b32_dpp v36, v22 row_ror:8 row_mask:0xf bank_mask:0xf
	v_pk_add_f32 v[36:37], v[22:23], v[36:37]
	s_nop 1
	v_mov_b32_dpp v39, v37 row_ror:4 row_mask:0xf bank_mask:0xf
	v_mov_b32_dpp v38, v36 row_ror:4 row_mask:0xf bank_mask:0xf
	v_pk_add_f32 v[36:37], v[36:37], v[38:39]
	v_mov_b32_e32 v39, v131
	v_mov_b32_e32 v38, v131
	s_nop 0
	v_mov_b32_dpp v39, v37 row_ror:2 row_mask:0xf bank_mask:0xf
	v_mov_b32_dpp v38, v36 row_ror:2 row_mask:0xf bank_mask:0xf
	v_pk_add_f32 v[36:37], v[36:37], v[38:39]
	v_mov_b32_e32 v39, v131
	v_mov_b32_e32 v38, v131
	s_nop 0
	v_mov_b32_dpp v39, v37 row_ror:1 row_mask:0xf bank_mask:0xf
	v_mov_b32_dpp v38, v36 row_ror:1 row_mask:0xf bank_mask:0xf
	v_pk_add_f32 v[36:37], v[36:37], v[38:39]
	ds_bpermute_b32 v39, v31, v37
	ds_bpermute_b32 v38, v31, v36
	s_waitcnt lgkmcnt(0)
	v_pk_add_f32 v[36:37], v[36:37], v[38:39]
	ds_bpermute_b32 v39, v32, v37
	ds_bpermute_b32 v38, v32, v36
	s_waitcnt lgkmcnt(0)
	v_pk_add_f32 v[36:37], v[36:37], v[38:39]
	s_nop 0
	v_pk_fma_f32 v[36:37], v[36:37], s[14:15], v[22:23] op_sel_hi:[1,0,1] neg_lo:[1,0,0] neg_hi:[1,0,0]
	v_mov_b32_e32 v39, v131
	v_pk_mul_f32 v[22:23], v[36:37], v[36:37]
	v_mov_b32_e32 v38, v131
	s_nop 0
	v_mov_b32_dpp v39, v23 row_ror:8 row_mask:0xf bank_mask:0xf
	v_mov_b32_dpp v38, v22 row_ror:8 row_mask:0xf bank_mask:0xf
	v_pk_fma_f32 v[22:23], v[36:37], v[36:37], v[38:39]
	v_mov_b32_e32 v39, v131
	v_mov_b32_e32 v38, v131
	s_nop 0
	v_mov_b32_dpp v39, v23 row_ror:4 row_mask:0xf bank_mask:0xf
	v_mov_b32_dpp v38, v22 row_ror:4 row_mask:0xf bank_mask:0xf
	v_pk_add_f32 v[22:23], v[22:23], v[38:39]
	v_mov_b32_e32 v39, v131
	v_mov_b32_e32 v38, v131
	s_nop 0
	v_mov_b32_dpp v39, v23 row_ror:2 row_mask:0xf bank_mask:0xf
	v_mov_b32_dpp v38, v22 row_ror:2 row_mask:0xf bank_mask:0xf
	v_pk_add_f32 v[22:23], v[22:23], v[38:39]
	v_mov_b32_e32 v39, v131
	v_mov_b32_e32 v38, v131
	s_nop 0
	v_mov_b32_dpp v39, v23 row_ror:1 row_mask:0xf bank_mask:0xf
	v_mov_b32_dpp v38, v22 row_ror:1 row_mask:0xf bank_mask:0xf
	v_pk_add_f32 v[22:23], v[22:23], v[38:39]
	ds_bpermute_b32 v39, v31, v23
	ds_bpermute_b32 v38, v31, v22
	s_waitcnt lgkmcnt(0)
	v_pk_add_f32 v[22:23], v[22:23], v[38:39]
	ds_bpermute_b32 v39, v32, v23
	ds_bpermute_b32 v38, v32, v22
	s_waitcnt lgkmcnt(0)
	v_pk_add_f32 v[38:39], v[22:23], v[38:39]
	v_mov_b64_e32 v[22:23], s[0:1]
	v_pk_fma_f32 v[38:39], v[38:39], s[14:15], v[22:23] op_sel_hi:[1,0,0]
	s_nop 0
	v_mul_f32_e32 v35, 0x4b800000, v39
	v_cmp_gt_f32_e64 s[0:1], s50, v39
	v_cmp_gt_f32_e32 vcc, s50, v38
	s_nop 0
	v_cndmask_b32_e64 v35, v39, v35, s[0:1]
	v_rsq_f32_e32 v35, v35
	s_nop 0
	v_mul_f32_e32 v39, 0x45800000, v35
	v_cndmask_b32_e64 v35, v35, v39, s[0:1]
	v_mul_f32_e32 v35, v37, v35
	v_fma_f32 v35, v1, v35, v27
	v_fmac_f32_e32 v35, v2, v48
	v_mul_f32_e32 v2, v35, v49
	v_add_co_u32_e64 v16, s[0:1], s49, v16
	v_cvt_pk_bf16_f32 v2, v2, v131
	s_nop 1
	v_addc_co_u32_e64 v17, s[0:1], 0, v17, s[0:1]
	global_store_short v[16:17], v2, off offset:2304 sc1
	v_mul_f32_e32 v2, 0x4b800000, v38
	v_cndmask_b32_e32 v2, v38, v2, vcc
	v_rsq_f32_e32 v2, v2
	s_nop 0
	v_mul_f32_e32 v35, 0x45800000, v2
	v_cndmask_b32_e32 v2, v2, v35, vcc
	v_mul_f32_e32 v2, v36, v2
	v_fma_f32 v2, v24, v2, v28
	v_fmac_f32_e32 v2, v3, v50
	v_mul_f32_e32 v2, v2, v51
	v_cvt_pk_bf16_f32 v2, v2, v131
	global_store_short v[16:17], v2, off offset:2432 sc1
	v_pk_add_f32 v[2:3], v[18:19], v[20:21]
	v_mov_b32_e32 v19, v131
	v_mov_b32_e32 v18, v131
	v_mov_b32_e32 v21, v131
	v_mov_b32_dpp v19, v3 row_ror:8 row_mask:0xf bank_mask:0xf
	v_mov_b32_dpp v18, v2 row_ror:8 row_mask:0xf bank_mask:0xf
	v_pk_add_f32 v[18:19], v[2:3], v[18:19]
	v_mov_b32_e32 v20, v131
	s_nop 0
	v_mov_b32_dpp v21, v19 row_ror:4 row_mask:0xf bank_mask:0xf
	v_mov_b32_dpp v20, v18 row_ror:4 row_mask:0xf bank_mask:0xf
	v_pk_add_f32 v[18:19], v[18:19], v[20:21]
	v_mov_b32_e32 v21, v131
	v_mov_b32_e32 v20, v131
	s_nop 0
	v_mov_b32_dpp v21, v19 row_ror:2 row_mask:0xf bank_mask:0xf
	v_mov_b32_dpp v20, v18 row_ror:2 row_mask:0xf bank_mask:0xf
	v_pk_add_f32 v[18:19], v[18:19], v[20:21]
	v_mov_b32_e32 v21, v131
	v_mov_b32_e32 v20, v131
	s_nop 0
	v_mov_b32_dpp v21, v19 row_ror:1 row_mask:0xf bank_mask:0xf
	v_mov_b32_dpp v20, v18 row_ror:1 row_mask:0xf bank_mask:0xf
	v_pk_add_f32 v[18:19], v[18:19], v[20:21]
	ds_bpermute_b32 v21, v31, v19
	ds_bpermute_b32 v20, v31, v18
	s_waitcnt lgkmcnt(0)
	v_pk_add_f32 v[18:19], v[18:19], v[20:21]
	ds_bpermute_b32 v21, v32, v19
	ds_bpermute_b32 v20, v32, v18
	s_waitcnt lgkmcnt(0)
	v_pk_add_f32 v[18:19], v[18:19], v[20:21]
	s_nop 0
	v_pk_fma_f32 v[2:3], v[18:19], s[14:15], v[2:3] op_sel_hi:[1,0,1] neg_lo:[1,0,0] neg_hi:[1,0,0]
	v_mov_b32_e32 v21, v131
	v_pk_mul_f32 v[18:19], v[2:3], v[2:3]
	v_mov_b32_e32 v20, v131
	s_nop 0
	v_mov_b32_dpp v21, v19 row_ror:8 row_mask:0xf bank_mask:0xf
	v_mov_b32_dpp v20, v18 row_ror:8 row_mask:0xf bank_mask:0xf
	v_pk_fma_f32 v[18:19], v[2:3], v[2:3], v[20:21]
	v_mov_b32_e32 v21, v131
	v_mov_b32_e32 v20, v131
	s_nop 0
	v_mov_b32_dpp v21, v19 row_ror:4 row_mask:0xf bank_mask:0xf
	v_mov_b32_dpp v20, v18 row_ror:4 row_mask:0xf bank_mask:0xf
	v_pk_add_f32 v[18:19], v[18:19], v[20:21]
	v_mov_b32_e32 v21, v131
	v_mov_b32_e32 v20, v131
	s_nop 0
	v_mov_b32_dpp v21, v19 row_ror:2 row_mask:0xf bank_mask:0xf
	v_mov_b32_dpp v20, v18 row_ror:2 row_mask:0xf bank_mask:0xf
	v_pk_add_f32 v[18:19], v[18:19], v[20:21]
	v_mov_b32_e32 v21, v131
	v_mov_b32_e32 v20, v131
	s_nop 0
	v_mov_b32_dpp v21, v19 row_ror:1 row_mask:0xf bank_mask:0xf
	v_mov_b32_dpp v20, v18 row_ror:1 row_mask:0xf bank_mask:0xf
	v_pk_add_f32 v[18:19], v[18:19], v[20:21]
	ds_bpermute_b32 v21, v31, v19
	ds_bpermute_b32 v20, v31, v18
	s_waitcnt lgkmcnt(0)
	v_pk_add_f32 v[18:19], v[18:19], v[20:21]
	ds_bpermute_b32 v21, v32, v19
	ds_bpermute_b32 v20, v32, v18
	s_waitcnt lgkmcnt(0)
	v_pk_add_f32 v[18:19], v[18:19], v[20:21]
	s_nop 0
	v_pk_fma_f32 v[18:19], v[18:19], s[14:15], v[22:23] op_sel_hi:[1,0,0]
	s_nop 0
	v_mul_f32_e32 v20, 0x4b800000, v19
	v_cmp_gt_f32_e64 s[0:1], s50, v19
	v_cmp_gt_f32_e32 vcc, s50, v18
	s_nop 0
	v_cndmask_b32_e64 v19, v19, v20, s[0:1]
	v_rsq_f32_e32 v19, v19
	s_nop 0
	v_mul_f32_e32 v20, 0x45800000, v19
	v_cndmask_b32_e64 v19, v19, v20, s[0:1]
	v_mul_f32_e32 v3, v3, v19
	v_fma_f32 v3, v25, v3, v29
	v_fmac_f32_e32 v3, v4, v33
	v_mul_f32_e32 v3, v3, v34
	v_cvt_pk_bf16_f32 v3, v3, v131
	global_store_short v[16:17], v3, off offset:2560 sc1
	v_mul_f32_e32 v3, 0x4b800000, v18
	v_cndmask_b32_e32 v3, v18, v3, vcc
	v_rsq_f32_e32 v3, v3
	s_movk_i32 s0, 0x1fff
	v_mul_f32_e32 v4, 0x45800000, v3
	v_cndmask_b32_e32 v3, v3, v4, vcc
	v_mul_f32_e32 v2, v2, v3
	v_fma_f32 v2, v26, v2, v30
	v_fmac_f32_e32 v2, v5, v7
	v_cmp_lt_i32_e32 vcc, s0, v6
	v_mul_f32_e32 v2, v2, v15
	s_or_b64 s[6:7], vcc, s[6:7]
	v_cvt_pk_bf16_f32 v2, v2, v131
	global_store_short v[16:17], v2, off offset:2688 sc1
	s_andn2_b64 exec, exec, s[6:7]
	s_cbranch_execnz .LBB0_809
.LBB0_810:
	s_or_b64 exec, exec, s[4:5]
	s_waitcnt vmcnt(0)
	s_barrier
	v_readlane_b32 s4, v253, 2
	v_readlane_b32 s5, v253, 3
	s_lshl_b32 s6, s80, 2
	s_add_u32 s6, s6, 24
	s_add_u32 s4, s4, s6
	s_addc_u32 s5, s5, 0
	v_cmp_eq_u32_e32 vcc, 0, v0
	s_and_saveexec_b64 s[6:7], vcc
	v_mov_b32_e32 v1, 1
	global_atomic_add v131, v1, s[4:5]
	s_or_b64 exec, exec, s[6:7]
	v_readlane_b32 s0, v253, 59
	v_mov_b32_e32 v1, v0
	v_readlane_b32 s1, v253, 60
	v_readlane_b32 s62, v254, 36
	v_readlane_b32 s70, v254, 38
	v_readlane_b32 s76, v254, 40
	v_readlane_b32 s86, v254, 42
	v_readlane_b32 s94, v254, 44
	s_andn2_b64 vcc, exec, s[0:1]
	v_readfirstlane_b32 s50, v1
	v_readlane_b32 s63, v254, 37
	v_readlane_b32 s71, v254, 39
	v_readlane_b32 s77, v254, 41
	v_readlane_b32 s87, v254, 43
	v_readlane_b32 s95, v254, 45
	s_mov_b64 s[52:53], 0x18000
	s_cbranch_vccnz .LBB0_826
	s_branch .Lc1_start

.Lc1_start:
	v_mov_b32_e32 v238, 0x200f0
	ds_read_b64 v[236:237], v238
	s_waitcnt lgkmcnt(0)
	v_readfirstlane_b32 s20, v236
	v_readfirstlane_b32 s21, v237
	s_barrier
	v_and_b32_e32 v236, 63, v0
	v_lshrrev_b32_e32 v237, 6, v0
	v_lshrrev_b32_e32 v238, 3, v236
	v_lshrrev_b32_e32 v239, 4, v236
	s_nop 0
	v_readfirstlane_b32 s0, v237
	v_add_u32_e32 v200, 0, v239
	v_xor_b32_e32 v200, v200, v236
	v_and_b32_e32 v200, 7, v200
	v_lshlrev_b32_e32 v200, 4, v200
	v_lshl_add_u32 v130, v237, 5, v238
	v_add_u32_e32 v130, 0, v130
	v_mul_u32_u24_e32 v130, 0x800, v130
	v_add_u32_e32 v200, v200, v130
	v_add_u32_e32 v201, 4, v239
	v_xor_b32_e32 v201, v201, v236
	v_and_b32_e32 v201, 7, v201
	v_lshlrev_b32_e32 v201, 4, v201
	v_lshl_add_u32 v130, v237, 5, v238
	v_add_u32_e32 v130, 8, v130
	v_mul_u32_u24_e32 v130, 0x800, v130
	v_add_u32_e32 v201, v201, v130
	v_add_u32_e32 v202, 8, v239
	v_xor_b32_e32 v202, v202, v236
	v_and_b32_e32 v202, 7, v202
	v_lshlrev_b32_e32 v202, 4, v202
	v_lshl_add_u32 v130, v237, 5, v238
	v_add_u32_e32 v130, 16, v130
	v_mul_u32_u24_e32 v130, 0x800, v130
	v_add_u32_e32 v202, v202, v130
	v_add_u32_e32 v203, 12, v239
	v_xor_b32_e32 v203, v203, v236
	v_and_b32_e32 v203, 7, v203
	v_lshlrev_b32_e32 v203, 4, v203
	v_lshl_add_u32 v130, v237, 5, v238
	v_add_u32_e32 v130, 24, v130
	v_mul_u32_u24_e32 v130, 0x800, v130
	v_add_u32_e32 v203, v203, v130
	v_add_u32_e32 v204, 0, v239
	v_xor_b32_e32 v204, v204, v236
	v_and_b32_e32 v204, 7, v204
	v_lshlrev_b32_e32 v204, 4, v204
	v_lshl_add_u32 v130, v237, 4, v238
	v_add_u32_e32 v130, 0, v130
	v_mul_u32_u24_e32 v130, 0x800, v130
	v_add_u32_e32 v204, v204, v130
	v_add_u32_e32 v205, 4, v239
	v_xor_b32_e32 v205, v205, v236
	v_and_b32_e32 v205, 7, v205
	v_lshlrev_b32_e32 v205, 4, v205
	v_lshl_add_u32 v130, v237, 4, v238
	v_add_u32_e32 v130, 8, v130
	v_mul_u32_u24_e32 v130, 0x800, v130
	v_add_u32_e32 v205, v205, v130
	v_and_b32_e32 v238, 15, v236
	v_lshrrev_b32_e32 v130, 1, v238
	v_xor_b32_e32 v130, v130, v239
	v_lshlrev_b32_e32 v130, 4, v130
	v_lshrrev_b32_e32 v236, 1, v237
	v_lshl_add_u32 v236, v236, 6, v238
	v_lshl_add_u32 v236, v236, 7, v130
	v_and_b32_e32 v237, 1, v237
	v_lshl_add_u32 v237, v237, 6, v238
	v_lshl_add_u32 v237, v237, 7, v130
	v_add_u32_e32 v218, 0x100, v236
	v_xor_b32_e32 v225, 64, v218
	v_add_u32_e32 v230, 0x8100, v237
	v_xor_b32_e32 v233, 64, v230
	v_add_u32_e32 v219, 0xc100, v236
	v_xor_b32_e32 v228, 64, v219
	v_add_u32_e32 v231, 0x14100, v237
	v_xor_b32_e32 v234, 64, v231
	v_add_u32_e32 v224, 0x18100, v236
	v_xor_b32_e32 v229, 64, v224
	v_add_u32_e32 v232, 0x20100, v237
	v_xor_b32_e32 v235, 64, v232
	s_lshl_b32 s1, s0, 12
	s_add_u32 s8, s1, 0x100
	s_lshl_b32 s1, s0, 11
	s_add_u32 s9, s1, 0x8100
	v_and_b32_e32 v236, 63, v0
	v_lshrrev_b32_e32 v237, 6, v0
	v_and_b32_e32 v238, 15, v236
	v_lshrrev_b32_e32 v239, 4, v236
	v_lshlrev_b32_e32 v240, 13, v237
	v_lshl_add_u32 v240, v236, 4, v240
	v_add_u32_e32 v241, 0x1000, v240
	s_and_b32 s1, s2, 7
	s_lshr_b32 s22, s2, 3
	s_and_b32 s23, s22, 3
	s_lshl_b32 s1, s1, 2
	s_add_u32 s1, s1, s23
	s_lshr_b32 s22, s22, 2
	s_lshl_b32 s23, s1, 19
	s_add_u32 s4, s26, s23
	s_addc_u32 s5, s27, 0
	v_readlane_b32 s6, v254, 57
	v_readlane_b32 s7, v254, 58
	s_lshl_b32 s23, s22, 20
	s_add_u32 s23, s23, 0x640000
	s_nop 0
	s_add_u32 s6, s6, s23
	s_addc_u32 s7, s7, 0
	s_lshr_b32 s23, s22, 1
	s_lshl_b32 s23, s23, 5
	s_add_u32 s23, s23, s1
	s_lshl_b32 s23, s23, 3
	s_and_b32 s24, s22, 1
	s_lshl_b32 s24, s24, 2
	s_add_u32 s23, s23, s24
	s_lshl_b32 s13, s23, 16
	s_mov_b32 s12, 0xbfb8aa3b
	s_mov_b32 m0, s8
	s_nop 0
	global_load_lds_dwordx4 v200, s[4:5]
	s_add_u32 m0, s8, 0x400
	s_nop 0
	global_load_lds_dwordx4 v201, s[4:5]
	s_add_u32 m0, s8, 0x800
	s_nop 0
	global_load_lds_dwordx4 v202, s[4:5]
	s_add_u32 m0, s8, 0xc00
	s_nop 0
	global_load_lds_dwordx4 v203, s[4:5]
	s_mov_b32 m0, s9
	s_nop 0
	global_load_lds_dwordx4 v204, s[6:7]
	s_add_u32 m0, s9, 0x400
	s_nop 0
	global_load_lds_dwordx4 v205, s[6:7]
	s_add_u32 s4, s4, 0x80
	s_addc_u32 s5, s5, 0
	s_add_u32 s6, s6, 0x80
	s_addc_u32 s7, s7, 0
	s_add_u32 m0, s8, 0xc000
	s_nop 0
	global_load_lds_dwordx4 v200, s[4:5]
	s_add_u32 m0, s8, 0xc400
	s_nop 0
	global_load_lds_dwordx4 v201, s[4:5]
	s_add_u32 m0, s8, 0xc800
	s_nop 0
	global_load_lds_dwordx4 v202, s[4:5]
	s_add_u32 m0, s8, 0xcc00
	s_nop 0
	global_load_lds_dwordx4 v203, s[4:5]
	s_add_u32 m0, s9, 0xc000
	s_nop 0
	global_load_lds_dwordx4 v204, s[6:7]
	s_add_u32 m0, s9, 0xc400
	s_nop 0
	global_load_lds_dwordx4 v205, s[6:7]
	s_add_u32 s4, s4, 0x80
	s_addc_u32 s5, s5, 0
	s_add_u32 s6, s6, 0x80
	s_addc_u32 s7, s7, 0
	s_add_u32 m0, s8, 0x18000
	s_nop 0
	global_load_lds_dwordx4 v200, s[4:5]
	s_add_u32 m0, s8, 0x18400
	s_nop 0
	global_load_lds_dwordx4 v201, s[4:5]
	s_add_u32 m0, s8, 0x18800
	s_nop 0
	global_load_lds_dwordx4 v202, s[4:5]
	s_add_u32 m0, s8, 0x18c00
	s_nop 0
	global_load_lds_dwordx4 v203, s[4:5]
	s_add_u32 m0, s9, 0x18000
	s_nop 0
	global_load_lds_dwordx4 v204, s[6:7]
	s_add_u32 m0, s9, 0x18400
	s_nop 0
	global_load_lds_dwordx4 v205, s[6:7]
	s_add_u32 s4, s4, 0x80
	s_addc_u32 s5, s5, 0
	s_add_u32 s6, s6, 0x80
	s_addc_u32 s7, s7, 0
	s_waitcnt vmcnt(12)
	s_barrier
	ds_read_b128 v[136:139], v218 offset:0
	ds_read_b128 v[140:143], v218 offset:2048
	ds_read_b128 v[144:147], v218 offset:4096
	ds_read_b128 v[148:151], v218 offset:6144
	ds_read_b128 v[152:155], v230 offset:0
	ds_read_b128 v[156:159], v230 offset:2048
	ds_read_b128 v[160:163], v230 offset:4096
	ds_read_b128 v[164:167], v230 offset:6144
	s_waitcnt lgkmcnt(0)
	v_mfma_f32_16x16x32_bf16 v[2:5], v[152:155], v[136:139], 0
	ds_read_b128 v[168:171], v225 offset:0
	v_mfma_f32_16x16x32_bf16 v[6:9], v[156:159], v[136:139], 0
	ds_read_b128 v[172:175], v225 offset:2048
	v_mfma_f32_16x16x32_bf16 v[10:13], v[160:163], v[136:139], 0
	ds_read_b128 v[176:179], v225 offset:4096
	v_mfma_f32_16x16x32_bf16 v[14:17], v[164:167], v[136:139], 0
	ds_read_b128 v[180:183], v225 offset:6144
	v_mfma_f32_16x16x32_bf16 v[18:21], v[152:155], v[140:143], 0
	ds_read_b128 v[184:187], v233 offset:0
	v_mfma_f32_16x16x32_bf16 v[22:25], v[156:159], v[140:143], 0
	ds_read_b128 v[188:191], v233 offset:2048
	v_mfma_f32_16x16x32_bf16 v[26:29], v[160:163], v[140:143], 0
	ds_read_b128 v[192:195], v233 offset:4096
	v_mfma_f32_16x16x32_bf16 v[30:33], v[164:167], v[140:143], 0
	ds_read_b128 v[196:199], v233 offset:6144
	v_mfma_f32_16x16x32_bf16 v[34:37], v[152:155], v[144:147], 0
	v_mfma_f32_16x16x32_bf16 v[38:41], v[156:159], v[144:147], 0
	v_mfma_f32_16x16x32_bf16 v[42:45], v[160:163], v[144:147], 0
	v_mfma_f32_16x16x32_bf16 v[46:49], v[164:167], v[144:147], 0
	v_mfma_f32_16x16x32_bf16 v[50:53], v[152:155], v[148:151], 0
	v_mfma_f32_16x16x32_bf16 v[54:57], v[156:159], v[148:151], 0
	v_mfma_f32_16x16x32_bf16 v[58:61], v[160:163], v[148:151], 0
	v_mfma_f32_16x16x32_bf16 v[62:65], v[164:167], v[148:151], 0
	s_waitcnt vmcnt(6) lgkmcnt(0)
	s_barrier
	v_mfma_f32_16x16x32_bf16 v[2:5], v[184:187], v[168:171], v[2:5]
	ds_read_b128 v[136:139], v219 offset:0
	v_mfma_f32_16x16x32_bf16 v[6:9], v[188:191], v[168:171], v[6:9]
	ds_read_b128 v[140:143], v219 offset:2048
	v_mfma_f32_16x16x32_bf16 v[10:13], v[192:195], v[168:171], v[10:13]
	ds_read_b128 v[144:147], v219 offset:4096
	v_mfma_f32_16x16x32_bf16 v[14:17], v[196:199], v[168:171], v[14:17]
	ds_read_b128 v[148:151], v219 offset:6144
	v_mfma_f32_16x16x32_bf16 v[18:21], v[184:187], v[172:175], v[18:21]
	ds_read_b128 v[152:155], v231 offset:0
	v_mfma_f32_16x16x32_bf16 v[22:25], v[188:191], v[172:175], v[22:25]
	ds_read_b128 v[156:159], v231 offset:2048
	v_mfma_f32_16x16x32_bf16 v[26:29], v[192:195], v[172:175], v[26:29]
	ds_read_b128 v[160:163], v231 offset:4096
	v_mfma_f32_16x16x32_bf16 v[30:33], v[196:199], v[172:175], v[30:33]
	ds_read_b128 v[164:167], v231 offset:6144
	s_mov_b32 m0, s8
	v_mfma_f32_16x16x32_bf16 v[34:37], v[184:187], v[176:179], v[34:37]
	global_load_lds_dwordx4 v200, s[4:5]
	s_add_u32 m0, s8, 0x400
	v_mfma_f32_16x16x32_bf16 v[38:41], v[188:191], v[176:179], v[38:41]
	global_load_lds_dwordx4 v201, s[4:5]
	s_add_u32 m0, s8, 0x800
	v_mfma_f32_16x16x32_bf16 v[42:45], v[192:195], v[176:179], v[42:45]
	global_load_lds_dwordx4 v202, s[4:5]
	s_add_u32 m0, s8, 0xc00
	v_mfma_f32_16x16x32_bf16 v[46:49], v[196:199], v[176:179], v[46:49]
	global_load_lds_dwordx4 v203, s[4:5]
	s_mov_b32 m0, s9
	v_mfma_f32_16x16x32_bf16 v[50:53], v[184:187], v[180:183], v[50:53]
	global_load_lds_dwordx4 v204, s[6:7]
	s_add_u32 m0, s9, 0x400
	v_mfma_f32_16x16x32_bf16 v[54:57], v[188:191], v[180:183], v[54:57]
	global_load_lds_dwordx4 v205, s[6:7]
	v_mfma_f32_16x16x32_bf16 v[58:61], v[192:195], v[180:183], v[58:61]
	s_add_u32 s4, s4, 0x80
	s_addc_u32 s5, s5, 0
	v_mfma_f32_16x16x32_bf16 v[62:65], v[196:199], v[180:183], v[62:65]
	s_add_u32 s6, s6, 0x80
	s_addc_u32 s7, s7, 0
	s_waitcnt lgkmcnt(0)
	v_mfma_f32_16x16x32_bf16 v[2:5], v[152:155], v[136:139], v[2:5]
	ds_read_b128 v[168:171], v228 offset:0
	v_mfma_f32_16x16x32_bf16 v[6:9], v[156:159], v[136:139], v[6:9]
	ds_read_b128 v[172:175], v228 offset:2048
	v_mfma_f32_16x16x32_bf16 v[10:13], v[160:163], v[136:139], v[10:13]
	ds_read_b128 v[176:179], v228 offset:4096
	v_mfma_f32_16x16x32_bf16 v[14:17], v[164:167], v[136:139], v[14:17]
	ds_read_b128 v[180:183], v228 offset:6144
	v_mfma_f32_16x16x32_bf16 v[18:21], v[152:155], v[140:143], v[18:21]
	ds_read_b128 v[184:187], v234 offset:0
	v_mfma_f32_16x16x32_bf16 v[22:25], v[156:159], v[140:143], v[22:25]
	ds_read_b128 v[188:191], v234 offset:2048
	v_mfma_f32_16x16x32_bf16 v[26:29], v[160:163], v[140:143], v[26:29]
	ds_read_b128 v[192:195], v234 offset:4096
	v_mfma_f32_16x16x32_bf16 v[30:33], v[164:167], v[140:143], v[30:33]
	ds_read_b128 v[196:199], v234 offset:6144
	v_mfma_f32_16x16x32_bf16 v[34:37], v[152:155], v[144:147], v[34:37]
	v_mfma_f32_16x16x32_bf16 v[38:41], v[156:159], v[144:147], v[38:41]
	v_mfma_f32_16x16x32_bf16 v[42:45], v[160:163], v[144:147], v[42:45]
	v_mfma_f32_16x16x32_bf16 v[46:49], v[164:167], v[144:147], v[46:49]
	v_mfma_f32_16x16x32_bf16 v[50:53], v[152:155], v[148:151], v[50:53]
	v_mfma_f32_16x16x32_bf16 v[54:57], v[156:159], v[148:151], v[54:57]
	v_mfma_f32_16x16x32_bf16 v[58:61], v[160:163], v[148:151], v[58:61]
	v_mfma_f32_16x16x32_bf16 v[62:65], v[164:167], v[148:151], v[62:65]
	s_waitcnt vmcnt(6) lgkmcnt(0)
	s_barrier
	v_mfma_f32_16x16x32_bf16 v[2:5], v[184:187], v[168:171], v[2:5]
	ds_read_b128 v[136:139], v224 offset:0
	v_mfma_f32_16x16x32_bf16 v[6:9], v[188:191], v[168:171], v[6:9]
	ds_read_b128 v[140:143], v224 offset:2048
	v_mfma_f32_16x16x32_bf16 v[10:13], v[192:195], v[168:171], v[10:13]
	ds_read_b128 v[144:147], v224 offset:4096
	v_mfma_f32_16x16x32_bf16 v[14:17], v[196:199], v[168:171], v[14:17]
	ds_read_b128 v[148:151], v224 offset:6144
	v_mfma_f32_16x16x32_bf16 v[18:21], v[184:187], v[172:175], v[18:21]
	ds_read_b128 v[152:155], v232 offset:0
	v_mfma_f32_16x16x32_bf16 v[22:25], v[188:191], v[172:175], v[22:25]
	ds_read_b128 v[156:159], v232 offset:2048
	v_mfma_f32_16x16x32_bf16 v[26:29], v[192:195], v[172:175], v[26:29]
	ds_read_b128 v[160:163], v232 offset:4096
	v_mfma_f32_16x16x32_bf16 v[30:33], v[196:199], v[172:175], v[30:33]
	ds_read_b128 v[164:167], v232 offset:6144
	s_add_u32 m0, s8, 0xc000
	v_mfma_f32_16x16x32_bf16 v[34:37], v[184:187], v[176:179], v[34:37]
	global_load_lds_dwordx4 v200, s[4:5]
	s_add_u32 m0, s8, 0xc400
	v_mfma_f32_16x16x32_bf16 v[38:41], v[188:191], v[176:179], v[38:41]
	global_load_lds_dwordx4 v201, s[4:5]
	s_add_u32 m0, s8, 0xc800
	v_mfma_f32_16x16x32_bf16 v[42:45], v[192:195], v[176:179], v[42:45]
	global_load_lds_dwordx4 v202, s[4:5]
	s_add_u32 m0, s8, 0xcc00
	v_mfma_f32_16x16x32_bf16 v[46:49], v[196:199], v[176:179], v[46:49]
	global_load_lds_dwordx4 v203, s[4:5]
	s_add_u32 m0, s9, 0xc000
	v_mfma_f32_16x16x32_bf16 v[50:53], v[184:187], v[180:183], v[50:53]
	global_load_lds_dwordx4 v204, s[6:7]
	s_add_u32 m0, s9, 0xc400
	v_mfma_f32_16x16x32_bf16 v[54:57], v[188:191], v[180:183], v[54:57]
	global_load_lds_dwordx4 v205, s[6:7]
	v_mfma_f32_16x16x32_bf16 v[58:61], v[192:195], v[180:183], v[58:61]
	s_add_u32 s4, s4, 0x80
	s_addc_u32 s5, s5, 0
	v_mfma_f32_16x16x32_bf16 v[62:65], v[196:199], v[180:183], v[62:65]
	s_add_u32 s6, s6, 0x80
	s_addc_u32 s7, s7, 0
	s_waitcnt lgkmcnt(0)
	v_mfma_f32_16x16x32_bf16 v[2:5], v[152:155], v[136:139], v[2:5]
	ds_read_b128 v[168:171], v229 offset:0
	v_mfma_f32_16x16x32_bf16 v[6:9], v[156:159], v[136:139], v[6:9]
	ds_read_b128 v[172:175], v229 offset:2048
	v_mfma_f32_16x16x32_bf16 v[10:13], v[160:163], v[136:139], v[10:13]
	ds_read_b128 v[176:179], v229 offset:4096
	v_mfma_f32_16x16x32_bf16 v[14:17], v[164:167], v[136:139], v[14:17]
	ds_read_b128 v[180:183], v229 offset:6144
	v_mfma_f32_16x16x32_bf16 v[18:21], v[152:155], v[140:143], v[18:21]
	ds_read_b128 v[184:187], v235 offset:0
	v_mfma_f32_16x16x32_bf16 v[22:25], v[156:159], v[140:143], v[22:25]
	ds_read_b128 v[188:191], v235 offset:2048
	v_mfma_f32_16x16x32_bf16 v[26:29], v[160:163], v[140:143], v[26:29]
	ds_read_b128 v[192:195], v235 offset:4096
	v_mfma_f32_16x16x32_bf16 v[30:33], v[164:167], v[140:143], v[30:33]
	ds_read_b128 v[196:199], v235 offset:6144
	v_mfma_f32_16x16x32_bf16 v[34:37], v[152:155], v[144:147], v[34:37]
	v_mfma_f32_16x16x32_bf16 v[38:41], v[156:159], v[144:147], v[38:41]
	v_mfma_f32_16x16x32_bf16 v[42:45], v[160:163], v[144:147], v[42:45]
	v_mfma_f32_16x16x32_bf16 v[46:49], v[164:167], v[144:147], v[46:49]
	v_mfma_f32_16x16x32_bf16 v[50:53], v[152:155], v[148:151], v[50:53]
	v_mfma_f32_16x16x32_bf16 v[54:57], v[156:159], v[148:151], v[54:57]
	v_mfma_f32_16x16x32_bf16 v[58:61], v[160:163], v[148:151], v[58:61]
	v_mfma_f32_16x16x32_bf16 v[62:65], v[164:167], v[148:151], v[62:65]
	s_waitcnt vmcnt(6) lgkmcnt(0)
	s_barrier
	v_mfma_f32_16x16x32_bf16 v[2:5], v[184:187], v[168:171], v[2:5]
	ds_read_b128 v[136:139], v218 offset:0
	v_mfma_f32_16x16x32_bf16 v[6:9], v[188:191], v[168:171], v[6:9]
	ds_read_b128 v[140:143], v218 offset:2048
	v_mfma_f32_16x16x32_bf16 v[10:13], v[192:195], v[168:171], v[10:13]
	ds_read_b128 v[144:147], v218 offset:4096
	v_mfma_f32_16x16x32_bf16 v[14:17], v[196:199], v[168:171], v[14:17]
	ds_read_b128 v[148:151], v218 offset:6144
	v_mfma_f32_16x16x32_bf16 v[18:21], v[184:187], v[172:175], v[18:21]
	ds_read_b128 v[152:155], v230 offset:0
	v_mfma_f32_16x16x32_bf16 v[22:25], v[188:191], v[172:175], v[22:25]
	ds_read_b128 v[156:159], v230 offset:2048
	v_mfma_f32_16x16x32_bf16 v[26:29], v[192:195], v[172:175], v[26:29]
	ds_read_b128 v[160:163], v230 offset:4096
	v_mfma_f32_16x16x32_bf16 v[30:33], v[196:199], v[172:175], v[30:33]
	ds_read_b128 v[164:167], v230 offset:6144
	s_add_u32 m0, s8, 0x18000
	v_mfma_f32_16x16x32_bf16 v[34:37], v[184:187], v[176:179], v[34:37]
	global_load_lds_dwordx4 v200, s[4:5]
	s_add_u32 m0, s8, 0x18400
	v_mfma_f32_16x16x32_bf16 v[38:41], v[188:191], v[176:179], v[38:41]
	global_load_lds_dwordx4 v201, s[4:5]
	s_add_u32 m0, s8, 0x18800
	v_mfma_f32_16x16x32_bf16 v[42:45], v[192:195], v[176:179], v[42:45]
	global_load_lds_dwordx4 v202, s[4:5]
	s_add_u32 m0, s8, 0x18c00
	v_mfma_f32_16x16x32_bf16 v[46:49], v[196:199], v[176:179], v[46:49]
	global_load_lds_dwordx4 v203, s[4:5]
	s_add_u32 m0, s9, 0x18000
	v_mfma_f32_16x16x32_bf16 v[50:53], v[184:187], v[180:183], v[50:53]
	global_load_lds_dwordx4 v204, s[6:7]
	s_add_u32 m0, s9, 0x18400
	v_mfma_f32_16x16x32_bf16 v[54:57], v[188:191], v[180:183], v[54:57]
	global_load_lds_dwordx4 v205, s[6:7]
	v_mfma_f32_16x16x32_bf16 v[58:61], v[192:195], v[180:183], v[58:61]
	s_add_u32 s4, s4, 0x80
	s_addc_u32 s5, s5, 0
	v_mfma_f32_16x16x32_bf16 v[62:65], v[196:199], v[180:183], v[62:65]
	s_add_u32 s6, s6, 0x80
	s_addc_u32 s7, s7, 0
	s_waitcnt lgkmcnt(0)
	v_mfma_f32_16x16x32_bf16 v[2:5], v[152:155], v[136:139], v[2:5]
	ds_read_b128 v[168:171], v225 offset:0
	v_mfma_f32_16x16x32_bf16 v[6:9], v[156:159], v[136:139], v[6:9]
	ds_read_b128 v[172:175], v225 offset:2048
	v_mfma_f32_16x16x32_bf16 v[10:13], v[160:163], v[136:139], v[10:13]
	ds_read_b128 v[176:179], v225 offset:4096
	v_mfma_f32_16x16x32_bf16 v[14:17], v[164:167], v[136:139], v[14:17]
	ds_read_b128 v[180:183], v225 offset:6144
	v_mfma_f32_16x16x32_bf16 v[18:21], v[152:155], v[140:143], v[18:21]
	ds_read_b128 v[184:187], v233 offset:0
	v_mfma_f32_16x16x32_bf16 v[22:25], v[156:159], v[140:143], v[22:25]
	ds_read_b128 v[188:191], v233 offset:2048
	v_mfma_f32_16x16x32_bf16 v[26:29], v[160:163], v[140:143], v[26:29]
	ds_read_b128 v[192:195], v233 offset:4096
	v_mfma_f32_16x16x32_bf16 v[30:33], v[164:167], v[140:143], v[30:33]
	ds_read_b128 v[196:199], v233 offset:6144
	v_mfma_f32_16x16x32_bf16 v[34:37], v[152:155], v[144:147], v[34:37]
	v_mfma_f32_16x16x32_bf16 v[38:41], v[156:159], v[144:147], v[38:41]
	v_mfma_f32_16x16x32_bf16 v[42:45], v[160:163], v[144:147], v[42:45]
	v_mfma_f32_16x16x32_bf16 v[46:49], v[164:167], v[144:147], v[46:49]
	v_mfma_f32_16x16x32_bf16 v[50:53], v[152:155], v[148:151], v[50:53]
	v_mfma_f32_16x16x32_bf16 v[54:57], v[156:159], v[148:151], v[54:57]
	v_mfma_f32_16x16x32_bf16 v[58:61], v[160:163], v[148:151], v[58:61]
	v_mfma_f32_16x16x32_bf16 v[62:65], v[164:167], v[148:151], v[62:65]
	s_waitcnt vmcnt(6) lgkmcnt(0)
	s_barrier
	v_mfma_f32_16x16x32_bf16 v[2:5], v[184:187], v[168:171], v[2:5]
	ds_read_b128 v[136:139], v219 offset:0
	v_mfma_f32_16x16x32_bf16 v[6:9], v[188:191], v[168:171], v[6:9]
	ds_read_b128 v[140:143], v219 offset:2048
	v_mfma_f32_16x16x32_bf16 v[10:13], v[192:195], v[168:171], v[10:13]
	ds_read_b128 v[144:147], v219 offset:4096
	v_mfma_f32_16x16x32_bf16 v[14:17], v[196:199], v[168:171], v[14:17]
	ds_read_b128 v[148:151], v219 offset:6144
	v_mfma_f32_16x16x32_bf16 v[18:21], v[184:187], v[172:175], v[18:21]
	ds_read_b128 v[152:155], v231 offset:0
	v_mfma_f32_16x16x32_bf16 v[22:25], v[188:191], v[172:175], v[22:25]
	ds_read_b128 v[156:159], v231 offset:2048
	v_mfma_f32_16x16x32_bf16 v[26:29], v[192:195], v[172:175], v[26:29]
	ds_read_b128 v[160:163], v231 offset:4096
	v_mfma_f32_16x16x32_bf16 v[30:33], v[196:199], v[172:175], v[30:33]
	ds_read_b128 v[164:167], v231 offset:6144
	s_mov_b32 m0, s8
	v_mfma_f32_16x16x32_bf16 v[34:37], v[184:187], v[176:179], v[34:37]
	global_load_lds_dwordx4 v200, s[4:5]
	s_add_u32 m0, s8, 0x400
	v_mfma_f32_16x16x32_bf16 v[38:41], v[188:191], v[176:179], v[38:41]
	global_load_lds_dwordx4 v201, s[4:5]
	s_add_u32 m0, s8, 0x800
	v_mfma_f32_16x16x32_bf16 v[42:45], v[192:195], v[176:179], v[42:45]
	global_load_lds_dwordx4 v202, s[4:5]
	s_add_u32 m0, s8, 0xc00
	v_mfma_f32_16x16x32_bf16 v[46:49], v[196:199], v[176:179], v[46:49]
	global_load_lds_dwordx4 v203, s[4:5]
	s_mov_b32 m0, s9
	v_mfma_f32_16x16x32_bf16 v[50:53], v[184:187], v[180:183], v[50:53]
	global_load_lds_dwordx4 v204, s[6:7]
	s_add_u32 m0, s9, 0x400
	v_mfma_f32_16x16x32_bf16 v[54:57], v[188:191], v[180:183], v[54:57]
	global_load_lds_dwordx4 v205, s[6:7]
	v_mfma_f32_16x16x32_bf16 v[58:61], v[192:195], v[180:183], v[58:61]
	s_add_u32 s4, s4, 0x80
	s_addc_u32 s5, s5, 0
	v_mfma_f32_16x16x32_bf16 v[62:65], v[196:199], v[180:183], v[62:65]
	s_add_u32 s6, s6, 0x80
	s_addc_u32 s7, s7, 0
	s_waitcnt lgkmcnt(0)
	v_mfma_f32_16x16x32_bf16 v[2:5], v[152:155], v[136:139], v[2:5]
	ds_read_b128 v[168:171], v228 offset:0
	v_mfma_f32_16x16x32_bf16 v[6:9], v[156:159], v[136:139], v[6:9]
	ds_read_b128 v[172:175], v228 offset:2048
	v_mfma_f32_16x16x32_bf16 v[10:13], v[160:163], v[136:139], v[10:13]
	ds_read_b128 v[176:179], v228 offset:4096
	v_mfma_f32_16x16x32_bf16 v[14:17], v[164:167], v[136:139], v[14:17]
	ds_read_b128 v[180:183], v228 offset:6144
	v_mfma_f32_16x16x32_bf16 v[18:21], v[152:155], v[140:143], v[18:21]
	ds_read_b128 v[184:187], v234 offset:0
	v_mfma_f32_16x16x32_bf16 v[22:25], v[156:159], v[140:143], v[22:25]
	ds_read_b128 v[188:191], v234 offset:2048
	v_mfma_f32_16x16x32_bf16 v[26:29], v[160:163], v[140:143], v[26:29]
	ds_read_b128 v[192:195], v234 offset:4096
	v_mfma_f32_16x16x32_bf16 v[30:33], v[164:167], v[140:143], v[30:33]
	ds_read_b128 v[196:199], v234 offset:6144
	v_mfma_f32_16x16x32_bf16 v[34:37], v[152:155], v[144:147], v[34:37]
	v_mfma_f32_16x16x32_bf16 v[38:41], v[156:159], v[144:147], v[38:41]
	v_mfma_f32_16x16x32_bf16 v[42:45], v[160:163], v[144:147], v[42:45]
	v_mfma_f32_16x16x32_bf16 v[46:49], v[164:167], v[144:147], v[46:49]
	v_mfma_f32_16x16x32_bf16 v[50:53], v[152:155], v[148:151], v[50:53]
	v_mfma_f32_16x16x32_bf16 v[54:57], v[156:159], v[148:151], v[54:57]
	v_mfma_f32_16x16x32_bf16 v[58:61], v[160:163], v[148:151], v[58:61]
	v_mfma_f32_16x16x32_bf16 v[62:65], v[164:167], v[148:151], v[62:65]
	s_waitcnt vmcnt(6) lgkmcnt(0)
	s_barrier
	v_mfma_f32_16x16x32_bf16 v[2:5], v[184:187], v[168:171], v[2:5]
	ds_read_b128 v[136:139], v224 offset:0
	v_mfma_f32_16x16x32_bf16 v[6:9], v[188:191], v[168:171], v[6:9]
	ds_read_b128 v[140:143], v224 offset:2048
	v_mfma_f32_16x16x32_bf16 v[10:13], v[192:195], v[168:171], v[10:13]
	ds_read_b128 v[144:147], v224 offset:4096
	v_mfma_f32_16x16x32_bf16 v[14:17], v[196:199], v[168:171], v[14:17]
	ds_read_b128 v[148:151], v224 offset:6144
	v_mfma_f32_16x16x32_bf16 v[18:21], v[184:187], v[172:175], v[18:21]
	ds_read_b128 v[152:155], v232 offset:0
	v_mfma_f32_16x16x32_bf16 v[22:25], v[188:191], v[172:175], v[22:25]
	ds_read_b128 v[156:159], v232 offset:2048
	v_mfma_f32_16x16x32_bf16 v[26:29], v[192:195], v[172:175], v[26:29]
	ds_read_b128 v[160:163], v232 offset:4096
	v_mfma_f32_16x16x32_bf16 v[30:33], v[196:199], v[172:175], v[30:33]
	ds_read_b128 v[164:167], v232 offset:6144
	s_add_u32 m0, s8, 0xc000
	v_mfma_f32_16x16x32_bf16 v[34:37], v[184:187], v[176:179], v[34:37]
	global_load_lds_dwordx4 v200, s[4:5]
	s_add_u32 m0, s8, 0xc400
	v_mfma_f32_16x16x32_bf16 v[38:41], v[188:191], v[176:179], v[38:41]
	global_load_lds_dwordx4 v201, s[4:5]
	s_add_u32 m0, s8, 0xc800
	v_mfma_f32_16x16x32_bf16 v[42:45], v[192:195], v[176:179], v[42:45]
	global_load_lds_dwordx4 v202, s[4:5]
	s_add_u32 m0, s8, 0xcc00
	v_mfma_f32_16x16x32_bf16 v[46:49], v[196:199], v[176:179], v[46:49]
	global_load_lds_dwordx4 v203, s[4:5]
	s_add_u32 m0, s9, 0xc000
	v_mfma_f32_16x16x32_bf16 v[50:53], v[184:187], v[180:183], v[50:53]
	global_load_lds_dwordx4 v204, s[6:7]
	s_add_u32 m0, s9, 0xc400
	v_mfma_f32_16x16x32_bf16 v[54:57], v[188:191], v[180:183], v[54:57]
	global_load_lds_dwordx4 v205, s[6:7]
	v_mfma_f32_16x16x32_bf16 v[58:61], v[192:195], v[180:183], v[58:61]
	s_add_u32 s4, s4, 0x80
	s_addc_u32 s5, s5, 0
	v_mfma_f32_16x16x32_bf16 v[62:65], v[196:199], v[180:183], v[62:65]
	s_add_u32 s6, s6, 0x80
	s_addc_u32 s7, s7, 0
	s_waitcnt lgkmcnt(0)
	v_mfma_f32_16x16x32_bf16 v[2:5], v[152:155], v[136:139], v[2:5]
	ds_read_b128 v[168:171], v229 offset:0
	v_mfma_f32_16x16x32_bf16 v[6:9], v[156:159], v[136:139], v[6:9]
	ds_read_b128 v[172:175], v229 offset:2048
	v_mfma_f32_16x16x32_bf16 v[10:13], v[160:163], v[136:139], v[10:13]
	ds_read_b128 v[176:179], v229 offset:4096
	v_mfma_f32_16x16x32_bf16 v[14:17], v[164:167], v[136:139], v[14:17]
	ds_read_b128 v[180:183], v229 offset:6144
	v_mfma_f32_16x16x32_bf16 v[18:21], v[152:155], v[140:143], v[18:21]
	ds_read_b128 v[184:187], v235 offset:0
	v_mfma_f32_16x16x32_bf16 v[22:25], v[156:159], v[140:143], v[22:25]
	ds_read_b128 v[188:191], v235 offset:2048
	v_mfma_f32_16x16x32_bf16 v[26:29], v[160:163], v[140:143], v[26:29]
	ds_read_b128 v[192:195], v235 offset:4096
	v_mfma_f32_16x16x32_bf16 v[30:33], v[164:167], v[140:143], v[30:33]
	ds_read_b128 v[196:199], v235 offset:6144
	v_mfma_f32_16x16x32_bf16 v[34:37], v[152:155], v[144:147], v[34:37]
	v_mfma_f32_16x16x32_bf16 v[38:41], v[156:159], v[144:147], v[38:41]
	v_mfma_f32_16x16x32_bf16 v[42:45], v[160:163], v[144:147], v[42:45]
	v_mfma_f32_16x16x32_bf16 v[46:49], v[164:167], v[144:147], v[46:49]
	v_mfma_f32_16x16x32_bf16 v[50:53], v[152:155], v[148:151], v[50:53]
	v_mfma_f32_16x16x32_bf16 v[54:57], v[156:159], v[148:151], v[54:57]
	v_mfma_f32_16x16x32_bf16 v[58:61], v[160:163], v[148:151], v[58:61]
	v_mfma_f32_16x16x32_bf16 v[62:65], v[164:167], v[148:151], v[62:65]
	s_waitcnt vmcnt(6) lgkmcnt(0)
	s_barrier
	v_mfma_f32_16x16x32_bf16 v[2:5], v[184:187], v[168:171], v[2:5]
	ds_read_b128 v[136:139], v218 offset:0
	v_mfma_f32_16x16x32_bf16 v[6:9], v[188:191], v[168:171], v[6:9]
	ds_read_b128 v[140:143], v218 offset:2048
	v_mfma_f32_16x16x32_bf16 v[10:13], v[192:195], v[168:171], v[10:13]
	ds_read_b128 v[144:147], v218 offset:4096
	v_mfma_f32_16x16x32_bf16 v[14:17], v[196:199], v[168:171], v[14:17]
	ds_read_b128 v[148:151], v218 offset:6144
	v_mfma_f32_16x16x32_bf16 v[18:21], v[184:187], v[172:175], v[18:21]
	ds_read_b128 v[152:155], v230 offset:0
	v_mfma_f32_16x16x32_bf16 v[22:25], v[188:191], v[172:175], v[22:25]
	ds_read_b128 v[156:159], v230 offset:2048
	v_mfma_f32_16x16x32_bf16 v[26:29], v[192:195], v[172:175], v[26:29]
	ds_read_b128 v[160:163], v230 offset:4096
	v_mfma_f32_16x16x32_bf16 v[30:33], v[196:199], v[172:175], v[30:33]
	ds_read_b128 v[164:167], v230 offset:6144
	s_add_u32 m0, s8, 0x18000
	v_mfma_f32_16x16x32_bf16 v[34:37], v[184:187], v[176:179], v[34:37]
	global_load_lds_dwordx4 v200, s[4:5]
	s_add_u32 m0, s8, 0x18400
	v_mfma_f32_16x16x32_bf16 v[38:41], v[188:191], v[176:179], v[38:41]
	global_load_lds_dwordx4 v201, s[4:5]
	s_add_u32 m0, s8, 0x18800
	v_mfma_f32_16x16x32_bf16 v[42:45], v[192:195], v[176:179], v[42:45]
	global_load_lds_dwordx4 v202, s[4:5]
	s_add_u32 m0, s8, 0x18c00
	v_mfma_f32_16x16x32_bf16 v[46:49], v[196:199], v[176:179], v[46:49]
	global_load_lds_dwordx4 v203, s[4:5]
	s_add_u32 m0, s9, 0x18000
	v_mfma_f32_16x16x32_bf16 v[50:53], v[184:187], v[180:183], v[50:53]
	global_load_lds_dwordx4 v204, s[6:7]
	s_add_u32 m0, s9, 0x18400
	v_mfma_f32_16x16x32_bf16 v[54:57], v[188:191], v[180:183], v[54:57]
	global_load_lds_dwordx4 v205, s[6:7]
	v_mfma_f32_16x16x32_bf16 v[58:61], v[192:195], v[180:183], v[58:61]
	s_add_u32 s4, s4, 0x80
	s_addc_u32 s5, s5, 0
	v_mfma_f32_16x16x32_bf16 v[62:65], v[196:199], v[180:183], v[62:65]
	s_add_u32 s6, s6, 0x80
	s_addc_u32 s7, s7, 0
	s_waitcnt lgkmcnt(0)
	v_mfma_f32_16x16x32_bf16 v[2:5], v[152:155], v[136:139], v[2:5]
	ds_read_b128 v[168:171], v225 offset:0
	v_mfma_f32_16x16x32_bf16 v[6:9], v[156:159], v[136:139], v[6:9]
	ds_read_b128 v[172:175], v225 offset:2048
	v_mfma_f32_16x16x32_bf16 v[10:13], v[160:163], v[136:139], v[10:13]
	ds_read_b128 v[176:179], v225 offset:4096
	v_mfma_f32_16x16x32_bf16 v[14:17], v[164:167], v[136:139], v[14:17]
	ds_read_b128 v[180:183], v225 offset:6144
	v_mfma_f32_16x16x32_bf16 v[18:21], v[152:155], v[140:143], v[18:21]
	ds_read_b128 v[184:187], v233 offset:0
	v_mfma_f32_16x16x32_bf16 v[22:25], v[156:159], v[140:143], v[22:25]
	ds_read_b128 v[188:191], v233 offset:2048
	v_mfma_f32_16x16x32_bf16 v[26:29], v[160:163], v[140:143], v[26:29]
	ds_read_b128 v[192:195], v233 offset:4096
	v_mfma_f32_16x16x32_bf16 v[30:33], v[164:167], v[140:143], v[30:33]
	ds_read_b128 v[196:199], v233 offset:6144
	v_mfma_f32_16x16x32_bf16 v[34:37], v[152:155], v[144:147], v[34:37]
	v_mfma_f32_16x16x32_bf16 v[38:41], v[156:159], v[144:147], v[38:41]
	v_mfma_f32_16x16x32_bf16 v[42:45], v[160:163], v[144:147], v[42:45]
	v_mfma_f32_16x16x32_bf16 v[46:49], v[164:167], v[144:147], v[46:49]
	v_mfma_f32_16x16x32_bf16 v[50:53], v[152:155], v[148:151], v[50:53]
	v_mfma_f32_16x16x32_bf16 v[54:57], v[156:159], v[148:151], v[54:57]
	v_mfma_f32_16x16x32_bf16 v[58:61], v[160:163], v[148:151], v[58:61]
	v_mfma_f32_16x16x32_bf16 v[62:65], v[164:167], v[148:151], v[62:65]
	s_waitcnt vmcnt(6) lgkmcnt(0)
	s_barrier
	v_mfma_f32_16x16x32_bf16 v[2:5], v[184:187], v[168:171], v[2:5]
	ds_read_b128 v[136:139], v219 offset:0
	v_mfma_f32_16x16x32_bf16 v[6:9], v[188:191], v[168:171], v[6:9]
	ds_read_b128 v[140:143], v219 offset:2048
	v_mfma_f32_16x16x32_bf16 v[10:13], v[192:195], v[168:171], v[10:13]
	ds_read_b128 v[144:147], v219 offset:4096
	v_mfma_f32_16x16x32_bf16 v[14:17], v[196:199], v[168:171], v[14:17]
	ds_read_b128 v[148:151], v219 offset:6144
	v_mfma_f32_16x16x32_bf16 v[18:21], v[184:187], v[172:175], v[18:21]
	ds_read_b128 v[152:155], v231 offset:0
	v_mfma_f32_16x16x32_bf16 v[22:25], v[188:191], v[172:175], v[22:25]
	ds_read_b128 v[156:159], v231 offset:2048
	v_mfma_f32_16x16x32_bf16 v[26:29], v[192:195], v[172:175], v[26:29]
	ds_read_b128 v[160:163], v231 offset:4096
	v_mfma_f32_16x16x32_bf16 v[30:33], v[196:199], v[172:175], v[30:33]
	ds_read_b128 v[164:167], v231 offset:6144
	s_mov_b32 m0, s8
	v_mfma_f32_16x16x32_bf16 v[34:37], v[184:187], v[176:179], v[34:37]
	global_load_lds_dwordx4 v200, s[4:5]
	s_add_u32 m0, s8, 0x400
	v_mfma_f32_16x16x32_bf16 v[38:41], v[188:191], v[176:179], v[38:41]
	global_load_lds_dwordx4 v201, s[4:5]
	s_add_u32 m0, s8, 0x800
	v_mfma_f32_16x16x32_bf16 v[42:45], v[192:195], v[176:179], v[42:45]
	global_load_lds_dwordx4 v202, s[4:5]
	s_add_u32 m0, s8, 0xc00
	v_mfma_f32_16x16x32_bf16 v[46:49], v[196:199], v[176:179], v[46:49]
	global_load_lds_dwordx4 v203, s[4:5]
	s_mov_b32 m0, s9
	v_mfma_f32_16x16x32_bf16 v[50:53], v[184:187], v[180:183], v[50:53]
	global_load_lds_dwordx4 v204, s[6:7]
	s_add_u32 m0, s9, 0x400
	v_mfma_f32_16x16x32_bf16 v[54:57], v[188:191], v[180:183], v[54:57]
	global_load_lds_dwordx4 v205, s[6:7]
	v_mfma_f32_16x16x32_bf16 v[58:61], v[192:195], v[180:183], v[58:61]
	s_add_u32 s4, s4, 0x80
	s_addc_u32 s5, s5, 0
	v_mfma_f32_16x16x32_bf16 v[62:65], v[196:199], v[180:183], v[62:65]
	s_add_u32 s6, s6, 0x80
	s_addc_u32 s7, s7, 0
	s_waitcnt lgkmcnt(0)
	v_mfma_f32_16x16x32_bf16 v[2:5], v[152:155], v[136:139], v[2:5]
	ds_read_b128 v[168:171], v228 offset:0
	v_mfma_f32_16x16x32_bf16 v[6:9], v[156:159], v[136:139], v[6:9]
	ds_read_b128 v[172:175], v228 offset:2048
	v_mfma_f32_16x16x32_bf16 v[10:13], v[160:163], v[136:139], v[10:13]
	ds_read_b128 v[176:179], v228 offset:4096
	v_mfma_f32_16x16x32_bf16 v[14:17], v[164:167], v[136:139], v[14:17]
	ds_read_b128 v[180:183], v228 offset:6144
	v_mfma_f32_16x16x32_bf16 v[18:21], v[152:155], v[140:143], v[18:21]
	ds_read_b128 v[184:187], v234 offset:0
	v_mfma_f32_16x16x32_bf16 v[22:25], v[156:159], v[140:143], v[22:25]
	ds_read_b128 v[188:191], v234 offset:2048
	v_mfma_f32_16x16x32_bf16 v[26:29], v[160:163], v[140:143], v[26:29]
	ds_read_b128 v[192:195], v234 offset:4096
	v_mfma_f32_16x16x32_bf16 v[30:33], v[164:167], v[140:143], v[30:33]
	ds_read_b128 v[196:199], v234 offset:6144
	v_mfma_f32_16x16x32_bf16 v[34:37], v[152:155], v[144:147], v[34:37]
	v_mfma_f32_16x16x32_bf16 v[38:41], v[156:159], v[144:147], v[38:41]
	v_mfma_f32_16x16x32_bf16 v[42:45], v[160:163], v[144:147], v[42:45]
	v_mfma_f32_16x16x32_bf16 v[46:49], v[164:167], v[144:147], v[46:49]
	v_mfma_f32_16x16x32_bf16 v[50:53], v[152:155], v[148:151], v[50:53]
	v_mfma_f32_16x16x32_bf16 v[54:57], v[156:159], v[148:151], v[54:57]
	v_mfma_f32_16x16x32_bf16 v[58:61], v[160:163], v[148:151], v[58:61]
	v_mfma_f32_16x16x32_bf16 v[62:65], v[164:167], v[148:151], v[62:65]
	s_waitcnt vmcnt(6) lgkmcnt(0)
	s_barrier
	v_mfma_f32_16x16x32_bf16 v[2:5], v[184:187], v[168:171], v[2:5]
	ds_read_b128 v[136:139], v224 offset:0
	v_mfma_f32_16x16x32_bf16 v[6:9], v[188:191], v[168:171], v[6:9]
	ds_read_b128 v[140:143], v224 offset:2048
	v_mfma_f32_16x16x32_bf16 v[10:13], v[192:195], v[168:171], v[10:13]
	ds_read_b128 v[144:147], v224 offset:4096
	v_mfma_f32_16x16x32_bf16 v[14:17], v[196:199], v[168:171], v[14:17]
	ds_read_b128 v[148:151], v224 offset:6144
	v_mfma_f32_16x16x32_bf16 v[18:21], v[184:187], v[172:175], v[18:21]
	ds_read_b128 v[152:155], v232 offset:0
	v_mfma_f32_16x16x32_bf16 v[22:25], v[188:191], v[172:175], v[22:25]
	ds_read_b128 v[156:159], v232 offset:2048
	v_mfma_f32_16x16x32_bf16 v[26:29], v[192:195], v[172:175], v[26:29]
	ds_read_b128 v[160:163], v232 offset:4096
	v_mfma_f32_16x16x32_bf16 v[30:33], v[196:199], v[172:175], v[30:33]
	ds_read_b128 v[164:167], v232 offset:6144
	s_add_u32 m0, s8, 0xc000
	v_mfma_f32_16x16x32_bf16 v[34:37], v[184:187], v[176:179], v[34:37]
	global_load_lds_dwordx4 v200, s[4:5]
	s_add_u32 m0, s8, 0xc400
	v_mfma_f32_16x16x32_bf16 v[38:41], v[188:191], v[176:179], v[38:41]
	global_load_lds_dwordx4 v201, s[4:5]
	s_add_u32 m0, s8, 0xc800
	v_mfma_f32_16x16x32_bf16 v[42:45], v[192:195], v[176:179], v[42:45]
	global_load_lds_dwordx4 v202, s[4:5]
	s_add_u32 m0, s8, 0xcc00
	v_mfma_f32_16x16x32_bf16 v[46:49], v[196:199], v[176:179], v[46:49]
	global_load_lds_dwordx4 v203, s[4:5]
	s_add_u32 m0, s9, 0xc000
	v_mfma_f32_16x16x32_bf16 v[50:53], v[184:187], v[180:183], v[50:53]
	global_load_lds_dwordx4 v204, s[6:7]
	s_add_u32 m0, s9, 0xc400
	v_mfma_f32_16x16x32_bf16 v[54:57], v[188:191], v[180:183], v[54:57]
	global_load_lds_dwordx4 v205, s[6:7]
	v_mfma_f32_16x16x32_bf16 v[58:61], v[192:195], v[180:183], v[58:61]
	s_add_u32 s4, s4, 0x80
	s_addc_u32 s5, s5, 0
	v_mfma_f32_16x16x32_bf16 v[62:65], v[196:199], v[180:183], v[62:65]
	s_add_u32 s6, s6, 0x80
	s_addc_u32 s7, s7, 0
	s_waitcnt lgkmcnt(0)
	v_mfma_f32_16x16x32_bf16 v[2:5], v[152:155], v[136:139], v[2:5]
	ds_read_b128 v[168:171], v229 offset:0
	v_mfma_f32_16x16x32_bf16 v[6:9], v[156:159], v[136:139], v[6:9]
	ds_read_b128 v[172:175], v229 offset:2048
	v_mfma_f32_16x16x32_bf16 v[10:13], v[160:163], v[136:139], v[10:13]
	ds_read_b128 v[176:179], v229 offset:4096
	v_mfma_f32_16x16x32_bf16 v[14:17], v[164:167], v[136:139], v[14:17]
	ds_read_b128 v[180:183], v229 offset:6144
	v_mfma_f32_16x16x32_bf16 v[18:21], v[152:155], v[140:143], v[18:21]
	ds_read_b128 v[184:187], v235 offset:0
	v_mfma_f32_16x16x32_bf16 v[22:25], v[156:159], v[140:143], v[22:25]
	ds_read_b128 v[188:191], v235 offset:2048
	v_mfma_f32_16x16x32_bf16 v[26:29], v[160:163], v[140:143], v[26:29]
	ds_read_b128 v[192:195], v235 offset:4096
	v_mfma_f32_16x16x32_bf16 v[30:33], v[164:167], v[140:143], v[30:33]
	ds_read_b128 v[196:199], v235 offset:6144
	v_mfma_f32_16x16x32_bf16 v[34:37], v[152:155], v[144:147], v[34:37]
	v_mfma_f32_16x16x32_bf16 v[38:41], v[156:159], v[144:147], v[38:41]
	v_mfma_f32_16x16x32_bf16 v[42:45], v[160:163], v[144:147], v[42:45]
	v_mfma_f32_16x16x32_bf16 v[46:49], v[164:167], v[144:147], v[46:49]
	v_mfma_f32_16x16x32_bf16 v[50:53], v[152:155], v[148:151], v[50:53]
	v_mfma_f32_16x16x32_bf16 v[54:57], v[156:159], v[148:151], v[54:57]
	v_mfma_f32_16x16x32_bf16 v[58:61], v[160:163], v[148:151], v[58:61]
	v_mfma_f32_16x16x32_bf16 v[62:65], v[164:167], v[148:151], v[62:65]
	s_waitcnt vmcnt(6) lgkmcnt(0)
	s_barrier
	v_mfma_f32_16x16x32_bf16 v[2:5], v[184:187], v[168:171], v[2:5]
	ds_read_b128 v[136:139], v218 offset:0
	v_mfma_f32_16x16x32_bf16 v[6:9], v[188:191], v[168:171], v[6:9]
	ds_read_b128 v[140:143], v218 offset:2048
	v_mfma_f32_16x16x32_bf16 v[10:13], v[192:195], v[168:171], v[10:13]
	ds_read_b128 v[144:147], v218 offset:4096
	v_mfma_f32_16x16x32_bf16 v[14:17], v[196:199], v[168:171], v[14:17]
	ds_read_b128 v[148:151], v218 offset:6144
	v_mfma_f32_16x16x32_bf16 v[18:21], v[184:187], v[172:175], v[18:21]
	ds_read_b128 v[152:155], v230 offset:0
	v_mfma_f32_16x16x32_bf16 v[22:25], v[188:191], v[172:175], v[22:25]
	ds_read_b128 v[156:159], v230 offset:2048
	v_mfma_f32_16x16x32_bf16 v[26:29], v[192:195], v[172:175], v[26:29]
	ds_read_b128 v[160:163], v230 offset:4096
	v_mfma_f32_16x16x32_bf16 v[30:33], v[196:199], v[172:175], v[30:33]
	ds_read_b128 v[164:167], v230 offset:6144
	s_add_u32 m0, s8, 0x18000
	v_mfma_f32_16x16x32_bf16 v[34:37], v[184:187], v[176:179], v[34:37]
	global_load_lds_dwordx4 v200, s[4:5]
	s_add_u32 m0, s8, 0x18400
	v_mfma_f32_16x16x32_bf16 v[38:41], v[188:191], v[176:179], v[38:41]
	global_load_lds_dwordx4 v201, s[4:5]
	s_add_u32 m0, s8, 0x18800
	v_mfma_f32_16x16x32_bf16 v[42:45], v[192:195], v[176:179], v[42:45]
	global_load_lds_dwordx4 v202, s[4:5]
	s_add_u32 m0, s8, 0x18c00
	v_mfma_f32_16x16x32_bf16 v[46:49], v[196:199], v[176:179], v[46:49]
	global_load_lds_dwordx4 v203, s[4:5]
	s_add_u32 m0, s9, 0x18000
	v_mfma_f32_16x16x32_bf16 v[50:53], v[184:187], v[180:183], v[50:53]
	global_load_lds_dwordx4 v204, s[6:7]
	s_add_u32 m0, s9, 0x18400
	v_mfma_f32_16x16x32_bf16 v[54:57], v[188:191], v[180:183], v[54:57]
	global_load_lds_dwordx4 v205, s[6:7]
	v_mfma_f32_16x16x32_bf16 v[58:61], v[192:195], v[180:183], v[58:61]
	s_add_u32 s4, s4, 0x80
	s_addc_u32 s5, s5, 0
	v_mfma_f32_16x16x32_bf16 v[62:65], v[196:199], v[180:183], v[62:65]
	s_add_u32 s6, s6, 0x80
	s_addc_u32 s7, s7, 0
	s_waitcnt lgkmcnt(0)
	v_mfma_f32_16x16x32_bf16 v[2:5], v[152:155], v[136:139], v[2:5]
	ds_read_b128 v[168:171], v225 offset:0
	v_mfma_f32_16x16x32_bf16 v[6:9], v[156:159], v[136:139], v[6:9]
	ds_read_b128 v[172:175], v225 offset:2048
	v_mfma_f32_16x16x32_bf16 v[10:13], v[160:163], v[136:139], v[10:13]
	ds_read_b128 v[176:179], v225 offset:4096
	v_mfma_f32_16x16x32_bf16 v[14:17], v[164:167], v[136:139], v[14:17]
	ds_read_b128 v[180:183], v225 offset:6144
	v_mfma_f32_16x16x32_bf16 v[18:21], v[152:155], v[140:143], v[18:21]
	ds_read_b128 v[184:187], v233 offset:0
	v_mfma_f32_16x16x32_bf16 v[22:25], v[156:159], v[140:143], v[22:25]
	ds_read_b128 v[188:191], v233 offset:2048
	v_mfma_f32_16x16x32_bf16 v[26:29], v[160:163], v[140:143], v[26:29]
	ds_read_b128 v[192:195], v233 offset:4096
	v_mfma_f32_16x16x32_bf16 v[30:33], v[164:167], v[140:143], v[30:33]
	ds_read_b128 v[196:199], v233 offset:6144
	v_mfma_f32_16x16x32_bf16 v[34:37], v[152:155], v[144:147], v[34:37]
	v_mfma_f32_16x16x32_bf16 v[38:41], v[156:159], v[144:147], v[38:41]
	v_mfma_f32_16x16x32_bf16 v[42:45], v[160:163], v[144:147], v[42:45]
	v_mfma_f32_16x16x32_bf16 v[46:49], v[164:167], v[144:147], v[46:49]
	v_mfma_f32_16x16x32_bf16 v[50:53], v[152:155], v[148:151], v[50:53]
	v_mfma_f32_16x16x32_bf16 v[54:57], v[156:159], v[148:151], v[54:57]
	v_mfma_f32_16x16x32_bf16 v[58:61], v[160:163], v[148:151], v[58:61]
	v_mfma_f32_16x16x32_bf16 v[62:65], v[164:167], v[148:151], v[62:65]
	s_waitcnt vmcnt(6) lgkmcnt(0)
	s_barrier
	v_mfma_f32_16x16x32_bf16 v[2:5], v[184:187], v[168:171], v[2:5]
	ds_read_b128 v[136:139], v219 offset:0
	v_mfma_f32_16x16x32_bf16 v[6:9], v[188:191], v[168:171], v[6:9]
	ds_read_b128 v[140:143], v219 offset:2048
	v_mfma_f32_16x16x32_bf16 v[10:13], v[192:195], v[168:171], v[10:13]
	ds_read_b128 v[144:147], v219 offset:4096
	v_mfma_f32_16x16x32_bf16 v[14:17], v[196:199], v[168:171], v[14:17]
	ds_read_b128 v[148:151], v219 offset:6144
	v_mfma_f32_16x16x32_bf16 v[18:21], v[184:187], v[172:175], v[18:21]
	ds_read_b128 v[152:155], v231 offset:0
	v_mfma_f32_16x16x32_bf16 v[22:25], v[188:191], v[172:175], v[22:25]
	ds_read_b128 v[156:159], v231 offset:2048
	v_mfma_f32_16x16x32_bf16 v[26:29], v[192:195], v[172:175], v[26:29]
	ds_read_b128 v[160:163], v231 offset:4096
	v_mfma_f32_16x16x32_bf16 v[30:33], v[196:199], v[172:175], v[30:33]
	ds_read_b128 v[164:167], v231 offset:6144
	s_mov_b32 m0, s8
	v_mfma_f32_16x16x32_bf16 v[34:37], v[184:187], v[176:179], v[34:37]
	global_load_lds_dwordx4 v200, s[4:5]
	s_add_u32 m0, s8, 0x400
	v_mfma_f32_16x16x32_bf16 v[38:41], v[188:191], v[176:179], v[38:41]
	global_load_lds_dwordx4 v201, s[4:5]
	s_add_u32 m0, s8, 0x800
	v_mfma_f32_16x16x32_bf16 v[42:45], v[192:195], v[176:179], v[42:45]
	global_load_lds_dwordx4 v202, s[4:5]
	s_add_u32 m0, s8, 0xc00
	v_mfma_f32_16x16x32_bf16 v[46:49], v[196:199], v[176:179], v[46:49]
	global_load_lds_dwordx4 v203, s[4:5]
	s_mov_b32 m0, s9
	v_mfma_f32_16x16x32_bf16 v[50:53], v[184:187], v[180:183], v[50:53]
	global_load_lds_dwordx4 v204, s[6:7]
	s_add_u32 m0, s9, 0x400
	v_mfma_f32_16x16x32_bf16 v[54:57], v[188:191], v[180:183], v[54:57]
	global_load_lds_dwordx4 v205, s[6:7]
	v_mfma_f32_16x16x32_bf16 v[58:61], v[192:195], v[180:183], v[58:61]
	s_add_u32 s4, s4, 0x80
	s_addc_u32 s5, s5, 0
	v_mfma_f32_16x16x32_bf16 v[62:65], v[196:199], v[180:183], v[62:65]
	s_add_u32 s6, s6, 0x80
	s_addc_u32 s7, s7, 0
	s_waitcnt lgkmcnt(0)
	v_mfma_f32_16x16x32_bf16 v[2:5], v[152:155], v[136:139], v[2:5]
	ds_read_b128 v[168:171], v228 offset:0
	v_mfma_f32_16x16x32_bf16 v[6:9], v[156:159], v[136:139], v[6:9]
	ds_read_b128 v[172:175], v228 offset:2048
	v_mfma_f32_16x16x32_bf16 v[10:13], v[160:163], v[136:139], v[10:13]
	ds_read_b128 v[176:179], v228 offset:4096
	v_mfma_f32_16x16x32_bf16 v[14:17], v[164:167], v[136:139], v[14:17]
	ds_read_b128 v[180:183], v228 offset:6144
	v_mfma_f32_16x16x32_bf16 v[18:21], v[152:155], v[140:143], v[18:21]
	ds_read_b128 v[184:187], v234 offset:0
	v_mfma_f32_16x16x32_bf16 v[22:25], v[156:159], v[140:143], v[22:25]
	ds_read_b128 v[188:191], v234 offset:2048
	v_mfma_f32_16x16x32_bf16 v[26:29], v[160:163], v[140:143], v[26:29]
	ds_read_b128 v[192:195], v234 offset:4096
	v_mfma_f32_16x16x32_bf16 v[30:33], v[164:167], v[140:143], v[30:33]
	ds_read_b128 v[196:199], v234 offset:6144
	v_mfma_f32_16x16x32_bf16 v[34:37], v[152:155], v[144:147], v[34:37]
	v_mfma_f32_16x16x32_bf16 v[38:41], v[156:159], v[144:147], v[38:41]
	v_mfma_f32_16x16x32_bf16 v[42:45], v[160:163], v[144:147], v[42:45]
	v_mfma_f32_16x16x32_bf16 v[46:49], v[164:167], v[144:147], v[46:49]
	v_mfma_f32_16x16x32_bf16 v[50:53], v[152:155], v[148:151], v[50:53]
	v_mfma_f32_16x16x32_bf16 v[54:57], v[156:159], v[148:151], v[54:57]
	v_mfma_f32_16x16x32_bf16 v[58:61], v[160:163], v[148:151], v[58:61]
	v_mfma_f32_16x16x32_bf16 v[62:65], v[164:167], v[148:151], v[62:65]
	s_waitcnt vmcnt(6) lgkmcnt(0)
	s_barrier
	v_mfma_f32_16x16x32_bf16 v[2:5], v[184:187], v[168:171], v[2:5]
	ds_read_b128 v[136:139], v224 offset:0
	v_mfma_f32_16x16x32_bf16 v[6:9], v[188:191], v[168:171], v[6:9]
	ds_read_b128 v[140:143], v224 offset:2048
	v_mfma_f32_16x16x32_bf16 v[10:13], v[192:195], v[168:171], v[10:13]
	ds_read_b128 v[144:147], v224 offset:4096
	v_mfma_f32_16x16x32_bf16 v[14:17], v[196:199], v[168:171], v[14:17]
	ds_read_b128 v[148:151], v224 offset:6144
	v_mfma_f32_16x16x32_bf16 v[18:21], v[184:187], v[172:175], v[18:21]
	ds_read_b128 v[152:155], v232 offset:0
	v_mfma_f32_16x16x32_bf16 v[22:25], v[188:191], v[172:175], v[22:25]
	ds_read_b128 v[156:159], v232 offset:2048
	v_mfma_f32_16x16x32_bf16 v[26:29], v[192:195], v[172:175], v[26:29]
	ds_read_b128 v[160:163], v232 offset:4096
	v_mfma_f32_16x16x32_bf16 v[30:33], v[196:199], v[172:175], v[30:33]
	ds_read_b128 v[164:167], v232 offset:6144
	s_add_u32 m0, s8, 0xc000
	v_mfma_f32_16x16x32_bf16 v[34:37], v[184:187], v[176:179], v[34:37]
	global_load_lds_dwordx4 v200, s[4:5]
	s_add_u32 m0, s8, 0xc400
	v_mfma_f32_16x16x32_bf16 v[38:41], v[188:191], v[176:179], v[38:41]
	global_load_lds_dwordx4 v201, s[4:5]
	s_add_u32 m0, s8, 0xc800
	v_mfma_f32_16x16x32_bf16 v[42:45], v[192:195], v[176:179], v[42:45]
	global_load_lds_dwordx4 v202, s[4:5]
	s_add_u32 m0, s8, 0xcc00
	v_mfma_f32_16x16x32_bf16 v[46:49], v[196:199], v[176:179], v[46:49]
	global_load_lds_dwordx4 v203, s[4:5]
	s_add_u32 m0, s9, 0xc000
	v_mfma_f32_16x16x32_bf16 v[50:53], v[184:187], v[180:183], v[50:53]
	global_load_lds_dwordx4 v204, s[6:7]
	s_add_u32 m0, s9, 0xc400
	v_mfma_f32_16x16x32_bf16 v[54:57], v[188:191], v[180:183], v[54:57]
	global_load_lds_dwordx4 v205, s[6:7]
	v_mfma_f32_16x16x32_bf16 v[58:61], v[192:195], v[180:183], v[58:61]
	s_add_u32 s4, s4, 0x80
	s_addc_u32 s5, s5, 0
	v_mfma_f32_16x16x32_bf16 v[62:65], v[196:199], v[180:183], v[62:65]
	s_add_u32 s6, s6, 0x80
	s_addc_u32 s7, s7, 0
	s_waitcnt lgkmcnt(0)
	v_mfma_f32_16x16x32_bf16 v[2:5], v[152:155], v[136:139], v[2:5]
	ds_read_b128 v[168:171], v229 offset:0
	v_mfma_f32_16x16x32_bf16 v[6:9], v[156:159], v[136:139], v[6:9]
	ds_read_b128 v[172:175], v229 offset:2048
	v_mfma_f32_16x16x32_bf16 v[10:13], v[160:163], v[136:139], v[10:13]
	ds_read_b128 v[176:179], v229 offset:4096
	v_mfma_f32_16x16x32_bf16 v[14:17], v[164:167], v[136:139], v[14:17]
	ds_read_b128 v[180:183], v229 offset:6144
	v_mfma_f32_16x16x32_bf16 v[18:21], v[152:155], v[140:143], v[18:21]
	ds_read_b128 v[184:187], v235 offset:0
	v_mfma_f32_16x16x32_bf16 v[22:25], v[156:159], v[140:143], v[22:25]
	ds_read_b128 v[188:191], v235 offset:2048
	v_mfma_f32_16x16x32_bf16 v[26:29], v[160:163], v[140:143], v[26:29]
	ds_read_b128 v[192:195], v235 offset:4096
	v_mfma_f32_16x16x32_bf16 v[30:33], v[164:167], v[140:143], v[30:33]
	ds_read_b128 v[196:199], v235 offset:6144
	v_mfma_f32_16x16x32_bf16 v[34:37], v[152:155], v[144:147], v[34:37]
	v_mfma_f32_16x16x32_bf16 v[38:41], v[156:159], v[144:147], v[38:41]
	v_mfma_f32_16x16x32_bf16 v[42:45], v[160:163], v[144:147], v[42:45]
	v_mfma_f32_16x16x32_bf16 v[46:49], v[164:167], v[144:147], v[46:49]
	v_mfma_f32_16x16x32_bf16 v[50:53], v[152:155], v[148:151], v[50:53]
	v_mfma_f32_16x16x32_bf16 v[54:57], v[156:159], v[148:151], v[54:57]
	v_mfma_f32_16x16x32_bf16 v[58:61], v[160:163], v[148:151], v[58:61]
	v_mfma_f32_16x16x32_bf16 v[62:65], v[164:167], v[148:151], v[62:65]
	s_waitcnt vmcnt(6) lgkmcnt(0)
	s_barrier
	v_mfma_f32_16x16x32_bf16 v[2:5], v[184:187], v[168:171], v[2:5]
	ds_read_b128 v[136:139], v218 offset:0
	v_mfma_f32_16x16x32_bf16 v[6:9], v[188:191], v[168:171], v[6:9]
	ds_read_b128 v[140:143], v218 offset:2048
	v_mfma_f32_16x16x32_bf16 v[10:13], v[192:195], v[168:171], v[10:13]
	ds_read_b128 v[144:147], v218 offset:4096
	v_mfma_f32_16x16x32_bf16 v[14:17], v[196:199], v[168:171], v[14:17]
	ds_read_b128 v[148:151], v218 offset:6144
	v_mfma_f32_16x16x32_bf16 v[18:21], v[184:187], v[172:175], v[18:21]
	ds_read_b128 v[152:155], v230 offset:0
	v_mfma_f32_16x16x32_bf16 v[22:25], v[188:191], v[172:175], v[22:25]
	ds_read_b128 v[156:159], v230 offset:2048
	v_mfma_f32_16x16x32_bf16 v[26:29], v[192:195], v[172:175], v[26:29]
	ds_read_b128 v[160:163], v230 offset:4096
	v_mfma_f32_16x16x32_bf16 v[30:33], v[196:199], v[172:175], v[30:33]
	ds_read_b128 v[164:167], v230 offset:6144
	s_add_u32 m0, s8, 0x18000
	v_mfma_f32_16x16x32_bf16 v[34:37], v[184:187], v[176:179], v[34:37]
	global_load_lds_dwordx4 v200, s[4:5]
	s_add_u32 m0, s8, 0x18400
	v_mfma_f32_16x16x32_bf16 v[38:41], v[188:191], v[176:179], v[38:41]
	global_load_lds_dwordx4 v201, s[4:5]
	s_add_u32 m0, s8, 0x18800
	v_mfma_f32_16x16x32_bf16 v[42:45], v[192:195], v[176:179], v[42:45]
	global_load_lds_dwordx4 v202, s[4:5]
	s_add_u32 m0, s8, 0x18c00
	v_mfma_f32_16x16x32_bf16 v[46:49], v[196:199], v[176:179], v[46:49]
	global_load_lds_dwordx4 v203, s[4:5]
	s_add_u32 m0, s9, 0x18000
	v_mfma_f32_16x16x32_bf16 v[50:53], v[184:187], v[180:183], v[50:53]
	global_load_lds_dwordx4 v204, s[6:7]
	s_add_u32 m0, s9, 0x18400
	v_mfma_f32_16x16x32_bf16 v[54:57], v[188:191], v[180:183], v[54:57]
	global_load_lds_dwordx4 v205, s[6:7]
	v_mfma_f32_16x16x32_bf16 v[58:61], v[192:195], v[180:183], v[58:61]
	s_add_u32 s4, s4, 0x80
	s_addc_u32 s5, s5, 0
	v_mfma_f32_16x16x32_bf16 v[62:65], v[196:199], v[180:183], v[62:65]
	s_add_u32 s6, s6, 0x80
	s_addc_u32 s7, s7, 0
	s_waitcnt lgkmcnt(0)
	v_mfma_f32_16x16x32_bf16 v[2:5], v[152:155], v[136:139], v[2:5]
	ds_read_b128 v[168:171], v225 offset:0
	v_mfma_f32_16x16x32_bf16 v[6:9], v[156:159], v[136:139], v[6:9]
	ds_read_b128 v[172:175], v225 offset:2048
	v_mfma_f32_16x16x32_bf16 v[10:13], v[160:163], v[136:139], v[10:13]
	ds_read_b128 v[176:179], v225 offset:4096
	v_mfma_f32_16x16x32_bf16 v[14:17], v[164:167], v[136:139], v[14:17]
	ds_read_b128 v[180:183], v225 offset:6144
	v_mfma_f32_16x16x32_bf16 v[18:21], v[152:155], v[140:143], v[18:21]
	ds_read_b128 v[184:187], v233 offset:0
	v_mfma_f32_16x16x32_bf16 v[22:25], v[156:159], v[140:143], v[22:25]
	ds_read_b128 v[188:191], v233 offset:2048
	v_mfma_f32_16x16x32_bf16 v[26:29], v[160:163], v[140:143], v[26:29]
	ds_read_b128 v[192:195], v233 offset:4096
	v_mfma_f32_16x16x32_bf16 v[30:33], v[164:167], v[140:143], v[30:33]
	ds_read_b128 v[196:199], v233 offset:6144
	v_mfma_f32_16x16x32_bf16 v[34:37], v[152:155], v[144:147], v[34:37]
	v_mfma_f32_16x16x32_bf16 v[38:41], v[156:159], v[144:147], v[38:41]
	v_mfma_f32_16x16x32_bf16 v[42:45], v[160:163], v[144:147], v[42:45]
	v_mfma_f32_16x16x32_bf16 v[46:49], v[164:167], v[144:147], v[46:49]
	v_mfma_f32_16x16x32_bf16 v[50:53], v[152:155], v[148:151], v[50:53]
	v_mfma_f32_16x16x32_bf16 v[54:57], v[156:159], v[148:151], v[54:57]
	v_mfma_f32_16x16x32_bf16 v[58:61], v[160:163], v[148:151], v[58:61]
	v_mfma_f32_16x16x32_bf16 v[62:65], v[164:167], v[148:151], v[62:65]
	s_waitcnt vmcnt(6) lgkmcnt(0)
	s_barrier
	v_mfma_f32_16x16x32_bf16 v[2:5], v[184:187], v[168:171], v[2:5]
	ds_read_b128 v[136:139], v219 offset:0
	v_mfma_f32_16x16x32_bf16 v[6:9], v[188:191], v[168:171], v[6:9]
	ds_read_b128 v[140:143], v219 offset:2048
	v_mfma_f32_16x16x32_bf16 v[10:13], v[192:195], v[168:171], v[10:13]
	ds_read_b128 v[144:147], v219 offset:4096
	v_mfma_f32_16x16x32_bf16 v[14:17], v[196:199], v[168:171], v[14:17]
	ds_read_b128 v[148:151], v219 offset:6144
	v_mfma_f32_16x16x32_bf16 v[18:21], v[184:187], v[172:175], v[18:21]
	ds_read_b128 v[152:155], v231 offset:0
	v_mfma_f32_16x16x32_bf16 v[22:25], v[188:191], v[172:175], v[22:25]
	ds_read_b128 v[156:159], v231 offset:2048
	v_mfma_f32_16x16x32_bf16 v[26:29], v[192:195], v[172:175], v[26:29]
	ds_read_b128 v[160:163], v231 offset:4096
	v_mfma_f32_16x16x32_bf16 v[30:33], v[196:199], v[172:175], v[30:33]
	ds_read_b128 v[164:167], v231 offset:6144
	s_mov_b32 m0, s8
	v_mfma_f32_16x16x32_bf16 v[34:37], v[184:187], v[176:179], v[34:37]
	global_load_lds_dwordx4 v200, s[4:5]
	s_add_u32 m0, s8, 0x400
	v_mfma_f32_16x16x32_bf16 v[38:41], v[188:191], v[176:179], v[38:41]
	global_load_lds_dwordx4 v201, s[4:5]
	s_add_u32 m0, s8, 0x800
	v_mfma_f32_16x16x32_bf16 v[42:45], v[192:195], v[176:179], v[42:45]
	global_load_lds_dwordx4 v202, s[4:5]
	s_add_u32 m0, s8, 0xc00
	v_mfma_f32_16x16x32_bf16 v[46:49], v[196:199], v[176:179], v[46:49]
	global_load_lds_dwordx4 v203, s[4:5]
	s_mov_b32 m0, s9
	v_mfma_f32_16x16x32_bf16 v[50:53], v[184:187], v[180:183], v[50:53]
	global_load_lds_dwordx4 v204, s[6:7]
	s_add_u32 m0, s9, 0x400
	v_mfma_f32_16x16x32_bf16 v[54:57], v[188:191], v[180:183], v[54:57]
	global_load_lds_dwordx4 v205, s[6:7]
	v_mfma_f32_16x16x32_bf16 v[58:61], v[192:195], v[180:183], v[58:61]
	s_sub_u32 s4, s4, 0x780
	s_subb_u32 s5, s5, 0
	v_mfma_f32_16x16x32_bf16 v[62:65], v[196:199], v[180:183], v[62:65]
	s_add_u32 s6, s6, 0x3f880
	s_addc_u32 s7, s7, 0
	s_waitcnt lgkmcnt(0)
	v_mfma_f32_16x16x32_bf16 v[2:5], v[152:155], v[136:139], v[2:5]
	ds_read_b128 v[168:171], v228 offset:0
	v_mfma_f32_16x16x32_bf16 v[6:9], v[156:159], v[136:139], v[6:9]
	ds_read_b128 v[172:175], v228 offset:2048
	v_mfma_f32_16x16x32_bf16 v[10:13], v[160:163], v[136:139], v[10:13]
	ds_read_b128 v[176:179], v228 offset:4096
	v_mfma_f32_16x16x32_bf16 v[14:17], v[164:167], v[136:139], v[14:17]
	ds_read_b128 v[180:183], v228 offset:6144
	v_mfma_f32_16x16x32_bf16 v[18:21], v[152:155], v[140:143], v[18:21]
	ds_read_b128 v[184:187], v234 offset:0
	v_mfma_f32_16x16x32_bf16 v[22:25], v[156:159], v[140:143], v[22:25]
	ds_read_b128 v[188:191], v234 offset:2048
	v_mfma_f32_16x16x32_bf16 v[26:29], v[160:163], v[140:143], v[26:29]
	ds_read_b128 v[192:195], v234 offset:4096
	v_mfma_f32_16x16x32_bf16 v[30:33], v[164:167], v[140:143], v[30:33]
	ds_read_b128 v[196:199], v234 offset:6144
	v_mfma_f32_16x16x32_bf16 v[34:37], v[152:155], v[144:147], v[34:37]
	v_mfma_f32_16x16x32_bf16 v[38:41], v[156:159], v[144:147], v[38:41]
	v_mfma_f32_16x16x32_bf16 v[42:45], v[160:163], v[144:147], v[42:45]
	v_mfma_f32_16x16x32_bf16 v[46:49], v[164:167], v[144:147], v[46:49]
	v_mfma_f32_16x16x32_bf16 v[50:53], v[152:155], v[148:151], v[50:53]
	v_mfma_f32_16x16x32_bf16 v[54:57], v[156:159], v[148:151], v[54:57]
	v_mfma_f32_16x16x32_bf16 v[58:61], v[160:163], v[148:151], v[58:61]
	v_mfma_f32_16x16x32_bf16 v[62:65], v[164:167], v[148:151], v[62:65]
	s_waitcnt vmcnt(6) lgkmcnt(0)
	s_barrier
	v_mfma_f32_16x16x32_bf16 v[2:5], v[184:187], v[168:171], v[2:5]
	ds_read_b128 v[136:139], v224 offset:0
	v_mfma_f32_16x16x32_bf16 v[6:9], v[188:191], v[168:171], v[6:9]
	ds_read_b128 v[140:143], v224 offset:2048
	v_mfma_f32_16x16x32_bf16 v[10:13], v[192:195], v[168:171], v[10:13]
	ds_read_b128 v[144:147], v224 offset:4096
	v_mfma_f32_16x16x32_bf16 v[14:17], v[196:199], v[168:171], v[14:17]
	ds_read_b128 v[148:151], v224 offset:6144
	v_mfma_f32_16x16x32_bf16 v[18:21], v[184:187], v[172:175], v[18:21]
	ds_read_b128 v[152:155], v232 offset:0
	v_mfma_f32_16x16x32_bf16 v[22:25], v[188:191], v[172:175], v[22:25]
	ds_read_b128 v[156:159], v232 offset:2048
	v_mfma_f32_16x16x32_bf16 v[26:29], v[192:195], v[172:175], v[26:29]
	ds_read_b128 v[160:163], v232 offset:4096
	v_mfma_f32_16x16x32_bf16 v[30:33], v[196:199], v[172:175], v[30:33]
	ds_read_b128 v[164:167], v232 offset:6144
	s_add_u32 m0, s8, 0xc000
	v_mfma_f32_16x16x32_bf16 v[34:37], v[184:187], v[176:179], v[34:37]
	global_load_lds_dwordx4 v200, s[4:5]
	s_add_u32 m0, s8, 0xc400
	v_mfma_f32_16x16x32_bf16 v[38:41], v[188:191], v[176:179], v[38:41]
	global_load_lds_dwordx4 v201, s[4:5]
	s_add_u32 m0, s8, 0xc800
	v_mfma_f32_16x16x32_bf16 v[42:45], v[192:195], v[176:179], v[42:45]
	global_load_lds_dwordx4 v202, s[4:5]
	s_add_u32 m0, s8, 0xcc00
	v_mfma_f32_16x16x32_bf16 v[46:49], v[196:199], v[176:179], v[46:49]
	global_load_lds_dwordx4 v203, s[4:5]
	s_add_u32 m0, s9, 0xc000
	v_mfma_f32_16x16x32_bf16 v[50:53], v[184:187], v[180:183], v[50:53]
	global_load_lds_dwordx4 v204, s[6:7]
	s_add_u32 m0, s9, 0xc400
	v_mfma_f32_16x16x32_bf16 v[54:57], v[188:191], v[180:183], v[54:57]
	global_load_lds_dwordx4 v205, s[6:7]
	v_mfma_f32_16x16x32_bf16 v[58:61], v[192:195], v[180:183], v[58:61]
	s_add_u32 s4, s4, 0x80
	s_addc_u32 s5, s5, 0
	v_mfma_f32_16x16x32_bf16 v[62:65], v[196:199], v[180:183], v[62:65]
	s_add_u32 s6, s6, 0x80
	s_addc_u32 s7, s7, 0
	s_waitcnt lgkmcnt(0)
	v_mfma_f32_16x16x32_bf16 v[2:5], v[152:155], v[136:139], v[2:5]
	ds_read_b128 v[168:171], v229 offset:0
	v_mfma_f32_16x16x32_bf16 v[6:9], v[156:159], v[136:139], v[6:9]
	ds_read_b128 v[172:175], v229 offset:2048
	v_mfma_f32_16x16x32_bf16 v[10:13], v[160:163], v[136:139], v[10:13]
	ds_read_b128 v[176:179], v229 offset:4096
	v_mfma_f32_16x16x32_bf16 v[14:17], v[164:167], v[136:139], v[14:17]
	ds_read_b128 v[180:183], v229 offset:6144
	v_mfma_f32_16x16x32_bf16 v[18:21], v[152:155], v[140:143], v[18:21]
	ds_read_b128 v[184:187], v235 offset:0
	v_mfma_f32_16x16x32_bf16 v[22:25], v[156:159], v[140:143], v[22:25]
	ds_read_b128 v[188:191], v235 offset:2048
	v_mfma_f32_16x16x32_bf16 v[26:29], v[160:163], v[140:143], v[26:29]
	ds_read_b128 v[192:195], v235 offset:4096
	v_mfma_f32_16x16x32_bf16 v[30:33], v[164:167], v[140:143], v[30:33]
	ds_read_b128 v[196:199], v235 offset:6144
	v_mfma_f32_16x16x32_bf16 v[34:37], v[152:155], v[144:147], v[34:37]
	v_mfma_f32_16x16x32_bf16 v[38:41], v[156:159], v[144:147], v[38:41]
	v_mfma_f32_16x16x32_bf16 v[42:45], v[160:163], v[144:147], v[42:45]
	v_mfma_f32_16x16x32_bf16 v[46:49], v[164:167], v[144:147], v[46:49]
	v_mfma_f32_16x16x32_bf16 v[50:53], v[152:155], v[148:151], v[50:53]
	v_mfma_f32_16x16x32_bf16 v[54:57], v[156:159], v[148:151], v[54:57]
	v_mfma_f32_16x16x32_bf16 v[58:61], v[160:163], v[148:151], v[58:61]
	v_mfma_f32_16x16x32_bf16 v[62:65], v[164:167], v[148:151], v[62:65]
	s_waitcnt vmcnt(6) lgkmcnt(0)
	s_barrier
	v_mfma_f32_16x16x32_bf16 v[2:5], v[184:187], v[168:171], v[2:5]
	ds_read_b128 v[136:139], v218 offset:0
	v_mfma_f32_16x16x32_bf16 v[6:9], v[188:191], v[168:171], v[6:9]
	ds_read_b128 v[140:143], v218 offset:2048
	v_mfma_f32_16x16x32_bf16 v[10:13], v[192:195], v[168:171], v[10:13]
	ds_read_b128 v[144:147], v218 offset:4096
	v_mfma_f32_16x16x32_bf16 v[14:17], v[196:199], v[168:171], v[14:17]
	ds_read_b128 v[148:151], v218 offset:6144
	v_mfma_f32_16x16x32_bf16 v[18:21], v[184:187], v[172:175], v[18:21]
	ds_read_b128 v[152:155], v230 offset:0
	v_mfma_f32_16x16x32_bf16 v[22:25], v[188:191], v[172:175], v[22:25]
	ds_read_b128 v[156:159], v230 offset:2048
	v_mfma_f32_16x16x32_bf16 v[26:29], v[192:195], v[172:175], v[26:29]
	ds_read_b128 v[160:163], v230 offset:4096
	v_mfma_f32_16x16x32_bf16 v[30:33], v[196:199], v[172:175], v[30:33]
	ds_read_b128 v[164:167], v230 offset:6144
	s_add_u32 m0, s8, 0x18000
	v_mfma_f32_16x16x32_bf16 v[34:37], v[184:187], v[176:179], v[34:37]
	global_load_lds_dwordx4 v200, s[4:5]
	s_add_u32 m0, s8, 0x18400
	v_mfma_f32_16x16x32_bf16 v[38:41], v[188:191], v[176:179], v[38:41]
	global_load_lds_dwordx4 v201, s[4:5]
	s_add_u32 m0, s8, 0x18800
	v_mfma_f32_16x16x32_bf16 v[42:45], v[192:195], v[176:179], v[42:45]
	global_load_lds_dwordx4 v202, s[4:5]
	s_add_u32 m0, s8, 0x18c00
	v_mfma_f32_16x16x32_bf16 v[46:49], v[196:199], v[176:179], v[46:49]
	global_load_lds_dwordx4 v203, s[4:5]
	s_add_u32 m0, s9, 0x18000
	v_mfma_f32_16x16x32_bf16 v[50:53], v[184:187], v[180:183], v[50:53]
	global_load_lds_dwordx4 v204, s[6:7]
	s_add_u32 m0, s9, 0x18400
	v_mfma_f32_16x16x32_bf16 v[54:57], v[188:191], v[180:183], v[54:57]
	global_load_lds_dwordx4 v205, s[6:7]
	v_mfma_f32_16x16x32_bf16 v[58:61], v[192:195], v[180:183], v[58:61]
	s_add_u32 s4, s4, 0x80
	s_addc_u32 s5, s5, 0
	v_mfma_f32_16x16x32_bf16 v[62:65], v[196:199], v[180:183], v[62:65]
	s_add_u32 s6, s6, 0x80
	s_addc_u32 s7, s7, 0
	s_waitcnt lgkmcnt(0)
	v_mfma_f32_16x16x32_bf16 v[2:5], v[152:155], v[136:139], v[2:5]
	ds_read_b128 v[168:171], v225 offset:0
	v_mfma_f32_16x16x32_bf16 v[6:9], v[156:159], v[136:139], v[6:9]
	ds_read_b128 v[172:175], v225 offset:2048
	v_mfma_f32_16x16x32_bf16 v[10:13], v[160:163], v[136:139], v[10:13]
	ds_read_b128 v[176:179], v225 offset:4096
	v_mfma_f32_16x16x32_bf16 v[14:17], v[164:167], v[136:139], v[14:17]
	ds_read_b128 v[180:183], v225 offset:6144
	v_mfma_f32_16x16x32_bf16 v[18:21], v[152:155], v[140:143], v[18:21]
	ds_read_b128 v[184:187], v233 offset:0
	v_mfma_f32_16x16x32_bf16 v[22:25], v[156:159], v[140:143], v[22:25]
	ds_read_b128 v[188:191], v233 offset:2048
	v_mfma_f32_16x16x32_bf16 v[26:29], v[160:163], v[140:143], v[26:29]
	ds_read_b128 v[192:195], v233 offset:4096
	v_mfma_f32_16x16x32_bf16 v[30:33], v[164:167], v[140:143], v[30:33]
	ds_read_b128 v[196:199], v233 offset:6144
	v_mfma_f32_16x16x32_bf16 v[34:37], v[152:155], v[144:147], v[34:37]
	v_mfma_f32_16x16x32_bf16 v[38:41], v[156:159], v[144:147], v[38:41]
	v_mfma_f32_16x16x32_bf16 v[42:45], v[160:163], v[144:147], v[42:45]
	v_mfma_f32_16x16x32_bf16 v[46:49], v[164:167], v[144:147], v[46:49]
	v_mfma_f32_16x16x32_bf16 v[50:53], v[152:155], v[148:151], v[50:53]
	v_mfma_f32_16x16x32_bf16 v[54:57], v[156:159], v[148:151], v[54:57]
	v_mfma_f32_16x16x32_bf16 v[58:61], v[160:163], v[148:151], v[58:61]
	v_mfma_f32_16x16x32_bf16 v[62:65], v[164:167], v[148:151], v[62:65]
	s_waitcnt vmcnt(6) lgkmcnt(0)
	s_barrier
	v_mfma_f32_16x16x32_bf16 v[2:5], v[184:187], v[168:171], v[2:5]
	ds_read_b128 v[136:139], v219 offset:0
	v_mfma_f32_16x16x32_bf16 v[6:9], v[188:191], v[168:171], v[6:9]
	ds_read_b128 v[140:143], v219 offset:2048
	v_mfma_f32_16x16x32_bf16 v[10:13], v[192:195], v[168:171], v[10:13]
	ds_read_b128 v[144:147], v219 offset:4096
	v_mfma_f32_16x16x32_bf16 v[14:17], v[196:199], v[168:171], v[14:17]
	ds_read_b128 v[148:151], v219 offset:6144
	v_mfma_f32_16x16x32_bf16 v[18:21], v[184:187], v[172:175], v[18:21]
	ds_read_b128 v[152:155], v231 offset:0
	v_mfma_f32_16x16x32_bf16 v[22:25], v[188:191], v[172:175], v[22:25]
	ds_read_b128 v[156:159], v231 offset:2048
	v_mfma_f32_16x16x32_bf16 v[26:29], v[192:195], v[172:175], v[26:29]
	ds_read_b128 v[160:163], v231 offset:4096
	v_mfma_f32_16x16x32_bf16 v[30:33], v[196:199], v[172:175], v[30:33]
	ds_read_b128 v[164:167], v231 offset:6144
	s_mov_b32 m0, s8
	v_mfma_f32_16x16x32_bf16 v[34:37], v[184:187], v[176:179], v[34:37]
	global_load_lds_dwordx4 v200, s[4:5]
	s_add_u32 m0, s8, 0x400
	v_mfma_f32_16x16x32_bf16 v[38:41], v[188:191], v[176:179], v[38:41]
	global_load_lds_dwordx4 v201, s[4:5]
	s_add_u32 m0, s8, 0x800
	v_mfma_f32_16x16x32_bf16 v[42:45], v[192:195], v[176:179], v[42:45]
	global_load_lds_dwordx4 v202, s[4:5]
	s_add_u32 m0, s8, 0xc00
	v_mfma_f32_16x16x32_bf16 v[46:49], v[196:199], v[176:179], v[46:49]
	global_load_lds_dwordx4 v203, s[4:5]
	s_mov_b32 m0, s9
	v_mfma_f32_16x16x32_bf16 v[50:53], v[184:187], v[180:183], v[50:53]
	global_load_lds_dwordx4 v204, s[6:7]
	s_add_u32 m0, s9, 0x400
	v_mfma_f32_16x16x32_bf16 v[54:57], v[188:191], v[180:183], v[54:57]
	global_load_lds_dwordx4 v205, s[6:7]
	v_mfma_f32_16x16x32_bf16 v[58:61], v[192:195], v[180:183], v[58:61]
	s_add_u32 s4, s4, 0x80
	s_addc_u32 s5, s5, 0
	v_mfma_f32_16x16x32_bf16 v[62:65], v[196:199], v[180:183], v[62:65]
	s_add_u32 s6, s6, 0x80
	s_addc_u32 s7, s7, 0
	s_waitcnt lgkmcnt(0)
	v_mfma_f32_16x16x32_bf16 v[66:69], v[152:155], v[136:139], 0
	ds_read_b128 v[168:171], v228 offset:0
	v_mfma_f32_16x16x32_bf16 v[70:73], v[156:159], v[136:139], 0
	ds_read_b128 v[172:175], v228 offset:2048
	s_add_u32 s10, s28, s13
	s_addc_u32 s11, s29, 0
	v_mfma_f32_16x16x32_bf16 v[74:77], v[160:163], v[136:139], 0
	ds_read_b128 v[176:179], v228 offset:4096
	s_add_u32 s13, s13, 0x10000
	v_mfma_f32_16x16x32_bf16 v[78:81], v[164:167], v[136:139], 0
	ds_read_b128 v[180:183], v228 offset:6144
	v_mul_f32_e32 v2, s12, v2
	v_mfma_f32_16x16x32_bf16 v[82:85], v[152:155], v[140:143], 0
	ds_read_b128 v[184:187], v234 offset:0
	v_mfma_f32_16x16x32_bf16 v[86:89], v[156:159], v[140:143], 0
	ds_read_b128 v[188:191], v234 offset:2048
	v_mul_f32_e32 v3, s12, v3
	v_mfma_f32_16x16x32_bf16 v[90:93], v[160:163], v[140:143], 0
	ds_read_b128 v[192:195], v234 offset:4096
	v_mul_f32_e32 v4, s12, v4
	v_mfma_f32_16x16x32_bf16 v[94:97], v[164:167], v[140:143], 0
	ds_read_b128 v[196:199], v234 offset:6144
	v_mul_f32_e32 v5, s12, v5
	v_mfma_f32_16x16x32_bf16 v[98:101], v[152:155], v[144:147], 0
	v_mfma_f32_16x16x32_bf16 v[102:105], v[156:159], v[144:147], 0
	v_mul_f32_e32 v6, s12, v6
	v_mfma_f32_16x16x32_bf16 v[106:109], v[160:163], v[144:147], 0
	v_mul_f32_e32 v7, s12, v7
	v_mfma_f32_16x16x32_bf16 v[110:113], v[164:167], v[144:147], 0
	v_mul_f32_e32 v8, s12, v8
	v_mfma_f32_16x16x32_bf16 v[114:117], v[152:155], v[148:151], 0
	v_mfma_f32_16x16x32_bf16 v[118:121], v[156:159], v[148:151], 0
	v_mul_f32_e32 v9, s12, v9
	v_mfma_f32_16x16x32_bf16 v[122:125], v[160:163], v[148:151], 0
	v_exp_f32_e32 v2, v2
	v_mfma_f32_16x16x32_bf16 v[126:129], v[164:167], v[148:151], 0
	v_exp_f32_e32 v3, v3
	s_waitcnt vmcnt(6) lgkmcnt(0)
	s_barrier
	v_mfma_f32_16x16x32_bf16 v[66:69], v[184:187], v[168:171], v[66:69]
	ds_read_b128 v[136:139], v224 offset:0
	v_mfma_f32_16x16x32_bf16 v[70:73], v[188:191], v[168:171], v[70:73]
	ds_read_b128 v[140:143], v224 offset:2048
	v_mfma_f32_16x16x32_bf16 v[74:77], v[192:195], v[168:171], v[74:77]
	ds_read_b128 v[144:147], v224 offset:4096
	v_exp_f32_e32 v4, v4
	v_mfma_f32_16x16x32_bf16 v[78:81], v[196:199], v[168:171], v[78:81]
	ds_read_b128 v[148:151], v224 offset:6144
	v_mfma_f32_16x16x32_bf16 v[82:85], v[184:187], v[172:175], v[82:85]
	ds_read_b128 v[152:155], v232 offset:0
	v_exp_f32_e32 v5, v5
	v_mfma_f32_16x16x32_bf16 v[86:89], v[188:191], v[172:175], v[86:89]
	ds_read_b128 v[156:159], v232 offset:2048
	v_mfma_f32_16x16x32_bf16 v[90:93], v[192:195], v[172:175], v[90:93]
	ds_read_b128 v[160:163], v232 offset:4096
	v_exp_f32_e32 v6, v6
	v_mfma_f32_16x16x32_bf16 v[94:97], v[196:199], v[172:175], v[94:97]
	ds_read_b128 v[164:167], v232 offset:6144
	s_add_u32 m0, s8, 0xc000
	v_mfma_f32_16x16x32_bf16 v[98:101], v[184:187], v[176:179], v[98:101]
	global_load_lds_dwordx4 v200, s[4:5]
	s_add_u32 m0, s8, 0xc400
	v_mfma_f32_16x16x32_bf16 v[102:105], v[188:191], v[176:179], v[102:105]
	global_load_lds_dwordx4 v201, s[4:5]
	v_exp_f32_e32 v7, v7
	s_add_u32 m0, s8, 0xc800
	v_mfma_f32_16x16x32_bf16 v[106:109], v[192:195], v[176:179], v[106:109]
	global_load_lds_dwordx4 v202, s[4:5]
	s_add_u32 m0, s8, 0xcc00
	v_mfma_f32_16x16x32_bf16 v[110:113], v[196:199], v[176:179], v[110:113]
	global_load_lds_dwordx4 v203, s[4:5]
	v_exp_f32_e32 v8, v8
	s_add_u32 m0, s9, 0xc000
	v_mfma_f32_16x16x32_bf16 v[114:117], v[184:187], v[180:183], v[114:117]
	global_load_lds_dwordx4 v204, s[6:7]
	s_add_u32 m0, s9, 0xc400
	v_mfma_f32_16x16x32_bf16 v[118:121], v[188:191], v[180:183], v[118:121]
	global_load_lds_dwordx4 v205, s[6:7]
	v_exp_f32_e32 v9, v9
	v_mfma_f32_16x16x32_bf16 v[122:125], v[192:195], v[180:183], v[122:125]
	s_add_u32 s4, s4, 0x80
	s_addc_u32 s5, s5, 0
	v_mfma_f32_16x16x32_bf16 v[126:129], v[196:199], v[180:183], v[126:129]
	s_add_u32 s6, s6, 0x80
	s_addc_u32 s7, s7, 0
	v_add_f32_e32 v2, 1.0, v2
	s_waitcnt lgkmcnt(0)
	v_mfma_f32_16x16x32_bf16 v[66:69], v[152:155], v[136:139], v[66:69]
	ds_read_b128 v[168:171], v229 offset:0
	v_mfma_f32_16x16x32_bf16 v[70:73], v[156:159], v[136:139], v[70:73]
	ds_read_b128 v[172:175], v229 offset:2048
	v_add_f32_e32 v3, 1.0, v3
	v_mfma_f32_16x16x32_bf16 v[74:77], v[160:163], v[136:139], v[74:77]
	ds_read_b128 v[176:179], v229 offset:4096
	v_add_f32_e32 v4, 1.0, v4
	v_mfma_f32_16x16x32_bf16 v[78:81], v[164:167], v[136:139], v[78:81]
	ds_read_b128 v[180:183], v229 offset:6144
	v_add_f32_e32 v5, 1.0, v5
	v_mfma_f32_16x16x32_bf16 v[82:85], v[152:155], v[140:143], v[82:85]
	ds_read_b128 v[184:187], v235 offset:0
	v_mfma_f32_16x16x32_bf16 v[86:89], v[156:159], v[140:143], v[86:89]
	ds_read_b128 v[188:191], v235 offset:2048
	v_add_f32_e32 v6, 1.0, v6
	v_mfma_f32_16x16x32_bf16 v[90:93], v[160:163], v[140:143], v[90:93]
	ds_read_b128 v[192:195], v235 offset:4096
	v_add_f32_e32 v7, 1.0, v7
	v_mfma_f32_16x16x32_bf16 v[94:97], v[164:167], v[140:143], v[94:97]
	ds_read_b128 v[196:199], v235 offset:6144
	v_add_f32_e32 v8, 1.0, v8
	v_mfma_f32_16x16x32_bf16 v[98:101], v[152:155], v[144:147], v[98:101]
	v_mfma_f32_16x16x32_bf16 v[102:105], v[156:159], v[144:147], v[102:105]
	v_add_f32_e32 v9, 1.0, v9
	v_mfma_f32_16x16x32_bf16 v[106:109], v[160:163], v[144:147], v[106:109]
	v_rcp_f32_e32 v2, v2
	v_mfma_f32_16x16x32_bf16 v[110:113], v[164:167], v[144:147], v[110:113]
	v_rcp_f32_e32 v3, v3
	v_mfma_f32_16x16x32_bf16 v[114:117], v[152:155], v[148:151], v[114:117]
	v_mfma_f32_16x16x32_bf16 v[118:121], v[156:159], v[148:151], v[118:121]
	v_rcp_f32_e32 v4, v4
	v_mfma_f32_16x16x32_bf16 v[122:125], v[160:163], v[148:151], v[122:125]
	v_rcp_f32_e32 v5, v5
	v_mfma_f32_16x16x32_bf16 v[126:129], v[164:167], v[148:151], v[126:129]
	v_rcp_f32_e32 v6, v6
	s_waitcnt vmcnt(6) lgkmcnt(0)
	s_barrier
	v_mfma_f32_16x16x32_bf16 v[66:69], v[184:187], v[168:171], v[66:69]
	ds_read_b128 v[136:139], v218 offset:0
	v_mfma_f32_16x16x32_bf16 v[70:73], v[188:191], v[168:171], v[70:73]
	ds_read_b128 v[140:143], v218 offset:2048
	v_mfma_f32_16x16x32_bf16 v[74:77], v[192:195], v[168:171], v[74:77]
	ds_read_b128 v[144:147], v218 offset:4096
	v_rcp_f32_e32 v7, v7
	v_mfma_f32_16x16x32_bf16 v[78:81], v[196:199], v[168:171], v[78:81]
	ds_read_b128 v[148:151], v218 offset:6144
	v_mfma_f32_16x16x32_bf16 v[82:85], v[184:187], v[172:175], v[82:85]
	ds_read_b128 v[152:155], v230 offset:0
	v_rcp_f32_e32 v8, v8
	v_mfma_f32_16x16x32_bf16 v[86:89], v[188:191], v[172:175], v[86:89]
	ds_read_b128 v[156:159], v230 offset:2048
	v_mfma_f32_16x16x32_bf16 v[90:93], v[192:195], v[172:175], v[90:93]
	ds_read_b128 v[160:163], v230 offset:4096
	v_rcp_f32_e32 v9, v9
	v_mfma_f32_16x16x32_bf16 v[94:97], v[196:199], v[172:175], v[94:97]
	ds_read_b128 v[164:167], v230 offset:6144
	s_add_u32 m0, s8, 0x18000
	v_mfma_f32_16x16x32_bf16 v[98:101], v[184:187], v[176:179], v[98:101]
	global_load_lds_dwordx4 v200, s[4:5]
	s_add_u32 m0, s8, 0x18400
	v_mfma_f32_16x16x32_bf16 v[102:105], v[188:191], v[176:179], v[102:105]
	global_load_lds_dwordx4 v201, s[4:5]
	v_cvt_pk_bf16_f32 v2, v2, v3
	s_add_u32 m0, s8, 0x18800
	v_mfma_f32_16x16x32_bf16 v[106:109], v[192:195], v[176:179], v[106:109]
	global_load_lds_dwordx4 v202, s[4:5]
	s_add_u32 m0, s8, 0x18c00
	v_mfma_f32_16x16x32_bf16 v[110:113], v[196:199], v[176:179], v[110:113]
	global_load_lds_dwordx4 v203, s[4:5]
	v_cvt_pk_bf16_f32 v3, v4, v5
	s_add_u32 m0, s9, 0x18000
	v_mfma_f32_16x16x32_bf16 v[114:117], v[184:187], v[180:183], v[114:117]
	global_load_lds_dwordx4 v204, s[6:7]
	s_add_u32 m0, s9, 0x18400
	v_mfma_f32_16x16x32_bf16 v[118:121], v[188:191], v[180:183], v[118:121]
	global_load_lds_dwordx4 v205, s[6:7]
	v_cvt_pk_bf16_f32 v4, v6, v7
	v_mfma_f32_16x16x32_bf16 v[122:125], v[192:195], v[180:183], v[122:125]
	s_add_u32 s4, s4, 0x80
	s_addc_u32 s5, s5, 0
	v_mfma_f32_16x16x32_bf16 v[126:129], v[196:199], v[180:183], v[126:129]
	s_add_u32 s6, s6, 0x80
	s_addc_u32 s7, s7, 0
	v_cvt_pk_bf16_f32 v5, v8, v9
	s_waitcnt lgkmcnt(0)
	v_mfma_f32_16x16x32_bf16 v[66:69], v[152:155], v[136:139], v[66:69]
	ds_read_b128 v[168:171], v225 offset:0
	v_mfma_f32_16x16x32_bf16 v[70:73], v[156:159], v[136:139], v[70:73]
	ds_read_b128 v[172:175], v225 offset:2048
	global_store_dwordx4 v240, v[2:5], s[10:11] offset:0 sc1
	v_mfma_f32_16x16x32_bf16 v[74:77], v[160:163], v[136:139], v[74:77]
	ds_read_b128 v[176:179], v225 offset:4096
	v_mul_f32_e32 v10, s12, v10
	v_mfma_f32_16x16x32_bf16 v[78:81], v[164:167], v[136:139], v[78:81]
	ds_read_b128 v[180:183], v225 offset:6144
	v_mul_f32_e32 v11, s12, v11
	v_mfma_f32_16x16x32_bf16 v[82:85], v[152:155], v[140:143], v[82:85]
	ds_read_b128 v[184:187], v233 offset:0
	v_mfma_f32_16x16x32_bf16 v[86:89], v[156:159], v[140:143], v[86:89]
	ds_read_b128 v[188:191], v233 offset:2048
	v_mul_f32_e32 v12, s12, v12
	v_mfma_f32_16x16x32_bf16 v[90:93], v[160:163], v[140:143], v[90:93]
	ds_read_b128 v[192:195], v233 offset:4096
	v_mul_f32_e32 v13, s12, v13
	v_mfma_f32_16x16x32_bf16 v[94:97], v[164:167], v[140:143], v[94:97]
	ds_read_b128 v[196:199], v233 offset:6144
	v_mul_f32_e32 v14, s12, v14
	v_mfma_f32_16x16x32_bf16 v[98:101], v[152:155], v[144:147], v[98:101]
	v_mfma_f32_16x16x32_bf16 v[102:105], v[156:159], v[144:147], v[102:105]
	v_mul_f32_e32 v15, s12, v15
	v_mfma_f32_16x16x32_bf16 v[106:109], v[160:163], v[144:147], v[106:109]
	v_mul_f32_e32 v16, s12, v16
	v_mfma_f32_16x16x32_bf16 v[110:113], v[164:167], v[144:147], v[110:113]
	v_mul_f32_e32 v17, s12, v17
	v_mfma_f32_16x16x32_bf16 v[114:117], v[152:155], v[148:151], v[114:117]
	v_mfma_f32_16x16x32_bf16 v[118:121], v[156:159], v[148:151], v[118:121]
	v_exp_f32_e32 v10, v10
	v_mfma_f32_16x16x32_bf16 v[122:125], v[160:163], v[148:151], v[122:125]
	v_exp_f32_e32 v11, v11
	v_mfma_f32_16x16x32_bf16 v[126:129], v[164:167], v[148:151], v[126:129]
	v_exp_f32_e32 v12, v12
	s_waitcnt vmcnt(7) lgkmcnt(0)
	s_barrier
	v_mfma_f32_16x16x32_bf16 v[66:69], v[184:187], v[168:171], v[66:69]
	ds_read_b128 v[136:139], v219 offset:0
	v_mfma_f32_16x16x32_bf16 v[70:73], v[188:191], v[168:171], v[70:73]
	ds_read_b128 v[140:143], v219 offset:2048
	v_mfma_f32_16x16x32_bf16 v[74:77], v[192:195], v[168:171], v[74:77]
	ds_read_b128 v[144:147], v219 offset:4096
	v_exp_f32_e32 v13, v13
	v_mfma_f32_16x16x32_bf16 v[78:81], v[196:199], v[168:171], v[78:81]
	ds_read_b128 v[148:151], v219 offset:6144
	v_mfma_f32_16x16x32_bf16 v[82:85], v[184:187], v[172:175], v[82:85]
	ds_read_b128 v[152:155], v231 offset:0
	v_exp_f32_e32 v14, v14
	v_mfma_f32_16x16x32_bf16 v[86:89], v[188:191], v[172:175], v[86:89]
	ds_read_b128 v[156:159], v231 offset:2048
	v_mfma_f32_16x16x32_bf16 v[90:93], v[192:195], v[172:175], v[90:93]
	ds_read_b128 v[160:163], v231 offset:4096
	v_exp_f32_e32 v15, v15
	v_mfma_f32_16x16x32_bf16 v[94:97], v[196:199], v[172:175], v[94:97]
	ds_read_b128 v[164:167], v231 offset:6144
	s_mov_b32 m0, s8
	v_mfma_f32_16x16x32_bf16 v[98:101], v[184:187], v[176:179], v[98:101]
	global_load_lds_dwordx4 v200, s[4:5]
	s_add_u32 m0, s8, 0x400
	v_mfma_f32_16x16x32_bf16 v[102:105], v[188:191], v[176:179], v[102:105]
	global_load_lds_dwordx4 v201, s[4:5]
	v_exp_f32_e32 v16, v16
	s_add_u32 m0, s8, 0x800
	v_mfma_f32_16x16x32_bf16 v[106:109], v[192:195], v[176:179], v[106:109]
	global_load_lds_dwordx4 v202, s[4:5]
	s_add_u32 m0, s8, 0xc00
	v_mfma_f32_16x16x32_bf16 v[110:113], v[196:199], v[176:179], v[110:113]
	global_load_lds_dwordx4 v203, s[4:5]
	v_exp_f32_e32 v17, v17
	s_mov_b32 m0, s9
	v_mfma_f32_16x16x32_bf16 v[114:117], v[184:187], v[180:183], v[114:117]
	global_load_lds_dwordx4 v204, s[6:7]
	s_add_u32 m0, s9, 0x400
	v_mfma_f32_16x16x32_bf16 v[118:121], v[188:191], v[180:183], v[118:121]
	global_load_lds_dwordx4 v205, s[6:7]
	v_add_f32_e32 v10, 1.0, v10
	v_mfma_f32_16x16x32_bf16 v[122:125], v[192:195], v[180:183], v[122:125]
	s_add_u32 s4, s4, 0x80
	s_addc_u32 s5, s5, 0
	v_mfma_f32_16x16x32_bf16 v[126:129], v[196:199], v[180:183], v[126:129]
	s_add_u32 s6, s6, 0x80
	s_addc_u32 s7, s7, 0
	v_add_f32_e32 v11, 1.0, v11
	s_waitcnt lgkmcnt(0)
	v_mfma_f32_16x16x32_bf16 v[66:69], v[152:155], v[136:139], v[66:69]
	ds_read_b128 v[168:171], v228 offset:0
	v_mfma_f32_16x16x32_bf16 v[70:73], v[156:159], v[136:139], v[70:73]
	ds_read_b128 v[172:175], v228 offset:2048
	v_add_f32_e32 v12, 1.0, v12
	v_mfma_f32_16x16x32_bf16 v[74:77], v[160:163], v[136:139], v[74:77]
	ds_read_b128 v[176:179], v228 offset:4096
	v_add_f32_e32 v13, 1.0, v13
	v_mfma_f32_16x16x32_bf16 v[78:81], v[164:167], v[136:139], v[78:81]
	ds_read_b128 v[180:183], v228 offset:6144
	v_add_f32_e32 v14, 1.0, v14
	v_mfma_f32_16x16x32_bf16 v[82:85], v[152:155], v[140:143], v[82:85]
	ds_read_b128 v[184:187], v234 offset:0
	v_mfma_f32_16x16x32_bf16 v[86:89], v[156:159], v[140:143], v[86:89]
	ds_read_b128 v[188:191], v234 offset:2048
	v_add_f32_e32 v15, 1.0, v15
	v_mfma_f32_16x16x32_bf16 v[90:93], v[160:163], v[140:143], v[90:93]
	ds_read_b128 v[192:195], v234 offset:4096
	v_add_f32_e32 v16, 1.0, v16
	v_mfma_f32_16x16x32_bf16 v[94:97], v[164:167], v[140:143], v[94:97]
	ds_read_b128 v[196:199], v234 offset:6144
	v_add_f32_e32 v17, 1.0, v17
	v_mfma_f32_16x16x32_bf16 v[98:101], v[152:155], v[144:147], v[98:101]
	v_mfma_f32_16x16x32_bf16 v[102:105], v[156:159], v[144:147], v[102:105]
	v_rcp_f32_e32 v10, v10
	v_mfma_f32_16x16x32_bf16 v[106:109], v[160:163], v[144:147], v[106:109]
	v_rcp_f32_e32 v11, v11
	v_mfma_f32_16x16x32_bf16 v[110:113], v[164:167], v[144:147], v[110:113]
	v_rcp_f32_e32 v12, v12
	v_mfma_f32_16x16x32_bf16 v[114:117], v[152:155], v[148:151], v[114:117]
	v_mfma_f32_16x16x32_bf16 v[118:121], v[156:159], v[148:151], v[118:121]
	v_rcp_f32_e32 v13, v13
	v_mfma_f32_16x16x32_bf16 v[122:125], v[160:163], v[148:151], v[122:125]
	v_rcp_f32_e32 v14, v14
	v_mfma_f32_16x16x32_bf16 v[126:129], v[164:167], v[148:151], v[126:129]
	v_rcp_f32_e32 v15, v15
	s_waitcnt vmcnt(7) lgkmcnt(0)
	s_barrier
	v_mfma_f32_16x16x32_bf16 v[66:69], v[184:187], v[168:171], v[66:69]
	ds_read_b128 v[136:139], v224 offset:0
	v_mfma_f32_16x16x32_bf16 v[70:73], v[188:191], v[168:171], v[70:73]
	ds_read_b128 v[140:143], v224 offset:2048
	v_mfma_f32_16x16x32_bf16 v[74:77], v[192:195], v[168:171], v[74:77]
	ds_read_b128 v[144:147], v224 offset:4096
	v_rcp_f32_e32 v16, v16
	v_mfma_f32_16x16x32_bf16 v[78:81], v[196:199], v[168:171], v[78:81]
	ds_read_b128 v[148:151], v224 offset:6144
	v_mfma_f32_16x16x32_bf16 v[82:85], v[184:187], v[172:175], v[82:85]
	ds_read_b128 v[152:155], v232 offset:0
	v_rcp_f32_e32 v17, v17
	v_mfma_f32_16x16x32_bf16 v[86:89], v[188:191], v[172:175], v[86:89]
	ds_read_b128 v[156:159], v232 offset:2048
	v_mfma_f32_16x16x32_bf16 v[90:93], v[192:195], v[172:175], v[90:93]
	ds_read_b128 v[160:163], v232 offset:4096
	v_cvt_pk_bf16_f32 v10, v10, v11
	v_mfma_f32_16x16x32_bf16 v[94:97], v[196:199], v[172:175], v[94:97]
	ds_read_b128 v[164:167], v232 offset:6144
	s_add_u32 m0, s8, 0xc000
	v_mfma_f32_16x16x32_bf16 v[98:101], v[184:187], v[176:179], v[98:101]
	global_load_lds_dwordx4 v200, s[4:5]
	s_add_u32 m0, s8, 0xc400
	v_mfma_f32_16x16x32_bf16 v[102:105], v[188:191], v[176:179], v[102:105]
	global_load_lds_dwordx4 v201, s[4:5]
	v_cvt_pk_bf16_f32 v11, v12, v13
	s_add_u32 m0, s8, 0xc800
	v_mfma_f32_16x16x32_bf16 v[106:109], v[192:195], v[176:179], v[106:109]
	global_load_lds_dwordx4 v202, s[4:5]
	s_add_u32 m0, s8, 0xcc00
	v_mfma_f32_16x16x32_bf16 v[110:113], v[196:199], v[176:179], v[110:113]
	global_load_lds_dwordx4 v203, s[4:5]
	v_cvt_pk_bf16_f32 v12, v14, v15
	s_add_u32 m0, s9, 0xc000
	v_mfma_f32_16x16x32_bf16 v[114:117], v[184:187], v[180:183], v[114:117]
	global_load_lds_dwordx4 v204, s[6:7]
	s_add_u32 m0, s9, 0xc400
	v_mfma_f32_16x16x32_bf16 v[118:121], v[188:191], v[180:183], v[118:121]
	global_load_lds_dwordx4 v205, s[6:7]
	v_cvt_pk_bf16_f32 v13, v16, v17
	v_mfma_f32_16x16x32_bf16 v[122:125], v[192:195], v[180:183], v[122:125]
	s_add_u32 s4, s4, 0x80
	s_addc_u32 s5, s5, 0
	v_mfma_f32_16x16x32_bf16 v[126:129], v[196:199], v[180:183], v[126:129]
	s_add_u32 s6, s6, 0x80
	s_addc_u32 s7, s7, 0
	global_store_dwordx4 v240, v[10:13], s[10:11] offset:1024 sc1
	s_waitcnt lgkmcnt(0)
	v_mfma_f32_16x16x32_bf16 v[66:69], v[152:155], v[136:139], v[66:69]
	ds_read_b128 v[168:171], v229 offset:0
	v_mfma_f32_16x16x32_bf16 v[70:73], v[156:159], v[136:139], v[70:73]
	ds_read_b128 v[172:175], v229 offset:2048
	v_mul_f32_e32 v18, s12, v18
	v_mfma_f32_16x16x32_bf16 v[74:77], v[160:163], v[136:139], v[74:77]
	ds_read_b128 v[176:179], v229 offset:4096
	v_mul_f32_e32 v19, s12, v19
	v_mfma_f32_16x16x32_bf16 v[78:81], v[164:167], v[136:139], v[78:81]
	ds_read_b128 v[180:183], v229 offset:6144
	v_mul_f32_e32 v20, s12, v20
	v_mfma_f32_16x16x32_bf16 v[82:85], v[152:155], v[140:143], v[82:85]
	ds_read_b128 v[184:187], v235 offset:0
	v_mfma_f32_16x16x32_bf16 v[86:89], v[156:159], v[140:143], v[86:89]
	ds_read_b128 v[188:191], v235 offset:2048
	v_mul_f32_e32 v21, s12, v21
	v_mfma_f32_16x16x32_bf16 v[90:93], v[160:163], v[140:143], v[90:93]
	ds_read_b128 v[192:195], v235 offset:4096
	v_mul_f32_e32 v22, s12, v22
	v_mfma_f32_16x16x32_bf16 v[94:97], v[164:167], v[140:143], v[94:97]
	ds_read_b128 v[196:199], v235 offset:6144
	v_mul_f32_e32 v23, s12, v23
	v_mfma_f32_16x16x32_bf16 v[98:101], v[152:155], v[144:147], v[98:101]
	v_mfma_f32_16x16x32_bf16 v[102:105], v[156:159], v[144:147], v[102:105]
	v_mul_f32_e32 v24, s12, v24
	v_mfma_f32_16x16x32_bf16 v[106:109], v[160:163], v[144:147], v[106:109]
	v_mul_f32_e32 v25, s12, v25
	v_mfma_f32_16x16x32_bf16 v[110:113], v[164:167], v[144:147], v[110:113]
	v_exp_f32_e32 v18, v18
	v_mfma_f32_16x16x32_bf16 v[114:117], v[152:155], v[148:151], v[114:117]
	v_mfma_f32_16x16x32_bf16 v[118:121], v[156:159], v[148:151], v[118:121]
	v_exp_f32_e32 v19, v19
	v_mfma_f32_16x16x32_bf16 v[122:125], v[160:163], v[148:151], v[122:125]
	v_exp_f32_e32 v20, v20
	v_mfma_f32_16x16x32_bf16 v[126:129], v[164:167], v[148:151], v[126:129]
	v_exp_f32_e32 v21, v21
	s_waitcnt vmcnt(7) lgkmcnt(0)
	s_barrier
	v_mfma_f32_16x16x32_bf16 v[66:69], v[184:187], v[168:171], v[66:69]
	ds_read_b128 v[136:139], v218 offset:0
	v_mfma_f32_16x16x32_bf16 v[70:73], v[188:191], v[168:171], v[70:73]
	ds_read_b128 v[140:143], v218 offset:2048
	v_mfma_f32_16x16x32_bf16 v[74:77], v[192:195], v[168:171], v[74:77]
	ds_read_b128 v[144:147], v218 offset:4096
	v_exp_f32_e32 v22, v22
	v_mfma_f32_16x16x32_bf16 v[78:81], v[196:199], v[168:171], v[78:81]
	ds_read_b128 v[148:151], v218 offset:6144
	v_mfma_f32_16x16x32_bf16 v[82:85], v[184:187], v[172:175], v[82:85]
	ds_read_b128 v[152:155], v230 offset:0
	v_exp_f32_e32 v23, v23
	v_mfma_f32_16x16x32_bf16 v[86:89], v[188:191], v[172:175], v[86:89]
	ds_read_b128 v[156:159], v230 offset:2048
	v_mfma_f32_16x16x32_bf16 v[90:93], v[192:195], v[172:175], v[90:93]
	ds_read_b128 v[160:163], v230 offset:4096
	v_exp_f32_e32 v24, v24
	v_mfma_f32_16x16x32_bf16 v[94:97], v[196:199], v[172:175], v[94:97]
	ds_read_b128 v[164:167], v230 offset:6144
	s_add_u32 m0, s8, 0x18000
	v_mfma_f32_16x16x32_bf16 v[98:101], v[184:187], v[176:179], v[98:101]
	global_load_lds_dwordx4 v200, s[4:5]
	s_add_u32 m0, s8, 0x18400
	v_mfma_f32_16x16x32_bf16 v[102:105], v[188:191], v[176:179], v[102:105]
	global_load_lds_dwordx4 v201, s[4:5]
	v_exp_f32_e32 v25, v25
	s_add_u32 m0, s8, 0x18800
	v_mfma_f32_16x16x32_bf16 v[106:109], v[192:195], v[176:179], v[106:109]
	global_load_lds_dwordx4 v202, s[4:5]
	s_add_u32 m0, s8, 0x18c00
	v_mfma_f32_16x16x32_bf16 v[110:113], v[196:199], v[176:179], v[110:113]
	global_load_lds_dwordx4 v203, s[4:5]
	v_add_f32_e32 v18, 1.0, v18
	s_add_u32 m0, s9, 0x18000
	v_mfma_f32_16x16x32_bf16 v[114:117], v[184:187], v[180:183], v[114:117]
	global_load_lds_dwordx4 v204, s[6:7]
	s_add_u32 m0, s9, 0x18400
	v_mfma_f32_16x16x32_bf16 v[118:121], v[188:191], v[180:183], v[118:121]
	global_load_lds_dwordx4 v205, s[6:7]
	v_add_f32_e32 v19, 1.0, v19
	v_mfma_f32_16x16x32_bf16 v[122:125], v[192:195], v[180:183], v[122:125]
	s_add_u32 s4, s4, 0x80
	s_addc_u32 s5, s5, 0
	v_mfma_f32_16x16x32_bf16 v[126:129], v[196:199], v[180:183], v[126:129]
	s_add_u32 s6, s6, 0x80
	s_addc_u32 s7, s7, 0
	v_add_f32_e32 v20, 1.0, v20
	s_waitcnt lgkmcnt(0)
	v_mfma_f32_16x16x32_bf16 v[66:69], v[152:155], v[136:139], v[66:69]
	ds_read_b128 v[168:171], v225 offset:0
	v_mfma_f32_16x16x32_bf16 v[70:73], v[156:159], v[136:139], v[70:73]
	ds_read_b128 v[172:175], v225 offset:2048
	v_add_f32_e32 v21, 1.0, v21
	v_mfma_f32_16x16x32_bf16 v[74:77], v[160:163], v[136:139], v[74:77]
	ds_read_b128 v[176:179], v225 offset:4096
	v_add_f32_e32 v22, 1.0, v22
	v_mfma_f32_16x16x32_bf16 v[78:81], v[164:167], v[136:139], v[78:81]
	ds_read_b128 v[180:183], v225 offset:6144
	v_add_f32_e32 v23, 1.0, v23
	v_mfma_f32_16x16x32_bf16 v[82:85], v[152:155], v[140:143], v[82:85]
	ds_read_b128 v[184:187], v233 offset:0
	v_mfma_f32_16x16x32_bf16 v[86:89], v[156:159], v[140:143], v[86:89]
	ds_read_b128 v[188:191], v233 offset:2048
	v_add_f32_e32 v24, 1.0, v24
	v_mfma_f32_16x16x32_bf16 v[90:93], v[160:163], v[140:143], v[90:93]
	ds_read_b128 v[192:195], v233 offset:4096
	v_add_f32_e32 v25, 1.0, v25
	v_mfma_f32_16x16x32_bf16 v[94:97], v[164:167], v[140:143], v[94:97]
	ds_read_b128 v[196:199], v233 offset:6144
	v_rcp_f32_e32 v18, v18
	v_mfma_f32_16x16x32_bf16 v[98:101], v[152:155], v[144:147], v[98:101]
	v_mfma_f32_16x16x32_bf16 v[102:105], v[156:159], v[144:147], v[102:105]
	v_rcp_f32_e32 v19, v19
	v_mfma_f32_16x16x32_bf16 v[106:109], v[160:163], v[144:147], v[106:109]
	v_rcp_f32_e32 v20, v20
	v_mfma_f32_16x16x32_bf16 v[110:113], v[164:167], v[144:147], v[110:113]
	v_rcp_f32_e32 v21, v21
	v_mfma_f32_16x16x32_bf16 v[114:117], v[152:155], v[148:151], v[114:117]
	v_mfma_f32_16x16x32_bf16 v[118:121], v[156:159], v[148:151], v[118:121]
	v_rcp_f32_e32 v22, v22
	v_mfma_f32_16x16x32_bf16 v[122:125], v[160:163], v[148:151], v[122:125]
	v_rcp_f32_e32 v23, v23
	v_mfma_f32_16x16x32_bf16 v[126:129], v[164:167], v[148:151], v[126:129]
	v_rcp_f32_e32 v24, v24
	s_waitcnt vmcnt(7) lgkmcnt(0)
	s_barrier
	v_mfma_f32_16x16x32_bf16 v[66:69], v[184:187], v[168:171], v[66:69]
	ds_read_b128 v[136:139], v219 offset:0
	v_mfma_f32_16x16x32_bf16 v[70:73], v[188:191], v[168:171], v[70:73]
	ds_read_b128 v[140:143], v219 offset:2048
	v_mfma_f32_16x16x32_bf16 v[74:77], v[192:195], v[168:171], v[74:77]
	ds_read_b128 v[144:147], v219 offset:4096
	v_rcp_f32_e32 v25, v25
	v_mfma_f32_16x16x32_bf16 v[78:81], v[196:199], v[168:171], v[78:81]
	ds_read_b128 v[148:151], v219 offset:6144
	v_mfma_f32_16x16x32_bf16 v[82:85], v[184:187], v[172:175], v[82:85]
	ds_read_b128 v[152:155], v231 offset:0
	v_cvt_pk_bf16_f32 v18, v18, v19
	v_mfma_f32_16x16x32_bf16 v[86:89], v[188:191], v[172:175], v[86:89]
	ds_read_b128 v[156:159], v231 offset:2048
	v_mfma_f32_16x16x32_bf16 v[90:93], v[192:195], v[172:175], v[90:93]
	ds_read_b128 v[160:163], v231 offset:4096
	v_cvt_pk_bf16_f32 v19, v20, v21
	v_mfma_f32_16x16x32_bf16 v[94:97], v[196:199], v[172:175], v[94:97]
	ds_read_b128 v[164:167], v231 offset:6144
	s_mov_b32 m0, s8
	v_mfma_f32_16x16x32_bf16 v[98:101], v[184:187], v[176:179], v[98:101]
	global_load_lds_dwordx4 v200, s[4:5]
	s_add_u32 m0, s8, 0x400
	v_mfma_f32_16x16x32_bf16 v[102:105], v[188:191], v[176:179], v[102:105]
	global_load_lds_dwordx4 v201, s[4:5]
	v_cvt_pk_bf16_f32 v20, v22, v23
	s_add_u32 m0, s8, 0x800
	v_mfma_f32_16x16x32_bf16 v[106:109], v[192:195], v[176:179], v[106:109]
	global_load_lds_dwordx4 v202, s[4:5]
	s_add_u32 m0, s8, 0xc00
	v_mfma_f32_16x16x32_bf16 v[110:113], v[196:199], v[176:179], v[110:113]
	global_load_lds_dwordx4 v203, s[4:5]
	v_cvt_pk_bf16_f32 v21, v24, v25
	s_mov_b32 m0, s9
	v_mfma_f32_16x16x32_bf16 v[114:117], v[184:187], v[180:183], v[114:117]
	global_load_lds_dwordx4 v204, s[6:7]
	s_add_u32 m0, s9, 0x400
	v_mfma_f32_16x16x32_bf16 v[118:121], v[188:191], v[180:183], v[118:121]
	global_load_lds_dwordx4 v205, s[6:7]
	global_store_dwordx4 v240, v[18:21], s[10:11] offset:2048 sc1
	v_mfma_f32_16x16x32_bf16 v[122:125], v[192:195], v[180:183], v[122:125]
	s_add_u32 s4, s4, 0x80
	s_addc_u32 s5, s5, 0
	v_mfma_f32_16x16x32_bf16 v[126:129], v[196:199], v[180:183], v[126:129]
	s_add_u32 s6, s6, 0x80
	s_addc_u32 s7, s7, 0
	v_mul_f32_e32 v26, s12, v26
	s_waitcnt lgkmcnt(0)
	v_mfma_f32_16x16x32_bf16 v[66:69], v[152:155], v[136:139], v[66:69]
	ds_read_b128 v[168:171], v228 offset:0
	v_mfma_f32_16x16x32_bf16 v[70:73], v[156:159], v[136:139], v[70:73]
	ds_read_b128 v[172:175], v228 offset:2048
	v_mul_f32_e32 v27, s12, v27
	v_mfma_f32_16x16x32_bf16 v[74:77], v[160:163], v[136:139], v[74:77]
	ds_read_b128 v[176:179], v228 offset:4096
	v_mul_f32_e32 v28, s12, v28
	v_mfma_f32_16x16x32_bf16 v[78:81], v[164:167], v[136:139], v[78:81]
	ds_read_b128 v[180:183], v228 offset:6144
	v_mul_f32_e32 v29, s12, v29
	v_mfma_f32_16x16x32_bf16 v[82:85], v[152:155], v[140:143], v[82:85]
	ds_read_b128 v[184:187], v234 offset:0
	v_mfma_f32_16x16x32_bf16 v[86:89], v[156:159], v[140:143], v[86:89]
	ds_read_b128 v[188:191], v234 offset:2048
	v_mul_f32_e32 v30, s12, v30
	v_mfma_f32_16x16x32_bf16 v[90:93], v[160:163], v[140:143], v[90:93]
	ds_read_b128 v[192:195], v234 offset:4096
	v_mul_f32_e32 v31, s12, v31
	v_mfma_f32_16x16x32_bf16 v[94:97], v[164:167], v[140:143], v[94:97]
	ds_read_b128 v[196:199], v234 offset:6144
	v_mul_f32_e32 v32, s12, v32
	v_mfma_f32_16x16x32_bf16 v[98:101], v[152:155], v[144:147], v[98:101]
	v_mfma_f32_16x16x32_bf16 v[102:105], v[156:159], v[144:147], v[102:105]
	v_mul_f32_e32 v33, s12, v33
	v_mfma_f32_16x16x32_bf16 v[106:109], v[160:163], v[144:147], v[106:109]
	v_exp_f32_e32 v26, v26
	v_mfma_f32_16x16x32_bf16 v[110:113], v[164:167], v[144:147], v[110:113]
	v_exp_f32_e32 v27, v27
	v_mfma_f32_16x16x32_bf16 v[114:117], v[152:155], v[148:151], v[114:117]
	v_mfma_f32_16x16x32_bf16 v[118:121], v[156:159], v[148:151], v[118:121]
	v_exp_f32_e32 v28, v28
	v_mfma_f32_16x16x32_bf16 v[122:125], v[160:163], v[148:151], v[122:125]
	v_exp_f32_e32 v29, v29
	v_mfma_f32_16x16x32_bf16 v[126:129], v[164:167], v[148:151], v[126:129]
	v_exp_f32_e32 v30, v30
	s_waitcnt vmcnt(7) lgkmcnt(0)
	s_barrier
	v_mfma_f32_16x16x32_bf16 v[66:69], v[184:187], v[168:171], v[66:69]
	ds_read_b128 v[136:139], v224 offset:0
	v_mfma_f32_16x16x32_bf16 v[70:73], v[188:191], v[168:171], v[70:73]
	ds_read_b128 v[140:143], v224 offset:2048
	v_mfma_f32_16x16x32_bf16 v[74:77], v[192:195], v[168:171], v[74:77]
	ds_read_b128 v[144:147], v224 offset:4096
	v_exp_f32_e32 v31, v31
	v_mfma_f32_16x16x32_bf16 v[78:81], v[196:199], v[168:171], v[78:81]
	ds_read_b128 v[148:151], v224 offset:6144
	v_mfma_f32_16x16x32_bf16 v[82:85], v[184:187], v[172:175], v[82:85]
	ds_read_b128 v[152:155], v232 offset:0
	v_exp_f32_e32 v32, v32
	v_mfma_f32_16x16x32_bf16 v[86:89], v[188:191], v[172:175], v[86:89]
	ds_read_b128 v[156:159], v232 offset:2048
	v_mfma_f32_16x16x32_bf16 v[90:93], v[192:195], v[172:175], v[90:93]
	ds_read_b128 v[160:163], v232 offset:4096
	v_exp_f32_e32 v33, v33
	v_mfma_f32_16x16x32_bf16 v[94:97], v[196:199], v[172:175], v[94:97]
	ds_read_b128 v[164:167], v232 offset:6144
	s_add_u32 m0, s8, 0xc000
	v_mfma_f32_16x16x32_bf16 v[98:101], v[184:187], v[176:179], v[98:101]
	global_load_lds_dwordx4 v200, s[4:5]
	s_add_u32 m0, s8, 0xc400
	v_mfma_f32_16x16x32_bf16 v[102:105], v[188:191], v[176:179], v[102:105]
	global_load_lds_dwordx4 v201, s[4:5]
	v_add_f32_e32 v26, 1.0, v26
	s_add_u32 m0, s8, 0xc800
	v_mfma_f32_16x16x32_bf16 v[106:109], v[192:195], v[176:179], v[106:109]
	global_load_lds_dwordx4 v202, s[4:5]
	s_add_u32 m0, s8, 0xcc00
	v_mfma_f32_16x16x32_bf16 v[110:113], v[196:199], v[176:179], v[110:113]
	global_load_lds_dwordx4 v203, s[4:5]
	v_add_f32_e32 v27, 1.0, v27
	s_add_u32 m0, s9, 0xc000
	v_mfma_f32_16x16x32_bf16 v[114:117], v[184:187], v[180:183], v[114:117]
	global_load_lds_dwordx4 v204, s[6:7]
	s_add_u32 m0, s9, 0xc400
	v_mfma_f32_16x16x32_bf16 v[118:121], v[188:191], v[180:183], v[118:121]
	global_load_lds_dwordx4 v205, s[6:7]
	v_add_f32_e32 v28, 1.0, v28
	v_mfma_f32_16x16x32_bf16 v[122:125], v[192:195], v[180:183], v[122:125]
	s_add_u32 s4, s4, 0x80
	s_addc_u32 s5, s5, 0
	v_mfma_f32_16x16x32_bf16 v[126:129], v[196:199], v[180:183], v[126:129]
	s_add_u32 s6, s6, 0x80
	s_addc_u32 s7, s7, 0
	v_add_f32_e32 v29, 1.0, v29
	s_waitcnt lgkmcnt(0)
	v_mfma_f32_16x16x32_bf16 v[66:69], v[152:155], v[136:139], v[66:69]
	ds_read_b128 v[168:171], v229 offset:0
	v_mfma_f32_16x16x32_bf16 v[70:73], v[156:159], v[136:139], v[70:73]
	ds_read_b128 v[172:175], v229 offset:2048
	v_add_f32_e32 v30, 1.0, v30
	v_mfma_f32_16x16x32_bf16 v[74:77], v[160:163], v[136:139], v[74:77]
	ds_read_b128 v[176:179], v229 offset:4096
	v_add_f32_e32 v31, 1.0, v31
	v_mfma_f32_16x16x32_bf16 v[78:81], v[164:167], v[136:139], v[78:81]
	ds_read_b128 v[180:183], v229 offset:6144
	v_add_f32_e32 v32, 1.0, v32
	v_mfma_f32_16x16x32_bf16 v[82:85], v[152:155], v[140:143], v[82:85]
	ds_read_b128 v[184:187], v235 offset:0
	v_mfma_f32_16x16x32_bf16 v[86:89], v[156:159], v[140:143], v[86:89]
	ds_read_b128 v[188:191], v235 offset:2048
	v_add_f32_e32 v33, 1.0, v33
	v_mfma_f32_16x16x32_bf16 v[90:93], v[160:163], v[140:143], v[90:93]
	ds_read_b128 v[192:195], v235 offset:4096
	v_rcp_f32_e32 v26, v26
	v_mfma_f32_16x16x32_bf16 v[94:97], v[164:167], v[140:143], v[94:97]
	ds_read_b128 v[196:199], v235 offset:6144
	v_rcp_f32_e32 v27, v27
	v_mfma_f32_16x16x32_bf16 v[98:101], v[152:155], v[144:147], v[98:101]
	v_mfma_f32_16x16x32_bf16 v[102:105], v[156:159], v[144:147], v[102:105]
	v_rcp_f32_e32 v28, v28
	v_mfma_f32_16x16x32_bf16 v[106:109], v[160:163], v[144:147], v[106:109]
	v_rcp_f32_e32 v29, v29
	v_mfma_f32_16x16x32_bf16 v[110:113], v[164:167], v[144:147], v[110:113]
	v_rcp_f32_e32 v30, v30
	v_mfma_f32_16x16x32_bf16 v[114:117], v[152:155], v[148:151], v[114:117]
	v_mfma_f32_16x16x32_bf16 v[118:121], v[156:159], v[148:151], v[118:121]
	v_rcp_f32_e32 v31, v31
	v_mfma_f32_16x16x32_bf16 v[122:125], v[160:163], v[148:151], v[122:125]
	v_rcp_f32_e32 v32, v32
	v_mfma_f32_16x16x32_bf16 v[126:129], v[164:167], v[148:151], v[126:129]
	v_rcp_f32_e32 v33, v33
	s_waitcnt vmcnt(7) lgkmcnt(0)
	s_barrier
	v_mfma_f32_16x16x32_bf16 v[66:69], v[184:187], v[168:171], v[66:69]
	ds_read_b128 v[136:139], v218 offset:0
	v_mfma_f32_16x16x32_bf16 v[70:73], v[188:191], v[168:171], v[70:73]
	ds_read_b128 v[140:143], v218 offset:2048
	v_mfma_f32_16x16x32_bf16 v[74:77], v[192:195], v[168:171], v[74:77]
	ds_read_b128 v[144:147], v218 offset:4096
	v_cvt_pk_bf16_f32 v26, v26, v27
	v_mfma_f32_16x16x32_bf16 v[78:81], v[196:199], v[168:171], v[78:81]
	ds_read_b128 v[148:151], v218 offset:6144
	v_mfma_f32_16x16x32_bf16 v[82:85], v[184:187], v[172:175], v[82:85]
	ds_read_b128 v[152:155], v230 offset:0
	v_cvt_pk_bf16_f32 v27, v28, v29
	v_mfma_f32_16x16x32_bf16 v[86:89], v[188:191], v[172:175], v[86:89]
	ds_read_b128 v[156:159], v230 offset:2048
	v_mfma_f32_16x16x32_bf16 v[90:93], v[192:195], v[172:175], v[90:93]
	ds_read_b128 v[160:163], v230 offset:4096
	v_cvt_pk_bf16_f32 v28, v30, v31
	v_mfma_f32_16x16x32_bf16 v[94:97], v[196:199], v[172:175], v[94:97]
	ds_read_b128 v[164:167], v230 offset:6144
	s_add_u32 m0, s8, 0x18000
	v_mfma_f32_16x16x32_bf16 v[98:101], v[184:187], v[176:179], v[98:101]
	global_load_lds_dwordx4 v200, s[4:5]
	s_add_u32 m0, s8, 0x18400
	v_mfma_f32_16x16x32_bf16 v[102:105], v[188:191], v[176:179], v[102:105]
	global_load_lds_dwordx4 v201, s[4:5]
	v_cvt_pk_bf16_f32 v29, v32, v33
	s_add_u32 m0, s8, 0x18800
	v_mfma_f32_16x16x32_bf16 v[106:109], v[192:195], v[176:179], v[106:109]
	global_load_lds_dwordx4 v202, s[4:5]
	s_add_u32 m0, s8, 0x18c00
	v_mfma_f32_16x16x32_bf16 v[110:113], v[196:199], v[176:179], v[110:113]
	global_load_lds_dwordx4 v203, s[4:5]
	global_store_dwordx4 v240, v[26:29], s[10:11] offset:3072 sc1
	s_add_u32 m0, s9, 0x18000
	v_mfma_f32_16x16x32_bf16 v[114:117], v[184:187], v[180:183], v[114:117]
	global_load_lds_dwordx4 v204, s[6:7]
	s_add_u32 m0, s9, 0x18400
	v_mfma_f32_16x16x32_bf16 v[118:121], v[188:191], v[180:183], v[118:121]
	global_load_lds_dwordx4 v205, s[6:7]
	v_mul_f32_e32 v34, s12, v34
	v_mfma_f32_16x16x32_bf16 v[122:125], v[192:195], v[180:183], v[122:125]
	s_add_u32 s4, s4, 0x80
	s_addc_u32 s5, s5, 0
	v_mfma_f32_16x16x32_bf16 v[126:129], v[196:199], v[180:183], v[126:129]
	s_add_u32 s6, s6, 0x80
	s_addc_u32 s7, s7, 0
	v_mul_f32_e32 v35, s12, v35
	s_waitcnt lgkmcnt(0)
	v_mfma_f32_16x16x32_bf16 v[66:69], v[152:155], v[136:139], v[66:69]
	ds_read_b128 v[168:171], v225 offset:0
	v_mfma_f32_16x16x32_bf16 v[70:73], v[156:159], v[136:139], v[70:73]
	ds_read_b128 v[172:175], v225 offset:2048
	v_mul_f32_e32 v36, s12, v36
	v_mfma_f32_16x16x32_bf16 v[74:77], v[160:163], v[136:139], v[74:77]
	ds_read_b128 v[176:179], v225 offset:4096
	v_mul_f32_e32 v37, s12, v37
	v_mfma_f32_16x16x32_bf16 v[78:81], v[164:167], v[136:139], v[78:81]
	ds_read_b128 v[180:183], v225 offset:6144
	v_mul_f32_e32 v38, s12, v38
	v_mfma_f32_16x16x32_bf16 v[82:85], v[152:155], v[140:143], v[82:85]
	ds_read_b128 v[184:187], v233 offset:0
	v_mfma_f32_16x16x32_bf16 v[86:89], v[156:159], v[140:143], v[86:89]
	ds_read_b128 v[188:191], v233 offset:2048
	v_mul_f32_e32 v39, s12, v39
	v_mfma_f32_16x16x32_bf16 v[90:93], v[160:163], v[140:143], v[90:93]
	ds_read_b128 v[192:195], v233 offset:4096
	v_mul_f32_e32 v40, s12, v40
	v_mfma_f32_16x16x32_bf16 v[94:97], v[164:167], v[140:143], v[94:97]
	ds_read_b128 v[196:199], v233 offset:6144
	v_mul_f32_e32 v41, s12, v41
	v_mfma_f32_16x16x32_bf16 v[98:101], v[152:155], v[144:147], v[98:101]
	v_mfma_f32_16x16x32_bf16 v[102:105], v[156:159], v[144:147], v[102:105]
	v_exp_f32_e32 v34, v34
	v_mfma_f32_16x16x32_bf16 v[106:109], v[160:163], v[144:147], v[106:109]
	v_exp_f32_e32 v35, v35
	v_mfma_f32_16x16x32_bf16 v[110:113], v[164:167], v[144:147], v[110:113]
	v_exp_f32_e32 v36, v36
	v_mfma_f32_16x16x32_bf16 v[114:117], v[152:155], v[148:151], v[114:117]
	v_mfma_f32_16x16x32_bf16 v[118:121], v[156:159], v[148:151], v[118:121]
	v_exp_f32_e32 v37, v37
	v_mfma_f32_16x16x32_bf16 v[122:125], v[160:163], v[148:151], v[122:125]
	v_exp_f32_e32 v38, v38
	v_mfma_f32_16x16x32_bf16 v[126:129], v[164:167], v[148:151], v[126:129]
	v_exp_f32_e32 v39, v39
	s_waitcnt vmcnt(7) lgkmcnt(0)
	s_barrier
	v_mfma_f32_16x16x32_bf16 v[66:69], v[184:187], v[168:171], v[66:69]
	ds_read_b128 v[136:139], v219 offset:0
	v_mfma_f32_16x16x32_bf16 v[70:73], v[188:191], v[168:171], v[70:73]
	ds_read_b128 v[140:143], v219 offset:2048
	v_mfma_f32_16x16x32_bf16 v[74:77], v[192:195], v[168:171], v[74:77]
	ds_read_b128 v[144:147], v219 offset:4096
	v_exp_f32_e32 v40, v40
	v_mfma_f32_16x16x32_bf16 v[78:81], v[196:199], v[168:171], v[78:81]
	ds_read_b128 v[148:151], v219 offset:6144
	v_mfma_f32_16x16x32_bf16 v[82:85], v[184:187], v[172:175], v[82:85]
	ds_read_b128 v[152:155], v231 offset:0
	v_exp_f32_e32 v41, v41
	v_mfma_f32_16x16x32_bf16 v[86:89], v[188:191], v[172:175], v[86:89]
	ds_read_b128 v[156:159], v231 offset:2048
	v_mfma_f32_16x16x32_bf16 v[90:93], v[192:195], v[172:175], v[90:93]
	ds_read_b128 v[160:163], v231 offset:4096
	v_add_f32_e32 v34, 1.0, v34
	v_mfma_f32_16x16x32_bf16 v[94:97], v[196:199], v[172:175], v[94:97]
	ds_read_b128 v[164:167], v231 offset:6144
	s_mov_b32 m0, s8
	v_mfma_f32_16x16x32_bf16 v[98:101], v[184:187], v[176:179], v[98:101]
	global_load_lds_dwordx4 v200, s[4:5]
	s_add_u32 m0, s8, 0x400
	v_mfma_f32_16x16x32_bf16 v[102:105], v[188:191], v[176:179], v[102:105]
	global_load_lds_dwordx4 v201, s[4:5]
	v_add_f32_e32 v35, 1.0, v35
	s_add_u32 m0, s8, 0x800
	v_mfma_f32_16x16x32_bf16 v[106:109], v[192:195], v[176:179], v[106:109]
	global_load_lds_dwordx4 v202, s[4:5]
	s_add_u32 m0, s8, 0xc00
	v_mfma_f32_16x16x32_bf16 v[110:113], v[196:199], v[176:179], v[110:113]
	global_load_lds_dwordx4 v203, s[4:5]
	v_add_f32_e32 v36, 1.0, v36
	s_mov_b32 m0, s9
	v_mfma_f32_16x16x32_bf16 v[114:117], v[184:187], v[180:183], v[114:117]
	global_load_lds_dwordx4 v204, s[6:7]
	s_add_u32 m0, s9, 0x400
	v_mfma_f32_16x16x32_bf16 v[118:121], v[188:191], v[180:183], v[118:121]
	global_load_lds_dwordx4 v205, s[6:7]
	v_add_f32_e32 v37, 1.0, v37
	v_mfma_f32_16x16x32_bf16 v[122:125], v[192:195], v[180:183], v[122:125]
	s_add_u32 s4, s4, 0x80
	s_addc_u32 s5, s5, 0
	v_mfma_f32_16x16x32_bf16 v[126:129], v[196:199], v[180:183], v[126:129]
	s_add_u32 s6, s6, 0x80
	s_addc_u32 s7, s7, 0
	v_add_f32_e32 v38, 1.0, v38
	s_waitcnt lgkmcnt(0)
	v_mfma_f32_16x16x32_bf16 v[66:69], v[152:155], v[136:139], v[66:69]
	ds_read_b128 v[168:171], v228 offset:0
	v_mfma_f32_16x16x32_bf16 v[70:73], v[156:159], v[136:139], v[70:73]
	ds_read_b128 v[172:175], v228 offset:2048
	v_add_f32_e32 v39, 1.0, v39
	v_mfma_f32_16x16x32_bf16 v[74:77], v[160:163], v[136:139], v[74:77]
	ds_read_b128 v[176:179], v228 offset:4096
	v_add_f32_e32 v40, 1.0, v40
	v_mfma_f32_16x16x32_bf16 v[78:81], v[164:167], v[136:139], v[78:81]
	ds_read_b128 v[180:183], v228 offset:6144
	v_add_f32_e32 v41, 1.0, v41
	v_mfma_f32_16x16x32_bf16 v[82:85], v[152:155], v[140:143], v[82:85]
	ds_read_b128 v[184:187], v234 offset:0
	v_mfma_f32_16x16x32_bf16 v[86:89], v[156:159], v[140:143], v[86:89]
	ds_read_b128 v[188:191], v234 offset:2048
	v_rcp_f32_e32 v34, v34
	v_mfma_f32_16x16x32_bf16 v[90:93], v[160:163], v[140:143], v[90:93]
	ds_read_b128 v[192:195], v234 offset:4096
	v_rcp_f32_e32 v35, v35
	v_mfma_f32_16x16x32_bf16 v[94:97], v[164:167], v[140:143], v[94:97]
	ds_read_b128 v[196:199], v234 offset:6144
	v_rcp_f32_e32 v36, v36
	v_mfma_f32_16x16x32_bf16 v[98:101], v[152:155], v[144:147], v[98:101]
	v_mfma_f32_16x16x32_bf16 v[102:105], v[156:159], v[144:147], v[102:105]
	v_rcp_f32_e32 v37, v37
	v_mfma_f32_16x16x32_bf16 v[106:109], v[160:163], v[144:147], v[106:109]
	v_rcp_f32_e32 v38, v38
	v_mfma_f32_16x16x32_bf16 v[110:113], v[164:167], v[144:147], v[110:113]
	v_rcp_f32_e32 v39, v39
	v_mfma_f32_16x16x32_bf16 v[114:117], v[152:155], v[148:151], v[114:117]
	v_mfma_f32_16x16x32_bf16 v[118:121], v[156:159], v[148:151], v[118:121]
	v_rcp_f32_e32 v40, v40
	v_mfma_f32_16x16x32_bf16 v[122:125], v[160:163], v[148:151], v[122:125]
	v_rcp_f32_e32 v41, v41
	v_mfma_f32_16x16x32_bf16 v[126:129], v[164:167], v[148:151], v[126:129]
	v_cvt_pk_bf16_f32 v34, v34, v35
	s_waitcnt vmcnt(6) lgkmcnt(0)
	s_barrier
	v_mfma_f32_16x16x32_bf16 v[66:69], v[184:187], v[168:171], v[66:69]
	ds_read_b128 v[136:139], v224 offset:0
	v_mfma_f32_16x16x32_bf16 v[70:73], v[188:191], v[168:171], v[70:73]
	ds_read_b128 v[140:143], v224 offset:2048
	v_mfma_f32_16x16x32_bf16 v[74:77], v[192:195], v[168:171], v[74:77]
	ds_read_b128 v[144:147], v224 offset:4096
	v_cvt_pk_bf16_f32 v35, v36, v37
	v_mfma_f32_16x16x32_bf16 v[78:81], v[196:199], v[168:171], v[78:81]
	ds_read_b128 v[148:151], v224 offset:6144
	v_mfma_f32_16x16x32_bf16 v[82:85], v[184:187], v[172:175], v[82:85]
	ds_read_b128 v[152:155], v232 offset:0
	v_cvt_pk_bf16_f32 v36, v38, v39
	v_mfma_f32_16x16x32_bf16 v[86:89], v[188:191], v[172:175], v[86:89]
	ds_read_b128 v[156:159], v232 offset:2048
	v_mfma_f32_16x16x32_bf16 v[90:93], v[192:195], v[172:175], v[90:93]
	ds_read_b128 v[160:163], v232 offset:4096
	v_cvt_pk_bf16_f32 v37, v40, v41
	v_mfma_f32_16x16x32_bf16 v[94:97], v[196:199], v[172:175], v[94:97]
	ds_read_b128 v[164:167], v232 offset:6144
	s_add_u32 m0, s8, 0xc000
	v_mfma_f32_16x16x32_bf16 v[98:101], v[184:187], v[176:179], v[98:101]
	global_load_lds_dwordx4 v200, s[4:5]
	s_add_u32 m0, s8, 0xc400
	v_mfma_f32_16x16x32_bf16 v[102:105], v[188:191], v[176:179], v[102:105]
	global_load_lds_dwordx4 v201, s[4:5]
	global_store_dwordx4 v241, v[34:37], s[10:11] offset:0 sc1
	s_add_u32 m0, s8, 0xc800
	v_mfma_f32_16x16x32_bf16 v[106:109], v[192:195], v[176:179], v[106:109]
	global_load_lds_dwordx4 v202, s[4:5]
	s_add_u32 m0, s8, 0xcc00
	v_mfma_f32_16x16x32_bf16 v[110:113], v[196:199], v[176:179], v[110:113]
	global_load_lds_dwordx4 v203, s[4:5]
	v_mul_f32_e32 v42, s12, v42
	s_add_u32 m0, s9, 0xc000
	v_mfma_f32_16x16x32_bf16 v[114:117], v[184:187], v[180:183], v[114:117]
	global_load_lds_dwordx4 v204, s[6:7]
	s_add_u32 m0, s9, 0xc400
	v_mfma_f32_16x16x32_bf16 v[118:121], v[188:191], v[180:183], v[118:121]
	global_load_lds_dwordx4 v205, s[6:7]
	v_mul_f32_e32 v43, s12, v43
	v_mfma_f32_16x16x32_bf16 v[122:125], v[192:195], v[180:183], v[122:125]
	s_add_u32 s4, s4, 0x80
	s_addc_u32 s5, s5, 0
	v_mfma_f32_16x16x32_bf16 v[126:129], v[196:199], v[180:183], v[126:129]
	s_add_u32 s6, s6, 0x80
	s_addc_u32 s7, s7, 0
	v_mul_f32_e32 v44, s12, v44
	s_waitcnt lgkmcnt(0)
	v_mfma_f32_16x16x32_bf16 v[66:69], v[152:155], v[136:139], v[66:69]
	ds_read_b128 v[168:171], v229 offset:0
	v_mfma_f32_16x16x32_bf16 v[70:73], v[156:159], v[136:139], v[70:73]
	ds_read_b128 v[172:175], v229 offset:2048
	v_mul_f32_e32 v45, s12, v45
	v_mfma_f32_16x16x32_bf16 v[74:77], v[160:163], v[136:139], v[74:77]
	ds_read_b128 v[176:179], v229 offset:4096
	v_mul_f32_e32 v46, s12, v46
	v_mfma_f32_16x16x32_bf16 v[78:81], v[164:167], v[136:139], v[78:81]
	ds_read_b128 v[180:183], v229 offset:6144
	v_mul_f32_e32 v47, s12, v47
	v_mfma_f32_16x16x32_bf16 v[82:85], v[152:155], v[140:143], v[82:85]
	ds_read_b128 v[184:187], v235 offset:0
	v_mfma_f32_16x16x32_bf16 v[86:89], v[156:159], v[140:143], v[86:89]
	ds_read_b128 v[188:191], v235 offset:2048
	v_mul_f32_e32 v48, s12, v48
	v_mfma_f32_16x16x32_bf16 v[90:93], v[160:163], v[140:143], v[90:93]
	ds_read_b128 v[192:195], v235 offset:4096
	v_mul_f32_e32 v49, s12, v49
	v_mfma_f32_16x16x32_bf16 v[94:97], v[164:167], v[140:143], v[94:97]
	ds_read_b128 v[196:199], v235 offset:6144
	v_exp_f32_e32 v42, v42
	v_mfma_f32_16x16x32_bf16 v[98:101], v[152:155], v[144:147], v[98:101]
	v_mfma_f32_16x16x32_bf16 v[102:105], v[156:159], v[144:147], v[102:105]
	v_exp_f32_e32 v43, v43
	v_mfma_f32_16x16x32_bf16 v[106:109], v[160:163], v[144:147], v[106:109]
	v_exp_f32_e32 v44, v44
	v_mfma_f32_16x16x32_bf16 v[110:113], v[164:167], v[144:147], v[110:113]
	v_exp_f32_e32 v45, v45
	v_mfma_f32_16x16x32_bf16 v[114:117], v[152:155], v[148:151], v[114:117]
	v_mfma_f32_16x16x32_bf16 v[118:121], v[156:159], v[148:151], v[118:121]
	v_exp_f32_e32 v46, v46
	v_mfma_f32_16x16x32_bf16 v[122:125], v[160:163], v[148:151], v[122:125]
	v_exp_f32_e32 v47, v47
	v_mfma_f32_16x16x32_bf16 v[126:129], v[164:167], v[148:151], v[126:129]
	v_exp_f32_e32 v48, v48
	s_waitcnt vmcnt(7) lgkmcnt(0)
	s_barrier
	v_mfma_f32_16x16x32_bf16 v[66:69], v[184:187], v[168:171], v[66:69]
	ds_read_b128 v[136:139], v218 offset:0
	v_mfma_f32_16x16x32_bf16 v[70:73], v[188:191], v[168:171], v[70:73]
	ds_read_b128 v[140:143], v218 offset:2048
	v_mfma_f32_16x16x32_bf16 v[74:77], v[192:195], v[168:171], v[74:77]
	ds_read_b128 v[144:147], v218 offset:4096
	v_exp_f32_e32 v49, v49
	v_mfma_f32_16x16x32_bf16 v[78:81], v[196:199], v[168:171], v[78:81]
	ds_read_b128 v[148:151], v218 offset:6144
	v_mfma_f32_16x16x32_bf16 v[82:85], v[184:187], v[172:175], v[82:85]
	ds_read_b128 v[152:155], v230 offset:0
	v_add_f32_e32 v42, 1.0, v42
	v_mfma_f32_16x16x32_bf16 v[86:89], v[188:191], v[172:175], v[86:89]
	ds_read_b128 v[156:159], v230 offset:2048
	v_mfma_f32_16x16x32_bf16 v[90:93], v[192:195], v[172:175], v[90:93]
	ds_read_b128 v[160:163], v230 offset:4096
	v_add_f32_e32 v43, 1.0, v43
	v_mfma_f32_16x16x32_bf16 v[94:97], v[196:199], v[172:175], v[94:97]
	ds_read_b128 v[164:167], v230 offset:6144
	s_add_u32 m0, s8, 0x18000
	v_mfma_f32_16x16x32_bf16 v[98:101], v[184:187], v[176:179], v[98:101]
	global_load_lds_dwordx4 v200, s[4:5]
	s_add_u32 m0, s8, 0x18400
	v_mfma_f32_16x16x32_bf16 v[102:105], v[188:191], v[176:179], v[102:105]
	global_load_lds_dwordx4 v201, s[4:5]
	v_add_f32_e32 v44, 1.0, v44
	s_add_u32 m0, s8, 0x18800
	v_mfma_f32_16x16x32_bf16 v[106:109], v[192:195], v[176:179], v[106:109]
	global_load_lds_dwordx4 v202, s[4:5]
	s_add_u32 m0, s8, 0x18c00
	v_mfma_f32_16x16x32_bf16 v[110:113], v[196:199], v[176:179], v[110:113]
	global_load_lds_dwordx4 v203, s[4:5]
	v_add_f32_e32 v45, 1.0, v45
	s_add_u32 m0, s9, 0x18000
	v_mfma_f32_16x16x32_bf16 v[114:117], v[184:187], v[180:183], v[114:117]
	global_load_lds_dwordx4 v204, s[6:7]
	s_add_u32 m0, s9, 0x18400
	v_mfma_f32_16x16x32_bf16 v[118:121], v[188:191], v[180:183], v[118:121]
	global_load_lds_dwordx4 v205, s[6:7]
	v_add_f32_e32 v46, 1.0, v46
	v_mfma_f32_16x16x32_bf16 v[122:125], v[192:195], v[180:183], v[122:125]
	s_add_u32 s4, s4, 0x80
	s_addc_u32 s5, s5, 0
	v_mfma_f32_16x16x32_bf16 v[126:129], v[196:199], v[180:183], v[126:129]
	s_add_u32 s6, s6, 0x80
	s_addc_u32 s7, s7, 0
	v_add_f32_e32 v47, 1.0, v47
	s_waitcnt lgkmcnt(0)
	v_mfma_f32_16x16x32_bf16 v[66:69], v[152:155], v[136:139], v[66:69]
	ds_read_b128 v[168:171], v225 offset:0
	v_mfma_f32_16x16x32_bf16 v[70:73], v[156:159], v[136:139], v[70:73]
	ds_read_b128 v[172:175], v225 offset:2048
	v_add_f32_e32 v48, 1.0, v48
	v_mfma_f32_16x16x32_bf16 v[74:77], v[160:163], v[136:139], v[74:77]
	ds_read_b128 v[176:179], v225 offset:4096
	v_add_f32_e32 v49, 1.0, v49
	v_mfma_f32_16x16x32_bf16 v[78:81], v[164:167], v[136:139], v[78:81]
	ds_read_b128 v[180:183], v225 offset:6144
	v_rcp_f32_e32 v42, v42
	v_mfma_f32_16x16x32_bf16 v[82:85], v[152:155], v[140:143], v[82:85]
	ds_read_b128 v[184:187], v233 offset:0
	v_mfma_f32_16x16x32_bf16 v[86:89], v[156:159], v[140:143], v[86:89]
	ds_read_b128 v[188:191], v233 offset:2048
	v_rcp_f32_e32 v43, v43
	v_mfma_f32_16x16x32_bf16 v[90:93], v[160:163], v[140:143], v[90:93]
	ds_read_b128 v[192:195], v233 offset:4096
	v_rcp_f32_e32 v44, v44
	v_mfma_f32_16x16x32_bf16 v[94:97], v[164:167], v[140:143], v[94:97]
	ds_read_b128 v[196:199], v233 offset:6144
	v_rcp_f32_e32 v45, v45
	v_mfma_f32_16x16x32_bf16 v[98:101], v[152:155], v[144:147], v[98:101]
	v_mfma_f32_16x16x32_bf16 v[102:105], v[156:159], v[144:147], v[102:105]
	v_rcp_f32_e32 v46, v46
	v_mfma_f32_16x16x32_bf16 v[106:109], v[160:163], v[144:147], v[106:109]
	v_rcp_f32_e32 v47, v47
	v_mfma_f32_16x16x32_bf16 v[110:113], v[164:167], v[144:147], v[110:113]
	v_rcp_f32_e32 v48, v48
	v_mfma_f32_16x16x32_bf16 v[114:117], v[152:155], v[148:151], v[114:117]
	v_mfma_f32_16x16x32_bf16 v[118:121], v[156:159], v[148:151], v[118:121]
	v_rcp_f32_e32 v49, v49
	v_mfma_f32_16x16x32_bf16 v[122:125], v[160:163], v[148:151], v[122:125]
	v_cvt_pk_bf16_f32 v42, v42, v43
	v_mfma_f32_16x16x32_bf16 v[126:129], v[164:167], v[148:151], v[126:129]
	v_cvt_pk_bf16_f32 v43, v44, v45
	s_waitcnt vmcnt(6) lgkmcnt(0)
	s_barrier
	v_mfma_f32_16x16x32_bf16 v[66:69], v[184:187], v[168:171], v[66:69]
	ds_read_b128 v[136:139], v219 offset:0
	v_mfma_f32_16x16x32_bf16 v[70:73], v[188:191], v[168:171], v[70:73]
	ds_read_b128 v[140:143], v219 offset:2048
	v_mfma_f32_16x16x32_bf16 v[74:77], v[192:195], v[168:171], v[74:77]
	ds_read_b128 v[144:147], v219 offset:4096
	v_cvt_pk_bf16_f32 v44, v46, v47
	v_mfma_f32_16x16x32_bf16 v[78:81], v[196:199], v[168:171], v[78:81]
	ds_read_b128 v[148:151], v219 offset:6144
	v_mfma_f32_16x16x32_bf16 v[82:85], v[184:187], v[172:175], v[82:85]
	ds_read_b128 v[152:155], v231 offset:0
	v_cvt_pk_bf16_f32 v45, v48, v49
	v_mfma_f32_16x16x32_bf16 v[86:89], v[188:191], v[172:175], v[86:89]
	ds_read_b128 v[156:159], v231 offset:2048
	v_mfma_f32_16x16x32_bf16 v[90:93], v[192:195], v[172:175], v[90:93]
	ds_read_b128 v[160:163], v231 offset:4096
	global_store_dwordx4 v241, v[42:45], s[10:11] offset:1024 sc1
	v_mfma_f32_16x16x32_bf16 v[94:97], v[196:199], v[172:175], v[94:97]
	ds_read_b128 v[164:167], v231 offset:6144
	s_mov_b32 m0, s8
	v_mfma_f32_16x16x32_bf16 v[98:101], v[184:187], v[176:179], v[98:101]
	global_load_lds_dwordx4 v200, s[4:5]
	s_add_u32 m0, s8, 0x400
	v_mfma_f32_16x16x32_bf16 v[102:105], v[188:191], v[176:179], v[102:105]
	global_load_lds_dwordx4 v201, s[4:5]
	v_mul_f32_e32 v50, s12, v50
	s_add_u32 m0, s8, 0x800
	v_mfma_f32_16x16x32_bf16 v[106:109], v[192:195], v[176:179], v[106:109]
	global_load_lds_dwordx4 v202, s[4:5]
	s_add_u32 m0, s8, 0xc00
	v_mfma_f32_16x16x32_bf16 v[110:113], v[196:199], v[176:179], v[110:113]
	global_load_lds_dwordx4 v203, s[4:5]
	v_mul_f32_e32 v51, s12, v51
	s_mov_b32 m0, s9
	v_mfma_f32_16x16x32_bf16 v[114:117], v[184:187], v[180:183], v[114:117]
	global_load_lds_dwordx4 v204, s[6:7]
	s_add_u32 m0, s9, 0x400
	v_mfma_f32_16x16x32_bf16 v[118:121], v[188:191], v[180:183], v[118:121]
	global_load_lds_dwordx4 v205, s[6:7]
	v_mul_f32_e32 v52, s12, v52
	v_mfma_f32_16x16x32_bf16 v[122:125], v[192:195], v[180:183], v[122:125]
	s_add_u32 s4, s4, 0x80
	s_addc_u32 s5, s5, 0
	v_mfma_f32_16x16x32_bf16 v[126:129], v[196:199], v[180:183], v[126:129]
	s_add_u32 s6, s6, 0x80
	s_addc_u32 s7, s7, 0
	v_mul_f32_e32 v53, s12, v53
	s_waitcnt lgkmcnt(0)
	v_mfma_f32_16x16x32_bf16 v[66:69], v[152:155], v[136:139], v[66:69]
	ds_read_b128 v[168:171], v228 offset:0
	v_mfma_f32_16x16x32_bf16 v[70:73], v[156:159], v[136:139], v[70:73]
	ds_read_b128 v[172:175], v228 offset:2048
	v_mul_f32_e32 v54, s12, v54
	v_mfma_f32_16x16x32_bf16 v[74:77], v[160:163], v[136:139], v[74:77]
	ds_read_b128 v[176:179], v228 offset:4096
	v_mul_f32_e32 v55, s12, v55
	v_mfma_f32_16x16x32_bf16 v[78:81], v[164:167], v[136:139], v[78:81]
	ds_read_b128 v[180:183], v228 offset:6144
	v_mul_f32_e32 v56, s12, v56
	v_mfma_f32_16x16x32_bf16 v[82:85], v[152:155], v[140:143], v[82:85]
	ds_read_b128 v[184:187], v234 offset:0
	v_mfma_f32_16x16x32_bf16 v[86:89], v[156:159], v[140:143], v[86:89]
	ds_read_b128 v[188:191], v234 offset:2048
	v_mul_f32_e32 v57, s12, v57
	v_mfma_f32_16x16x32_bf16 v[90:93], v[160:163], v[140:143], v[90:93]
	ds_read_b128 v[192:195], v234 offset:4096
	v_exp_f32_e32 v50, v50
	v_mfma_f32_16x16x32_bf16 v[94:97], v[164:167], v[140:143], v[94:97]
	ds_read_b128 v[196:199], v234 offset:6144
	v_exp_f32_e32 v51, v51
	v_mfma_f32_16x16x32_bf16 v[98:101], v[152:155], v[144:147], v[98:101]
	v_mfma_f32_16x16x32_bf16 v[102:105], v[156:159], v[144:147], v[102:105]
	v_exp_f32_e32 v52, v52
	v_mfma_f32_16x16x32_bf16 v[106:109], v[160:163], v[144:147], v[106:109]
	v_exp_f32_e32 v53, v53
	v_mfma_f32_16x16x32_bf16 v[110:113], v[164:167], v[144:147], v[110:113]
	v_exp_f32_e32 v54, v54
	v_mfma_f32_16x16x32_bf16 v[114:117], v[152:155], v[148:151], v[114:117]
	v_mfma_f32_16x16x32_bf16 v[118:121], v[156:159], v[148:151], v[118:121]
	v_exp_f32_e32 v55, v55
	v_mfma_f32_16x16x32_bf16 v[122:125], v[160:163], v[148:151], v[122:125]
	v_exp_f32_e32 v56, v56
	v_mfma_f32_16x16x32_bf16 v[126:129], v[164:167], v[148:151], v[126:129]
	v_exp_f32_e32 v57, v57
	s_waitcnt vmcnt(7) lgkmcnt(0)
	s_barrier
	v_mfma_f32_16x16x32_bf16 v[66:69], v[184:187], v[168:171], v[66:69]
	ds_read_b128 v[136:139], v224 offset:0
	v_mfma_f32_16x16x32_bf16 v[70:73], v[188:191], v[168:171], v[70:73]
	ds_read_b128 v[140:143], v224 offset:2048
	v_mfma_f32_16x16x32_bf16 v[74:77], v[192:195], v[168:171], v[74:77]
	ds_read_b128 v[144:147], v224 offset:4096
	v_add_f32_e32 v50, 1.0, v50
	v_mfma_f32_16x16x32_bf16 v[78:81], v[196:199], v[168:171], v[78:81]
	ds_read_b128 v[148:151], v224 offset:6144
	v_mfma_f32_16x16x32_bf16 v[82:85], v[184:187], v[172:175], v[82:85]
	ds_read_b128 v[152:155], v232 offset:0
	v_add_f32_e32 v51, 1.0, v51
	v_mfma_f32_16x16x32_bf16 v[86:89], v[188:191], v[172:175], v[86:89]
	ds_read_b128 v[156:159], v232 offset:2048
	v_mfma_f32_16x16x32_bf16 v[90:93], v[192:195], v[172:175], v[90:93]
	ds_read_b128 v[160:163], v232 offset:4096
	v_add_f32_e32 v52, 1.0, v52
	v_mfma_f32_16x16x32_bf16 v[94:97], v[196:199], v[172:175], v[94:97]
	ds_read_b128 v[164:167], v232 offset:6144
	s_add_u32 m0, s8, 0xc000
	v_mfma_f32_16x16x32_bf16 v[98:101], v[184:187], v[176:179], v[98:101]
	global_load_lds_dwordx4 v200, s[4:5]
	s_add_u32 m0, s8, 0xc400
	v_mfma_f32_16x16x32_bf16 v[102:105], v[188:191], v[176:179], v[102:105]
	global_load_lds_dwordx4 v201, s[4:5]
	v_add_f32_e32 v53, 1.0, v53
	s_add_u32 m0, s8, 0xc800
	v_mfma_f32_16x16x32_bf16 v[106:109], v[192:195], v[176:179], v[106:109]
	global_load_lds_dwordx4 v202, s[4:5]
	s_add_u32 m0, s8, 0xcc00
	v_mfma_f32_16x16x32_bf16 v[110:113], v[196:199], v[176:179], v[110:113]
	global_load_lds_dwordx4 v203, s[4:5]
	v_add_f32_e32 v54, 1.0, v54
	s_add_u32 m0, s9, 0xc000
	v_mfma_f32_16x16x32_bf16 v[114:117], v[184:187], v[180:183], v[114:117]
	global_load_lds_dwordx4 v204, s[6:7]
	s_add_u32 m0, s9, 0xc400
	v_mfma_f32_16x16x32_bf16 v[118:121], v[188:191], v[180:183], v[118:121]
	global_load_lds_dwordx4 v205, s[6:7]
	v_add_f32_e32 v55, 1.0, v55
	v_mfma_f32_16x16x32_bf16 v[122:125], v[192:195], v[180:183], v[122:125]
	s_sub_u32 s4, s4, 0x780
	s_subb_u32 s5, s5, 0
	v_mfma_f32_16x16x32_bf16 v[126:129], v[196:199], v[180:183], v[126:129]
	s_add_u32 s6, s6, 0x3f880
	s_addc_u32 s7, s7, 0
	v_add_f32_e32 v56, 1.0, v56
	s_waitcnt lgkmcnt(0)
	v_mfma_f32_16x16x32_bf16 v[66:69], v[152:155], v[136:139], v[66:69]
	ds_read_b128 v[168:171], v229 offset:0
	v_mfma_f32_16x16x32_bf16 v[70:73], v[156:159], v[136:139], v[70:73]
	ds_read_b128 v[172:175], v229 offset:2048
	v_add_f32_e32 v57, 1.0, v57
	v_mfma_f32_16x16x32_bf16 v[74:77], v[160:163], v[136:139], v[74:77]
	ds_read_b128 v[176:179], v229 offset:4096
	v_rcp_f32_e32 v50, v50
	v_mfma_f32_16x16x32_bf16 v[78:81], v[164:167], v[136:139], v[78:81]
	ds_read_b128 v[180:183], v229 offset:6144
	v_rcp_f32_e32 v51, v51
	v_mfma_f32_16x16x32_bf16 v[82:85], v[152:155], v[140:143], v[82:85]
	ds_read_b128 v[184:187], v235 offset:0
	v_mfma_f32_16x16x32_bf16 v[86:89], v[156:159], v[140:143], v[86:89]
	ds_read_b128 v[188:191], v235 offset:2048
	v_rcp_f32_e32 v52, v52
	v_mfma_f32_16x16x32_bf16 v[90:93], v[160:163], v[140:143], v[90:93]
	ds_read_b128 v[192:195], v235 offset:4096
	v_rcp_f32_e32 v53, v53
	v_mfma_f32_16x16x32_bf16 v[94:97], v[164:167], v[140:143], v[94:97]
	ds_read_b128 v[196:199], v235 offset:6144
	v_rcp_f32_e32 v54, v54
	v_mfma_f32_16x16x32_bf16 v[98:101], v[152:155], v[144:147], v[98:101]
	v_mfma_f32_16x16x32_bf16 v[102:105], v[156:159], v[144:147], v[102:105]
	v_rcp_f32_e32 v55, v55
	v_mfma_f32_16x16x32_bf16 v[106:109], v[160:163], v[144:147], v[106:109]
	v_rcp_f32_e32 v56, v56
	v_mfma_f32_16x16x32_bf16 v[110:113], v[164:167], v[144:147], v[110:113]
	v_rcp_f32_e32 v57, v57
	v_mfma_f32_16x16x32_bf16 v[114:117], v[152:155], v[148:151], v[114:117]
	v_mfma_f32_16x16x32_bf16 v[118:121], v[156:159], v[148:151], v[118:121]
	v_cvt_pk_bf16_f32 v50, v50, v51
	v_mfma_f32_16x16x32_bf16 v[122:125], v[160:163], v[148:151], v[122:125]
	v_cvt_pk_bf16_f32 v51, v52, v53
	v_mfma_f32_16x16x32_bf16 v[126:129], v[164:167], v[148:151], v[126:129]
	v_cvt_pk_bf16_f32 v52, v54, v55
	s_waitcnt vmcnt(6) lgkmcnt(0)
	s_barrier
	v_mfma_f32_16x16x32_bf16 v[66:69], v[184:187], v[168:171], v[66:69]
	ds_read_b128 v[136:139], v218 offset:0
	v_mfma_f32_16x16x32_bf16 v[70:73], v[188:191], v[168:171], v[70:73]
	ds_read_b128 v[140:143], v218 offset:2048
	v_mfma_f32_16x16x32_bf16 v[74:77], v[192:195], v[168:171], v[74:77]
	ds_read_b128 v[144:147], v218 offset:4096
	v_cvt_pk_bf16_f32 v53, v56, v57
	v_mfma_f32_16x16x32_bf16 v[78:81], v[196:199], v[168:171], v[78:81]
	ds_read_b128 v[148:151], v218 offset:6144
	v_mfma_f32_16x16x32_bf16 v[82:85], v[184:187], v[172:175], v[82:85]
	ds_read_b128 v[152:155], v230 offset:0
	global_store_dwordx4 v241, v[50:53], s[10:11] offset:2048 sc1
	v_mfma_f32_16x16x32_bf16 v[86:89], v[188:191], v[172:175], v[86:89]
	ds_read_b128 v[156:159], v230 offset:2048
	v_mfma_f32_16x16x32_bf16 v[90:93], v[192:195], v[172:175], v[90:93]
	ds_read_b128 v[160:163], v230 offset:4096
	v_mul_f32_e32 v58, s12, v58
	v_mfma_f32_16x16x32_bf16 v[94:97], v[196:199], v[172:175], v[94:97]
	ds_read_b128 v[164:167], v230 offset:6144
	s_add_u32 m0, s8, 0x18000
	v_mfma_f32_16x16x32_bf16 v[98:101], v[184:187], v[176:179], v[98:101]
	global_load_lds_dwordx4 v200, s[4:5]
	s_add_u32 m0, s8, 0x18400
	v_mfma_f32_16x16x32_bf16 v[102:105], v[188:191], v[176:179], v[102:105]
	global_load_lds_dwordx4 v201, s[4:5]
	v_mul_f32_e32 v59, s12, v59
	s_add_u32 m0, s8, 0x18800
	v_mfma_f32_16x16x32_bf16 v[106:109], v[192:195], v[176:179], v[106:109]
	global_load_lds_dwordx4 v202, s[4:5]
	s_add_u32 m0, s8, 0x18c00
	v_mfma_f32_16x16x32_bf16 v[110:113], v[196:199], v[176:179], v[110:113]
	global_load_lds_dwordx4 v203, s[4:5]
	v_mul_f32_e32 v60, s12, v60
	s_add_u32 m0, s9, 0x18000
	v_mfma_f32_16x16x32_bf16 v[114:117], v[184:187], v[180:183], v[114:117]
	global_load_lds_dwordx4 v204, s[6:7]
	s_add_u32 m0, s9, 0x18400
	v_mfma_f32_16x16x32_bf16 v[118:121], v[188:191], v[180:183], v[118:121]
	global_load_lds_dwordx4 v205, s[6:7]
	v_mul_f32_e32 v61, s12, v61
	v_mfma_f32_16x16x32_bf16 v[122:125], v[192:195], v[180:183], v[122:125]
	s_add_u32 s4, s4, 0x80
	s_addc_u32 s5, s5, 0
	v_mfma_f32_16x16x32_bf16 v[126:129], v[196:199], v[180:183], v[126:129]
	s_add_u32 s6, s6, 0x80
	s_addc_u32 s7, s7, 0
	v_mul_f32_e32 v62, s12, v62
	s_waitcnt lgkmcnt(0)
	v_mfma_f32_16x16x32_bf16 v[66:69], v[152:155], v[136:139], v[66:69]
	ds_read_b128 v[168:171], v225 offset:0
	v_mfma_f32_16x16x32_bf16 v[70:73], v[156:159], v[136:139], v[70:73]
	ds_read_b128 v[172:175], v225 offset:2048
	v_mul_f32_e32 v63, s12, v63
	v_mfma_f32_16x16x32_bf16 v[74:77], v[160:163], v[136:139], v[74:77]
	ds_read_b128 v[176:179], v225 offset:4096
	v_mul_f32_e32 v64, s12, v64
	v_mfma_f32_16x16x32_bf16 v[78:81], v[164:167], v[136:139], v[78:81]
	ds_read_b128 v[180:183], v225 offset:6144
	v_mul_f32_e32 v65, s12, v65
	v_mfma_f32_16x16x32_bf16 v[82:85], v[152:155], v[140:143], v[82:85]
	ds_read_b128 v[184:187], v233 offset:0
	v_mfma_f32_16x16x32_bf16 v[86:89], v[156:159], v[140:143], v[86:89]
	ds_read_b128 v[188:191], v233 offset:2048
	v_exp_f32_e32 v58, v58
	v_mfma_f32_16x16x32_bf16 v[90:93], v[160:163], v[140:143], v[90:93]
	ds_read_b128 v[192:195], v233 offset:4096
	v_exp_f32_e32 v59, v59
	v_mfma_f32_16x16x32_bf16 v[94:97], v[164:167], v[140:143], v[94:97]
	ds_read_b128 v[196:199], v233 offset:6144
	v_exp_f32_e32 v60, v60
	v_mfma_f32_16x16x32_bf16 v[98:101], v[152:155], v[144:147], v[98:101]
	v_mfma_f32_16x16x32_bf16 v[102:105], v[156:159], v[144:147], v[102:105]
	v_exp_f32_e32 v61, v61
	v_mfma_f32_16x16x32_bf16 v[106:109], v[160:163], v[144:147], v[106:109]
	v_exp_f32_e32 v62, v62
	v_mfma_f32_16x16x32_bf16 v[110:113], v[164:167], v[144:147], v[110:113]
	v_exp_f32_e32 v63, v63
	v_mfma_f32_16x16x32_bf16 v[114:117], v[152:155], v[148:151], v[114:117]
	v_mfma_f32_16x16x32_bf16 v[118:121], v[156:159], v[148:151], v[118:121]
	v_exp_f32_e32 v64, v64
	v_mfma_f32_16x16x32_bf16 v[122:125], v[160:163], v[148:151], v[122:125]
	v_exp_f32_e32 v65, v65
	v_mfma_f32_16x16x32_bf16 v[126:129], v[164:167], v[148:151], v[126:129]
	v_add_f32_e32 v58, 1.0, v58
	s_waitcnt vmcnt(7) lgkmcnt(0)
	s_barrier
	v_mfma_f32_16x16x32_bf16 v[66:69], v[184:187], v[168:171], v[66:69]
	ds_read_b128 v[136:139], v219 offset:0
	v_mfma_f32_16x16x32_bf16 v[70:73], v[188:191], v[168:171], v[70:73]
	ds_read_b128 v[140:143], v219 offset:2048
	v_mfma_f32_16x16x32_bf16 v[74:77], v[192:195], v[168:171], v[74:77]
	ds_read_b128 v[144:147], v219 offset:4096
	v_add_f32_e32 v59, 1.0, v59
	v_mfma_f32_16x16x32_bf16 v[78:81], v[196:199], v[168:171], v[78:81]
	ds_read_b128 v[148:151], v219 offset:6144
	v_mfma_f32_16x16x32_bf16 v[82:85], v[184:187], v[172:175], v[82:85]
	ds_read_b128 v[152:155], v231 offset:0
	v_add_f32_e32 v60, 1.0, v60
	v_mfma_f32_16x16x32_bf16 v[86:89], v[188:191], v[172:175], v[86:89]
	ds_read_b128 v[156:159], v231 offset:2048
	v_mfma_f32_16x16x32_bf16 v[90:93], v[192:195], v[172:175], v[90:93]
	ds_read_b128 v[160:163], v231 offset:4096
	v_add_f32_e32 v61, 1.0, v61
	v_mfma_f32_16x16x32_bf16 v[94:97], v[196:199], v[172:175], v[94:97]
	ds_read_b128 v[164:167], v231 offset:6144
	s_mov_b32 m0, s8
	v_mfma_f32_16x16x32_bf16 v[98:101], v[184:187], v[176:179], v[98:101]
	global_load_lds_dwordx4 v200, s[4:5]
	s_add_u32 m0, s8, 0x400
	v_mfma_f32_16x16x32_bf16 v[102:105], v[188:191], v[176:179], v[102:105]
	global_load_lds_dwordx4 v201, s[4:5]
	v_add_f32_e32 v62, 1.0, v62
	s_add_u32 m0, s8, 0x800
	v_mfma_f32_16x16x32_bf16 v[106:109], v[192:195], v[176:179], v[106:109]
	global_load_lds_dwordx4 v202, s[4:5]
	s_add_u32 m0, s8, 0xc00
	v_mfma_f32_16x16x32_bf16 v[110:113], v[196:199], v[176:179], v[110:113]
	global_load_lds_dwordx4 v203, s[4:5]
	v_add_f32_e32 v63, 1.0, v63
	s_mov_b32 m0, s9
	v_mfma_f32_16x16x32_bf16 v[114:117], v[184:187], v[180:183], v[114:117]
	global_load_lds_dwordx4 v204, s[6:7]
	s_add_u32 m0, s9, 0x400
	v_mfma_f32_16x16x32_bf16 v[118:121], v[188:191], v[180:183], v[118:121]
	global_load_lds_dwordx4 v205, s[6:7]
	v_add_f32_e32 v64, 1.0, v64
	v_mfma_f32_16x16x32_bf16 v[122:125], v[192:195], v[180:183], v[122:125]
	s_add_u32 s4, s4, 0x80
	s_addc_u32 s5, s5, 0
	v_mfma_f32_16x16x32_bf16 v[126:129], v[196:199], v[180:183], v[126:129]
	s_add_u32 s6, s6, 0x80
	s_addc_u32 s7, s7, 0
	v_add_f32_e32 v65, 1.0, v65
	s_waitcnt lgkmcnt(0)
	v_mfma_f32_16x16x32_bf16 v[66:69], v[152:155], v[136:139], v[66:69]
	ds_read_b128 v[168:171], v228 offset:0
	v_mfma_f32_16x16x32_bf16 v[70:73], v[156:159], v[136:139], v[70:73]
	ds_read_b128 v[172:175], v228 offset:2048
	v_rcp_f32_e32 v58, v58
	v_mfma_f32_16x16x32_bf16 v[74:77], v[160:163], v[136:139], v[74:77]
	ds_read_b128 v[176:179], v228 offset:4096
	v_rcp_f32_e32 v59, v59
	v_mfma_f32_16x16x32_bf16 v[78:81], v[164:167], v[136:139], v[78:81]
	ds_read_b128 v[180:183], v228 offset:6144
	v_rcp_f32_e32 v60, v60
	v_mfma_f32_16x16x32_bf16 v[82:85], v[152:155], v[140:143], v[82:85]
	ds_read_b128 v[184:187], v234 offset:0
	v_mfma_f32_16x16x32_bf16 v[86:89], v[156:159], v[140:143], v[86:89]
	ds_read_b128 v[188:191], v234 offset:2048
	v_rcp_f32_e32 v61, v61
	v_mfma_f32_16x16x32_bf16 v[90:93], v[160:163], v[140:143], v[90:93]
	ds_read_b128 v[192:195], v234 offset:4096
	v_rcp_f32_e32 v62, v62
	v_mfma_f32_16x16x32_bf16 v[94:97], v[164:167], v[140:143], v[94:97]
	ds_read_b128 v[196:199], v234 offset:6144
	v_rcp_f32_e32 v63, v63
	v_mfma_f32_16x16x32_bf16 v[98:101], v[152:155], v[144:147], v[98:101]
	v_mfma_f32_16x16x32_bf16 v[102:105], v[156:159], v[144:147], v[102:105]
	v_rcp_f32_e32 v64, v64
	v_mfma_f32_16x16x32_bf16 v[106:109], v[160:163], v[144:147], v[106:109]
	v_rcp_f32_e32 v65, v65
	v_mfma_f32_16x16x32_bf16 v[110:113], v[164:167], v[144:147], v[110:113]
	v_cvt_pk_bf16_f32 v58, v58, v59
	v_mfma_f32_16x16x32_bf16 v[114:117], v[152:155], v[148:151], v[114:117]
	v_mfma_f32_16x16x32_bf16 v[118:121], v[156:159], v[148:151], v[118:121]
	v_cvt_pk_bf16_f32 v59, v60, v61
	v_mfma_f32_16x16x32_bf16 v[122:125], v[160:163], v[148:151], v[122:125]
	v_cvt_pk_bf16_f32 v60, v62, v63
	v_mfma_f32_16x16x32_bf16 v[126:129], v[164:167], v[148:151], v[126:129]
	v_cvt_pk_bf16_f32 v61, v64, v65
	s_waitcnt vmcnt(6) lgkmcnt(0)
	s_barrier
	v_mfma_f32_16x16x32_bf16 v[66:69], v[184:187], v[168:171], v[66:69]
	ds_read_b128 v[136:139], v224 offset:0
	v_mfma_f32_16x16x32_bf16 v[70:73], v[188:191], v[168:171], v[70:73]
	ds_read_b128 v[140:143], v224 offset:2048
	v_mfma_f32_16x16x32_bf16 v[74:77], v[192:195], v[168:171], v[74:77]
	ds_read_b128 v[144:147], v224 offset:4096
	v_mfma_f32_16x16x32_bf16 v[78:81], v[196:199], v[168:171], v[78:81]
	ds_read_b128 v[148:151], v224 offset:6144
	v_mfma_f32_16x16x32_bf16 v[82:85], v[184:187], v[172:175], v[82:85]
	ds_read_b128 v[152:155], v232 offset:0
	v_mfma_f32_16x16x32_bf16 v[86:89], v[188:191], v[172:175], v[86:89]
	ds_read_b128 v[156:159], v232 offset:2048
	v_mfma_f32_16x16x32_bf16 v[90:93], v[192:195], v[172:175], v[90:93]
	ds_read_b128 v[160:163], v232 offset:4096
	v_mfma_f32_16x16x32_bf16 v[94:97], v[196:199], v[172:175], v[94:97]
	ds_read_b128 v[164:167], v232 offset:6144
	s_add_u32 m0, s8, 0xc000
	v_mfma_f32_16x16x32_bf16 v[98:101], v[184:187], v[176:179], v[98:101]
	global_load_lds_dwordx4 v200, s[4:5]
	s_add_u32 m0, s8, 0xc400
	v_mfma_f32_16x16x32_bf16 v[102:105], v[188:191], v[176:179], v[102:105]
	global_load_lds_dwordx4 v201, s[4:5]
	s_add_u32 m0, s8, 0xc800
	v_mfma_f32_16x16x32_bf16 v[106:109], v[192:195], v[176:179], v[106:109]
	global_load_lds_dwordx4 v202, s[4:5]
	s_add_u32 m0, s8, 0xcc00
	v_mfma_f32_16x16x32_bf16 v[110:113], v[196:199], v[176:179], v[110:113]
	global_load_lds_dwordx4 v203, s[4:5]
	s_add_u32 m0, s9, 0xc000
	v_mfma_f32_16x16x32_bf16 v[114:117], v[184:187], v[180:183], v[114:117]
	global_load_lds_dwordx4 v204, s[6:7]
	s_add_u32 m0, s9, 0xc400
	v_mfma_f32_16x16x32_bf16 v[118:121], v[188:191], v[180:183], v[118:121]
	global_load_lds_dwordx4 v205, s[6:7]
	v_mfma_f32_16x16x32_bf16 v[122:125], v[192:195], v[180:183], v[122:125]
	s_add_u32 s4, s4, 0x80
	s_addc_u32 s5, s5, 0
	v_mfma_f32_16x16x32_bf16 v[126:129], v[196:199], v[180:183], v[126:129]
	s_add_u32 s6, s6, 0x80
	s_addc_u32 s7, s7, 0
	global_store_dwordx4 v241, v[58:61], s[10:11] offset:3072 sc1
	s_waitcnt lgkmcnt(0)
	v_mfma_f32_16x16x32_bf16 v[2:5], v[152:155], v[136:139], 0
	ds_read_b128 v[168:171], v229 offset:0
	v_mfma_f32_16x16x32_bf16 v[6:9], v[156:159], v[136:139], 0
	ds_read_b128 v[172:175], v229 offset:2048
	s_add_u32 s10, s28, s13
	s_addc_u32 s11, s29, 0
	v_mfma_f32_16x16x32_bf16 v[10:13], v[160:163], v[136:139], 0
	ds_read_b128 v[176:179], v229 offset:4096
	s_add_u32 s13, s13, 0x10000
	v_mfma_f32_16x16x32_bf16 v[14:17], v[164:167], v[136:139], 0
	ds_read_b128 v[180:183], v229 offset:6144
	v_mul_f32_e32 v66, s12, v66
	v_mfma_f32_16x16x32_bf16 v[18:21], v[152:155], v[140:143], 0
	ds_read_b128 v[184:187], v235 offset:0
	v_mfma_f32_16x16x32_bf16 v[22:25], v[156:159], v[140:143], 0
	ds_read_b128 v[188:191], v235 offset:2048
	v_mul_f32_e32 v67, s12, v67
	v_mfma_f32_16x16x32_bf16 v[26:29], v[160:163], v[140:143], 0
	ds_read_b128 v[192:195], v235 offset:4096
	v_mul_f32_e32 v68, s12, v68
	v_mfma_f32_16x16x32_bf16 v[30:33], v[164:167], v[140:143], 0
	ds_read_b128 v[196:199], v235 offset:6144
	v_mul_f32_e32 v69, s12, v69
	v_mfma_f32_16x16x32_bf16 v[34:37], v[152:155], v[144:147], 0
	v_mfma_f32_16x16x32_bf16 v[38:41], v[156:159], v[144:147], 0
	v_mul_f32_e32 v70, s12, v70
	v_mfma_f32_16x16x32_bf16 v[42:45], v[160:163], v[144:147], 0
	v_mul_f32_e32 v71, s12, v71
	v_mfma_f32_16x16x32_bf16 v[46:49], v[164:167], v[144:147], 0
	v_mul_f32_e32 v72, s12, v72
	v_mfma_f32_16x16x32_bf16 v[50:53], v[152:155], v[148:151], 0
	v_mfma_f32_16x16x32_bf16 v[54:57], v[156:159], v[148:151], 0
	v_mul_f32_e32 v73, s12, v73
	v_mfma_f32_16x16x32_bf16 v[58:61], v[160:163], v[148:151], 0
	v_exp_f32_e32 v66, v66
	v_mfma_f32_16x16x32_bf16 v[62:65], v[164:167], v[148:151], 0
	v_exp_f32_e32 v67, v67
	s_waitcnt vmcnt(7) lgkmcnt(0)
	s_barrier
	v_mfma_f32_16x16x32_bf16 v[2:5], v[184:187], v[168:171], v[2:5]
	ds_read_b128 v[136:139], v218 offset:0
	v_mfma_f32_16x16x32_bf16 v[6:9], v[188:191], v[168:171], v[6:9]
	ds_read_b128 v[140:143], v218 offset:2048
	v_mfma_f32_16x16x32_bf16 v[10:13], v[192:195], v[168:171], v[10:13]
	ds_read_b128 v[144:147], v218 offset:4096
	v_exp_f32_e32 v68, v68
	v_mfma_f32_16x16x32_bf16 v[14:17], v[196:199], v[168:171], v[14:17]
	ds_read_b128 v[148:151], v218 offset:6144
	v_mfma_f32_16x16x32_bf16 v[18:21], v[184:187], v[172:175], v[18:21]
	ds_read_b128 v[152:155], v230 offset:0
	v_exp_f32_e32 v69, v69
	v_mfma_f32_16x16x32_bf16 v[22:25], v[188:191], v[172:175], v[22:25]
	ds_read_b128 v[156:159], v230 offset:2048
	v_mfma_f32_16x16x32_bf16 v[26:29], v[192:195], v[172:175], v[26:29]
	ds_read_b128 v[160:163], v230 offset:4096
	v_exp_f32_e32 v70, v70
	v_mfma_f32_16x16x32_bf16 v[30:33], v[196:199], v[172:175], v[30:33]
	ds_read_b128 v[164:167], v230 offset:6144
	s_add_u32 m0, s8, 0x18000
	v_mfma_f32_16x16x32_bf16 v[34:37], v[184:187], v[176:179], v[34:37]
	global_load_lds_dwordx4 v200, s[4:5]
	s_add_u32 m0, s8, 0x18400
	v_mfma_f32_16x16x32_bf16 v[38:41], v[188:191], v[176:179], v[38:41]
	global_load_lds_dwordx4 v201, s[4:5]
	v_exp_f32_e32 v71, v71
	s_add_u32 m0, s8, 0x18800
	v_mfma_f32_16x16x32_bf16 v[42:45], v[192:195], v[176:179], v[42:45]
	global_load_lds_dwordx4 v202, s[4:5]
	s_add_u32 m0, s8, 0x18c00
	v_mfma_f32_16x16x32_bf16 v[46:49], v[196:199], v[176:179], v[46:49]
	global_load_lds_dwordx4 v203, s[4:5]
	v_exp_f32_e32 v72, v72
	s_add_u32 m0, s9, 0x18000
	v_mfma_f32_16x16x32_bf16 v[50:53], v[184:187], v[180:183], v[50:53]
	global_load_lds_dwordx4 v204, s[6:7]
	s_add_u32 m0, s9, 0x18400
	v_mfma_f32_16x16x32_bf16 v[54:57], v[188:191], v[180:183], v[54:57]
	global_load_lds_dwordx4 v205, s[6:7]
	v_exp_f32_e32 v73, v73
	v_mfma_f32_16x16x32_bf16 v[58:61], v[192:195], v[180:183], v[58:61]
	s_add_u32 s4, s4, 0x80
	s_addc_u32 s5, s5, 0
	v_mfma_f32_16x16x32_bf16 v[62:65], v[196:199], v[180:183], v[62:65]
	s_add_u32 s6, s6, 0x80
	s_addc_u32 s7, s7, 0
	v_add_f32_e32 v66, 1.0, v66
	s_waitcnt lgkmcnt(0)
	v_mfma_f32_16x16x32_bf16 v[2:5], v[152:155], v[136:139], v[2:5]
	ds_read_b128 v[168:171], v225 offset:0
	v_mfma_f32_16x16x32_bf16 v[6:9], v[156:159], v[136:139], v[6:9]
	ds_read_b128 v[172:175], v225 offset:2048
	v_add_f32_e32 v67, 1.0, v67
	v_mfma_f32_16x16x32_bf16 v[10:13], v[160:163], v[136:139], v[10:13]
	ds_read_b128 v[176:179], v225 offset:4096
	v_add_f32_e32 v68, 1.0, v68
	v_mfma_f32_16x16x32_bf16 v[14:17], v[164:167], v[136:139], v[14:17]
	ds_read_b128 v[180:183], v225 offset:6144
	v_add_f32_e32 v69, 1.0, v69
	v_mfma_f32_16x16x32_bf16 v[18:21], v[152:155], v[140:143], v[18:21]
	ds_read_b128 v[184:187], v233 offset:0
	v_mfma_f32_16x16x32_bf16 v[22:25], v[156:159], v[140:143], v[22:25]
	ds_read_b128 v[188:191], v233 offset:2048
	v_add_f32_e32 v70, 1.0, v70
	v_mfma_f32_16x16x32_bf16 v[26:29], v[160:163], v[140:143], v[26:29]
	ds_read_b128 v[192:195], v233 offset:4096
	v_add_f32_e32 v71, 1.0, v71
	v_mfma_f32_16x16x32_bf16 v[30:33], v[164:167], v[140:143], v[30:33]
	ds_read_b128 v[196:199], v233 offset:6144
	v_add_f32_e32 v72, 1.0, v72
	v_mfma_f32_16x16x32_bf16 v[34:37], v[152:155], v[144:147], v[34:37]
	v_mfma_f32_16x16x32_bf16 v[38:41], v[156:159], v[144:147], v[38:41]
	v_add_f32_e32 v73, 1.0, v73
	v_mfma_f32_16x16x32_bf16 v[42:45], v[160:163], v[144:147], v[42:45]
	v_rcp_f32_e32 v66, v66
	v_mfma_f32_16x16x32_bf16 v[46:49], v[164:167], v[144:147], v[46:49]
	v_rcp_f32_e32 v67, v67
	v_mfma_f32_16x16x32_bf16 v[50:53], v[152:155], v[148:151], v[50:53]
	v_mfma_f32_16x16x32_bf16 v[54:57], v[156:159], v[148:151], v[54:57]
	v_rcp_f32_e32 v68, v68
	v_mfma_f32_16x16x32_bf16 v[58:61], v[160:163], v[148:151], v[58:61]
	v_rcp_f32_e32 v69, v69
	v_mfma_f32_16x16x32_bf16 v[62:65], v[164:167], v[148:151], v[62:65]
	v_rcp_f32_e32 v70, v70
	s_waitcnt vmcnt(7) lgkmcnt(0)
	s_barrier
	v_mfma_f32_16x16x32_bf16 v[2:5], v[184:187], v[168:171], v[2:5]
	ds_read_b128 v[136:139], v219 offset:0
	v_mfma_f32_16x16x32_bf16 v[6:9], v[188:191], v[168:171], v[6:9]
	ds_read_b128 v[140:143], v219 offset:2048
	v_mfma_f32_16x16x32_bf16 v[10:13], v[192:195], v[168:171], v[10:13]
	ds_read_b128 v[144:147], v219 offset:4096
	v_rcp_f32_e32 v71, v71
	v_mfma_f32_16x16x32_bf16 v[14:17], v[196:199], v[168:171], v[14:17]
	ds_read_b128 v[148:151], v219 offset:6144
	v_mfma_f32_16x16x32_bf16 v[18:21], v[184:187], v[172:175], v[18:21]
	ds_read_b128 v[152:155], v231 offset:0
	v_rcp_f32_e32 v72, v72
	v_mfma_f32_16x16x32_bf16 v[22:25], v[188:191], v[172:175], v[22:25]
	ds_read_b128 v[156:159], v231 offset:2048
	v_mfma_f32_16x16x32_bf16 v[26:29], v[192:195], v[172:175], v[26:29]
	ds_read_b128 v[160:163], v231 offset:4096
	v_rcp_f32_e32 v73, v73
	v_mfma_f32_16x16x32_bf16 v[30:33], v[196:199], v[172:175], v[30:33]
	ds_read_b128 v[164:167], v231 offset:6144
	s_mov_b32 m0, s8
	v_mfma_f32_16x16x32_bf16 v[34:37], v[184:187], v[176:179], v[34:37]
	global_load_lds_dwordx4 v200, s[4:5]
	s_add_u32 m0, s8, 0x400
	v_mfma_f32_16x16x32_bf16 v[38:41], v[188:191], v[176:179], v[38:41]
	global_load_lds_dwordx4 v201, s[4:5]
	v_cvt_pk_bf16_f32 v66, v66, v67
	s_add_u32 m0, s8, 0x800
	v_mfma_f32_16x16x32_bf16 v[42:45], v[192:195], v[176:179], v[42:45]
	global_load_lds_dwordx4 v202, s[4:5]
	s_add_u32 m0, s8, 0xc00
	v_mfma_f32_16x16x32_bf16 v[46:49], v[196:199], v[176:179], v[46:49]
	global_load_lds_dwordx4 v203, s[4:5]
	v_cvt_pk_bf16_f32 v67, v68, v69
	s_mov_b32 m0, s9
	v_mfma_f32_16x16x32_bf16 v[50:53], v[184:187], v[180:183], v[50:53]
	global_load_lds_dwordx4 v204, s[6:7]
	s_add_u32 m0, s9, 0x400
	v_mfma_f32_16x16x32_bf16 v[54:57], v[188:191], v[180:183], v[54:57]
	global_load_lds_dwordx4 v205, s[6:7]
	v_cvt_pk_bf16_f32 v68, v70, v71
	v_mfma_f32_16x16x32_bf16 v[58:61], v[192:195], v[180:183], v[58:61]
	s_add_u32 s4, s4, 0x80
	s_addc_u32 s5, s5, 0
	v_mfma_f32_16x16x32_bf16 v[62:65], v[196:199], v[180:183], v[62:65]
	s_add_u32 s6, s6, 0x80
	s_addc_u32 s7, s7, 0
	v_cvt_pk_bf16_f32 v69, v72, v73
	s_waitcnt lgkmcnt(0)
	v_mfma_f32_16x16x32_bf16 v[2:5], v[152:155], v[136:139], v[2:5]
	ds_read_b128 v[168:171], v228 offset:0
	v_mfma_f32_16x16x32_bf16 v[6:9], v[156:159], v[136:139], v[6:9]
	ds_read_b128 v[172:175], v228 offset:2048
	global_store_dwordx4 v240, v[66:69], s[10:11] offset:0 sc1
	v_mfma_f32_16x16x32_bf16 v[10:13], v[160:163], v[136:139], v[10:13]
	ds_read_b128 v[176:179], v228 offset:4096
	v_mul_f32_e32 v74, s12, v74
	v_mfma_f32_16x16x32_bf16 v[14:17], v[164:167], v[136:139], v[14:17]
	ds_read_b128 v[180:183], v228 offset:6144
	v_mul_f32_e32 v75, s12, v75
	v_mfma_f32_16x16x32_bf16 v[18:21], v[152:155], v[140:143], v[18:21]
	ds_read_b128 v[184:187], v234 offset:0
	v_mfma_f32_16x16x32_bf16 v[22:25], v[156:159], v[140:143], v[22:25]
	ds_read_b128 v[188:191], v234 offset:2048
	v_mul_f32_e32 v76, s12, v76
	v_mfma_f32_16x16x32_bf16 v[26:29], v[160:163], v[140:143], v[26:29]
	ds_read_b128 v[192:195], v234 offset:4096
	v_mul_f32_e32 v77, s12, v77
	v_mfma_f32_16x16x32_bf16 v[30:33], v[164:167], v[140:143], v[30:33]
	ds_read_b128 v[196:199], v234 offset:6144
	v_mul_f32_e32 v78, s12, v78
	v_mfma_f32_16x16x32_bf16 v[34:37], v[152:155], v[144:147], v[34:37]
	v_mfma_f32_16x16x32_bf16 v[38:41], v[156:159], v[144:147], v[38:41]
	v_mul_f32_e32 v79, s12, v79
	v_mfma_f32_16x16x32_bf16 v[42:45], v[160:163], v[144:147], v[42:45]
	v_mul_f32_e32 v80, s12, v80
	v_mfma_f32_16x16x32_bf16 v[46:49], v[164:167], v[144:147], v[46:49]
	v_mul_f32_e32 v81, s12, v81
	v_mfma_f32_16x16x32_bf16 v[50:53], v[152:155], v[148:151], v[50:53]
	v_mfma_f32_16x16x32_bf16 v[54:57], v[156:159], v[148:151], v[54:57]
	v_exp_f32_e32 v74, v74
	v_mfma_f32_16x16x32_bf16 v[58:61], v[160:163], v[148:151], v[58:61]
	v_exp_f32_e32 v75, v75
	v_mfma_f32_16x16x32_bf16 v[62:65], v[164:167], v[148:151], v[62:65]
	v_exp_f32_e32 v76, v76
	s_waitcnt vmcnt(7) lgkmcnt(0)
	s_barrier
	v_mfma_f32_16x16x32_bf16 v[2:5], v[184:187], v[168:171], v[2:5]
	ds_read_b128 v[136:139], v224 offset:0
	v_mfma_f32_16x16x32_bf16 v[6:9], v[188:191], v[168:171], v[6:9]
	ds_read_b128 v[140:143], v224 offset:2048
	v_mfma_f32_16x16x32_bf16 v[10:13], v[192:195], v[168:171], v[10:13]
	ds_read_b128 v[144:147], v224 offset:4096
	v_exp_f32_e32 v77, v77
	v_mfma_f32_16x16x32_bf16 v[14:17], v[196:199], v[168:171], v[14:17]
	ds_read_b128 v[148:151], v224 offset:6144
	v_mfma_f32_16x16x32_bf16 v[18:21], v[184:187], v[172:175], v[18:21]
	ds_read_b128 v[152:155], v232 offset:0
	v_exp_f32_e32 v78, v78
	v_mfma_f32_16x16x32_bf16 v[22:25], v[188:191], v[172:175], v[22:25]
	ds_read_b128 v[156:159], v232 offset:2048
	v_mfma_f32_16x16x32_bf16 v[26:29], v[192:195], v[172:175], v[26:29]
	ds_read_b128 v[160:163], v232 offset:4096
	v_exp_f32_e32 v79, v79
	v_mfma_f32_16x16x32_bf16 v[30:33], v[196:199], v[172:175], v[30:33]
	ds_read_b128 v[164:167], v232 offset:6144
	s_add_u32 m0, s8, 0xc000
	v_mfma_f32_16x16x32_bf16 v[34:37], v[184:187], v[176:179], v[34:37]
	global_load_lds_dwordx4 v200, s[4:5]
	s_add_u32 m0, s8, 0xc400
	v_mfma_f32_16x16x32_bf16 v[38:41], v[188:191], v[176:179], v[38:41]
	global_load_lds_dwordx4 v201, s[4:5]
	v_exp_f32_e32 v80, v80
	s_add_u32 m0, s8, 0xc800
	v_mfma_f32_16x16x32_bf16 v[42:45], v[192:195], v[176:179], v[42:45]
	global_load_lds_dwordx4 v202, s[4:5]
	s_add_u32 m0, s8, 0xcc00
	v_mfma_f32_16x16x32_bf16 v[46:49], v[196:199], v[176:179], v[46:49]
	global_load_lds_dwordx4 v203, s[4:5]
	v_exp_f32_e32 v81, v81
	s_add_u32 m0, s9, 0xc000
	v_mfma_f32_16x16x32_bf16 v[50:53], v[184:187], v[180:183], v[50:53]
	global_load_lds_dwordx4 v204, s[6:7]
	s_add_u32 m0, s9, 0xc400
	v_mfma_f32_16x16x32_bf16 v[54:57], v[188:191], v[180:183], v[54:57]
	global_load_lds_dwordx4 v205, s[6:7]
	v_add_f32_e32 v74, 1.0, v74
	v_mfma_f32_16x16x32_bf16 v[58:61], v[192:195], v[180:183], v[58:61]
	s_add_u32 s4, s4, 0x80
	s_addc_u32 s5, s5, 0
	v_mfma_f32_16x16x32_bf16 v[62:65], v[196:199], v[180:183], v[62:65]
	s_add_u32 s6, s6, 0x80
	s_addc_u32 s7, s7, 0
	v_add_f32_e32 v75, 1.0, v75
	s_waitcnt lgkmcnt(0)
	v_mfma_f32_16x16x32_bf16 v[2:5], v[152:155], v[136:139], v[2:5]
	ds_read_b128 v[168:171], v229 offset:0
	v_mfma_f32_16x16x32_bf16 v[6:9], v[156:159], v[136:139], v[6:9]
	ds_read_b128 v[172:175], v229 offset:2048
	v_add_f32_e32 v76, 1.0, v76
	v_mfma_f32_16x16x32_bf16 v[10:13], v[160:163], v[136:139], v[10:13]
	ds_read_b128 v[176:179], v229 offset:4096
	v_add_f32_e32 v77, 1.0, v77
	v_mfma_f32_16x16x32_bf16 v[14:17], v[164:167], v[136:139], v[14:17]
	ds_read_b128 v[180:183], v229 offset:6144
	v_add_f32_e32 v78, 1.0, v78
	v_mfma_f32_16x16x32_bf16 v[18:21], v[152:155], v[140:143], v[18:21]
	ds_read_b128 v[184:187], v235 offset:0
	v_mfma_f32_16x16x32_bf16 v[22:25], v[156:159], v[140:143], v[22:25]
	ds_read_b128 v[188:191], v235 offset:2048
	v_add_f32_e32 v79, 1.0, v79
	v_mfma_f32_16x16x32_bf16 v[26:29], v[160:163], v[140:143], v[26:29]
	ds_read_b128 v[192:195], v235 offset:4096
	v_add_f32_e32 v80, 1.0, v80
	v_mfma_f32_16x16x32_bf16 v[30:33], v[164:167], v[140:143], v[30:33]
	ds_read_b128 v[196:199], v235 offset:6144
	v_add_f32_e32 v81, 1.0, v81
	v_mfma_f32_16x16x32_bf16 v[34:37], v[152:155], v[144:147], v[34:37]
	v_mfma_f32_16x16x32_bf16 v[38:41], v[156:159], v[144:147], v[38:41]
	v_rcp_f32_e32 v74, v74
	v_mfma_f32_16x16x32_bf16 v[42:45], v[160:163], v[144:147], v[42:45]
	v_rcp_f32_e32 v75, v75
	v_mfma_f32_16x16x32_bf16 v[46:49], v[164:167], v[144:147], v[46:49]
	v_rcp_f32_e32 v76, v76
	v_mfma_f32_16x16x32_bf16 v[50:53], v[152:155], v[148:151], v[50:53]
	v_mfma_f32_16x16x32_bf16 v[54:57], v[156:159], v[148:151], v[54:57]
	v_rcp_f32_e32 v77, v77
	v_mfma_f32_16x16x32_bf16 v[58:61], v[160:163], v[148:151], v[58:61]
	v_rcp_f32_e32 v78, v78
	v_mfma_f32_16x16x32_bf16 v[62:65], v[164:167], v[148:151], v[62:65]
	v_rcp_f32_e32 v79, v79
	s_waitcnt vmcnt(7) lgkmcnt(0)
	s_barrier
	v_mfma_f32_16x16x32_bf16 v[2:5], v[184:187], v[168:171], v[2:5]
	ds_read_b128 v[136:139], v218 offset:0
	v_mfma_f32_16x16x32_bf16 v[6:9], v[188:191], v[168:171], v[6:9]
	ds_read_b128 v[140:143], v218 offset:2048
	v_mfma_f32_16x16x32_bf16 v[10:13], v[192:195], v[168:171], v[10:13]
	ds_read_b128 v[144:147], v218 offset:4096
	v_rcp_f32_e32 v80, v80
	v_mfma_f32_16x16x32_bf16 v[14:17], v[196:199], v[168:171], v[14:17]
	ds_read_b128 v[148:151], v218 offset:6144
	v_mfma_f32_16x16x32_bf16 v[18:21], v[184:187], v[172:175], v[18:21]
	ds_read_b128 v[152:155], v230 offset:0
	v_rcp_f32_e32 v81, v81
	v_mfma_f32_16x16x32_bf16 v[22:25], v[188:191], v[172:175], v[22:25]
	ds_read_b128 v[156:159], v230 offset:2048
	v_mfma_f32_16x16x32_bf16 v[26:29], v[192:195], v[172:175], v[26:29]
	ds_read_b128 v[160:163], v230 offset:4096
	v_cvt_pk_bf16_f32 v74, v74, v75
	v_mfma_f32_16x16x32_bf16 v[30:33], v[196:199], v[172:175], v[30:33]
	ds_read_b128 v[164:167], v230 offset:6144
	s_add_u32 m0, s8, 0x18000
	v_mfma_f32_16x16x32_bf16 v[34:37], v[184:187], v[176:179], v[34:37]
	global_load_lds_dwordx4 v200, s[4:5]
	s_add_u32 m0, s8, 0x18400
	v_mfma_f32_16x16x32_bf16 v[38:41], v[188:191], v[176:179], v[38:41]
	global_load_lds_dwordx4 v201, s[4:5]
	v_cvt_pk_bf16_f32 v75, v76, v77
	s_add_u32 m0, s8, 0x18800
	v_mfma_f32_16x16x32_bf16 v[42:45], v[192:195], v[176:179], v[42:45]
	global_load_lds_dwordx4 v202, s[4:5]
	s_add_u32 m0, s8, 0x18c00
	v_mfma_f32_16x16x32_bf16 v[46:49], v[196:199], v[176:179], v[46:49]
	global_load_lds_dwordx4 v203, s[4:5]
	v_cvt_pk_bf16_f32 v76, v78, v79
	s_add_u32 m0, s9, 0x18000
	v_mfma_f32_16x16x32_bf16 v[50:53], v[184:187], v[180:183], v[50:53]
	global_load_lds_dwordx4 v204, s[6:7]
	s_add_u32 m0, s9, 0x18400
	v_mfma_f32_16x16x32_bf16 v[54:57], v[188:191], v[180:183], v[54:57]
	global_load_lds_dwordx4 v205, s[6:7]
	v_cvt_pk_bf16_f32 v77, v80, v81
	v_mfma_f32_16x16x32_bf16 v[58:61], v[192:195], v[180:183], v[58:61]
	s_add_u32 s4, s4, 0x80
	s_addc_u32 s5, s5, 0
	v_mfma_f32_16x16x32_bf16 v[62:65], v[196:199], v[180:183], v[62:65]
	s_add_u32 s6, s6, 0x80
	s_addc_u32 s7, s7, 0
	global_store_dwordx4 v240, v[74:77], s[10:11] offset:1024 sc1
	s_waitcnt lgkmcnt(0)
	v_mfma_f32_16x16x32_bf16 v[2:5], v[152:155], v[136:139], v[2:5]
	ds_read_b128 v[168:171], v225 offset:0
	v_mfma_f32_16x16x32_bf16 v[6:9], v[156:159], v[136:139], v[6:9]
	ds_read_b128 v[172:175], v225 offset:2048
	v_mul_f32_e32 v82, s12, v82
	v_mfma_f32_16x16x32_bf16 v[10:13], v[160:163], v[136:139], v[10:13]
	ds_read_b128 v[176:179], v225 offset:4096
	v_mul_f32_e32 v83, s12, v83
	v_mfma_f32_16x16x32_bf16 v[14:17], v[164:167], v[136:139], v[14:17]
	ds_read_b128 v[180:183], v225 offset:6144
	v_mul_f32_e32 v84, s12, v84
	v_mfma_f32_16x16x32_bf16 v[18:21], v[152:155], v[140:143], v[18:21]
	ds_read_b128 v[184:187], v233 offset:0
	v_mfma_f32_16x16x32_bf16 v[22:25], v[156:159], v[140:143], v[22:25]
	ds_read_b128 v[188:191], v233 offset:2048
	v_mul_f32_e32 v85, s12, v85
	v_mfma_f32_16x16x32_bf16 v[26:29], v[160:163], v[140:143], v[26:29]
	ds_read_b128 v[192:195], v233 offset:4096
	v_mul_f32_e32 v86, s12, v86
	v_mfma_f32_16x16x32_bf16 v[30:33], v[164:167], v[140:143], v[30:33]
	ds_read_b128 v[196:199], v233 offset:6144
	v_mul_f32_e32 v87, s12, v87
	v_mfma_f32_16x16x32_bf16 v[34:37], v[152:155], v[144:147], v[34:37]
	v_mfma_f32_16x16x32_bf16 v[38:41], v[156:159], v[144:147], v[38:41]
	v_mul_f32_e32 v88, s12, v88
	v_mfma_f32_16x16x32_bf16 v[42:45], v[160:163], v[144:147], v[42:45]
	v_mul_f32_e32 v89, s12, v89
	v_mfma_f32_16x16x32_bf16 v[46:49], v[164:167], v[144:147], v[46:49]
	v_exp_f32_e32 v82, v82
	v_mfma_f32_16x16x32_bf16 v[50:53], v[152:155], v[148:151], v[50:53]
	v_mfma_f32_16x16x32_bf16 v[54:57], v[156:159], v[148:151], v[54:57]
	v_exp_f32_e32 v83, v83
	v_mfma_f32_16x16x32_bf16 v[58:61], v[160:163], v[148:151], v[58:61]
	v_exp_f32_e32 v84, v84
	v_mfma_f32_16x16x32_bf16 v[62:65], v[164:167], v[148:151], v[62:65]
	v_exp_f32_e32 v85, v85
	s_waitcnt vmcnt(7) lgkmcnt(0)
	s_barrier
	v_mfma_f32_16x16x32_bf16 v[2:5], v[184:187], v[168:171], v[2:5]
	ds_read_b128 v[136:139], v219 offset:0
	v_mfma_f32_16x16x32_bf16 v[6:9], v[188:191], v[168:171], v[6:9]
	ds_read_b128 v[140:143], v219 offset:2048
	v_mfma_f32_16x16x32_bf16 v[10:13], v[192:195], v[168:171], v[10:13]
	ds_read_b128 v[144:147], v219 offset:4096
	v_exp_f32_e32 v86, v86
	v_mfma_f32_16x16x32_bf16 v[14:17], v[196:199], v[168:171], v[14:17]
	ds_read_b128 v[148:151], v219 offset:6144
	v_mfma_f32_16x16x32_bf16 v[18:21], v[184:187], v[172:175], v[18:21]
	ds_read_b128 v[152:155], v231 offset:0
	v_exp_f32_e32 v87, v87
	v_mfma_f32_16x16x32_bf16 v[22:25], v[188:191], v[172:175], v[22:25]
	ds_read_b128 v[156:159], v231 offset:2048
	v_mfma_f32_16x16x32_bf16 v[26:29], v[192:195], v[172:175], v[26:29]
	ds_read_b128 v[160:163], v231 offset:4096
	v_exp_f32_e32 v88, v88
	v_mfma_f32_16x16x32_bf16 v[30:33], v[196:199], v[172:175], v[30:33]
	ds_read_b128 v[164:167], v231 offset:6144
	s_mov_b32 m0, s8
	v_mfma_f32_16x16x32_bf16 v[34:37], v[184:187], v[176:179], v[34:37]
	global_load_lds_dwordx4 v200, s[4:5]
	s_add_u32 m0, s8, 0x400
	v_mfma_f32_16x16x32_bf16 v[38:41], v[188:191], v[176:179], v[38:41]
	global_load_lds_dwordx4 v201, s[4:5]
	v_exp_f32_e32 v89, v89
	s_add_u32 m0, s8, 0x800
	v_mfma_f32_16x16x32_bf16 v[42:45], v[192:195], v[176:179], v[42:45]
	global_load_lds_dwordx4 v202, s[4:5]
	s_add_u32 m0, s8, 0xc00
	v_mfma_f32_16x16x32_bf16 v[46:49], v[196:199], v[176:179], v[46:49]
	global_load_lds_dwordx4 v203, s[4:5]
	v_add_f32_e32 v82, 1.0, v82
	s_mov_b32 m0, s9
	v_mfma_f32_16x16x32_bf16 v[50:53], v[184:187], v[180:183], v[50:53]
	global_load_lds_dwordx4 v204, s[6:7]
	s_add_u32 m0, s9, 0x400
	v_mfma_f32_16x16x32_bf16 v[54:57], v[188:191], v[180:183], v[54:57]
	global_load_lds_dwordx4 v205, s[6:7]
	v_add_f32_e32 v83, 1.0, v83
	v_mfma_f32_16x16x32_bf16 v[58:61], v[192:195], v[180:183], v[58:61]
	s_add_u32 s4, s4, 0x80
	s_addc_u32 s5, s5, 0
	v_mfma_f32_16x16x32_bf16 v[62:65], v[196:199], v[180:183], v[62:65]
	s_add_u32 s6, s6, 0x80
	s_addc_u32 s7, s7, 0
	v_add_f32_e32 v84, 1.0, v84
	s_waitcnt lgkmcnt(0)
	v_mfma_f32_16x16x32_bf16 v[2:5], v[152:155], v[136:139], v[2:5]
	ds_read_b128 v[168:171], v228 offset:0
	v_mfma_f32_16x16x32_bf16 v[6:9], v[156:159], v[136:139], v[6:9]
	ds_read_b128 v[172:175], v228 offset:2048
	v_add_f32_e32 v85, 1.0, v85
	v_mfma_f32_16x16x32_bf16 v[10:13], v[160:163], v[136:139], v[10:13]
	ds_read_b128 v[176:179], v228 offset:4096
	v_add_f32_e32 v86, 1.0, v86
	v_mfma_f32_16x16x32_bf16 v[14:17], v[164:167], v[136:139], v[14:17]
	ds_read_b128 v[180:183], v228 offset:6144
	v_add_f32_e32 v87, 1.0, v87
	v_mfma_f32_16x16x32_bf16 v[18:21], v[152:155], v[140:143], v[18:21]
	ds_read_b128 v[184:187], v234 offset:0
	v_mfma_f32_16x16x32_bf16 v[22:25], v[156:159], v[140:143], v[22:25]
	ds_read_b128 v[188:191], v234 offset:2048
	v_add_f32_e32 v88, 1.0, v88
	v_mfma_f32_16x16x32_bf16 v[26:29], v[160:163], v[140:143], v[26:29]
	ds_read_b128 v[192:195], v234 offset:4096
	v_add_f32_e32 v89, 1.0, v89
	v_mfma_f32_16x16x32_bf16 v[30:33], v[164:167], v[140:143], v[30:33]
	ds_read_b128 v[196:199], v234 offset:6144
	v_rcp_f32_e32 v82, v82
	v_mfma_f32_16x16x32_bf16 v[34:37], v[152:155], v[144:147], v[34:37]
	v_mfma_f32_16x16x32_bf16 v[38:41], v[156:159], v[144:147], v[38:41]
	v_rcp_f32_e32 v83, v83
	v_mfma_f32_16x16x32_bf16 v[42:45], v[160:163], v[144:147], v[42:45]
	v_rcp_f32_e32 v84, v84
	v_mfma_f32_16x16x32_bf16 v[46:49], v[164:167], v[144:147], v[46:49]
	v_rcp_f32_e32 v85, v85
	v_mfma_f32_16x16x32_bf16 v[50:53], v[152:155], v[148:151], v[50:53]
	v_mfma_f32_16x16x32_bf16 v[54:57], v[156:159], v[148:151], v[54:57]
	v_rcp_f32_e32 v86, v86
	v_mfma_f32_16x16x32_bf16 v[58:61], v[160:163], v[148:151], v[58:61]
	v_rcp_f32_e32 v87, v87
	v_mfma_f32_16x16x32_bf16 v[62:65], v[164:167], v[148:151], v[62:65]
	v_rcp_f32_e32 v88, v88
	s_waitcnt vmcnt(7) lgkmcnt(0)
	s_barrier
	v_mfma_f32_16x16x32_bf16 v[2:5], v[184:187], v[168:171], v[2:5]
	ds_read_b128 v[136:139], v224 offset:0
	v_mfma_f32_16x16x32_bf16 v[6:9], v[188:191], v[168:171], v[6:9]
	ds_read_b128 v[140:143], v224 offset:2048
	v_mfma_f32_16x16x32_bf16 v[10:13], v[192:195], v[168:171], v[10:13]
	ds_read_b128 v[144:147], v224 offset:4096
	v_rcp_f32_e32 v89, v89
	v_mfma_f32_16x16x32_bf16 v[14:17], v[196:199], v[168:171], v[14:17]
	ds_read_b128 v[148:151], v224 offset:6144
	v_mfma_f32_16x16x32_bf16 v[18:21], v[184:187], v[172:175], v[18:21]
	ds_read_b128 v[152:155], v232 offset:0
	v_cvt_pk_bf16_f32 v82, v82, v83
	v_mfma_f32_16x16x32_bf16 v[22:25], v[188:191], v[172:175], v[22:25]
	ds_read_b128 v[156:159], v232 offset:2048
	v_mfma_f32_16x16x32_bf16 v[26:29], v[192:195], v[172:175], v[26:29]
	ds_read_b128 v[160:163], v232 offset:4096
	v_cvt_pk_bf16_f32 v83, v84, v85
	v_mfma_f32_16x16x32_bf16 v[30:33], v[196:199], v[172:175], v[30:33]
	ds_read_b128 v[164:167], v232 offset:6144
	s_add_u32 m0, s8, 0xc000
	v_mfma_f32_16x16x32_bf16 v[34:37], v[184:187], v[176:179], v[34:37]
	global_load_lds_dwordx4 v200, s[4:5]
	s_add_u32 m0, s8, 0xc400
	v_mfma_f32_16x16x32_bf16 v[38:41], v[188:191], v[176:179], v[38:41]
	global_load_lds_dwordx4 v201, s[4:5]
	v_cvt_pk_bf16_f32 v84, v86, v87
	s_add_u32 m0, s8, 0xc800
	v_mfma_f32_16x16x32_bf16 v[42:45], v[192:195], v[176:179], v[42:45]
	global_load_lds_dwordx4 v202, s[4:5]
	s_add_u32 m0, s8, 0xcc00
	v_mfma_f32_16x16x32_bf16 v[46:49], v[196:199], v[176:179], v[46:49]
	global_load_lds_dwordx4 v203, s[4:5]
	v_cvt_pk_bf16_f32 v85, v88, v89
	s_add_u32 m0, s9, 0xc000
	v_mfma_f32_16x16x32_bf16 v[50:53], v[184:187], v[180:183], v[50:53]
	global_load_lds_dwordx4 v204, s[6:7]
	s_add_u32 m0, s9, 0xc400
	v_mfma_f32_16x16x32_bf16 v[54:57], v[188:191], v[180:183], v[54:57]
	global_load_lds_dwordx4 v205, s[6:7]
	global_store_dwordx4 v240, v[82:85], s[10:11] offset:2048 sc1
	v_mfma_f32_16x16x32_bf16 v[58:61], v[192:195], v[180:183], v[58:61]
	s_add_u32 s4, s4, 0x80
	s_addc_u32 s5, s5, 0
	v_mfma_f32_16x16x32_bf16 v[62:65], v[196:199], v[180:183], v[62:65]
	s_add_u32 s6, s6, 0x80
	s_addc_u32 s7, s7, 0
	v_mul_f32_e32 v90, s12, v90
	s_waitcnt lgkmcnt(0)
	v_mfma_f32_16x16x32_bf16 v[2:5], v[152:155], v[136:139], v[2:5]
	ds_read_b128 v[168:171], v229 offset:0
	v_mfma_f32_16x16x32_bf16 v[6:9], v[156:159], v[136:139], v[6:9]
	ds_read_b128 v[172:175], v229 offset:2048
	v_mul_f32_e32 v91, s12, v91
	v_mfma_f32_16x16x32_bf16 v[10:13], v[160:163], v[136:139], v[10:13]
	ds_read_b128 v[176:179], v229 offset:4096
	v_mul_f32_e32 v92, s12, v92
	v_mfma_f32_16x16x32_bf16 v[14:17], v[164:167], v[136:139], v[14:17]
	ds_read_b128 v[180:183], v229 offset:6144
	v_mul_f32_e32 v93, s12, v93
	v_mfma_f32_16x16x32_bf16 v[18:21], v[152:155], v[140:143], v[18:21]
	ds_read_b128 v[184:187], v235 offset:0
	v_mfma_f32_16x16x32_bf16 v[22:25], v[156:159], v[140:143], v[22:25]
	ds_read_b128 v[188:191], v235 offset:2048
	v_mul_f32_e32 v94, s12, v94
	v_mfma_f32_16x16x32_bf16 v[26:29], v[160:163], v[140:143], v[26:29]
	ds_read_b128 v[192:195], v235 offset:4096
	v_mul_f32_e32 v95, s12, v95
	v_mfma_f32_16x16x32_bf16 v[30:33], v[164:167], v[140:143], v[30:33]
	ds_read_b128 v[196:199], v235 offset:6144
	v_mul_f32_e32 v96, s12, v96
	v_mfma_f32_16x16x32_bf16 v[34:37], v[152:155], v[144:147], v[34:37]
	v_mfma_f32_16x16x32_bf16 v[38:41], v[156:159], v[144:147], v[38:41]
	v_mul_f32_e32 v97, s12, v97
	v_mfma_f32_16x16x32_bf16 v[42:45], v[160:163], v[144:147], v[42:45]
	v_exp_f32_e32 v90, v90
	v_mfma_f32_16x16x32_bf16 v[46:49], v[164:167], v[144:147], v[46:49]
	v_exp_f32_e32 v91, v91
	v_mfma_f32_16x16x32_bf16 v[50:53], v[152:155], v[148:151], v[50:53]
	v_mfma_f32_16x16x32_bf16 v[54:57], v[156:159], v[148:151], v[54:57]
	v_exp_f32_e32 v92, v92
	v_mfma_f32_16x16x32_bf16 v[58:61], v[160:163], v[148:151], v[58:61]
	v_exp_f32_e32 v93, v93
	v_mfma_f32_16x16x32_bf16 v[62:65], v[164:167], v[148:151], v[62:65]
	v_exp_f32_e32 v94, v94
	s_waitcnt vmcnt(7) lgkmcnt(0)
	s_barrier
	v_mfma_f32_16x16x32_bf16 v[2:5], v[184:187], v[168:171], v[2:5]
	ds_read_b128 v[136:139], v218 offset:0
	v_mfma_f32_16x16x32_bf16 v[6:9], v[188:191], v[168:171], v[6:9]
	ds_read_b128 v[140:143], v218 offset:2048
	v_mfma_f32_16x16x32_bf16 v[10:13], v[192:195], v[168:171], v[10:13]
	ds_read_b128 v[144:147], v218 offset:4096
	v_exp_f32_e32 v95, v95
	v_mfma_f32_16x16x32_bf16 v[14:17], v[196:199], v[168:171], v[14:17]
	ds_read_b128 v[148:151], v218 offset:6144
	v_mfma_f32_16x16x32_bf16 v[18:21], v[184:187], v[172:175], v[18:21]
	ds_read_b128 v[152:155], v230 offset:0
	v_exp_f32_e32 v96, v96
	v_mfma_f32_16x16x32_bf16 v[22:25], v[188:191], v[172:175], v[22:25]
	ds_read_b128 v[156:159], v230 offset:2048
	v_mfma_f32_16x16x32_bf16 v[26:29], v[192:195], v[172:175], v[26:29]
	ds_read_b128 v[160:163], v230 offset:4096
	v_exp_f32_e32 v97, v97
	v_mfma_f32_16x16x32_bf16 v[30:33], v[196:199], v[172:175], v[30:33]
	ds_read_b128 v[164:167], v230 offset:6144
	s_add_u32 m0, s8, 0x18000
	v_mfma_f32_16x16x32_bf16 v[34:37], v[184:187], v[176:179], v[34:37]
	global_load_lds_dwordx4 v200, s[4:5]
	s_add_u32 m0, s8, 0x18400
	v_mfma_f32_16x16x32_bf16 v[38:41], v[188:191], v[176:179], v[38:41]
	global_load_lds_dwordx4 v201, s[4:5]
	v_add_f32_e32 v90, 1.0, v90
	s_add_u32 m0, s8, 0x18800
	v_mfma_f32_16x16x32_bf16 v[42:45], v[192:195], v[176:179], v[42:45]
	global_load_lds_dwordx4 v202, s[4:5]
	s_add_u32 m0, s8, 0x18c00
	v_mfma_f32_16x16x32_bf16 v[46:49], v[196:199], v[176:179], v[46:49]
	global_load_lds_dwordx4 v203, s[4:5]
	v_add_f32_e32 v91, 1.0, v91
	s_add_u32 m0, s9, 0x18000
	v_mfma_f32_16x16x32_bf16 v[50:53], v[184:187], v[180:183], v[50:53]
	global_load_lds_dwordx4 v204, s[6:7]
	s_add_u32 m0, s9, 0x18400
	v_mfma_f32_16x16x32_bf16 v[54:57], v[188:191], v[180:183], v[54:57]
	global_load_lds_dwordx4 v205, s[6:7]
	v_add_f32_e32 v92, 1.0, v92
	v_mfma_f32_16x16x32_bf16 v[58:61], v[192:195], v[180:183], v[58:61]
	s_add_u32 s4, s4, 0x80
	s_addc_u32 s5, s5, 0
	v_mfma_f32_16x16x32_bf16 v[62:65], v[196:199], v[180:183], v[62:65]
	s_add_u32 s6, s6, 0x80
	s_addc_u32 s7, s7, 0
	v_add_f32_e32 v93, 1.0, v93
	s_waitcnt lgkmcnt(0)
	v_mfma_f32_16x16x32_bf16 v[2:5], v[152:155], v[136:139], v[2:5]
	ds_read_b128 v[168:171], v225 offset:0
	v_mfma_f32_16x16x32_bf16 v[6:9], v[156:159], v[136:139], v[6:9]
	ds_read_b128 v[172:175], v225 offset:2048
	v_add_f32_e32 v94, 1.0, v94
	v_mfma_f32_16x16x32_bf16 v[10:13], v[160:163], v[136:139], v[10:13]
	ds_read_b128 v[176:179], v225 offset:4096
	v_add_f32_e32 v95, 1.0, v95
	v_mfma_f32_16x16x32_bf16 v[14:17], v[164:167], v[136:139], v[14:17]
	ds_read_b128 v[180:183], v225 offset:6144
	v_add_f32_e32 v96, 1.0, v96
	v_mfma_f32_16x16x32_bf16 v[18:21], v[152:155], v[140:143], v[18:21]
	ds_read_b128 v[184:187], v233 offset:0
	v_mfma_f32_16x16x32_bf16 v[22:25], v[156:159], v[140:143], v[22:25]
	ds_read_b128 v[188:191], v233 offset:2048
	v_add_f32_e32 v97, 1.0, v97
	v_mfma_f32_16x16x32_bf16 v[26:29], v[160:163], v[140:143], v[26:29]
	ds_read_b128 v[192:195], v233 offset:4096
	v_rcp_f32_e32 v90, v90
	v_mfma_f32_16x16x32_bf16 v[30:33], v[164:167], v[140:143], v[30:33]
	ds_read_b128 v[196:199], v233 offset:6144
	v_rcp_f32_e32 v91, v91
	v_mfma_f32_16x16x32_bf16 v[34:37], v[152:155], v[144:147], v[34:37]
	v_mfma_f32_16x16x32_bf16 v[38:41], v[156:159], v[144:147], v[38:41]
	v_rcp_f32_e32 v92, v92
	v_mfma_f32_16x16x32_bf16 v[42:45], v[160:163], v[144:147], v[42:45]
	v_rcp_f32_e32 v93, v93
	v_mfma_f32_16x16x32_bf16 v[46:49], v[164:167], v[144:147], v[46:49]
	v_rcp_f32_e32 v94, v94
	v_mfma_f32_16x16x32_bf16 v[50:53], v[152:155], v[148:151], v[50:53]
	v_mfma_f32_16x16x32_bf16 v[54:57], v[156:159], v[148:151], v[54:57]
	v_rcp_f32_e32 v95, v95
	v_mfma_f32_16x16x32_bf16 v[58:61], v[160:163], v[148:151], v[58:61]
	v_rcp_f32_e32 v96, v96
	v_mfma_f32_16x16x32_bf16 v[62:65], v[164:167], v[148:151], v[62:65]
	v_rcp_f32_e32 v97, v97
	s_waitcnt vmcnt(7) lgkmcnt(0)
	s_barrier
	v_mfma_f32_16x16x32_bf16 v[2:5], v[184:187], v[168:171], v[2:5]
	ds_read_b128 v[136:139], v219 offset:0
	v_mfma_f32_16x16x32_bf16 v[6:9], v[188:191], v[168:171], v[6:9]
	ds_read_b128 v[140:143], v219 offset:2048
	v_mfma_f32_16x16x32_bf16 v[10:13], v[192:195], v[168:171], v[10:13]
	ds_read_b128 v[144:147], v219 offset:4096
	v_cvt_pk_bf16_f32 v90, v90, v91
	v_mfma_f32_16x16x32_bf16 v[14:17], v[196:199], v[168:171], v[14:17]
	ds_read_b128 v[148:151], v219 offset:6144
	v_mfma_f32_16x16x32_bf16 v[18:21], v[184:187], v[172:175], v[18:21]
	ds_read_b128 v[152:155], v231 offset:0
	v_cvt_pk_bf16_f32 v91, v92, v93
	v_mfma_f32_16x16x32_bf16 v[22:25], v[188:191], v[172:175], v[22:25]
	ds_read_b128 v[156:159], v231 offset:2048
	v_mfma_f32_16x16x32_bf16 v[26:29], v[192:195], v[172:175], v[26:29]
	ds_read_b128 v[160:163], v231 offset:4096
	v_cvt_pk_bf16_f32 v92, v94, v95
	v_mfma_f32_16x16x32_bf16 v[30:33], v[196:199], v[172:175], v[30:33]
	ds_read_b128 v[164:167], v231 offset:6144
	s_mov_b32 m0, s8
	v_mfma_f32_16x16x32_bf16 v[34:37], v[184:187], v[176:179], v[34:37]
	global_load_lds_dwordx4 v200, s[4:5]
	s_add_u32 m0, s8, 0x400
	v_mfma_f32_16x16x32_bf16 v[38:41], v[188:191], v[176:179], v[38:41]
	global_load_lds_dwordx4 v201, s[4:5]
	v_cvt_pk_bf16_f32 v93, v96, v97
	s_add_u32 m0, s8, 0x800
	v_mfma_f32_16x16x32_bf16 v[42:45], v[192:195], v[176:179], v[42:45]
	global_load_lds_dwordx4 v202, s[4:5]
	s_add_u32 m0, s8, 0xc00
	v_mfma_f32_16x16x32_bf16 v[46:49], v[196:199], v[176:179], v[46:49]
	global_load_lds_dwordx4 v203, s[4:5]
	global_store_dwordx4 v240, v[90:93], s[10:11] offset:3072 sc1
	s_mov_b32 m0, s9
	v_mfma_f32_16x16x32_bf16 v[50:53], v[184:187], v[180:183], v[50:53]
	global_load_lds_dwordx4 v204, s[6:7]
	s_add_u32 m0, s9, 0x400
	v_mfma_f32_16x16x32_bf16 v[54:57], v[188:191], v[180:183], v[54:57]
	global_load_lds_dwordx4 v205, s[6:7]
	v_mul_f32_e32 v98, s12, v98
	v_mfma_f32_16x16x32_bf16 v[58:61], v[192:195], v[180:183], v[58:61]
	s_add_u32 s4, s4, 0x80
	s_addc_u32 s5, s5, 0
	v_mfma_f32_16x16x32_bf16 v[62:65], v[196:199], v[180:183], v[62:65]
	s_add_u32 s6, s6, 0x80
	s_addc_u32 s7, s7, 0
	v_mul_f32_e32 v99, s12, v99
	s_waitcnt lgkmcnt(0)
	v_mfma_f32_16x16x32_bf16 v[2:5], v[152:155], v[136:139], v[2:5]
	ds_read_b128 v[168:171], v228 offset:0
	v_mfma_f32_16x16x32_bf16 v[6:9], v[156:159], v[136:139], v[6:9]
	ds_read_b128 v[172:175], v228 offset:2048
	v_mul_f32_e32 v100, s12, v100
	v_mfma_f32_16x16x32_bf16 v[10:13], v[160:163], v[136:139], v[10:13]
	ds_read_b128 v[176:179], v228 offset:4096
	v_mul_f32_e32 v101, s12, v101
	v_mfma_f32_16x16x32_bf16 v[14:17], v[164:167], v[136:139], v[14:17]
	ds_read_b128 v[180:183], v228 offset:6144
	v_mul_f32_e32 v102, s12, v102
	v_mfma_f32_16x16x32_bf16 v[18:21], v[152:155], v[140:143], v[18:21]
	ds_read_b128 v[184:187], v234 offset:0
	v_mfma_f32_16x16x32_bf16 v[22:25], v[156:159], v[140:143], v[22:25]
	ds_read_b128 v[188:191], v234 offset:2048
	v_mul_f32_e32 v103, s12, v103
	v_mfma_f32_16x16x32_bf16 v[26:29], v[160:163], v[140:143], v[26:29]
	ds_read_b128 v[192:195], v234 offset:4096
	v_mul_f32_e32 v104, s12, v104
	v_mfma_f32_16x16x32_bf16 v[30:33], v[164:167], v[140:143], v[30:33]
	ds_read_b128 v[196:199], v234 offset:6144
	v_mul_f32_e32 v105, s12, v105
	v_mfma_f32_16x16x32_bf16 v[34:37], v[152:155], v[144:147], v[34:37]
	v_mfma_f32_16x16x32_bf16 v[38:41], v[156:159], v[144:147], v[38:41]
	v_exp_f32_e32 v98, v98
	v_mfma_f32_16x16x32_bf16 v[42:45], v[160:163], v[144:147], v[42:45]
	v_exp_f32_e32 v99, v99
	v_mfma_f32_16x16x32_bf16 v[46:49], v[164:167], v[144:147], v[46:49]
	v_exp_f32_e32 v100, v100
	v_mfma_f32_16x16x32_bf16 v[50:53], v[152:155], v[148:151], v[50:53]
	v_mfma_f32_16x16x32_bf16 v[54:57], v[156:159], v[148:151], v[54:57]
	v_exp_f32_e32 v101, v101
	v_mfma_f32_16x16x32_bf16 v[58:61], v[160:163], v[148:151], v[58:61]
	v_exp_f32_e32 v102, v102
	v_mfma_f32_16x16x32_bf16 v[62:65], v[164:167], v[148:151], v[62:65]
	v_exp_f32_e32 v103, v103
	s_waitcnt vmcnt(7) lgkmcnt(0)
	s_barrier
	v_mfma_f32_16x16x32_bf16 v[2:5], v[184:187], v[168:171], v[2:5]
	ds_read_b128 v[136:139], v224 offset:0
	v_mfma_f32_16x16x32_bf16 v[6:9], v[188:191], v[168:171], v[6:9]
	ds_read_b128 v[140:143], v224 offset:2048
	v_mfma_f32_16x16x32_bf16 v[10:13], v[192:195], v[168:171], v[10:13]
	ds_read_b128 v[144:147], v224 offset:4096
	v_exp_f32_e32 v104, v104
	v_mfma_f32_16x16x32_bf16 v[14:17], v[196:199], v[168:171], v[14:17]
	ds_read_b128 v[148:151], v224 offset:6144
	v_mfma_f32_16x16x32_bf16 v[18:21], v[184:187], v[172:175], v[18:21]
	ds_read_b128 v[152:155], v232 offset:0
	v_exp_f32_e32 v105, v105
	v_mfma_f32_16x16x32_bf16 v[22:25], v[188:191], v[172:175], v[22:25]
	ds_read_b128 v[156:159], v232 offset:2048
	v_mfma_f32_16x16x32_bf16 v[26:29], v[192:195], v[172:175], v[26:29]
	ds_read_b128 v[160:163], v232 offset:4096
	v_add_f32_e32 v98, 1.0, v98
	v_mfma_f32_16x16x32_bf16 v[30:33], v[196:199], v[172:175], v[30:33]
	ds_read_b128 v[164:167], v232 offset:6144
	s_add_u32 m0, s8, 0xc000
	v_mfma_f32_16x16x32_bf16 v[34:37], v[184:187], v[176:179], v[34:37]
	global_load_lds_dwordx4 v200, s[4:5]
	s_add_u32 m0, s8, 0xc400
	v_mfma_f32_16x16x32_bf16 v[38:41], v[188:191], v[176:179], v[38:41]
	global_load_lds_dwordx4 v201, s[4:5]
	v_add_f32_e32 v99, 1.0, v99
	s_add_u32 m0, s8, 0xc800
	v_mfma_f32_16x16x32_bf16 v[42:45], v[192:195], v[176:179], v[42:45]
	global_load_lds_dwordx4 v202, s[4:5]
	s_add_u32 m0, s8, 0xcc00
	v_mfma_f32_16x16x32_bf16 v[46:49], v[196:199], v[176:179], v[46:49]
	global_load_lds_dwordx4 v203, s[4:5]
	v_add_f32_e32 v100, 1.0, v100
	s_add_u32 m0, s9, 0xc000
	v_mfma_f32_16x16x32_bf16 v[50:53], v[184:187], v[180:183], v[50:53]
	global_load_lds_dwordx4 v204, s[6:7]
	s_add_u32 m0, s9, 0xc400
	v_mfma_f32_16x16x32_bf16 v[54:57], v[188:191], v[180:183], v[54:57]
	global_load_lds_dwordx4 v205, s[6:7]
	v_add_f32_e32 v101, 1.0, v101
	v_mfma_f32_16x16x32_bf16 v[58:61], v[192:195], v[180:183], v[58:61]
	s_add_u32 s4, s4, 0x80
	s_addc_u32 s5, s5, 0
	v_mfma_f32_16x16x32_bf16 v[62:65], v[196:199], v[180:183], v[62:65]
	s_add_u32 s6, s6, 0x80
	s_addc_u32 s7, s7, 0
	v_add_f32_e32 v102, 1.0, v102
	s_waitcnt lgkmcnt(0)
	v_mfma_f32_16x16x32_bf16 v[2:5], v[152:155], v[136:139], v[2:5]
	ds_read_b128 v[168:171], v229 offset:0
	v_mfma_f32_16x16x32_bf16 v[6:9], v[156:159], v[136:139], v[6:9]
	ds_read_b128 v[172:175], v229 offset:2048
	v_add_f32_e32 v103, 1.0, v103
	v_mfma_f32_16x16x32_bf16 v[10:13], v[160:163], v[136:139], v[10:13]
	ds_read_b128 v[176:179], v229 offset:4096
	v_add_f32_e32 v104, 1.0, v104
	v_mfma_f32_16x16x32_bf16 v[14:17], v[164:167], v[136:139], v[14:17]
	ds_read_b128 v[180:183], v229 offset:6144
	v_add_f32_e32 v105, 1.0, v105
	v_mfma_f32_16x16x32_bf16 v[18:21], v[152:155], v[140:143], v[18:21]
	ds_read_b128 v[184:187], v235 offset:0
	v_mfma_f32_16x16x32_bf16 v[22:25], v[156:159], v[140:143], v[22:25]
	ds_read_b128 v[188:191], v235 offset:2048
	v_rcp_f32_e32 v98, v98
	v_mfma_f32_16x16x32_bf16 v[26:29], v[160:163], v[140:143], v[26:29]
	ds_read_b128 v[192:195], v235 offset:4096
	v_rcp_f32_e32 v99, v99
	v_mfma_f32_16x16x32_bf16 v[30:33], v[164:167], v[140:143], v[30:33]
	ds_read_b128 v[196:199], v235 offset:6144
	v_rcp_f32_e32 v100, v100
	v_mfma_f32_16x16x32_bf16 v[34:37], v[152:155], v[144:147], v[34:37]
	v_mfma_f32_16x16x32_bf16 v[38:41], v[156:159], v[144:147], v[38:41]
	v_rcp_f32_e32 v101, v101
	v_mfma_f32_16x16x32_bf16 v[42:45], v[160:163], v[144:147], v[42:45]
	v_rcp_f32_e32 v102, v102
	v_mfma_f32_16x16x32_bf16 v[46:49], v[164:167], v[144:147], v[46:49]
	v_rcp_f32_e32 v103, v103
	v_mfma_f32_16x16x32_bf16 v[50:53], v[152:155], v[148:151], v[50:53]
	v_mfma_f32_16x16x32_bf16 v[54:57], v[156:159], v[148:151], v[54:57]
	v_rcp_f32_e32 v104, v104
	v_mfma_f32_16x16x32_bf16 v[58:61], v[160:163], v[148:151], v[58:61]
	v_rcp_f32_e32 v105, v105
	v_mfma_f32_16x16x32_bf16 v[62:65], v[164:167], v[148:151], v[62:65]
	v_cvt_pk_bf16_f32 v98, v98, v99
	s_waitcnt vmcnt(6) lgkmcnt(0)
	s_barrier
	v_mfma_f32_16x16x32_bf16 v[2:5], v[184:187], v[168:171], v[2:5]
	ds_read_b128 v[136:139], v218 offset:0
	v_mfma_f32_16x16x32_bf16 v[6:9], v[188:191], v[168:171], v[6:9]
	ds_read_b128 v[140:143], v218 offset:2048
	v_mfma_f32_16x16x32_bf16 v[10:13], v[192:195], v[168:171], v[10:13]
	ds_read_b128 v[144:147], v218 offset:4096
	v_cvt_pk_bf16_f32 v99, v100, v101
	v_mfma_f32_16x16x32_bf16 v[14:17], v[196:199], v[168:171], v[14:17]
	ds_read_b128 v[148:151], v218 offset:6144
	v_mfma_f32_16x16x32_bf16 v[18:21], v[184:187], v[172:175], v[18:21]
	ds_read_b128 v[152:155], v230 offset:0
	v_cvt_pk_bf16_f32 v100, v102, v103
	v_mfma_f32_16x16x32_bf16 v[22:25], v[188:191], v[172:175], v[22:25]
	ds_read_b128 v[156:159], v230 offset:2048
	v_mfma_f32_16x16x32_bf16 v[26:29], v[192:195], v[172:175], v[26:29]
	ds_read_b128 v[160:163], v230 offset:4096
	v_cvt_pk_bf16_f32 v101, v104, v105
	v_mfma_f32_16x16x32_bf16 v[30:33], v[196:199], v[172:175], v[30:33]
	ds_read_b128 v[164:167], v230 offset:6144
	s_add_u32 m0, s8, 0x18000
	v_mfma_f32_16x16x32_bf16 v[34:37], v[184:187], v[176:179], v[34:37]
	global_load_lds_dwordx4 v200, s[4:5]
	s_add_u32 m0, s8, 0x18400
	v_mfma_f32_16x16x32_bf16 v[38:41], v[188:191], v[176:179], v[38:41]
	global_load_lds_dwordx4 v201, s[4:5]
	global_store_dwordx4 v241, v[98:101], s[10:11] offset:0 sc1
	s_add_u32 m0, s8, 0x18800
	v_mfma_f32_16x16x32_bf16 v[42:45], v[192:195], v[176:179], v[42:45]
	global_load_lds_dwordx4 v202, s[4:5]
	s_add_u32 m0, s8, 0x18c00
	v_mfma_f32_16x16x32_bf16 v[46:49], v[196:199], v[176:179], v[46:49]
	global_load_lds_dwordx4 v203, s[4:5]
	v_mul_f32_e32 v106, s12, v106
	s_add_u32 m0, s9, 0x18000
	v_mfma_f32_16x16x32_bf16 v[50:53], v[184:187], v[180:183], v[50:53]
	global_load_lds_dwordx4 v204, s[6:7]
	s_add_u32 m0, s9, 0x18400
	v_mfma_f32_16x16x32_bf16 v[54:57], v[188:191], v[180:183], v[54:57]
	global_load_lds_dwordx4 v205, s[6:7]
	v_mul_f32_e32 v107, s12, v107
	v_mfma_f32_16x16x32_bf16 v[58:61], v[192:195], v[180:183], v[58:61]
	s_add_u32 s4, s4, 0x80
	s_addc_u32 s5, s5, 0
	v_mfma_f32_16x16x32_bf16 v[62:65], v[196:199], v[180:183], v[62:65]
	s_add_u32 s6, s6, 0x80
	s_addc_u32 s7, s7, 0
	v_mul_f32_e32 v108, s12, v108
	s_waitcnt lgkmcnt(0)
	v_mfma_f32_16x16x32_bf16 v[2:5], v[152:155], v[136:139], v[2:5]
	ds_read_b128 v[168:171], v225 offset:0
	v_mfma_f32_16x16x32_bf16 v[6:9], v[156:159], v[136:139], v[6:9]
	ds_read_b128 v[172:175], v225 offset:2048
	v_mul_f32_e32 v109, s12, v109
	v_mfma_f32_16x16x32_bf16 v[10:13], v[160:163], v[136:139], v[10:13]
	ds_read_b128 v[176:179], v225 offset:4096
	v_mul_f32_e32 v110, s12, v110
	v_mfma_f32_16x16x32_bf16 v[14:17], v[164:167], v[136:139], v[14:17]
	ds_read_b128 v[180:183], v225 offset:6144
	v_mul_f32_e32 v111, s12, v111
	v_mfma_f32_16x16x32_bf16 v[18:21], v[152:155], v[140:143], v[18:21]
	ds_read_b128 v[184:187], v233 offset:0
	v_mfma_f32_16x16x32_bf16 v[22:25], v[156:159], v[140:143], v[22:25]
	ds_read_b128 v[188:191], v233 offset:2048
	v_mul_f32_e32 v112, s12, v112
	v_mfma_f32_16x16x32_bf16 v[26:29], v[160:163], v[140:143], v[26:29]
	ds_read_b128 v[192:195], v233 offset:4096
	v_mul_f32_e32 v113, s12, v113
	v_mfma_f32_16x16x32_bf16 v[30:33], v[164:167], v[140:143], v[30:33]
	ds_read_b128 v[196:199], v233 offset:6144
	v_exp_f32_e32 v106, v106
	v_mfma_f32_16x16x32_bf16 v[34:37], v[152:155], v[144:147], v[34:37]
	v_mfma_f32_16x16x32_bf16 v[38:41], v[156:159], v[144:147], v[38:41]
	v_exp_f32_e32 v107, v107
	v_mfma_f32_16x16x32_bf16 v[42:45], v[160:163], v[144:147], v[42:45]
	v_exp_f32_e32 v108, v108
	v_mfma_f32_16x16x32_bf16 v[46:49], v[164:167], v[144:147], v[46:49]
	v_exp_f32_e32 v109, v109
	v_mfma_f32_16x16x32_bf16 v[50:53], v[152:155], v[148:151], v[50:53]
	v_mfma_f32_16x16x32_bf16 v[54:57], v[156:159], v[148:151], v[54:57]
	v_exp_f32_e32 v110, v110
	v_mfma_f32_16x16x32_bf16 v[58:61], v[160:163], v[148:151], v[58:61]
	v_exp_f32_e32 v111, v111
	v_mfma_f32_16x16x32_bf16 v[62:65], v[164:167], v[148:151], v[62:65]
	v_exp_f32_e32 v112, v112
	s_waitcnt vmcnt(7) lgkmcnt(0)
	s_barrier
	v_mfma_f32_16x16x32_bf16 v[2:5], v[184:187], v[168:171], v[2:5]
	ds_read_b128 v[136:139], v219 offset:0
	v_mfma_f32_16x16x32_bf16 v[6:9], v[188:191], v[168:171], v[6:9]
	ds_read_b128 v[140:143], v219 offset:2048
	v_mfma_f32_16x16x32_bf16 v[10:13], v[192:195], v[168:171], v[10:13]
	ds_read_b128 v[144:147], v219 offset:4096
	v_exp_f32_e32 v113, v113
	v_mfma_f32_16x16x32_bf16 v[14:17], v[196:199], v[168:171], v[14:17]
	ds_read_b128 v[148:151], v219 offset:6144
	v_mfma_f32_16x16x32_bf16 v[18:21], v[184:187], v[172:175], v[18:21]
	ds_read_b128 v[152:155], v231 offset:0
	v_add_f32_e32 v106, 1.0, v106
	v_mfma_f32_16x16x32_bf16 v[22:25], v[188:191], v[172:175], v[22:25]
	ds_read_b128 v[156:159], v231 offset:2048
	v_mfma_f32_16x16x32_bf16 v[26:29], v[192:195], v[172:175], v[26:29]
	ds_read_b128 v[160:163], v231 offset:4096
	v_add_f32_e32 v107, 1.0, v107
	v_mfma_f32_16x16x32_bf16 v[30:33], v[196:199], v[172:175], v[30:33]
	ds_read_b128 v[164:167], v231 offset:6144
	s_mov_b32 m0, s8
	v_mfma_f32_16x16x32_bf16 v[34:37], v[184:187], v[176:179], v[34:37]
	global_load_lds_dwordx4 v200, s[4:5]
	s_add_u32 m0, s8, 0x400
	v_mfma_f32_16x16x32_bf16 v[38:41], v[188:191], v[176:179], v[38:41]
	global_load_lds_dwordx4 v201, s[4:5]
	v_add_f32_e32 v108, 1.0, v108
	s_add_u32 m0, s8, 0x800
	v_mfma_f32_16x16x32_bf16 v[42:45], v[192:195], v[176:179], v[42:45]
	global_load_lds_dwordx4 v202, s[4:5]
	s_add_u32 m0, s8, 0xc00
	v_mfma_f32_16x16x32_bf16 v[46:49], v[196:199], v[176:179], v[46:49]
	global_load_lds_dwordx4 v203, s[4:5]
	v_add_f32_e32 v109, 1.0, v109
	s_mov_b32 m0, s9
	v_mfma_f32_16x16x32_bf16 v[50:53], v[184:187], v[180:183], v[50:53]
	global_load_lds_dwordx4 v204, s[6:7]
	s_add_u32 m0, s9, 0x400
	v_mfma_f32_16x16x32_bf16 v[54:57], v[188:191], v[180:183], v[54:57]
	global_load_lds_dwordx4 v205, s[6:7]
	v_add_f32_e32 v110, 1.0, v110
	v_mfma_f32_16x16x32_bf16 v[58:61], v[192:195], v[180:183], v[58:61]
	s_add_u32 s4, s4, 0x80
	s_addc_u32 s5, s5, 0
	v_mfma_f32_16x16x32_bf16 v[62:65], v[196:199], v[180:183], v[62:65]
	s_add_u32 s6, s6, 0x80
	s_addc_u32 s7, s7, 0
	v_add_f32_e32 v111, 1.0, v111
	s_waitcnt lgkmcnt(0)
	v_mfma_f32_16x16x32_bf16 v[2:5], v[152:155], v[136:139], v[2:5]
	ds_read_b128 v[168:171], v228 offset:0
	v_mfma_f32_16x16x32_bf16 v[6:9], v[156:159], v[136:139], v[6:9]
	ds_read_b128 v[172:175], v228 offset:2048
	v_add_f32_e32 v112, 1.0, v112
	v_mfma_f32_16x16x32_bf16 v[10:13], v[160:163], v[136:139], v[10:13]
	ds_read_b128 v[176:179], v228 offset:4096
	v_add_f32_e32 v113, 1.0, v113
	v_mfma_f32_16x16x32_bf16 v[14:17], v[164:167], v[136:139], v[14:17]
	ds_read_b128 v[180:183], v228 offset:6144
	v_rcp_f32_e32 v106, v106
	v_mfma_f32_16x16x32_bf16 v[18:21], v[152:155], v[140:143], v[18:21]
	ds_read_b128 v[184:187], v234 offset:0
	v_mfma_f32_16x16x32_bf16 v[22:25], v[156:159], v[140:143], v[22:25]
	ds_read_b128 v[188:191], v234 offset:2048
	v_rcp_f32_e32 v107, v107
	v_mfma_f32_16x16x32_bf16 v[26:29], v[160:163], v[140:143], v[26:29]
	ds_read_b128 v[192:195], v234 offset:4096
	v_rcp_f32_e32 v108, v108
	v_mfma_f32_16x16x32_bf16 v[30:33], v[164:167], v[140:143], v[30:33]
	ds_read_b128 v[196:199], v234 offset:6144
	v_rcp_f32_e32 v109, v109
	v_mfma_f32_16x16x32_bf16 v[34:37], v[152:155], v[144:147], v[34:37]
	v_mfma_f32_16x16x32_bf16 v[38:41], v[156:159], v[144:147], v[38:41]
	v_rcp_f32_e32 v110, v110
	v_mfma_f32_16x16x32_bf16 v[42:45], v[160:163], v[144:147], v[42:45]
	v_rcp_f32_e32 v111, v111
	v_mfma_f32_16x16x32_bf16 v[46:49], v[164:167], v[144:147], v[46:49]
	v_rcp_f32_e32 v112, v112
	v_mfma_f32_16x16x32_bf16 v[50:53], v[152:155], v[148:151], v[50:53]
	v_mfma_f32_16x16x32_bf16 v[54:57], v[156:159], v[148:151], v[54:57]
	v_rcp_f32_e32 v113, v113
	v_mfma_f32_16x16x32_bf16 v[58:61], v[160:163], v[148:151], v[58:61]
	v_cvt_pk_bf16_f32 v106, v106, v107
	v_mfma_f32_16x16x32_bf16 v[62:65], v[164:167], v[148:151], v[62:65]
	v_cvt_pk_bf16_f32 v107, v108, v109
	s_waitcnt vmcnt(6) lgkmcnt(0)
	s_barrier
	v_mfma_f32_16x16x32_bf16 v[2:5], v[184:187], v[168:171], v[2:5]
	ds_read_b128 v[136:139], v224 offset:0
	v_mfma_f32_16x16x32_bf16 v[6:9], v[188:191], v[168:171], v[6:9]
	ds_read_b128 v[140:143], v224 offset:2048
	v_mfma_f32_16x16x32_bf16 v[10:13], v[192:195], v[168:171], v[10:13]
	ds_read_b128 v[144:147], v224 offset:4096
	v_cvt_pk_bf16_f32 v108, v110, v111
	v_mfma_f32_16x16x32_bf16 v[14:17], v[196:199], v[168:171], v[14:17]
	ds_read_b128 v[148:151], v224 offset:6144
	v_mfma_f32_16x16x32_bf16 v[18:21], v[184:187], v[172:175], v[18:21]
	ds_read_b128 v[152:155], v232 offset:0
	v_cvt_pk_bf16_f32 v109, v112, v113
	v_mfma_f32_16x16x32_bf16 v[22:25], v[188:191], v[172:175], v[22:25]
	ds_read_b128 v[156:159], v232 offset:2048
	v_mfma_f32_16x16x32_bf16 v[26:29], v[192:195], v[172:175], v[26:29]
	ds_read_b128 v[160:163], v232 offset:4096
	global_store_dwordx4 v241, v[106:109], s[10:11] offset:1024 sc1
	v_mfma_f32_16x16x32_bf16 v[30:33], v[196:199], v[172:175], v[30:33]
	ds_read_b128 v[164:167], v232 offset:6144
	s_add_u32 m0, s8, 0xc000
	v_mfma_f32_16x16x32_bf16 v[34:37], v[184:187], v[176:179], v[34:37]
	global_load_lds_dwordx4 v200, s[4:5]
	s_add_u32 m0, s8, 0xc400
	v_mfma_f32_16x16x32_bf16 v[38:41], v[188:191], v[176:179], v[38:41]
	global_load_lds_dwordx4 v201, s[4:5]
	v_mul_f32_e32 v114, s12, v114
	s_add_u32 m0, s8, 0xc800
	v_mfma_f32_16x16x32_bf16 v[42:45], v[192:195], v[176:179], v[42:45]
	global_load_lds_dwordx4 v202, s[4:5]
	s_add_u32 m0, s8, 0xcc00
	v_mfma_f32_16x16x32_bf16 v[46:49], v[196:199], v[176:179], v[46:49]
	global_load_lds_dwordx4 v203, s[4:5]
	v_mul_f32_e32 v115, s12, v115
	s_add_u32 m0, s9, 0xc000
	v_mfma_f32_16x16x32_bf16 v[50:53], v[184:187], v[180:183], v[50:53]
	global_load_lds_dwordx4 v204, s[6:7]
	s_add_u32 m0, s9, 0xc400
	v_mfma_f32_16x16x32_bf16 v[54:57], v[188:191], v[180:183], v[54:57]
	global_load_lds_dwordx4 v205, s[6:7]
	v_mul_f32_e32 v116, s12, v116
	v_mfma_f32_16x16x32_bf16 v[58:61], v[192:195], v[180:183], v[58:61]
	s_add_u32 s4, s4, 0x80
	s_addc_u32 s5, s5, 0
	v_mfma_f32_16x16x32_bf16 v[62:65], v[196:199], v[180:183], v[62:65]
	s_add_u32 s6, s6, 0x80
	s_addc_u32 s7, s7, 0
	v_mul_f32_e32 v117, s12, v117
	s_waitcnt lgkmcnt(0)
	v_mfma_f32_16x16x32_bf16 v[2:5], v[152:155], v[136:139], v[2:5]
	ds_read_b128 v[168:171], v229 offset:0
	v_mfma_f32_16x16x32_bf16 v[6:9], v[156:159], v[136:139], v[6:9]
	ds_read_b128 v[172:175], v229 offset:2048
	v_mul_f32_e32 v118, s12, v118
	v_mfma_f32_16x16x32_bf16 v[10:13], v[160:163], v[136:139], v[10:13]
	ds_read_b128 v[176:179], v229 offset:4096
	v_mul_f32_e32 v119, s12, v119
	v_mfma_f32_16x16x32_bf16 v[14:17], v[164:167], v[136:139], v[14:17]
	ds_read_b128 v[180:183], v229 offset:6144
	v_mul_f32_e32 v120, s12, v120
	v_mfma_f32_16x16x32_bf16 v[18:21], v[152:155], v[140:143], v[18:21]
	ds_read_b128 v[184:187], v235 offset:0
	v_mfma_f32_16x16x32_bf16 v[22:25], v[156:159], v[140:143], v[22:25]
	ds_read_b128 v[188:191], v235 offset:2048
	v_mul_f32_e32 v121, s12, v121
	v_mfma_f32_16x16x32_bf16 v[26:29], v[160:163], v[140:143], v[26:29]
	ds_read_b128 v[192:195], v235 offset:4096
	v_exp_f32_e32 v114, v114
	v_mfma_f32_16x16x32_bf16 v[30:33], v[164:167], v[140:143], v[30:33]
	ds_read_b128 v[196:199], v235 offset:6144
	v_exp_f32_e32 v115, v115
	v_mfma_f32_16x16x32_bf16 v[34:37], v[152:155], v[144:147], v[34:37]
	v_mfma_f32_16x16x32_bf16 v[38:41], v[156:159], v[144:147], v[38:41]
	v_exp_f32_e32 v116, v116
	v_mfma_f32_16x16x32_bf16 v[42:45], v[160:163], v[144:147], v[42:45]
	v_exp_f32_e32 v117, v117
	v_mfma_f32_16x16x32_bf16 v[46:49], v[164:167], v[144:147], v[46:49]
	v_exp_f32_e32 v118, v118
	v_mfma_f32_16x16x32_bf16 v[50:53], v[152:155], v[148:151], v[50:53]
	v_mfma_f32_16x16x32_bf16 v[54:57], v[156:159], v[148:151], v[54:57]
	v_exp_f32_e32 v119, v119
	v_mfma_f32_16x16x32_bf16 v[58:61], v[160:163], v[148:151], v[58:61]
	v_exp_f32_e32 v120, v120
	v_mfma_f32_16x16x32_bf16 v[62:65], v[164:167], v[148:151], v[62:65]
	v_exp_f32_e32 v121, v121
	s_waitcnt vmcnt(7) lgkmcnt(0)
	s_barrier
	v_mfma_f32_16x16x32_bf16 v[2:5], v[184:187], v[168:171], v[2:5]
	ds_read_b128 v[136:139], v218 offset:0
	v_mfma_f32_16x16x32_bf16 v[6:9], v[188:191], v[168:171], v[6:9]
	ds_read_b128 v[140:143], v218 offset:2048
	v_mfma_f32_16x16x32_bf16 v[10:13], v[192:195], v[168:171], v[10:13]
	ds_read_b128 v[144:147], v218 offset:4096
	v_add_f32_e32 v114, 1.0, v114
	v_mfma_f32_16x16x32_bf16 v[14:17], v[196:199], v[168:171], v[14:17]
	ds_read_b128 v[148:151], v218 offset:6144
	v_mfma_f32_16x16x32_bf16 v[18:21], v[184:187], v[172:175], v[18:21]
	ds_read_b128 v[152:155], v230 offset:0
	v_add_f32_e32 v115, 1.0, v115
	v_mfma_f32_16x16x32_bf16 v[22:25], v[188:191], v[172:175], v[22:25]
	ds_read_b128 v[156:159], v230 offset:2048
	v_mfma_f32_16x16x32_bf16 v[26:29], v[192:195], v[172:175], v[26:29]
	ds_read_b128 v[160:163], v230 offset:4096
	v_add_f32_e32 v116, 1.0, v116
	v_mfma_f32_16x16x32_bf16 v[30:33], v[196:199], v[172:175], v[30:33]
	ds_read_b128 v[164:167], v230 offset:6144
	s_add_u32 m0, s8, 0x18000
	v_mfma_f32_16x16x32_bf16 v[34:37], v[184:187], v[176:179], v[34:37]
	global_load_lds_dwordx4 v200, s[4:5]
	s_add_u32 m0, s8, 0x18400
	v_mfma_f32_16x16x32_bf16 v[38:41], v[188:191], v[176:179], v[38:41]
	global_load_lds_dwordx4 v201, s[4:5]
	v_add_f32_e32 v117, 1.0, v117
	s_add_u32 m0, s8, 0x18800
	v_mfma_f32_16x16x32_bf16 v[42:45], v[192:195], v[176:179], v[42:45]
	global_load_lds_dwordx4 v202, s[4:5]
	s_add_u32 m0, s8, 0x18c00
	v_mfma_f32_16x16x32_bf16 v[46:49], v[196:199], v[176:179], v[46:49]
	global_load_lds_dwordx4 v203, s[4:5]
	v_add_f32_e32 v118, 1.0, v118
	s_add_u32 m0, s9, 0x18000
	v_mfma_f32_16x16x32_bf16 v[50:53], v[184:187], v[180:183], v[50:53]
	global_load_lds_dwordx4 v204, s[6:7]
	s_add_u32 m0, s9, 0x18400
	v_mfma_f32_16x16x32_bf16 v[54:57], v[188:191], v[180:183], v[54:57]
	global_load_lds_dwordx4 v205, s[6:7]
	v_add_f32_e32 v119, 1.0, v119
	v_mfma_f32_16x16x32_bf16 v[58:61], v[192:195], v[180:183], v[58:61]
	s_sub_u32 s4, s4, 0x780
	s_subb_u32 s5, s5, 0
	v_mfma_f32_16x16x32_bf16 v[62:65], v[196:199], v[180:183], v[62:65]
	s_add_u32 s6, s6, 0x3f880
	s_addc_u32 s7, s7, 0
	v_add_f32_e32 v120, 1.0, v120
	s_waitcnt lgkmcnt(0)
	v_mfma_f32_16x16x32_bf16 v[2:5], v[152:155], v[136:139], v[2:5]
	ds_read_b128 v[168:171], v225 offset:0
	v_mfma_f32_16x16x32_bf16 v[6:9], v[156:159], v[136:139], v[6:9]
	ds_read_b128 v[172:175], v225 offset:2048
	v_add_f32_e32 v121, 1.0, v121
	v_mfma_f32_16x16x32_bf16 v[10:13], v[160:163], v[136:139], v[10:13]
	ds_read_b128 v[176:179], v225 offset:4096
	v_rcp_f32_e32 v114, v114
	v_mfma_f32_16x16x32_bf16 v[14:17], v[164:167], v[136:139], v[14:17]
	ds_read_b128 v[180:183], v225 offset:6144
	v_rcp_f32_e32 v115, v115
	v_mfma_f32_16x16x32_bf16 v[18:21], v[152:155], v[140:143], v[18:21]
	ds_read_b128 v[184:187], v233 offset:0
	v_mfma_f32_16x16x32_bf16 v[22:25], v[156:159], v[140:143], v[22:25]
	ds_read_b128 v[188:191], v233 offset:2048
	v_rcp_f32_e32 v116, v116
	v_mfma_f32_16x16x32_bf16 v[26:29], v[160:163], v[140:143], v[26:29]
	ds_read_b128 v[192:195], v233 offset:4096
	v_rcp_f32_e32 v117, v117
	v_mfma_f32_16x16x32_bf16 v[30:33], v[164:167], v[140:143], v[30:33]
	ds_read_b128 v[196:199], v233 offset:6144
	v_rcp_f32_e32 v118, v118
	v_mfma_f32_16x16x32_bf16 v[34:37], v[152:155], v[144:147], v[34:37]
	v_mfma_f32_16x16x32_bf16 v[38:41], v[156:159], v[144:147], v[38:41]
	v_rcp_f32_e32 v119, v119
	v_mfma_f32_16x16x32_bf16 v[42:45], v[160:163], v[144:147], v[42:45]
	v_rcp_f32_e32 v120, v120
	v_mfma_f32_16x16x32_bf16 v[46:49], v[164:167], v[144:147], v[46:49]
	v_rcp_f32_e32 v121, v121
	v_mfma_f32_16x16x32_bf16 v[50:53], v[152:155], v[148:151], v[50:53]
	v_mfma_f32_16x16x32_bf16 v[54:57], v[156:159], v[148:151], v[54:57]
	v_cvt_pk_bf16_f32 v114, v114, v115
	v_mfma_f32_16x16x32_bf16 v[58:61], v[160:163], v[148:151], v[58:61]
	v_cvt_pk_bf16_f32 v115, v116, v117
	v_mfma_f32_16x16x32_bf16 v[62:65], v[164:167], v[148:151], v[62:65]
	v_cvt_pk_bf16_f32 v116, v118, v119
	s_waitcnt vmcnt(6) lgkmcnt(0)
	s_barrier
	v_mfma_f32_16x16x32_bf16 v[2:5], v[184:187], v[168:171], v[2:5]
	ds_read_b128 v[136:139], v219 offset:0
	v_mfma_f32_16x16x32_bf16 v[6:9], v[188:191], v[168:171], v[6:9]
	ds_read_b128 v[140:143], v219 offset:2048
	v_mfma_f32_16x16x32_bf16 v[10:13], v[192:195], v[168:171], v[10:13]
	ds_read_b128 v[144:147], v219 offset:4096
	v_cvt_pk_bf16_f32 v117, v120, v121
	v_mfma_f32_16x16x32_bf16 v[14:17], v[196:199], v[168:171], v[14:17]
	ds_read_b128 v[148:151], v219 offset:6144
	v_mfma_f32_16x16x32_bf16 v[18:21], v[184:187], v[172:175], v[18:21]
	ds_read_b128 v[152:155], v231 offset:0
	global_store_dwordx4 v241, v[114:117], s[10:11] offset:2048 sc1
	v_mfma_f32_16x16x32_bf16 v[22:25], v[188:191], v[172:175], v[22:25]
	ds_read_b128 v[156:159], v231 offset:2048
	v_mfma_f32_16x16x32_bf16 v[26:29], v[192:195], v[172:175], v[26:29]
	ds_read_b128 v[160:163], v231 offset:4096
	v_mul_f32_e32 v122, s12, v122
	v_mfma_f32_16x16x32_bf16 v[30:33], v[196:199], v[172:175], v[30:33]
	ds_read_b128 v[164:167], v231 offset:6144
	s_mov_b32 m0, s8
	v_mfma_f32_16x16x32_bf16 v[34:37], v[184:187], v[176:179], v[34:37]
	global_load_lds_dwordx4 v200, s[4:5]
	s_add_u32 m0, s8, 0x400
	v_mfma_f32_16x16x32_bf16 v[38:41], v[188:191], v[176:179], v[38:41]
	global_load_lds_dwordx4 v201, s[4:5]
	v_mul_f32_e32 v123, s12, v123
	s_add_u32 m0, s8, 0x800
	v_mfma_f32_16x16x32_bf16 v[42:45], v[192:195], v[176:179], v[42:45]
	global_load_lds_dwordx4 v202, s[4:5]
	s_add_u32 m0, s8, 0xc00
	v_mfma_f32_16x16x32_bf16 v[46:49], v[196:199], v[176:179], v[46:49]
	global_load_lds_dwordx4 v203, s[4:5]
	v_mul_f32_e32 v124, s12, v124
	s_mov_b32 m0, s9
	v_mfma_f32_16x16x32_bf16 v[50:53], v[184:187], v[180:183], v[50:53]
	global_load_lds_dwordx4 v204, s[6:7]
	s_add_u32 m0, s9, 0x400
	v_mfma_f32_16x16x32_bf16 v[54:57], v[188:191], v[180:183], v[54:57]
	global_load_lds_dwordx4 v205, s[6:7]
	v_mul_f32_e32 v125, s12, v125
	v_mfma_f32_16x16x32_bf16 v[58:61], v[192:195], v[180:183], v[58:61]
	s_add_u32 s4, s4, 0x80
	s_addc_u32 s5, s5, 0
	v_mfma_f32_16x16x32_bf16 v[62:65], v[196:199], v[180:183], v[62:65]
	s_add_u32 s6, s6, 0x80
	s_addc_u32 s7, s7, 0
	v_mul_f32_e32 v126, s12, v126
	s_waitcnt lgkmcnt(0)
	v_mfma_f32_16x16x32_bf16 v[2:5], v[152:155], v[136:139], v[2:5]
	ds_read_b128 v[168:171], v228 offset:0
	v_mfma_f32_16x16x32_bf16 v[6:9], v[156:159], v[136:139], v[6:9]
	ds_read_b128 v[172:175], v228 offset:2048
	v_mul_f32_e32 v127, s12, v127
	v_mfma_f32_16x16x32_bf16 v[10:13], v[160:163], v[136:139], v[10:13]
	ds_read_b128 v[176:179], v228 offset:4096
	v_mul_f32_e32 v128, s12, v128
	v_mfma_f32_16x16x32_bf16 v[14:17], v[164:167], v[136:139], v[14:17]
	ds_read_b128 v[180:183], v228 offset:6144
	v_mul_f32_e32 v129, s12, v129
	v_mfma_f32_16x16x32_bf16 v[18:21], v[152:155], v[140:143], v[18:21]
	ds_read_b128 v[184:187], v234 offset:0
	v_mfma_f32_16x16x32_bf16 v[22:25], v[156:159], v[140:143], v[22:25]
	ds_read_b128 v[188:191], v234 offset:2048
	v_exp_f32_e32 v122, v122
	v_mfma_f32_16x16x32_bf16 v[26:29], v[160:163], v[140:143], v[26:29]
	ds_read_b128 v[192:195], v234 offset:4096
	v_exp_f32_e32 v123, v123
	v_mfma_f32_16x16x32_bf16 v[30:33], v[164:167], v[140:143], v[30:33]
	ds_read_b128 v[196:199], v234 offset:6144
	v_exp_f32_e32 v124, v124
	v_mfma_f32_16x16x32_bf16 v[34:37], v[152:155], v[144:147], v[34:37]
	v_mfma_f32_16x16x32_bf16 v[38:41], v[156:159], v[144:147], v[38:41]
	v_exp_f32_e32 v125, v125
	v_mfma_f32_16x16x32_bf16 v[42:45], v[160:163], v[144:147], v[42:45]
	v_exp_f32_e32 v126, v126
	v_mfma_f32_16x16x32_bf16 v[46:49], v[164:167], v[144:147], v[46:49]
	v_exp_f32_e32 v127, v127
	v_mfma_f32_16x16x32_bf16 v[50:53], v[152:155], v[148:151], v[50:53]
	v_mfma_f32_16x16x32_bf16 v[54:57], v[156:159], v[148:151], v[54:57]
	v_exp_f32_e32 v128, v128
	v_mfma_f32_16x16x32_bf16 v[58:61], v[160:163], v[148:151], v[58:61]
	v_exp_f32_e32 v129, v129
	v_mfma_f32_16x16x32_bf16 v[62:65], v[164:167], v[148:151], v[62:65]
	v_add_f32_e32 v122, 1.0, v122
	s_waitcnt vmcnt(7) lgkmcnt(0)
	s_barrier
	v_mfma_f32_16x16x32_bf16 v[2:5], v[184:187], v[168:171], v[2:5]
	ds_read_b128 v[136:139], v224 offset:0
	v_mfma_f32_16x16x32_bf16 v[6:9], v[188:191], v[168:171], v[6:9]
	ds_read_b128 v[140:143], v224 offset:2048
	v_mfma_f32_16x16x32_bf16 v[10:13], v[192:195], v[168:171], v[10:13]
	ds_read_b128 v[144:147], v224 offset:4096
	v_add_f32_e32 v123, 1.0, v123
	v_mfma_f32_16x16x32_bf16 v[14:17], v[196:199], v[168:171], v[14:17]
	ds_read_b128 v[148:151], v224 offset:6144
	v_mfma_f32_16x16x32_bf16 v[18:21], v[184:187], v[172:175], v[18:21]
	ds_read_b128 v[152:155], v232 offset:0
	v_add_f32_e32 v124, 1.0, v124
	v_mfma_f32_16x16x32_bf16 v[22:25], v[188:191], v[172:175], v[22:25]
	ds_read_b128 v[156:159], v232 offset:2048
	v_mfma_f32_16x16x32_bf16 v[26:29], v[192:195], v[172:175], v[26:29]
	ds_read_b128 v[160:163], v232 offset:4096
	v_add_f32_e32 v125, 1.0, v125
	v_mfma_f32_16x16x32_bf16 v[30:33], v[196:199], v[172:175], v[30:33]
	ds_read_b128 v[164:167], v232 offset:6144
	s_add_u32 m0, s8, 0xc000
	v_mfma_f32_16x16x32_bf16 v[34:37], v[184:187], v[176:179], v[34:37]
	global_load_lds_dwordx4 v200, s[4:5]
	s_add_u32 m0, s8, 0xc400
	v_mfma_f32_16x16x32_bf16 v[38:41], v[188:191], v[176:179], v[38:41]
	global_load_lds_dwordx4 v201, s[4:5]
	v_add_f32_e32 v126, 1.0, v126
	s_add_u32 m0, s8, 0xc800
	v_mfma_f32_16x16x32_bf16 v[42:45], v[192:195], v[176:179], v[42:45]
	global_load_lds_dwordx4 v202, s[4:5]
	s_add_u32 m0, s8, 0xcc00
	v_mfma_f32_16x16x32_bf16 v[46:49], v[196:199], v[176:179], v[46:49]
	global_load_lds_dwordx4 v203, s[4:5]
	v_add_f32_e32 v127, 1.0, v127
	s_add_u32 m0, s9, 0xc000
	v_mfma_f32_16x16x32_bf16 v[50:53], v[184:187], v[180:183], v[50:53]
	global_load_lds_dwordx4 v204, s[6:7]
	s_add_u32 m0, s9, 0xc400
	v_mfma_f32_16x16x32_bf16 v[54:57], v[188:191], v[180:183], v[54:57]
	global_load_lds_dwordx4 v205, s[6:7]
	v_add_f32_e32 v128, 1.0, v128
	v_mfma_f32_16x16x32_bf16 v[58:61], v[192:195], v[180:183], v[58:61]
	s_add_u32 s4, s4, 0x80
	s_addc_u32 s5, s5, 0
	v_mfma_f32_16x16x32_bf16 v[62:65], v[196:199], v[180:183], v[62:65]
	s_add_u32 s6, s6, 0x80
	s_addc_u32 s7, s7, 0
	v_add_f32_e32 v129, 1.0, v129
	s_waitcnt lgkmcnt(0)
	v_mfma_f32_16x16x32_bf16 v[2:5], v[152:155], v[136:139], v[2:5]
	ds_read_b128 v[168:171], v229 offset:0
	v_mfma_f32_16x16x32_bf16 v[6:9], v[156:159], v[136:139], v[6:9]
	ds_read_b128 v[172:175], v229 offset:2048
	v_rcp_f32_e32 v122, v122
	v_mfma_f32_16x16x32_bf16 v[10:13], v[160:163], v[136:139], v[10:13]
	ds_read_b128 v[176:179], v229 offset:4096
	v_rcp_f32_e32 v123, v123
	v_mfma_f32_16x16x32_bf16 v[14:17], v[164:167], v[136:139], v[14:17]
	ds_read_b128 v[180:183], v229 offset:6144
	v_rcp_f32_e32 v124, v124
	v_mfma_f32_16x16x32_bf16 v[18:21], v[152:155], v[140:143], v[18:21]
	ds_read_b128 v[184:187], v235 offset:0
	v_mfma_f32_16x16x32_bf16 v[22:25], v[156:159], v[140:143], v[22:25]
	ds_read_b128 v[188:191], v235 offset:2048
	v_rcp_f32_e32 v125, v125
	v_mfma_f32_16x16x32_bf16 v[26:29], v[160:163], v[140:143], v[26:29]
	ds_read_b128 v[192:195], v235 offset:4096
	v_rcp_f32_e32 v126, v126
	v_mfma_f32_16x16x32_bf16 v[30:33], v[164:167], v[140:143], v[30:33]
	ds_read_b128 v[196:199], v235 offset:6144
	v_rcp_f32_e32 v127, v127
	v_mfma_f32_16x16x32_bf16 v[34:37], v[152:155], v[144:147], v[34:37]
	v_mfma_f32_16x16x32_bf16 v[38:41], v[156:159], v[144:147], v[38:41]
	v_rcp_f32_e32 v128, v128
	v_mfma_f32_16x16x32_bf16 v[42:45], v[160:163], v[144:147], v[42:45]
	v_rcp_f32_e32 v129, v129
	v_mfma_f32_16x16x32_bf16 v[46:49], v[164:167], v[144:147], v[46:49]
	v_cvt_pk_bf16_f32 v122, v122, v123
	v_mfma_f32_16x16x32_bf16 v[50:53], v[152:155], v[148:151], v[50:53]
	v_mfma_f32_16x16x32_bf16 v[54:57], v[156:159], v[148:151], v[54:57]
	v_cvt_pk_bf16_f32 v123, v124, v125
	v_mfma_f32_16x16x32_bf16 v[58:61], v[160:163], v[148:151], v[58:61]
	v_cvt_pk_bf16_f32 v124, v126, v127
	v_mfma_f32_16x16x32_bf16 v[62:65], v[164:167], v[148:151], v[62:65]
	v_cvt_pk_bf16_f32 v125, v128, v129
	s_waitcnt vmcnt(6) lgkmcnt(0)
	s_barrier
	v_mfma_f32_16x16x32_bf16 v[2:5], v[184:187], v[168:171], v[2:5]
	ds_read_b128 v[136:139], v218 offset:0
	v_mfma_f32_16x16x32_bf16 v[6:9], v[188:191], v[168:171], v[6:9]
	ds_read_b128 v[140:143], v218 offset:2048
	v_mfma_f32_16x16x32_bf16 v[10:13], v[192:195], v[168:171], v[10:13]
	ds_read_b128 v[144:147], v218 offset:4096
	v_mfma_f32_16x16x32_bf16 v[14:17], v[196:199], v[168:171], v[14:17]
	ds_read_b128 v[148:151], v218 offset:6144
	v_mfma_f32_16x16x32_bf16 v[18:21], v[184:187], v[172:175], v[18:21]
	ds_read_b128 v[152:155], v230 offset:0
	v_mfma_f32_16x16x32_bf16 v[22:25], v[188:191], v[172:175], v[22:25]
	ds_read_b128 v[156:159], v230 offset:2048
	v_mfma_f32_16x16x32_bf16 v[26:29], v[192:195], v[172:175], v[26:29]
	ds_read_b128 v[160:163], v230 offset:4096
	v_mfma_f32_16x16x32_bf16 v[30:33], v[196:199], v[172:175], v[30:33]
	ds_read_b128 v[164:167], v230 offset:6144
	s_add_u32 m0, s8, 0x18000
	v_mfma_f32_16x16x32_bf16 v[34:37], v[184:187], v[176:179], v[34:37]
	global_load_lds_dwordx4 v200, s[4:5]
	s_add_u32 m0, s8, 0x18400
	v_mfma_f32_16x16x32_bf16 v[38:41], v[188:191], v[176:179], v[38:41]
	global_load_lds_dwordx4 v201, s[4:5]
	s_add_u32 m0, s8, 0x18800
	v_mfma_f32_16x16x32_bf16 v[42:45], v[192:195], v[176:179], v[42:45]
	global_load_lds_dwordx4 v202, s[4:5]
	s_add_u32 m0, s8, 0x18c00
	v_mfma_f32_16x16x32_bf16 v[46:49], v[196:199], v[176:179], v[46:49]
	global_load_lds_dwordx4 v203, s[4:5]
	s_add_u32 m0, s9, 0x18000
	v_mfma_f32_16x16x32_bf16 v[50:53], v[184:187], v[180:183], v[50:53]
	global_load_lds_dwordx4 v204, s[6:7]
	s_add_u32 m0, s9, 0x18400
	v_mfma_f32_16x16x32_bf16 v[54:57], v[188:191], v[180:183], v[54:57]
	global_load_lds_dwordx4 v205, s[6:7]
	v_mfma_f32_16x16x32_bf16 v[58:61], v[192:195], v[180:183], v[58:61]
	s_add_u32 s4, s4, 0x80
	s_addc_u32 s5, s5, 0
	v_mfma_f32_16x16x32_bf16 v[62:65], v[196:199], v[180:183], v[62:65]
	s_add_u32 s6, s6, 0x80
	s_addc_u32 s7, s7, 0
	global_store_dwordx4 v241, v[122:125], s[10:11] offset:3072 sc1
	s_waitcnt lgkmcnt(0)
	v_mfma_f32_16x16x32_bf16 v[66:69], v[152:155], v[136:139], 0
	ds_read_b128 v[168:171], v225 offset:0
	v_mfma_f32_16x16x32_bf16 v[70:73], v[156:159], v[136:139], 0
	ds_read_b128 v[172:175], v225 offset:2048
	s_add_u32 s10, s28, s13
	s_addc_u32 s11, s29, 0
	v_mfma_f32_16x16x32_bf16 v[74:77], v[160:163], v[136:139], 0
	ds_read_b128 v[176:179], v225 offset:4096
	s_add_u32 s13, s13, 0x10000
	v_mfma_f32_16x16x32_bf16 v[78:81], v[164:167], v[136:139], 0
	ds_read_b128 v[180:183], v225 offset:6144
	v_mul_f32_e32 v2, s12, v2
	v_mfma_f32_16x16x32_bf16 v[82:85], v[152:155], v[140:143], 0
	ds_read_b128 v[184:187], v233 offset:0
	v_mfma_f32_16x16x32_bf16 v[86:89], v[156:159], v[140:143], 0
	ds_read_b128 v[188:191], v233 offset:2048
	v_mul_f32_e32 v3, s12, v3
	v_mfma_f32_16x16x32_bf16 v[90:93], v[160:163], v[140:143], 0
	ds_read_b128 v[192:195], v233 offset:4096
	v_mul_f32_e32 v4, s12, v4
	v_mfma_f32_16x16x32_bf16 v[94:97], v[164:167], v[140:143], 0
	ds_read_b128 v[196:199], v233 offset:6144
	v_mul_f32_e32 v5, s12, v5
	v_mfma_f32_16x16x32_bf16 v[98:101], v[152:155], v[144:147], 0
	v_mfma_f32_16x16x32_bf16 v[102:105], v[156:159], v[144:147], 0
	v_mul_f32_e32 v6, s12, v6
	v_mfma_f32_16x16x32_bf16 v[106:109], v[160:163], v[144:147], 0
	v_mul_f32_e32 v7, s12, v7
	v_mfma_f32_16x16x32_bf16 v[110:113], v[164:167], v[144:147], 0
	v_mul_f32_e32 v8, s12, v8
	v_mfma_f32_16x16x32_bf16 v[114:117], v[152:155], v[148:151], 0
	v_mfma_f32_16x16x32_bf16 v[118:121], v[156:159], v[148:151], 0
	v_mul_f32_e32 v9, s12, v9
	v_mfma_f32_16x16x32_bf16 v[122:125], v[160:163], v[148:151], 0
	v_exp_f32_e32 v2, v2
	v_mfma_f32_16x16x32_bf16 v[126:129], v[164:167], v[148:151], 0
	v_exp_f32_e32 v3, v3
	s_waitcnt vmcnt(7) lgkmcnt(0)
	s_barrier
	v_mfma_f32_16x16x32_bf16 v[66:69], v[184:187], v[168:171], v[66:69]
	ds_read_b128 v[136:139], v219 offset:0
	v_mfma_f32_16x16x32_bf16 v[70:73], v[188:191], v[168:171], v[70:73]
	ds_read_b128 v[140:143], v219 offset:2048
	v_mfma_f32_16x16x32_bf16 v[74:77], v[192:195], v[168:171], v[74:77]
	ds_read_b128 v[144:147], v219 offset:4096
	v_exp_f32_e32 v4, v4
	v_mfma_f32_16x16x32_bf16 v[78:81], v[196:199], v[168:171], v[78:81]
	ds_read_b128 v[148:151], v219 offset:6144
	v_mfma_f32_16x16x32_bf16 v[82:85], v[184:187], v[172:175], v[82:85]
	ds_read_b128 v[152:155], v231 offset:0
	v_exp_f32_e32 v5, v5
	v_mfma_f32_16x16x32_bf16 v[86:89], v[188:191], v[172:175], v[86:89]
	ds_read_b128 v[156:159], v231 offset:2048
	v_mfma_f32_16x16x32_bf16 v[90:93], v[192:195], v[172:175], v[90:93]
	ds_read_b128 v[160:163], v231 offset:4096
	v_exp_f32_e32 v6, v6
	v_mfma_f32_16x16x32_bf16 v[94:97], v[196:199], v[172:175], v[94:97]
	ds_read_b128 v[164:167], v231 offset:6144
	s_mov_b32 m0, s8
	v_mfma_f32_16x16x32_bf16 v[98:101], v[184:187], v[176:179], v[98:101]
	global_load_lds_dwordx4 v200, s[4:5]
	s_add_u32 m0, s8, 0x400
	v_mfma_f32_16x16x32_bf16 v[102:105], v[188:191], v[176:179], v[102:105]
	global_load_lds_dwordx4 v201, s[4:5]
	v_exp_f32_e32 v7, v7
	s_add_u32 m0, s8, 0x800
	v_mfma_f32_16x16x32_bf16 v[106:109], v[192:195], v[176:179], v[106:109]
	global_load_lds_dwordx4 v202, s[4:5]
	s_add_u32 m0, s8, 0xc00
	v_mfma_f32_16x16x32_bf16 v[110:113], v[196:199], v[176:179], v[110:113]
	global_load_lds_dwordx4 v203, s[4:5]
	v_exp_f32_e32 v8, v8
	s_mov_b32 m0, s9
	v_mfma_f32_16x16x32_bf16 v[114:117], v[184:187], v[180:183], v[114:117]
	global_load_lds_dwordx4 v204, s[6:7]
	s_add_u32 m0, s9, 0x400
	v_mfma_f32_16x16x32_bf16 v[118:121], v[188:191], v[180:183], v[118:121]
	global_load_lds_dwordx4 v205, s[6:7]
	v_exp_f32_e32 v9, v9
	v_mfma_f32_16x16x32_bf16 v[122:125], v[192:195], v[180:183], v[122:125]
	s_add_u32 s4, s4, 0x80
	s_addc_u32 s5, s5, 0
	v_mfma_f32_16x16x32_bf16 v[126:129], v[196:199], v[180:183], v[126:129]
	s_add_u32 s6, s6, 0x80
	s_addc_u32 s7, s7, 0
	v_add_f32_e32 v2, 1.0, v2
	s_waitcnt lgkmcnt(0)
	v_mfma_f32_16x16x32_bf16 v[66:69], v[152:155], v[136:139], v[66:69]
	ds_read_b128 v[168:171], v228 offset:0
	v_mfma_f32_16x16x32_bf16 v[70:73], v[156:159], v[136:139], v[70:73]
	ds_read_b128 v[172:175], v228 offset:2048
	v_add_f32_e32 v3, 1.0, v3
	v_mfma_f32_16x16x32_bf16 v[74:77], v[160:163], v[136:139], v[74:77]
	ds_read_b128 v[176:179], v228 offset:4096
	v_add_f32_e32 v4, 1.0, v4
	v_mfma_f32_16x16x32_bf16 v[78:81], v[164:167], v[136:139], v[78:81]
	ds_read_b128 v[180:183], v228 offset:6144
	v_add_f32_e32 v5, 1.0, v5
	v_mfma_f32_16x16x32_bf16 v[82:85], v[152:155], v[140:143], v[82:85]
	ds_read_b128 v[184:187], v234 offset:0
	v_mfma_f32_16x16x32_bf16 v[86:89], v[156:159], v[140:143], v[86:89]
	ds_read_b128 v[188:191], v234 offset:2048
	v_add_f32_e32 v6, 1.0, v6
	v_mfma_f32_16x16x32_bf16 v[90:93], v[160:163], v[140:143], v[90:93]
	ds_read_b128 v[192:195], v234 offset:4096
	v_add_f32_e32 v7, 1.0, v7
	v_mfma_f32_16x16x32_bf16 v[94:97], v[164:167], v[140:143], v[94:97]
	ds_read_b128 v[196:199], v234 offset:6144
	v_add_f32_e32 v8, 1.0, v8
	v_mfma_f32_16x16x32_bf16 v[98:101], v[152:155], v[144:147], v[98:101]
	v_mfma_f32_16x16x32_bf16 v[102:105], v[156:159], v[144:147], v[102:105]
	v_add_f32_e32 v9, 1.0, v9
	v_mfma_f32_16x16x32_bf16 v[106:109], v[160:163], v[144:147], v[106:109]
	v_rcp_f32_e32 v2, v2
	v_mfma_f32_16x16x32_bf16 v[110:113], v[164:167], v[144:147], v[110:113]
	v_rcp_f32_e32 v3, v3
	v_mfma_f32_16x16x32_bf16 v[114:117], v[152:155], v[148:151], v[114:117]
	v_mfma_f32_16x16x32_bf16 v[118:121], v[156:159], v[148:151], v[118:121]
	v_rcp_f32_e32 v4, v4
	v_mfma_f32_16x16x32_bf16 v[122:125], v[160:163], v[148:151], v[122:125]
	v_rcp_f32_e32 v5, v5
	v_mfma_f32_16x16x32_bf16 v[126:129], v[164:167], v[148:151], v[126:129]
	v_rcp_f32_e32 v6, v6
	s_waitcnt vmcnt(7) lgkmcnt(0)
	s_barrier
	v_mfma_f32_16x16x32_bf16 v[66:69], v[184:187], v[168:171], v[66:69]
	ds_read_b128 v[136:139], v224 offset:0
	v_mfma_f32_16x16x32_bf16 v[70:73], v[188:191], v[168:171], v[70:73]
	ds_read_b128 v[140:143], v224 offset:2048
	v_mfma_f32_16x16x32_bf16 v[74:77], v[192:195], v[168:171], v[74:77]
	ds_read_b128 v[144:147], v224 offset:4096
	v_rcp_f32_e32 v7, v7
	v_mfma_f32_16x16x32_bf16 v[78:81], v[196:199], v[168:171], v[78:81]
	ds_read_b128 v[148:151], v224 offset:6144
	v_mfma_f32_16x16x32_bf16 v[82:85], v[184:187], v[172:175], v[82:85]
	ds_read_b128 v[152:155], v232 offset:0
	v_rcp_f32_e32 v8, v8
	v_mfma_f32_16x16x32_bf16 v[86:89], v[188:191], v[172:175], v[86:89]
	ds_read_b128 v[156:159], v232 offset:2048
	v_mfma_f32_16x16x32_bf16 v[90:93], v[192:195], v[172:175], v[90:93]
	ds_read_b128 v[160:163], v232 offset:4096
	v_rcp_f32_e32 v9, v9
	v_mfma_f32_16x16x32_bf16 v[94:97], v[196:199], v[172:175], v[94:97]
	ds_read_b128 v[164:167], v232 offset:6144
	s_add_u32 m0, s8, 0xc000
	v_mfma_f32_16x16x32_bf16 v[98:101], v[184:187], v[176:179], v[98:101]
	global_load_lds_dwordx4 v200, s[4:5]
	s_add_u32 m0, s8, 0xc400
	v_mfma_f32_16x16x32_bf16 v[102:105], v[188:191], v[176:179], v[102:105]
	global_load_lds_dwordx4 v201, s[4:5]
	v_cvt_pk_bf16_f32 v2, v2, v3
	s_add_u32 m0, s8, 0xc800
	v_mfma_f32_16x16x32_bf16 v[106:109], v[192:195], v[176:179], v[106:109]
	global_load_lds_dwordx4 v202, s[4:5]
	s_add_u32 m0, s8, 0xcc00
	v_mfma_f32_16x16x32_bf16 v[110:113], v[196:199], v[176:179], v[110:113]
	global_load_lds_dwordx4 v203, s[4:5]
	v_cvt_pk_bf16_f32 v3, v4, v5
	s_add_u32 m0, s9, 0xc000
	v_mfma_f32_16x16x32_bf16 v[114:117], v[184:187], v[180:183], v[114:117]
	global_load_lds_dwordx4 v204, s[6:7]
	s_add_u32 m0, s9, 0xc400
	v_mfma_f32_16x16x32_bf16 v[118:121], v[188:191], v[180:183], v[118:121]
	global_load_lds_dwordx4 v205, s[6:7]
	v_cvt_pk_bf16_f32 v4, v6, v7
	v_mfma_f32_16x16x32_bf16 v[122:125], v[192:195], v[180:183], v[122:125]
	s_add_u32 s4, s4, 0x80
	s_addc_u32 s5, s5, 0
	v_mfma_f32_16x16x32_bf16 v[126:129], v[196:199], v[180:183], v[126:129]
	s_add_u32 s6, s6, 0x80
	s_addc_u32 s7, s7, 0
	v_cvt_pk_bf16_f32 v5, v8, v9
	s_waitcnt lgkmcnt(0)
	v_mfma_f32_16x16x32_bf16 v[66:69], v[152:155], v[136:139], v[66:69]
	ds_read_b128 v[168:171], v229 offset:0
	v_mfma_f32_16x16x32_bf16 v[70:73], v[156:159], v[136:139], v[70:73]
	ds_read_b128 v[172:175], v229 offset:2048
	global_store_dwordx4 v240, v[2:5], s[10:11] offset:0 sc1
	v_mfma_f32_16x16x32_bf16 v[74:77], v[160:163], v[136:139], v[74:77]
	ds_read_b128 v[176:179], v229 offset:4096
	v_mul_f32_e32 v10, s12, v10
	v_mfma_f32_16x16x32_bf16 v[78:81], v[164:167], v[136:139], v[78:81]
	ds_read_b128 v[180:183], v229 offset:6144
	v_mul_f32_e32 v11, s12, v11
	v_mfma_f32_16x16x32_bf16 v[82:85], v[152:155], v[140:143], v[82:85]
	ds_read_b128 v[184:187], v235 offset:0
	v_mfma_f32_16x16x32_bf16 v[86:89], v[156:159], v[140:143], v[86:89]
	ds_read_b128 v[188:191], v235 offset:2048
	v_mul_f32_e32 v12, s12, v12
	v_mfma_f32_16x16x32_bf16 v[90:93], v[160:163], v[140:143], v[90:93]
	ds_read_b128 v[192:195], v235 offset:4096
	v_mul_f32_e32 v13, s12, v13
	v_mfma_f32_16x16x32_bf16 v[94:97], v[164:167], v[140:143], v[94:97]
	ds_read_b128 v[196:199], v235 offset:6144
	v_mul_f32_e32 v14, s12, v14
	v_mfma_f32_16x16x32_bf16 v[98:101], v[152:155], v[144:147], v[98:101]
	v_mfma_f32_16x16x32_bf16 v[102:105], v[156:159], v[144:147], v[102:105]
	v_mul_f32_e32 v15, s12, v15
	v_mfma_f32_16x16x32_bf16 v[106:109], v[160:163], v[144:147], v[106:109]
	v_mul_f32_e32 v16, s12, v16
	v_mfma_f32_16x16x32_bf16 v[110:113], v[164:167], v[144:147], v[110:113]
	v_mul_f32_e32 v17, s12, v17
	v_mfma_f32_16x16x32_bf16 v[114:117], v[152:155], v[148:151], v[114:117]
	v_mfma_f32_16x16x32_bf16 v[118:121], v[156:159], v[148:151], v[118:121]
	v_exp_f32_e32 v10, v10
	v_mfma_f32_16x16x32_bf16 v[122:125], v[160:163], v[148:151], v[122:125]
	v_exp_f32_e32 v11, v11
	v_mfma_f32_16x16x32_bf16 v[126:129], v[164:167], v[148:151], v[126:129]
	v_exp_f32_e32 v12, v12
	s_waitcnt vmcnt(7) lgkmcnt(0)
	s_barrier
	v_mfma_f32_16x16x32_bf16 v[66:69], v[184:187], v[168:171], v[66:69]
	ds_read_b128 v[136:139], v218 offset:0
	v_mfma_f32_16x16x32_bf16 v[70:73], v[188:191], v[168:171], v[70:73]
	ds_read_b128 v[140:143], v218 offset:2048
	v_mfma_f32_16x16x32_bf16 v[74:77], v[192:195], v[168:171], v[74:77]
	ds_read_b128 v[144:147], v218 offset:4096
	v_exp_f32_e32 v13, v13
	v_mfma_f32_16x16x32_bf16 v[78:81], v[196:199], v[168:171], v[78:81]
	ds_read_b128 v[148:151], v218 offset:6144
	v_mfma_f32_16x16x32_bf16 v[82:85], v[184:187], v[172:175], v[82:85]
	ds_read_b128 v[152:155], v230 offset:0
	v_exp_f32_e32 v14, v14
	v_mfma_f32_16x16x32_bf16 v[86:89], v[188:191], v[172:175], v[86:89]
	ds_read_b128 v[156:159], v230 offset:2048
	v_mfma_f32_16x16x32_bf16 v[90:93], v[192:195], v[172:175], v[90:93]
	ds_read_b128 v[160:163], v230 offset:4096
	v_exp_f32_e32 v15, v15
	v_mfma_f32_16x16x32_bf16 v[94:97], v[196:199], v[172:175], v[94:97]
	ds_read_b128 v[164:167], v230 offset:6144
	s_add_u32 m0, s8, 0x18000
	v_mfma_f32_16x16x32_bf16 v[98:101], v[184:187], v[176:179], v[98:101]
	global_load_lds_dwordx4 v200, s[4:5]
	s_add_u32 m0, s8, 0x18400
	v_mfma_f32_16x16x32_bf16 v[102:105], v[188:191], v[176:179], v[102:105]
	global_load_lds_dwordx4 v201, s[4:5]
	v_exp_f32_e32 v16, v16
	s_add_u32 m0, s8, 0x18800
	v_mfma_f32_16x16x32_bf16 v[106:109], v[192:195], v[176:179], v[106:109]
	global_load_lds_dwordx4 v202, s[4:5]
	s_add_u32 m0, s8, 0x18c00
	v_mfma_f32_16x16x32_bf16 v[110:113], v[196:199], v[176:179], v[110:113]
	global_load_lds_dwordx4 v203, s[4:5]
	v_exp_f32_e32 v17, v17
	s_add_u32 m0, s9, 0x18000
	v_mfma_f32_16x16x32_bf16 v[114:117], v[184:187], v[180:183], v[114:117]
	global_load_lds_dwordx4 v204, s[6:7]
	s_add_u32 m0, s9, 0x18400
	v_mfma_f32_16x16x32_bf16 v[118:121], v[188:191], v[180:183], v[118:121]
	global_load_lds_dwordx4 v205, s[6:7]
	v_add_f32_e32 v10, 1.0, v10
	v_mfma_f32_16x16x32_bf16 v[122:125], v[192:195], v[180:183], v[122:125]
	s_add_u32 s4, s4, 0x80
	s_addc_u32 s5, s5, 0
	v_mfma_f32_16x16x32_bf16 v[126:129], v[196:199], v[180:183], v[126:129]
	s_add_u32 s6, s6, 0x80
	s_addc_u32 s7, s7, 0
	v_add_f32_e32 v11, 1.0, v11
	s_waitcnt lgkmcnt(0)
	v_mfma_f32_16x16x32_bf16 v[66:69], v[152:155], v[136:139], v[66:69]
	ds_read_b128 v[168:171], v225 offset:0
	v_mfma_f32_16x16x32_bf16 v[70:73], v[156:159], v[136:139], v[70:73]
	ds_read_b128 v[172:175], v225 offset:2048
	v_add_f32_e32 v12, 1.0, v12
	v_mfma_f32_16x16x32_bf16 v[74:77], v[160:163], v[136:139], v[74:77]
	ds_read_b128 v[176:179], v225 offset:4096
	v_add_f32_e32 v13, 1.0, v13
	v_mfma_f32_16x16x32_bf16 v[78:81], v[164:167], v[136:139], v[78:81]
	ds_read_b128 v[180:183], v225 offset:6144
	v_add_f32_e32 v14, 1.0, v14
	v_mfma_f32_16x16x32_bf16 v[82:85], v[152:155], v[140:143], v[82:85]
	ds_read_b128 v[184:187], v233 offset:0
	v_mfma_f32_16x16x32_bf16 v[86:89], v[156:159], v[140:143], v[86:89]
	ds_read_b128 v[188:191], v233 offset:2048
	v_add_f32_e32 v15, 1.0, v15
	v_mfma_f32_16x16x32_bf16 v[90:93], v[160:163], v[140:143], v[90:93]
	ds_read_b128 v[192:195], v233 offset:4096
	v_add_f32_e32 v16, 1.0, v16
	v_mfma_f32_16x16x32_bf16 v[94:97], v[164:167], v[140:143], v[94:97]
	ds_read_b128 v[196:199], v233 offset:6144
	v_add_f32_e32 v17, 1.0, v17
	v_mfma_f32_16x16x32_bf16 v[98:101], v[152:155], v[144:147], v[98:101]
	v_mfma_f32_16x16x32_bf16 v[102:105], v[156:159], v[144:147], v[102:105]
	v_rcp_f32_e32 v10, v10
	v_mfma_f32_16x16x32_bf16 v[106:109], v[160:163], v[144:147], v[106:109]
	v_rcp_f32_e32 v11, v11
	v_mfma_f32_16x16x32_bf16 v[110:113], v[164:167], v[144:147], v[110:113]
	v_rcp_f32_e32 v12, v12
	v_mfma_f32_16x16x32_bf16 v[114:117], v[152:155], v[148:151], v[114:117]
	v_mfma_f32_16x16x32_bf16 v[118:121], v[156:159], v[148:151], v[118:121]
	v_rcp_f32_e32 v13, v13
	v_mfma_f32_16x16x32_bf16 v[122:125], v[160:163], v[148:151], v[122:125]
	v_rcp_f32_e32 v14, v14
	v_mfma_f32_16x16x32_bf16 v[126:129], v[164:167], v[148:151], v[126:129]
	v_rcp_f32_e32 v15, v15
	s_waitcnt vmcnt(7) lgkmcnt(0)
	s_barrier
	v_mfma_f32_16x16x32_bf16 v[66:69], v[184:187], v[168:171], v[66:69]
	ds_read_b128 v[136:139], v219 offset:0
	v_mfma_f32_16x16x32_bf16 v[70:73], v[188:191], v[168:171], v[70:73]
	ds_read_b128 v[140:143], v219 offset:2048
	v_mfma_f32_16x16x32_bf16 v[74:77], v[192:195], v[168:171], v[74:77]
	ds_read_b128 v[144:147], v219 offset:4096
	v_rcp_f32_e32 v16, v16
	v_mfma_f32_16x16x32_bf16 v[78:81], v[196:199], v[168:171], v[78:81]
	ds_read_b128 v[148:151], v219 offset:6144
	v_mfma_f32_16x16x32_bf16 v[82:85], v[184:187], v[172:175], v[82:85]
	ds_read_b128 v[152:155], v231 offset:0
	v_rcp_f32_e32 v17, v17
	v_mfma_f32_16x16x32_bf16 v[86:89], v[188:191], v[172:175], v[86:89]
	ds_read_b128 v[156:159], v231 offset:2048
	v_mfma_f32_16x16x32_bf16 v[90:93], v[192:195], v[172:175], v[90:93]
	ds_read_b128 v[160:163], v231 offset:4096
	v_cvt_pk_bf16_f32 v10, v10, v11
	v_mfma_f32_16x16x32_bf16 v[94:97], v[196:199], v[172:175], v[94:97]
	ds_read_b128 v[164:167], v231 offset:6144
	s_mov_b32 m0, s8
	v_mfma_f32_16x16x32_bf16 v[98:101], v[184:187], v[176:179], v[98:101]
	global_load_lds_dwordx4 v200, s[4:5]
	s_add_u32 m0, s8, 0x400
	v_mfma_f32_16x16x32_bf16 v[102:105], v[188:191], v[176:179], v[102:105]
	global_load_lds_dwordx4 v201, s[4:5]
	v_cvt_pk_bf16_f32 v11, v12, v13
	s_add_u32 m0, s8, 0x800
	v_mfma_f32_16x16x32_bf16 v[106:109], v[192:195], v[176:179], v[106:109]
	global_load_lds_dwordx4 v202, s[4:5]
	s_add_u32 m0, s8, 0xc00
	v_mfma_f32_16x16x32_bf16 v[110:113], v[196:199], v[176:179], v[110:113]
	global_load_lds_dwordx4 v203, s[4:5]
	v_cvt_pk_bf16_f32 v12, v14, v15
	s_mov_b32 m0, s9
	v_mfma_f32_16x16x32_bf16 v[114:117], v[184:187], v[180:183], v[114:117]
	global_load_lds_dwordx4 v204, s[6:7]
	s_add_u32 m0, s9, 0x400
	v_mfma_f32_16x16x32_bf16 v[118:121], v[188:191], v[180:183], v[118:121]
	global_load_lds_dwordx4 v205, s[6:7]
	v_cvt_pk_bf16_f32 v13, v16, v17
	v_mfma_f32_16x16x32_bf16 v[122:125], v[192:195], v[180:183], v[122:125]
	s_add_u32 s4, s4, 0x80
	s_addc_u32 s5, s5, 0
	v_mfma_f32_16x16x32_bf16 v[126:129], v[196:199], v[180:183], v[126:129]
	s_add_u32 s6, s6, 0x80
	s_addc_u32 s7, s7, 0
	global_store_dwordx4 v240, v[10:13], s[10:11] offset:1024 sc1
	s_waitcnt lgkmcnt(0)
	v_mfma_f32_16x16x32_bf16 v[66:69], v[152:155], v[136:139], v[66:69]
	ds_read_b128 v[168:171], v228 offset:0
	v_mfma_f32_16x16x32_bf16 v[70:73], v[156:159], v[136:139], v[70:73]
	ds_read_b128 v[172:175], v228 offset:2048
	v_mul_f32_e32 v18, s12, v18
	v_mfma_f32_16x16x32_bf16 v[74:77], v[160:163], v[136:139], v[74:77]
	ds_read_b128 v[176:179], v228 offset:4096
	v_mul_f32_e32 v19, s12, v19
	v_mfma_f32_16x16x32_bf16 v[78:81], v[164:167], v[136:139], v[78:81]
	ds_read_b128 v[180:183], v228 offset:6144
	v_mul_f32_e32 v20, s12, v20
	v_mfma_f32_16x16x32_bf16 v[82:85], v[152:155], v[140:143], v[82:85]
	ds_read_b128 v[184:187], v234 offset:0
	v_mfma_f32_16x16x32_bf16 v[86:89], v[156:159], v[140:143], v[86:89]
	ds_read_b128 v[188:191], v234 offset:2048
	v_mul_f32_e32 v21, s12, v21
	v_mfma_f32_16x16x32_bf16 v[90:93], v[160:163], v[140:143], v[90:93]
	ds_read_b128 v[192:195], v234 offset:4096
	v_mul_f32_e32 v22, s12, v22
	v_mfma_f32_16x16x32_bf16 v[94:97], v[164:167], v[140:143], v[94:97]
	ds_read_b128 v[196:199], v234 offset:6144
	v_mul_f32_e32 v23, s12, v23
	v_mfma_f32_16x16x32_bf16 v[98:101], v[152:155], v[144:147], v[98:101]
	v_mfma_f32_16x16x32_bf16 v[102:105], v[156:159], v[144:147], v[102:105]
	v_mul_f32_e32 v24, s12, v24
	v_mfma_f32_16x16x32_bf16 v[106:109], v[160:163], v[144:147], v[106:109]
	v_mul_f32_e32 v25, s12, v25
	v_mfma_f32_16x16x32_bf16 v[110:113], v[164:167], v[144:147], v[110:113]
	v_exp_f32_e32 v18, v18
	v_mfma_f32_16x16x32_bf16 v[114:117], v[152:155], v[148:151], v[114:117]
	v_mfma_f32_16x16x32_bf16 v[118:121], v[156:159], v[148:151], v[118:121]
	v_exp_f32_e32 v19, v19
	v_mfma_f32_16x16x32_bf16 v[122:125], v[160:163], v[148:151], v[122:125]
	v_exp_f32_e32 v20, v20
	v_mfma_f32_16x16x32_bf16 v[126:129], v[164:167], v[148:151], v[126:129]
	v_exp_f32_e32 v21, v21
	s_waitcnt vmcnt(7) lgkmcnt(0)
	s_barrier
	v_mfma_f32_16x16x32_bf16 v[66:69], v[184:187], v[168:171], v[66:69]
	ds_read_b128 v[136:139], v224 offset:0
	v_mfma_f32_16x16x32_bf16 v[70:73], v[188:191], v[168:171], v[70:73]
	ds_read_b128 v[140:143], v224 offset:2048
	v_mfma_f32_16x16x32_bf16 v[74:77], v[192:195], v[168:171], v[74:77]
	ds_read_b128 v[144:147], v224 offset:4096
	v_exp_f32_e32 v22, v22
	v_mfma_f32_16x16x32_bf16 v[78:81], v[196:199], v[168:171], v[78:81]
	ds_read_b128 v[148:151], v224 offset:6144
	v_mfma_f32_16x16x32_bf16 v[82:85], v[184:187], v[172:175], v[82:85]
	ds_read_b128 v[152:155], v232 offset:0
	v_exp_f32_e32 v23, v23
	v_mfma_f32_16x16x32_bf16 v[86:89], v[188:191], v[172:175], v[86:89]
	ds_read_b128 v[156:159], v232 offset:2048
	v_mfma_f32_16x16x32_bf16 v[90:93], v[192:195], v[172:175], v[90:93]
	ds_read_b128 v[160:163], v232 offset:4096
	v_exp_f32_e32 v24, v24
	v_mfma_f32_16x16x32_bf16 v[94:97], v[196:199], v[172:175], v[94:97]
	ds_read_b128 v[164:167], v232 offset:6144
	s_add_u32 m0, s8, 0xc000
	v_mfma_f32_16x16x32_bf16 v[98:101], v[184:187], v[176:179], v[98:101]
	global_load_lds_dwordx4 v200, s[4:5]
	s_add_u32 m0, s8, 0xc400
	v_mfma_f32_16x16x32_bf16 v[102:105], v[188:191], v[176:179], v[102:105]
	global_load_lds_dwordx4 v201, s[4:5]
	v_exp_f32_e32 v25, v25
	s_add_u32 m0, s8, 0xc800
	v_mfma_f32_16x16x32_bf16 v[106:109], v[192:195], v[176:179], v[106:109]
	global_load_lds_dwordx4 v202, s[4:5]
	s_add_u32 m0, s8, 0xcc00
	v_mfma_f32_16x16x32_bf16 v[110:113], v[196:199], v[176:179], v[110:113]
	global_load_lds_dwordx4 v203, s[4:5]
	v_add_f32_e32 v18, 1.0, v18
	s_add_u32 m0, s9, 0xc000
	v_mfma_f32_16x16x32_bf16 v[114:117], v[184:187], v[180:183], v[114:117]
	global_load_lds_dwordx4 v204, s[6:7]
	s_add_u32 m0, s9, 0xc400
	v_mfma_f32_16x16x32_bf16 v[118:121], v[188:191], v[180:183], v[118:121]
	global_load_lds_dwordx4 v205, s[6:7]
	v_add_f32_e32 v19, 1.0, v19
	v_mfma_f32_16x16x32_bf16 v[122:125], v[192:195], v[180:183], v[122:125]
	s_add_u32 s4, s4, 0x80
	s_addc_u32 s5, s5, 0
	v_mfma_f32_16x16x32_bf16 v[126:129], v[196:199], v[180:183], v[126:129]
	s_add_u32 s6, s6, 0x80
	s_addc_u32 s7, s7, 0
	v_add_f32_e32 v20, 1.0, v20
	s_waitcnt lgkmcnt(0)
	v_mfma_f32_16x16x32_bf16 v[66:69], v[152:155], v[136:139], v[66:69]
	ds_read_b128 v[168:171], v229 offset:0
	v_mfma_f32_16x16x32_bf16 v[70:73], v[156:159], v[136:139], v[70:73]
	ds_read_b128 v[172:175], v229 offset:2048
	v_add_f32_e32 v21, 1.0, v21
	v_mfma_f32_16x16x32_bf16 v[74:77], v[160:163], v[136:139], v[74:77]
	ds_read_b128 v[176:179], v229 offset:4096
	v_add_f32_e32 v22, 1.0, v22
	v_mfma_f32_16x16x32_bf16 v[78:81], v[164:167], v[136:139], v[78:81]
	ds_read_b128 v[180:183], v229 offset:6144
	v_add_f32_e32 v23, 1.0, v23
	v_mfma_f32_16x16x32_bf16 v[82:85], v[152:155], v[140:143], v[82:85]
	ds_read_b128 v[184:187], v235 offset:0
	v_mfma_f32_16x16x32_bf16 v[86:89], v[156:159], v[140:143], v[86:89]
	ds_read_b128 v[188:191], v235 offset:2048
	v_add_f32_e32 v24, 1.0, v24
	v_mfma_f32_16x16x32_bf16 v[90:93], v[160:163], v[140:143], v[90:93]
	ds_read_b128 v[192:195], v235 offset:4096
	v_add_f32_e32 v25, 1.0, v25
	v_mfma_f32_16x16x32_bf16 v[94:97], v[164:167], v[140:143], v[94:97]
	ds_read_b128 v[196:199], v235 offset:6144
	v_rcp_f32_e32 v18, v18
	v_mfma_f32_16x16x32_bf16 v[98:101], v[152:155], v[144:147], v[98:101]
	v_mfma_f32_16x16x32_bf16 v[102:105], v[156:159], v[144:147], v[102:105]
	v_rcp_f32_e32 v19, v19
	v_mfma_f32_16x16x32_bf16 v[106:109], v[160:163], v[144:147], v[106:109]
	v_rcp_f32_e32 v20, v20
	v_mfma_f32_16x16x32_bf16 v[110:113], v[164:167], v[144:147], v[110:113]
	v_rcp_f32_e32 v21, v21
	v_mfma_f32_16x16x32_bf16 v[114:117], v[152:155], v[148:151], v[114:117]
	v_mfma_f32_16x16x32_bf16 v[118:121], v[156:159], v[148:151], v[118:121]
	v_rcp_f32_e32 v22, v22
	v_mfma_f32_16x16x32_bf16 v[122:125], v[160:163], v[148:151], v[122:125]
	v_rcp_f32_e32 v23, v23
	v_mfma_f32_16x16x32_bf16 v[126:129], v[164:167], v[148:151], v[126:129]
	v_rcp_f32_e32 v24, v24
	s_waitcnt vmcnt(7) lgkmcnt(0)
	s_barrier
	v_mfma_f32_16x16x32_bf16 v[66:69], v[184:187], v[168:171], v[66:69]
	ds_read_b128 v[136:139], v218 offset:0
	v_mfma_f32_16x16x32_bf16 v[70:73], v[188:191], v[168:171], v[70:73]
	ds_read_b128 v[140:143], v218 offset:2048
	v_mfma_f32_16x16x32_bf16 v[74:77], v[192:195], v[168:171], v[74:77]
	ds_read_b128 v[144:147], v218 offset:4096
	v_rcp_f32_e32 v25, v25
	v_mfma_f32_16x16x32_bf16 v[78:81], v[196:199], v[168:171], v[78:81]
	ds_read_b128 v[148:151], v218 offset:6144
	v_mfma_f32_16x16x32_bf16 v[82:85], v[184:187], v[172:175], v[82:85]
	ds_read_b128 v[152:155], v230 offset:0
	v_cvt_pk_bf16_f32 v18, v18, v19
	v_mfma_f32_16x16x32_bf16 v[86:89], v[188:191], v[172:175], v[86:89]
	ds_read_b128 v[156:159], v230 offset:2048
	v_mfma_f32_16x16x32_bf16 v[90:93], v[192:195], v[172:175], v[90:93]
	ds_read_b128 v[160:163], v230 offset:4096
	v_cvt_pk_bf16_f32 v19, v20, v21
	v_mfma_f32_16x16x32_bf16 v[94:97], v[196:199], v[172:175], v[94:97]
	ds_read_b128 v[164:167], v230 offset:6144
	s_add_u32 m0, s8, 0x18000
	v_mfma_f32_16x16x32_bf16 v[98:101], v[184:187], v[176:179], v[98:101]
	global_load_lds_dwordx4 v200, s[4:5]
	s_add_u32 m0, s8, 0x18400
	v_mfma_f32_16x16x32_bf16 v[102:105], v[188:191], v[176:179], v[102:105]
	global_load_lds_dwordx4 v201, s[4:5]
	v_cvt_pk_bf16_f32 v20, v22, v23
	s_add_u32 m0, s8, 0x18800
	v_mfma_f32_16x16x32_bf16 v[106:109], v[192:195], v[176:179], v[106:109]
	global_load_lds_dwordx4 v202, s[4:5]
	s_add_u32 m0, s8, 0x18c00
	v_mfma_f32_16x16x32_bf16 v[110:113], v[196:199], v[176:179], v[110:113]
	global_load_lds_dwordx4 v203, s[4:5]
	v_cvt_pk_bf16_f32 v21, v24, v25
	s_add_u32 m0, s9, 0x18000
	v_mfma_f32_16x16x32_bf16 v[114:117], v[184:187], v[180:183], v[114:117]
	global_load_lds_dwordx4 v204, s[6:7]
	s_add_u32 m0, s9, 0x18400
	v_mfma_f32_16x16x32_bf16 v[118:121], v[188:191], v[180:183], v[118:121]
	global_load_lds_dwordx4 v205, s[6:7]
	global_store_dwordx4 v240, v[18:21], s[10:11] offset:2048 sc1
	v_mfma_f32_16x16x32_bf16 v[122:125], v[192:195], v[180:183], v[122:125]
	s_add_u32 s4, s4, 0x80
	s_addc_u32 s5, s5, 0
	v_mfma_f32_16x16x32_bf16 v[126:129], v[196:199], v[180:183], v[126:129]
	s_add_u32 s6, s6, 0x80
	s_addc_u32 s7, s7, 0
	v_mul_f32_e32 v26, s12, v26
	s_waitcnt lgkmcnt(0)
	v_mfma_f32_16x16x32_bf16 v[66:69], v[152:155], v[136:139], v[66:69]
	ds_read_b128 v[168:171], v225 offset:0
	v_mfma_f32_16x16x32_bf16 v[70:73], v[156:159], v[136:139], v[70:73]
	ds_read_b128 v[172:175], v225 offset:2048
	v_mul_f32_e32 v27, s12, v27
	v_mfma_f32_16x16x32_bf16 v[74:77], v[160:163], v[136:139], v[74:77]
	ds_read_b128 v[176:179], v225 offset:4096
	v_mul_f32_e32 v28, s12, v28
	v_mfma_f32_16x16x32_bf16 v[78:81], v[164:167], v[136:139], v[78:81]
	ds_read_b128 v[180:183], v225 offset:6144
	v_mul_f32_e32 v29, s12, v29
	v_mfma_f32_16x16x32_bf16 v[82:85], v[152:155], v[140:143], v[82:85]
	ds_read_b128 v[184:187], v233 offset:0
	v_mfma_f32_16x16x32_bf16 v[86:89], v[156:159], v[140:143], v[86:89]
	ds_read_b128 v[188:191], v233 offset:2048
	v_mul_f32_e32 v30, s12, v30
	v_mfma_f32_16x16x32_bf16 v[90:93], v[160:163], v[140:143], v[90:93]
	ds_read_b128 v[192:195], v233 offset:4096
	v_mul_f32_e32 v31, s12, v31
	v_mfma_f32_16x16x32_bf16 v[94:97], v[164:167], v[140:143], v[94:97]
	ds_read_b128 v[196:199], v233 offset:6144
	v_mul_f32_e32 v32, s12, v32
	v_mfma_f32_16x16x32_bf16 v[98:101], v[152:155], v[144:147], v[98:101]
	v_mfma_f32_16x16x32_bf16 v[102:105], v[156:159], v[144:147], v[102:105]
	v_mul_f32_e32 v33, s12, v33
	v_mfma_f32_16x16x32_bf16 v[106:109], v[160:163], v[144:147], v[106:109]
	v_exp_f32_e32 v26, v26
	v_mfma_f32_16x16x32_bf16 v[110:113], v[164:167], v[144:147], v[110:113]
	v_exp_f32_e32 v27, v27
	v_mfma_f32_16x16x32_bf16 v[114:117], v[152:155], v[148:151], v[114:117]
	v_mfma_f32_16x16x32_bf16 v[118:121], v[156:159], v[148:151], v[118:121]
	v_exp_f32_e32 v28, v28
	v_mfma_f32_16x16x32_bf16 v[122:125], v[160:163], v[148:151], v[122:125]
	v_exp_f32_e32 v29, v29
	v_mfma_f32_16x16x32_bf16 v[126:129], v[164:167], v[148:151], v[126:129]
	v_exp_f32_e32 v30, v30
	s_waitcnt vmcnt(7) lgkmcnt(0)
	s_barrier
	v_mfma_f32_16x16x32_bf16 v[66:69], v[184:187], v[168:171], v[66:69]
	ds_read_b128 v[136:139], v219 offset:0
	v_mfma_f32_16x16x32_bf16 v[70:73], v[188:191], v[168:171], v[70:73]
	ds_read_b128 v[140:143], v219 offset:2048
	v_mfma_f32_16x16x32_bf16 v[74:77], v[192:195], v[168:171], v[74:77]
	ds_read_b128 v[144:147], v219 offset:4096
	v_exp_f32_e32 v31, v31
	v_mfma_f32_16x16x32_bf16 v[78:81], v[196:199], v[168:171], v[78:81]
	ds_read_b128 v[148:151], v219 offset:6144
	v_mfma_f32_16x16x32_bf16 v[82:85], v[184:187], v[172:175], v[82:85]
	ds_read_b128 v[152:155], v231 offset:0
	v_exp_f32_e32 v32, v32
	v_mfma_f32_16x16x32_bf16 v[86:89], v[188:191], v[172:175], v[86:89]
	ds_read_b128 v[156:159], v231 offset:2048
	v_mfma_f32_16x16x32_bf16 v[90:93], v[192:195], v[172:175], v[90:93]
	ds_read_b128 v[160:163], v231 offset:4096
	v_exp_f32_e32 v33, v33
	v_mfma_f32_16x16x32_bf16 v[94:97], v[196:199], v[172:175], v[94:97]
	ds_read_b128 v[164:167], v231 offset:6144
	s_mov_b32 m0, s8
	v_mfma_f32_16x16x32_bf16 v[98:101], v[184:187], v[176:179], v[98:101]
	global_load_lds_dwordx4 v200, s[4:5]
	s_add_u32 m0, s8, 0x400
	v_mfma_f32_16x16x32_bf16 v[102:105], v[188:191], v[176:179], v[102:105]
	global_load_lds_dwordx4 v201, s[4:5]
	v_add_f32_e32 v26, 1.0, v26
	s_add_u32 m0, s8, 0x800
	v_mfma_f32_16x16x32_bf16 v[106:109], v[192:195], v[176:179], v[106:109]
	global_load_lds_dwordx4 v202, s[4:5]
	s_add_u32 m0, s8, 0xc00
	v_mfma_f32_16x16x32_bf16 v[110:113], v[196:199], v[176:179], v[110:113]
	global_load_lds_dwordx4 v203, s[4:5]
	v_add_f32_e32 v27, 1.0, v27
	s_mov_b32 m0, s9
	v_mfma_f32_16x16x32_bf16 v[114:117], v[184:187], v[180:183], v[114:117]
	global_load_lds_dwordx4 v204, s[6:7]
	s_add_u32 m0, s9, 0x400
	v_mfma_f32_16x16x32_bf16 v[118:121], v[188:191], v[180:183], v[118:121]
	global_load_lds_dwordx4 v205, s[6:7]
	v_add_f32_e32 v28, 1.0, v28
	v_mfma_f32_16x16x32_bf16 v[122:125], v[192:195], v[180:183], v[122:125]
	s_add_u32 s4, s4, 0x80
	s_addc_u32 s5, s5, 0
	v_mfma_f32_16x16x32_bf16 v[126:129], v[196:199], v[180:183], v[126:129]
	s_add_u32 s6, s6, 0x80
	s_addc_u32 s7, s7, 0
	v_add_f32_e32 v29, 1.0, v29
	s_waitcnt lgkmcnt(0)
	v_mfma_f32_16x16x32_bf16 v[66:69], v[152:155], v[136:139], v[66:69]
	ds_read_b128 v[168:171], v228 offset:0
	v_mfma_f32_16x16x32_bf16 v[70:73], v[156:159], v[136:139], v[70:73]
	ds_read_b128 v[172:175], v228 offset:2048
	v_add_f32_e32 v30, 1.0, v30
	v_mfma_f32_16x16x32_bf16 v[74:77], v[160:163], v[136:139], v[74:77]
	ds_read_b128 v[176:179], v228 offset:4096
	v_add_f32_e32 v31, 1.0, v31
	v_mfma_f32_16x16x32_bf16 v[78:81], v[164:167], v[136:139], v[78:81]
	ds_read_b128 v[180:183], v228 offset:6144
	v_add_f32_e32 v32, 1.0, v32
	v_mfma_f32_16x16x32_bf16 v[82:85], v[152:155], v[140:143], v[82:85]
	ds_read_b128 v[184:187], v234 offset:0
	v_mfma_f32_16x16x32_bf16 v[86:89], v[156:159], v[140:143], v[86:89]
	ds_read_b128 v[188:191], v234 offset:2048
	v_add_f32_e32 v33, 1.0, v33
	v_mfma_f32_16x16x32_bf16 v[90:93], v[160:163], v[140:143], v[90:93]
	ds_read_b128 v[192:195], v234 offset:4096
	v_rcp_f32_e32 v26, v26
	v_mfma_f32_16x16x32_bf16 v[94:97], v[164:167], v[140:143], v[94:97]
	ds_read_b128 v[196:199], v234 offset:6144
	v_rcp_f32_e32 v27, v27
	v_mfma_f32_16x16x32_bf16 v[98:101], v[152:155], v[144:147], v[98:101]
	v_mfma_f32_16x16x32_bf16 v[102:105], v[156:159], v[144:147], v[102:105]
	v_rcp_f32_e32 v28, v28
	v_mfma_f32_16x16x32_bf16 v[106:109], v[160:163], v[144:147], v[106:109]
	v_rcp_f32_e32 v29, v29
	v_mfma_f32_16x16x32_bf16 v[110:113], v[164:167], v[144:147], v[110:113]
	v_rcp_f32_e32 v30, v30
	v_mfma_f32_16x16x32_bf16 v[114:117], v[152:155], v[148:151], v[114:117]
	v_mfma_f32_16x16x32_bf16 v[118:121], v[156:159], v[148:151], v[118:121]
	v_rcp_f32_e32 v31, v31
	v_mfma_f32_16x16x32_bf16 v[122:125], v[160:163], v[148:151], v[122:125]
	v_rcp_f32_e32 v32, v32
	v_mfma_f32_16x16x32_bf16 v[126:129], v[164:167], v[148:151], v[126:129]
	v_rcp_f32_e32 v33, v33
	s_waitcnt vmcnt(7) lgkmcnt(0)
	s_barrier
	v_mfma_f32_16x16x32_bf16 v[66:69], v[184:187], v[168:171], v[66:69]
	ds_read_b128 v[136:139], v224 offset:0
	v_mfma_f32_16x16x32_bf16 v[70:73], v[188:191], v[168:171], v[70:73]
	ds_read_b128 v[140:143], v224 offset:2048
	v_mfma_f32_16x16x32_bf16 v[74:77], v[192:195], v[168:171], v[74:77]
	ds_read_b128 v[144:147], v224 offset:4096
	v_cvt_pk_bf16_f32 v26, v26, v27
	v_mfma_f32_16x16x32_bf16 v[78:81], v[196:199], v[168:171], v[78:81]
	ds_read_b128 v[148:151], v224 offset:6144
	v_mfma_f32_16x16x32_bf16 v[82:85], v[184:187], v[172:175], v[82:85]
	ds_read_b128 v[152:155], v232 offset:0
	v_cvt_pk_bf16_f32 v27, v28, v29
	v_mfma_f32_16x16x32_bf16 v[86:89], v[188:191], v[172:175], v[86:89]
	ds_read_b128 v[156:159], v232 offset:2048
	v_mfma_f32_16x16x32_bf16 v[90:93], v[192:195], v[172:175], v[90:93]
	ds_read_b128 v[160:163], v232 offset:4096
	v_cvt_pk_bf16_f32 v28, v30, v31
	v_mfma_f32_16x16x32_bf16 v[94:97], v[196:199], v[172:175], v[94:97]
	ds_read_b128 v[164:167], v232 offset:6144
	s_add_u32 m0, s8, 0xc000
	v_mfma_f32_16x16x32_bf16 v[98:101], v[184:187], v[176:179], v[98:101]
	global_load_lds_dwordx4 v200, s[4:5]
	s_add_u32 m0, s8, 0xc400
	v_mfma_f32_16x16x32_bf16 v[102:105], v[188:191], v[176:179], v[102:105]
	global_load_lds_dwordx4 v201, s[4:5]
	v_cvt_pk_bf16_f32 v29, v32, v33
	s_add_u32 m0, s8, 0xc800
	v_mfma_f32_16x16x32_bf16 v[106:109], v[192:195], v[176:179], v[106:109]
	global_load_lds_dwordx4 v202, s[4:5]
	s_add_u32 m0, s8, 0xcc00
	v_mfma_f32_16x16x32_bf16 v[110:113], v[196:199], v[176:179], v[110:113]
	global_load_lds_dwordx4 v203, s[4:5]
	global_store_dwordx4 v240, v[26:29], s[10:11] offset:3072 sc1
	s_add_u32 m0, s9, 0xc000
	v_mfma_f32_16x16x32_bf16 v[114:117], v[184:187], v[180:183], v[114:117]
	global_load_lds_dwordx4 v204, s[6:7]
	s_add_u32 m0, s9, 0xc400
	v_mfma_f32_16x16x32_bf16 v[118:121], v[188:191], v[180:183], v[118:121]
	global_load_lds_dwordx4 v205, s[6:7]
	v_mul_f32_e32 v34, s12, v34
	v_mfma_f32_16x16x32_bf16 v[122:125], v[192:195], v[180:183], v[122:125]
	s_add_u32 s4, s4, 0x80
	s_addc_u32 s5, s5, 0
	v_mfma_f32_16x16x32_bf16 v[126:129], v[196:199], v[180:183], v[126:129]
	s_add_u32 s6, s6, 0x80
	s_addc_u32 s7, s7, 0
	v_mul_f32_e32 v35, s12, v35
	s_waitcnt lgkmcnt(0)
	v_mfma_f32_16x16x32_bf16 v[66:69], v[152:155], v[136:139], v[66:69]
	ds_read_b128 v[168:171], v229 offset:0
	v_mfma_f32_16x16x32_bf16 v[70:73], v[156:159], v[136:139], v[70:73]
	ds_read_b128 v[172:175], v229 offset:2048
	v_mul_f32_e32 v36, s12, v36
	v_mfma_f32_16x16x32_bf16 v[74:77], v[160:163], v[136:139], v[74:77]
	ds_read_b128 v[176:179], v229 offset:4096
	v_mul_f32_e32 v37, s12, v37
	v_mfma_f32_16x16x32_bf16 v[78:81], v[164:167], v[136:139], v[78:81]
	ds_read_b128 v[180:183], v229 offset:6144
	v_mul_f32_e32 v38, s12, v38
	v_mfma_f32_16x16x32_bf16 v[82:85], v[152:155], v[140:143], v[82:85]
	ds_read_b128 v[184:187], v235 offset:0
	v_mfma_f32_16x16x32_bf16 v[86:89], v[156:159], v[140:143], v[86:89]
	ds_read_b128 v[188:191], v235 offset:2048
	v_mul_f32_e32 v39, s12, v39
	v_mfma_f32_16x16x32_bf16 v[90:93], v[160:163], v[140:143], v[90:93]
	ds_read_b128 v[192:195], v235 offset:4096
	v_mul_f32_e32 v40, s12, v40
	v_mfma_f32_16x16x32_bf16 v[94:97], v[164:167], v[140:143], v[94:97]
	ds_read_b128 v[196:199], v235 offset:6144
	v_mul_f32_e32 v41, s12, v41
	v_mfma_f32_16x16x32_bf16 v[98:101], v[152:155], v[144:147], v[98:101]
	v_mfma_f32_16x16x32_bf16 v[102:105], v[156:159], v[144:147], v[102:105]
	v_exp_f32_e32 v34, v34
	v_mfma_f32_16x16x32_bf16 v[106:109], v[160:163], v[144:147], v[106:109]
	v_exp_f32_e32 v35, v35
	v_mfma_f32_16x16x32_bf16 v[110:113], v[164:167], v[144:147], v[110:113]
	v_exp_f32_e32 v36, v36
	v_mfma_f32_16x16x32_bf16 v[114:117], v[152:155], v[148:151], v[114:117]
	v_mfma_f32_16x16x32_bf16 v[118:121], v[156:159], v[148:151], v[118:121]
	v_exp_f32_e32 v37, v37
	v_mfma_f32_16x16x32_bf16 v[122:125], v[160:163], v[148:151], v[122:125]
	v_exp_f32_e32 v38, v38
	v_mfma_f32_16x16x32_bf16 v[126:129], v[164:167], v[148:151], v[126:129]
	v_exp_f32_e32 v39, v39
	s_waitcnt vmcnt(7) lgkmcnt(0)
	s_barrier
	v_mfma_f32_16x16x32_bf16 v[66:69], v[184:187], v[168:171], v[66:69]
	ds_read_b128 v[136:139], v218 offset:0
	v_mfma_f32_16x16x32_bf16 v[70:73], v[188:191], v[168:171], v[70:73]
	ds_read_b128 v[140:143], v218 offset:2048
	v_mfma_f32_16x16x32_bf16 v[74:77], v[192:195], v[168:171], v[74:77]
	ds_read_b128 v[144:147], v218 offset:4096
	v_exp_f32_e32 v40, v40
	v_mfma_f32_16x16x32_bf16 v[78:81], v[196:199], v[168:171], v[78:81]
	ds_read_b128 v[148:151], v218 offset:6144
	v_mfma_f32_16x16x32_bf16 v[82:85], v[184:187], v[172:175], v[82:85]
	ds_read_b128 v[152:155], v230 offset:0
	v_exp_f32_e32 v41, v41
	v_mfma_f32_16x16x32_bf16 v[86:89], v[188:191], v[172:175], v[86:89]
	ds_read_b128 v[156:159], v230 offset:2048
	v_mfma_f32_16x16x32_bf16 v[90:93], v[192:195], v[172:175], v[90:93]
	ds_read_b128 v[160:163], v230 offset:4096
	v_add_f32_e32 v34, 1.0, v34
	v_mfma_f32_16x16x32_bf16 v[94:97], v[196:199], v[172:175], v[94:97]
	ds_read_b128 v[164:167], v230 offset:6144
	s_add_u32 m0, s8, 0x18000
	v_mfma_f32_16x16x32_bf16 v[98:101], v[184:187], v[176:179], v[98:101]
	global_load_lds_dwordx4 v200, s[4:5]
	s_add_u32 m0, s8, 0x18400
	v_mfma_f32_16x16x32_bf16 v[102:105], v[188:191], v[176:179], v[102:105]
	global_load_lds_dwordx4 v201, s[4:5]
	v_add_f32_e32 v35, 1.0, v35
	s_add_u32 m0, s8, 0x18800
	v_mfma_f32_16x16x32_bf16 v[106:109], v[192:195], v[176:179], v[106:109]
	global_load_lds_dwordx4 v202, s[4:5]
	s_add_u32 m0, s8, 0x18c00
	v_mfma_f32_16x16x32_bf16 v[110:113], v[196:199], v[176:179], v[110:113]
	global_load_lds_dwordx4 v203, s[4:5]
	v_add_f32_e32 v36, 1.0, v36
	s_add_u32 m0, s9, 0x18000
	v_mfma_f32_16x16x32_bf16 v[114:117], v[184:187], v[180:183], v[114:117]
	global_load_lds_dwordx4 v204, s[6:7]
	s_add_u32 m0, s9, 0x18400
	v_mfma_f32_16x16x32_bf16 v[118:121], v[188:191], v[180:183], v[118:121]
	global_load_lds_dwordx4 v205, s[6:7]
	v_add_f32_e32 v37, 1.0, v37
	v_mfma_f32_16x16x32_bf16 v[122:125], v[192:195], v[180:183], v[122:125]
	s_add_u32 s4, s4, 0x80
	s_addc_u32 s5, s5, 0
	v_mfma_f32_16x16x32_bf16 v[126:129], v[196:199], v[180:183], v[126:129]
	s_add_u32 s6, s6, 0x80
	s_addc_u32 s7, s7, 0
	v_add_f32_e32 v38, 1.0, v38
	s_waitcnt lgkmcnt(0)
	v_mfma_f32_16x16x32_bf16 v[66:69], v[152:155], v[136:139], v[66:69]
	ds_read_b128 v[168:171], v225 offset:0
	v_mfma_f32_16x16x32_bf16 v[70:73], v[156:159], v[136:139], v[70:73]
	ds_read_b128 v[172:175], v225 offset:2048
	v_add_f32_e32 v39, 1.0, v39
	v_mfma_f32_16x16x32_bf16 v[74:77], v[160:163], v[136:139], v[74:77]
	ds_read_b128 v[176:179], v225 offset:4096
	v_add_f32_e32 v40, 1.0, v40
	v_mfma_f32_16x16x32_bf16 v[78:81], v[164:167], v[136:139], v[78:81]
	ds_read_b128 v[180:183], v225 offset:6144
	v_add_f32_e32 v41, 1.0, v41
	v_mfma_f32_16x16x32_bf16 v[82:85], v[152:155], v[140:143], v[82:85]
	ds_read_b128 v[184:187], v233 offset:0
	v_mfma_f32_16x16x32_bf16 v[86:89], v[156:159], v[140:143], v[86:89]
	ds_read_b128 v[188:191], v233 offset:2048
	v_rcp_f32_e32 v34, v34
	v_mfma_f32_16x16x32_bf16 v[90:93], v[160:163], v[140:143], v[90:93]
	ds_read_b128 v[192:195], v233 offset:4096
	v_rcp_f32_e32 v35, v35
	v_mfma_f32_16x16x32_bf16 v[94:97], v[164:167], v[140:143], v[94:97]
	ds_read_b128 v[196:199], v233 offset:6144
	v_rcp_f32_e32 v36, v36
	v_mfma_f32_16x16x32_bf16 v[98:101], v[152:155], v[144:147], v[98:101]
	v_mfma_f32_16x16x32_bf16 v[102:105], v[156:159], v[144:147], v[102:105]
	v_rcp_f32_e32 v37, v37
	v_mfma_f32_16x16x32_bf16 v[106:109], v[160:163], v[144:147], v[106:109]
	v_rcp_f32_e32 v38, v38
	v_mfma_f32_16x16x32_bf16 v[110:113], v[164:167], v[144:147], v[110:113]
	v_rcp_f32_e32 v39, v39
	v_mfma_f32_16x16x32_bf16 v[114:117], v[152:155], v[148:151], v[114:117]
	v_mfma_f32_16x16x32_bf16 v[118:121], v[156:159], v[148:151], v[118:121]
	v_rcp_f32_e32 v40, v40
	v_mfma_f32_16x16x32_bf16 v[122:125], v[160:163], v[148:151], v[122:125]
	v_rcp_f32_e32 v41, v41
	v_mfma_f32_16x16x32_bf16 v[126:129], v[164:167], v[148:151], v[126:129]
	v_cvt_pk_bf16_f32 v34, v34, v35
	s_waitcnt vmcnt(6) lgkmcnt(0)
	s_barrier
	v_mfma_f32_16x16x32_bf16 v[66:69], v[184:187], v[168:171], v[66:69]
	ds_read_b128 v[136:139], v219 offset:0
	v_mfma_f32_16x16x32_bf16 v[70:73], v[188:191], v[168:171], v[70:73]
	ds_read_b128 v[140:143], v219 offset:2048
	v_mfma_f32_16x16x32_bf16 v[74:77], v[192:195], v[168:171], v[74:77]
	ds_read_b128 v[144:147], v219 offset:4096
	v_cvt_pk_bf16_f32 v35, v36, v37
	v_mfma_f32_16x16x32_bf16 v[78:81], v[196:199], v[168:171], v[78:81]
	ds_read_b128 v[148:151], v219 offset:6144
	v_mfma_f32_16x16x32_bf16 v[82:85], v[184:187], v[172:175], v[82:85]
	ds_read_b128 v[152:155], v231 offset:0
	v_cvt_pk_bf16_f32 v36, v38, v39
	v_mfma_f32_16x16x32_bf16 v[86:89], v[188:191], v[172:175], v[86:89]
	ds_read_b128 v[156:159], v231 offset:2048
	v_mfma_f32_16x16x32_bf16 v[90:93], v[192:195], v[172:175], v[90:93]
	ds_read_b128 v[160:163], v231 offset:4096
	v_cvt_pk_bf16_f32 v37, v40, v41
	v_mfma_f32_16x16x32_bf16 v[94:97], v[196:199], v[172:175], v[94:97]
	ds_read_b128 v[164:167], v231 offset:6144
	s_mov_b32 m0, s8
	v_mfma_f32_16x16x32_bf16 v[98:101], v[184:187], v[176:179], v[98:101]
	global_load_lds_dwordx4 v200, s[4:5]
	s_add_u32 m0, s8, 0x400
	v_mfma_f32_16x16x32_bf16 v[102:105], v[188:191], v[176:179], v[102:105]
	global_load_lds_dwordx4 v201, s[4:5]
	global_store_dwordx4 v241, v[34:37], s[10:11] offset:0 sc1
	s_add_u32 m0, s8, 0x800
	v_mfma_f32_16x16x32_bf16 v[106:109], v[192:195], v[176:179], v[106:109]
	global_load_lds_dwordx4 v202, s[4:5]
	s_add_u32 m0, s8, 0xc00
	v_mfma_f32_16x16x32_bf16 v[110:113], v[196:199], v[176:179], v[110:113]
	global_load_lds_dwordx4 v203, s[4:5]
	v_mul_f32_e32 v42, s12, v42
	s_mov_b32 m0, s9
	v_mfma_f32_16x16x32_bf16 v[114:117], v[184:187], v[180:183], v[114:117]
	global_load_lds_dwordx4 v204, s[6:7]
	s_add_u32 m0, s9, 0x400
	v_mfma_f32_16x16x32_bf16 v[118:121], v[188:191], v[180:183], v[118:121]
	global_load_lds_dwordx4 v205, s[6:7]
	v_mul_f32_e32 v43, s12, v43
	v_mfma_f32_16x16x32_bf16 v[122:125], v[192:195], v[180:183], v[122:125]
	s_add_u32 s4, s4, 0x80
	s_addc_u32 s5, s5, 0
	v_mfma_f32_16x16x32_bf16 v[126:129], v[196:199], v[180:183], v[126:129]
	s_add_u32 s6, s6, 0x80
	s_addc_u32 s7, s7, 0
	v_mul_f32_e32 v44, s12, v44
	s_waitcnt lgkmcnt(0)
	v_mfma_f32_16x16x32_bf16 v[66:69], v[152:155], v[136:139], v[66:69]
	ds_read_b128 v[168:171], v228 offset:0
	v_mfma_f32_16x16x32_bf16 v[70:73], v[156:159], v[136:139], v[70:73]
	ds_read_b128 v[172:175], v228 offset:2048
	v_mul_f32_e32 v45, s12, v45
	v_mfma_f32_16x16x32_bf16 v[74:77], v[160:163], v[136:139], v[74:77]
	ds_read_b128 v[176:179], v228 offset:4096
	v_mul_f32_e32 v46, s12, v46
	v_mfma_f32_16x16x32_bf16 v[78:81], v[164:167], v[136:139], v[78:81]
	ds_read_b128 v[180:183], v228 offset:6144
	v_mul_f32_e32 v47, s12, v47
	v_mfma_f32_16x16x32_bf16 v[82:85], v[152:155], v[140:143], v[82:85]
	ds_read_b128 v[184:187], v234 offset:0
	v_mfma_f32_16x16x32_bf16 v[86:89], v[156:159], v[140:143], v[86:89]
	ds_read_b128 v[188:191], v234 offset:2048
	v_mul_f32_e32 v48, s12, v48
	v_mfma_f32_16x16x32_bf16 v[90:93], v[160:163], v[140:143], v[90:93]
	ds_read_b128 v[192:195], v234 offset:4096
	v_mul_f32_e32 v49, s12, v49
	v_mfma_f32_16x16x32_bf16 v[94:97], v[164:167], v[140:143], v[94:97]
	ds_read_b128 v[196:199], v234 offset:6144
	v_exp_f32_e32 v42, v42
	v_mfma_f32_16x16x32_bf16 v[98:101], v[152:155], v[144:147], v[98:101]
	v_mfma_f32_16x16x32_bf16 v[102:105], v[156:159], v[144:147], v[102:105]
	v_exp_f32_e32 v43, v43
	v_mfma_f32_16x16x32_bf16 v[106:109], v[160:163], v[144:147], v[106:109]
	v_exp_f32_e32 v44, v44
	v_mfma_f32_16x16x32_bf16 v[110:113], v[164:167], v[144:147], v[110:113]
	v_exp_f32_e32 v45, v45
	v_mfma_f32_16x16x32_bf16 v[114:117], v[152:155], v[148:151], v[114:117]
	v_mfma_f32_16x16x32_bf16 v[118:121], v[156:159], v[148:151], v[118:121]
	v_exp_f32_e32 v46, v46
	v_mfma_f32_16x16x32_bf16 v[122:125], v[160:163], v[148:151], v[122:125]
	v_exp_f32_e32 v47, v47
	v_mfma_f32_16x16x32_bf16 v[126:129], v[164:167], v[148:151], v[126:129]
	v_exp_f32_e32 v48, v48
	s_waitcnt vmcnt(7) lgkmcnt(0)
	s_barrier
	v_mfma_f32_16x16x32_bf16 v[66:69], v[184:187], v[168:171], v[66:69]
	ds_read_b128 v[136:139], v224 offset:0
	v_mfma_f32_16x16x32_bf16 v[70:73], v[188:191], v[168:171], v[70:73]
	ds_read_b128 v[140:143], v224 offset:2048
	v_mfma_f32_16x16x32_bf16 v[74:77], v[192:195], v[168:171], v[74:77]
	ds_read_b128 v[144:147], v224 offset:4096
	v_exp_f32_e32 v49, v49
	v_mfma_f32_16x16x32_bf16 v[78:81], v[196:199], v[168:171], v[78:81]
	ds_read_b128 v[148:151], v224 offset:6144
	v_mfma_f32_16x16x32_bf16 v[82:85], v[184:187], v[172:175], v[82:85]
	ds_read_b128 v[152:155], v232 offset:0
	v_add_f32_e32 v42, 1.0, v42
	v_mfma_f32_16x16x32_bf16 v[86:89], v[188:191], v[172:175], v[86:89]
	ds_read_b128 v[156:159], v232 offset:2048
	v_mfma_f32_16x16x32_bf16 v[90:93], v[192:195], v[172:175], v[90:93]
	ds_read_b128 v[160:163], v232 offset:4096
	v_add_f32_e32 v43, 1.0, v43
	v_mfma_f32_16x16x32_bf16 v[94:97], v[196:199], v[172:175], v[94:97]
	ds_read_b128 v[164:167], v232 offset:6144
	s_add_u32 m0, s8, 0xc000
	v_mfma_f32_16x16x32_bf16 v[98:101], v[184:187], v[176:179], v[98:101]
	global_load_lds_dwordx4 v200, s[4:5]
	s_add_u32 m0, s8, 0xc400
	v_mfma_f32_16x16x32_bf16 v[102:105], v[188:191], v[176:179], v[102:105]
	global_load_lds_dwordx4 v201, s[4:5]
	v_add_f32_e32 v44, 1.0, v44
	s_add_u32 m0, s8, 0xc800
	v_mfma_f32_16x16x32_bf16 v[106:109], v[192:195], v[176:179], v[106:109]
	global_load_lds_dwordx4 v202, s[4:5]
	s_add_u32 m0, s8, 0xcc00
	v_mfma_f32_16x16x32_bf16 v[110:113], v[196:199], v[176:179], v[110:113]
	global_load_lds_dwordx4 v203, s[4:5]
	v_add_f32_e32 v45, 1.0, v45
	s_add_u32 m0, s9, 0xc000
	v_mfma_f32_16x16x32_bf16 v[114:117], v[184:187], v[180:183], v[114:117]
	global_load_lds_dwordx4 v204, s[6:7]
	s_add_u32 m0, s9, 0xc400
	v_mfma_f32_16x16x32_bf16 v[118:121], v[188:191], v[180:183], v[118:121]
	global_load_lds_dwordx4 v205, s[6:7]
	v_add_f32_e32 v46, 1.0, v46
	v_mfma_f32_16x16x32_bf16 v[122:125], v[192:195], v[180:183], v[122:125]
	s_add_u32 s4, s4, 0x80
	s_addc_u32 s5, s5, 0
	v_mfma_f32_16x16x32_bf16 v[126:129], v[196:199], v[180:183], v[126:129]
	s_add_u32 s6, s6, 0x80
	s_addc_u32 s7, s7, 0
	v_add_f32_e32 v47, 1.0, v47
	s_waitcnt lgkmcnt(0)
	v_mfma_f32_16x16x32_bf16 v[66:69], v[152:155], v[136:139], v[66:69]
	ds_read_b128 v[168:171], v229 offset:0
	v_mfma_f32_16x16x32_bf16 v[70:73], v[156:159], v[136:139], v[70:73]
	ds_read_b128 v[172:175], v229 offset:2048
	v_add_f32_e32 v48, 1.0, v48
	v_mfma_f32_16x16x32_bf16 v[74:77], v[160:163], v[136:139], v[74:77]
	ds_read_b128 v[176:179], v229 offset:4096
	v_add_f32_e32 v49, 1.0, v49
	v_mfma_f32_16x16x32_bf16 v[78:81], v[164:167], v[136:139], v[78:81]
	ds_read_b128 v[180:183], v229 offset:6144
	v_rcp_f32_e32 v42, v42
	v_mfma_f32_16x16x32_bf16 v[82:85], v[152:155], v[140:143], v[82:85]
	ds_read_b128 v[184:187], v235 offset:0
	v_mfma_f32_16x16x32_bf16 v[86:89], v[156:159], v[140:143], v[86:89]
	ds_read_b128 v[188:191], v235 offset:2048
	v_rcp_f32_e32 v43, v43
	v_mfma_f32_16x16x32_bf16 v[90:93], v[160:163], v[140:143], v[90:93]
	ds_read_b128 v[192:195], v235 offset:4096
	v_rcp_f32_e32 v44, v44
	v_mfma_f32_16x16x32_bf16 v[94:97], v[164:167], v[140:143], v[94:97]
	ds_read_b128 v[196:199], v235 offset:6144
	v_rcp_f32_e32 v45, v45
	v_mfma_f32_16x16x32_bf16 v[98:101], v[152:155], v[144:147], v[98:101]
	v_mfma_f32_16x16x32_bf16 v[102:105], v[156:159], v[144:147], v[102:105]
	v_rcp_f32_e32 v46, v46
	v_mfma_f32_16x16x32_bf16 v[106:109], v[160:163], v[144:147], v[106:109]
	v_rcp_f32_e32 v47, v47
	v_mfma_f32_16x16x32_bf16 v[110:113], v[164:167], v[144:147], v[110:113]
	v_rcp_f32_e32 v48, v48
	v_mfma_f32_16x16x32_bf16 v[114:117], v[152:155], v[148:151], v[114:117]
	v_mfma_f32_16x16x32_bf16 v[118:121], v[156:159], v[148:151], v[118:121]
	v_rcp_f32_e32 v49, v49
	v_mfma_f32_16x16x32_bf16 v[122:125], v[160:163], v[148:151], v[122:125]
	v_cvt_pk_bf16_f32 v42, v42, v43
	v_mfma_f32_16x16x32_bf16 v[126:129], v[164:167], v[148:151], v[126:129]
	v_cvt_pk_bf16_f32 v43, v44, v45
	s_waitcnt vmcnt(6) lgkmcnt(0)
	s_barrier
	v_mfma_f32_16x16x32_bf16 v[66:69], v[184:187], v[168:171], v[66:69]
	ds_read_b128 v[136:139], v218 offset:0
	v_mfma_f32_16x16x32_bf16 v[70:73], v[188:191], v[168:171], v[70:73]
	ds_read_b128 v[140:143], v218 offset:2048
	v_mfma_f32_16x16x32_bf16 v[74:77], v[192:195], v[168:171], v[74:77]
	ds_read_b128 v[144:147], v218 offset:4096
	v_cvt_pk_bf16_f32 v44, v46, v47
	v_mfma_f32_16x16x32_bf16 v[78:81], v[196:199], v[168:171], v[78:81]
	ds_read_b128 v[148:151], v218 offset:6144
	v_mfma_f32_16x16x32_bf16 v[82:85], v[184:187], v[172:175], v[82:85]
	ds_read_b128 v[152:155], v230 offset:0
	v_cvt_pk_bf16_f32 v45, v48, v49
	v_mfma_f32_16x16x32_bf16 v[86:89], v[188:191], v[172:175], v[86:89]
	ds_read_b128 v[156:159], v230 offset:2048
	v_mfma_f32_16x16x32_bf16 v[90:93], v[192:195], v[172:175], v[90:93]
	ds_read_b128 v[160:163], v230 offset:4096
	global_store_dwordx4 v241, v[42:45], s[10:11] offset:1024 sc1
	v_mfma_f32_16x16x32_bf16 v[94:97], v[196:199], v[172:175], v[94:97]
	ds_read_b128 v[164:167], v230 offset:6144
	s_add_u32 m0, s8, 0x18000
	v_mfma_f32_16x16x32_bf16 v[98:101], v[184:187], v[176:179], v[98:101]
	global_load_lds_dwordx4 v200, s[4:5]
	s_add_u32 m0, s8, 0x18400
	v_mfma_f32_16x16x32_bf16 v[102:105], v[188:191], v[176:179], v[102:105]
	global_load_lds_dwordx4 v201, s[4:5]
	v_mul_f32_e32 v50, s12, v50
	s_add_u32 m0, s8, 0x18800
	v_mfma_f32_16x16x32_bf16 v[106:109], v[192:195], v[176:179], v[106:109]
	global_load_lds_dwordx4 v202, s[4:5]
	s_add_u32 m0, s8, 0x18c00
	v_mfma_f32_16x16x32_bf16 v[110:113], v[196:199], v[176:179], v[110:113]
	global_load_lds_dwordx4 v203, s[4:5]
	v_mul_f32_e32 v51, s12, v51
	s_add_u32 m0, s9, 0x18000
	v_mfma_f32_16x16x32_bf16 v[114:117], v[184:187], v[180:183], v[114:117]
	global_load_lds_dwordx4 v204, s[6:7]
	s_add_u32 m0, s9, 0x18400
	v_mfma_f32_16x16x32_bf16 v[118:121], v[188:191], v[180:183], v[118:121]
	global_load_lds_dwordx4 v205, s[6:7]
	v_mul_f32_e32 v52, s12, v52
	v_mfma_f32_16x16x32_bf16 v[122:125], v[192:195], v[180:183], v[122:125]
	s_add_u32 s4, s4, 0x80
	s_addc_u32 s5, s5, 0
	v_mfma_f32_16x16x32_bf16 v[126:129], v[196:199], v[180:183], v[126:129]
	s_add_u32 s6, s6, 0x80
	s_addc_u32 s7, s7, 0
	v_mul_f32_e32 v53, s12, v53
	s_waitcnt lgkmcnt(0)
	v_mfma_f32_16x16x32_bf16 v[66:69], v[152:155], v[136:139], v[66:69]
	ds_read_b128 v[168:171], v225 offset:0
	v_mfma_f32_16x16x32_bf16 v[70:73], v[156:159], v[136:139], v[70:73]
	ds_read_b128 v[172:175], v225 offset:2048
	v_mul_f32_e32 v54, s12, v54
	v_mfma_f32_16x16x32_bf16 v[74:77], v[160:163], v[136:139], v[74:77]
	ds_read_b128 v[176:179], v225 offset:4096
	v_mul_f32_e32 v55, s12, v55
	v_mfma_f32_16x16x32_bf16 v[78:81], v[164:167], v[136:139], v[78:81]
	ds_read_b128 v[180:183], v225 offset:6144
	v_mul_f32_e32 v56, s12, v56
	v_mfma_f32_16x16x32_bf16 v[82:85], v[152:155], v[140:143], v[82:85]
	ds_read_b128 v[184:187], v233 offset:0
	v_mfma_f32_16x16x32_bf16 v[86:89], v[156:159], v[140:143], v[86:89]
	ds_read_b128 v[188:191], v233 offset:2048
	v_mul_f32_e32 v57, s12, v57
	v_mfma_f32_16x16x32_bf16 v[90:93], v[160:163], v[140:143], v[90:93]
	ds_read_b128 v[192:195], v233 offset:4096
	v_exp_f32_e32 v50, v50
	v_mfma_f32_16x16x32_bf16 v[94:97], v[164:167], v[140:143], v[94:97]
	ds_read_b128 v[196:199], v233 offset:6144
	v_exp_f32_e32 v51, v51
	v_mfma_f32_16x16x32_bf16 v[98:101], v[152:155], v[144:147], v[98:101]
	v_mfma_f32_16x16x32_bf16 v[102:105], v[156:159], v[144:147], v[102:105]
	v_exp_f32_e32 v52, v52
	v_mfma_f32_16x16x32_bf16 v[106:109], v[160:163], v[144:147], v[106:109]
	v_exp_f32_e32 v53, v53
	v_mfma_f32_16x16x32_bf16 v[110:113], v[164:167], v[144:147], v[110:113]
	v_exp_f32_e32 v54, v54
	v_mfma_f32_16x16x32_bf16 v[114:117], v[152:155], v[148:151], v[114:117]
	v_mfma_f32_16x16x32_bf16 v[118:121], v[156:159], v[148:151], v[118:121]
	v_exp_f32_e32 v55, v55
	v_mfma_f32_16x16x32_bf16 v[122:125], v[160:163], v[148:151], v[122:125]
	v_exp_f32_e32 v56, v56
	v_mfma_f32_16x16x32_bf16 v[126:129], v[164:167], v[148:151], v[126:129]
	v_exp_f32_e32 v57, v57
	s_waitcnt vmcnt(7) lgkmcnt(0)
	s_barrier
	v_mfma_f32_16x16x32_bf16 v[66:69], v[184:187], v[168:171], v[66:69]
	ds_read_b128 v[136:139], v219 offset:0
	v_mfma_f32_16x16x32_bf16 v[70:73], v[188:191], v[168:171], v[70:73]
	ds_read_b128 v[140:143], v219 offset:2048
	v_mfma_f32_16x16x32_bf16 v[74:77], v[192:195], v[168:171], v[74:77]
	ds_read_b128 v[144:147], v219 offset:4096
	v_add_f32_e32 v50, 1.0, v50
	v_mfma_f32_16x16x32_bf16 v[78:81], v[196:199], v[168:171], v[78:81]
	ds_read_b128 v[148:151], v219 offset:6144
	v_mfma_f32_16x16x32_bf16 v[82:85], v[184:187], v[172:175], v[82:85]
	ds_read_b128 v[152:155], v231 offset:0
	v_add_f32_e32 v51, 1.0, v51
	v_mfma_f32_16x16x32_bf16 v[86:89], v[188:191], v[172:175], v[86:89]
	ds_read_b128 v[156:159], v231 offset:2048
	v_mfma_f32_16x16x32_bf16 v[90:93], v[192:195], v[172:175], v[90:93]
	ds_read_b128 v[160:163], v231 offset:4096
	v_add_f32_e32 v52, 1.0, v52
	v_mfma_f32_16x16x32_bf16 v[94:97], v[196:199], v[172:175], v[94:97]
	ds_read_b128 v[164:167], v231 offset:6144
	s_mov_b32 m0, s8
	v_mfma_f32_16x16x32_bf16 v[98:101], v[184:187], v[176:179], v[98:101]
	global_load_lds_dwordx4 v200, s[4:5]
	s_add_u32 m0, s8, 0x400
	v_mfma_f32_16x16x32_bf16 v[102:105], v[188:191], v[176:179], v[102:105]
	global_load_lds_dwordx4 v201, s[4:5]
	v_add_f32_e32 v53, 1.0, v53
	s_add_u32 m0, s8, 0x800
	v_mfma_f32_16x16x32_bf16 v[106:109], v[192:195], v[176:179], v[106:109]
	global_load_lds_dwordx4 v202, s[4:5]
	s_add_u32 m0, s8, 0xc00
	v_mfma_f32_16x16x32_bf16 v[110:113], v[196:199], v[176:179], v[110:113]
	global_load_lds_dwordx4 v203, s[4:5]
	v_add_f32_e32 v54, 1.0, v54
	s_mov_b32 m0, s9
	v_mfma_f32_16x16x32_bf16 v[114:117], v[184:187], v[180:183], v[114:117]
	global_load_lds_dwordx4 v204, s[6:7]
	s_add_u32 m0, s9, 0x400
	v_mfma_f32_16x16x32_bf16 v[118:121], v[188:191], v[180:183], v[118:121]
	global_load_lds_dwordx4 v205, s[6:7]
	v_add_f32_e32 v55, 1.0, v55
	v_mfma_f32_16x16x32_bf16 v[122:125], v[192:195], v[180:183], v[122:125]
	s_sub_u32 s4, s4, 0x780
	s_subb_u32 s5, s5, 0
	v_mfma_f32_16x16x32_bf16 v[126:129], v[196:199], v[180:183], v[126:129]
	s_add_u32 s6, s6, 0x3f880
	s_addc_u32 s7, s7, 0
	v_add_f32_e32 v56, 1.0, v56
	s_waitcnt lgkmcnt(0)
	v_mfma_f32_16x16x32_bf16 v[66:69], v[152:155], v[136:139], v[66:69]
	ds_read_b128 v[168:171], v228 offset:0
	v_mfma_f32_16x16x32_bf16 v[70:73], v[156:159], v[136:139], v[70:73]
	ds_read_b128 v[172:175], v228 offset:2048
	v_add_f32_e32 v57, 1.0, v57
	v_mfma_f32_16x16x32_bf16 v[74:77], v[160:163], v[136:139], v[74:77]
	ds_read_b128 v[176:179], v228 offset:4096
	v_rcp_f32_e32 v50, v50
	v_mfma_f32_16x16x32_bf16 v[78:81], v[164:167], v[136:139], v[78:81]
	ds_read_b128 v[180:183], v228 offset:6144
	v_rcp_f32_e32 v51, v51
	v_mfma_f32_16x16x32_bf16 v[82:85], v[152:155], v[140:143], v[82:85]
	ds_read_b128 v[184:187], v234 offset:0
	v_mfma_f32_16x16x32_bf16 v[86:89], v[156:159], v[140:143], v[86:89]
	ds_read_b128 v[188:191], v234 offset:2048
	v_rcp_f32_e32 v52, v52
	v_mfma_f32_16x16x32_bf16 v[90:93], v[160:163], v[140:143], v[90:93]
	ds_read_b128 v[192:195], v234 offset:4096
	v_rcp_f32_e32 v53, v53
	v_mfma_f32_16x16x32_bf16 v[94:97], v[164:167], v[140:143], v[94:97]
	ds_read_b128 v[196:199], v234 offset:6144
	v_rcp_f32_e32 v54, v54
	v_mfma_f32_16x16x32_bf16 v[98:101], v[152:155], v[144:147], v[98:101]
	v_mfma_f32_16x16x32_bf16 v[102:105], v[156:159], v[144:147], v[102:105]
	v_rcp_f32_e32 v55, v55
	v_mfma_f32_16x16x32_bf16 v[106:109], v[160:163], v[144:147], v[106:109]
	v_rcp_f32_e32 v56, v56
	v_mfma_f32_16x16x32_bf16 v[110:113], v[164:167], v[144:147], v[110:113]
	v_rcp_f32_e32 v57, v57
	v_mfma_f32_16x16x32_bf16 v[114:117], v[152:155], v[148:151], v[114:117]
	v_mfma_f32_16x16x32_bf16 v[118:121], v[156:159], v[148:151], v[118:121]
	v_cvt_pk_bf16_f32 v50, v50, v51
	v_mfma_f32_16x16x32_bf16 v[122:125], v[160:163], v[148:151], v[122:125]
	v_cvt_pk_bf16_f32 v51, v52, v53
	v_mfma_f32_16x16x32_bf16 v[126:129], v[164:167], v[148:151], v[126:129]
	v_cvt_pk_bf16_f32 v52, v54, v55
	s_waitcnt vmcnt(6) lgkmcnt(0)
	s_barrier
	v_mfma_f32_16x16x32_bf16 v[66:69], v[184:187], v[168:171], v[66:69]
	ds_read_b128 v[136:139], v224 offset:0
	v_mfma_f32_16x16x32_bf16 v[70:73], v[188:191], v[168:171], v[70:73]
	ds_read_b128 v[140:143], v224 offset:2048
	v_mfma_f32_16x16x32_bf16 v[74:77], v[192:195], v[168:171], v[74:77]
	ds_read_b128 v[144:147], v224 offset:4096
	v_cvt_pk_bf16_f32 v53, v56, v57
	v_mfma_f32_16x16x32_bf16 v[78:81], v[196:199], v[168:171], v[78:81]
	ds_read_b128 v[148:151], v224 offset:6144
	v_mfma_f32_16x16x32_bf16 v[82:85], v[184:187], v[172:175], v[82:85]
	ds_read_b128 v[152:155], v232 offset:0
	global_store_dwordx4 v241, v[50:53], s[10:11] offset:2048 sc1
	v_mfma_f32_16x16x32_bf16 v[86:89], v[188:191], v[172:175], v[86:89]
	ds_read_b128 v[156:159], v232 offset:2048
	v_mfma_f32_16x16x32_bf16 v[90:93], v[192:195], v[172:175], v[90:93]
	ds_read_b128 v[160:163], v232 offset:4096
	v_mul_f32_e32 v58, s12, v58
	v_mfma_f32_16x16x32_bf16 v[94:97], v[196:199], v[172:175], v[94:97]
	ds_read_b128 v[164:167], v232 offset:6144
	v_mfma_f32_16x16x32_bf16 v[98:101], v[184:187], v[176:179], v[98:101]
	v_mfma_f32_16x16x32_bf16 v[102:105], v[188:191], v[176:179], v[102:105]
	v_mul_f32_e32 v59, s12, v59
	v_mfma_f32_16x16x32_bf16 v[106:109], v[192:195], v[176:179], v[106:109]
	v_mfma_f32_16x16x32_bf16 v[110:113], v[196:199], v[176:179], v[110:113]
	v_mul_f32_e32 v60, s12, v60
	v_mfma_f32_16x16x32_bf16 v[114:117], v[184:187], v[180:183], v[114:117]
	v_mfma_f32_16x16x32_bf16 v[118:121], v[188:191], v[180:183], v[118:121]
	v_mul_f32_e32 v61, s12, v61
	v_mfma_f32_16x16x32_bf16 v[122:125], v[192:195], v[180:183], v[122:125]
	v_mfma_f32_16x16x32_bf16 v[126:129], v[196:199], v[180:183], v[126:129]
	v_mul_f32_e32 v62, s12, v62
	s_waitcnt lgkmcnt(0)
	v_mfma_f32_16x16x32_bf16 v[66:69], v[152:155], v[136:139], v[66:69]
	ds_read_b128 v[168:171], v229 offset:0
	v_mfma_f32_16x16x32_bf16 v[70:73], v[156:159], v[136:139], v[70:73]
	ds_read_b128 v[172:175], v229 offset:2048
	v_mul_f32_e32 v63, s12, v63
	v_mfma_f32_16x16x32_bf16 v[74:77], v[160:163], v[136:139], v[74:77]
	ds_read_b128 v[176:179], v229 offset:4096
	v_mul_f32_e32 v64, s12, v64
	v_mfma_f32_16x16x32_bf16 v[78:81], v[164:167], v[136:139], v[78:81]
	ds_read_b128 v[180:183], v229 offset:6144
	v_mul_f32_e32 v65, s12, v65
	v_mfma_f32_16x16x32_bf16 v[82:85], v[152:155], v[140:143], v[82:85]
	ds_read_b128 v[184:187], v235 offset:0
	v_mfma_f32_16x16x32_bf16 v[86:89], v[156:159], v[140:143], v[86:89]
	ds_read_b128 v[188:191], v235 offset:2048
	v_exp_f32_e32 v58, v58
	v_mfma_f32_16x16x32_bf16 v[90:93], v[160:163], v[140:143], v[90:93]
	ds_read_b128 v[192:195], v235 offset:4096
	v_exp_f32_e32 v59, v59
	v_mfma_f32_16x16x32_bf16 v[94:97], v[164:167], v[140:143], v[94:97]
	ds_read_b128 v[196:199], v235 offset:6144
	v_exp_f32_e32 v60, v60
	v_mfma_f32_16x16x32_bf16 v[98:101], v[152:155], v[144:147], v[98:101]
	v_mfma_f32_16x16x32_bf16 v[102:105], v[156:159], v[144:147], v[102:105]
	v_exp_f32_e32 v61, v61
	v_mfma_f32_16x16x32_bf16 v[106:109], v[160:163], v[144:147], v[106:109]
	v_exp_f32_e32 v62, v62
	v_mfma_f32_16x16x32_bf16 v[110:113], v[164:167], v[144:147], v[110:113]
	v_exp_f32_e32 v63, v63
	v_mfma_f32_16x16x32_bf16 v[114:117], v[152:155], v[148:151], v[114:117]
	v_mfma_f32_16x16x32_bf16 v[118:121], v[156:159], v[148:151], v[118:121]
	v_exp_f32_e32 v64, v64
	v_mfma_f32_16x16x32_bf16 v[122:125], v[160:163], v[148:151], v[122:125]
	v_exp_f32_e32 v65, v65
	v_mfma_f32_16x16x32_bf16 v[126:129], v[164:167], v[148:151], v[126:129]
	v_add_f32_e32 v58, 1.0, v58
	s_waitcnt vmcnt(1) lgkmcnt(0)
	s_barrier
	v_mfma_f32_16x16x32_bf16 v[66:69], v[184:187], v[168:171], v[66:69]
	ds_read_b128 v[136:139], v218 offset:0
	v_mfma_f32_16x16x32_bf16 v[70:73], v[188:191], v[168:171], v[70:73]
	ds_read_b128 v[140:143], v218 offset:2048
	v_mfma_f32_16x16x32_bf16 v[74:77], v[192:195], v[168:171], v[74:77]
	ds_read_b128 v[144:147], v218 offset:4096
	v_add_f32_e32 v59, 1.0, v59
	v_mfma_f32_16x16x32_bf16 v[78:81], v[196:199], v[168:171], v[78:81]
	ds_read_b128 v[148:151], v218 offset:6144
	v_mfma_f32_16x16x32_bf16 v[82:85], v[184:187], v[172:175], v[82:85]
	ds_read_b128 v[152:155], v230 offset:0
	v_add_f32_e32 v60, 1.0, v60
	v_mfma_f32_16x16x32_bf16 v[86:89], v[188:191], v[172:175], v[86:89]
	ds_read_b128 v[156:159], v230 offset:2048
	v_mfma_f32_16x16x32_bf16 v[90:93], v[192:195], v[172:175], v[90:93]
	ds_read_b128 v[160:163], v230 offset:4096
	v_add_f32_e32 v61, 1.0, v61
	v_mfma_f32_16x16x32_bf16 v[94:97], v[196:199], v[172:175], v[94:97]
	ds_read_b128 v[164:167], v230 offset:6144
	v_mfma_f32_16x16x32_bf16 v[98:101], v[184:187], v[176:179], v[98:101]
	v_mfma_f32_16x16x32_bf16 v[102:105], v[188:191], v[176:179], v[102:105]
	v_add_f32_e32 v62, 1.0, v62
	v_mfma_f32_16x16x32_bf16 v[106:109], v[192:195], v[176:179], v[106:109]
	v_mfma_f32_16x16x32_bf16 v[110:113], v[196:199], v[176:179], v[110:113]
	v_add_f32_e32 v63, 1.0, v63
	v_mfma_f32_16x16x32_bf16 v[114:117], v[184:187], v[180:183], v[114:117]
	v_mfma_f32_16x16x32_bf16 v[118:121], v[188:191], v[180:183], v[118:121]
	v_add_f32_e32 v64, 1.0, v64
	v_mfma_f32_16x16x32_bf16 v[122:125], v[192:195], v[180:183], v[122:125]
	v_mfma_f32_16x16x32_bf16 v[126:129], v[196:199], v[180:183], v[126:129]
	v_add_f32_e32 v65, 1.0, v65
	s_waitcnt lgkmcnt(0)
	v_mfma_f32_16x16x32_bf16 v[66:69], v[152:155], v[136:139], v[66:69]
	ds_read_b128 v[168:171], v225 offset:0
	v_mfma_f32_16x16x32_bf16 v[70:73], v[156:159], v[136:139], v[70:73]
	ds_read_b128 v[172:175], v225 offset:2048
	v_rcp_f32_e32 v58, v58
	v_mfma_f32_16x16x32_bf16 v[74:77], v[160:163], v[136:139], v[74:77]
	ds_read_b128 v[176:179], v225 offset:4096
	v_rcp_f32_e32 v59, v59
	v_mfma_f32_16x16x32_bf16 v[78:81], v[164:167], v[136:139], v[78:81]
	ds_read_b128 v[180:183], v225 offset:6144
	v_rcp_f32_e32 v60, v60
	v_mfma_f32_16x16x32_bf16 v[82:85], v[152:155], v[140:143], v[82:85]
	ds_read_b128 v[184:187], v233 offset:0
	v_mfma_f32_16x16x32_bf16 v[86:89], v[156:159], v[140:143], v[86:89]
	ds_read_b128 v[188:191], v233 offset:2048
	v_rcp_f32_e32 v61, v61
	v_mfma_f32_16x16x32_bf16 v[90:93], v[160:163], v[140:143], v[90:93]
	ds_read_b128 v[192:195], v233 offset:4096
	v_rcp_f32_e32 v62, v62
	v_mfma_f32_16x16x32_bf16 v[94:97], v[164:167], v[140:143], v[94:97]
	ds_read_b128 v[196:199], v233 offset:6144
	v_rcp_f32_e32 v63, v63
	v_mfma_f32_16x16x32_bf16 v[98:101], v[152:155], v[144:147], v[98:101]
	v_mfma_f32_16x16x32_bf16 v[102:105], v[156:159], v[144:147], v[102:105]
	v_rcp_f32_e32 v64, v64
	v_mfma_f32_16x16x32_bf16 v[106:109], v[160:163], v[144:147], v[106:109]
	v_rcp_f32_e32 v65, v65
	v_mfma_f32_16x16x32_bf16 v[110:113], v[164:167], v[144:147], v[110:113]
	v_cvt_pk_bf16_f32 v58, v58, v59
	v_mfma_f32_16x16x32_bf16 v[114:117], v[152:155], v[148:151], v[114:117]
	v_mfma_f32_16x16x32_bf16 v[118:121], v[156:159], v[148:151], v[118:121]
	v_cvt_pk_bf16_f32 v59, v60, v61
	v_mfma_f32_16x16x32_bf16 v[122:125], v[160:163], v[148:151], v[122:125]
	v_cvt_pk_bf16_f32 v60, v62, v63
	v_mfma_f32_16x16x32_bf16 v[126:129], v[164:167], v[148:151], v[126:129]
	v_cvt_pk_bf16_f32 v61, v64, v65
	s_waitcnt lgkmcnt(0)
	v_mfma_f32_16x16x32_bf16 v[66:69], v[184:187], v[168:171], v[66:69]
	v_mfma_f32_16x16x32_bf16 v[70:73], v[188:191], v[168:171], v[70:73]
	v_mfma_f32_16x16x32_bf16 v[74:77], v[192:195], v[168:171], v[74:77]
	v_mfma_f32_16x16x32_bf16 v[78:81], v[196:199], v[168:171], v[78:81]
	v_mfma_f32_16x16x32_bf16 v[82:85], v[184:187], v[172:175], v[82:85]
	v_mfma_f32_16x16x32_bf16 v[86:89], v[188:191], v[172:175], v[86:89]
	v_mfma_f32_16x16x32_bf16 v[90:93], v[192:195], v[172:175], v[90:93]
	v_mfma_f32_16x16x32_bf16 v[94:97], v[196:199], v[172:175], v[94:97]
	v_mfma_f32_16x16x32_bf16 v[98:101], v[184:187], v[176:179], v[98:101]
	v_mfma_f32_16x16x32_bf16 v[102:105], v[188:191], v[176:179], v[102:105]
	v_mfma_f32_16x16x32_bf16 v[106:109], v[192:195], v[176:179], v[106:109]
	v_mfma_f32_16x16x32_bf16 v[110:113], v[196:199], v[176:179], v[110:113]
	v_mfma_f32_16x16x32_bf16 v[114:117], v[184:187], v[180:183], v[114:117]
	v_mfma_f32_16x16x32_bf16 v[118:121], v[188:191], v[180:183], v[118:121]
	v_mfma_f32_16x16x32_bf16 v[122:125], v[192:195], v[180:183], v[122:125]
	v_mfma_f32_16x16x32_bf16 v[126:129], v[196:199], v[180:183], v[126:129]
	global_store_dwordx4 v241, v[58:61], s[10:11] offset:3072 sc1
	s_add_u32 s10, s28, s13
	s_addc_u32 s11, s29, 0
	s_add_u32 s13, s13, 0x10000
	v_mul_f32_e32 v66, s12, v66
	v_mul_f32_e32 v67, s12, v67
	v_mul_f32_e32 v68, s12, v68
	v_mul_f32_e32 v69, s12, v69
	v_mul_f32_e32 v70, s12, v70
	v_mul_f32_e32 v71, s12, v71
	v_mul_f32_e32 v72, s12, v72
	v_mul_f32_e32 v73, s12, v73
	v_exp_f32_e32 v66, v66
	v_exp_f32_e32 v67, v67
	v_exp_f32_e32 v68, v68
	v_exp_f32_e32 v69, v69
	v_exp_f32_e32 v70, v70
	v_exp_f32_e32 v71, v71
	v_exp_f32_e32 v72, v72
	v_exp_f32_e32 v73, v73
	v_add_f32_e32 v66, 1.0, v66
	v_add_f32_e32 v67, 1.0, v67
	v_add_f32_e32 v68, 1.0, v68
	v_add_f32_e32 v69, 1.0, v69
	v_add_f32_e32 v70, 1.0, v70
	v_add_f32_e32 v71, 1.0, v71
	v_add_f32_e32 v72, 1.0, v72
	v_add_f32_e32 v73, 1.0, v73
	v_rcp_f32_e32 v66, v66
	v_rcp_f32_e32 v67, v67
	v_rcp_f32_e32 v68, v68
	v_rcp_f32_e32 v69, v69
	v_rcp_f32_e32 v70, v70
	v_rcp_f32_e32 v71, v71
	v_rcp_f32_e32 v72, v72
	v_rcp_f32_e32 v73, v73
	v_cvt_pk_bf16_f32 v66, v66, v67
	v_cvt_pk_bf16_f32 v67, v68, v69
	v_cvt_pk_bf16_f32 v68, v70, v71
	v_cvt_pk_bf16_f32 v69, v72, v73
	global_store_dwordx4 v240, v[66:69], s[10:11] offset:0 sc1
	v_mul_f32_e32 v74, s12, v74
	v_mul_f32_e32 v75, s12, v75
	v_mul_f32_e32 v76, s12, v76
	v_mul_f32_e32 v77, s12, v77
	v_mul_f32_e32 v78, s12, v78
	v_mul_f32_e32 v79, s12, v79
	v_mul_f32_e32 v80, s12, v80
	v_mul_f32_e32 v81, s12, v81
	v_exp_f32_e32 v74, v74
	v_exp_f32_e32 v75, v75
	v_exp_f32_e32 v76, v76
	v_exp_f32_e32 v77, v77
	v_exp_f32_e32 v78, v78
	v_exp_f32_e32 v79, v79
	v_exp_f32_e32 v80, v80
	v_exp_f32_e32 v81, v81
	v_add_f32_e32 v74, 1.0, v74
	v_add_f32_e32 v75, 1.0, v75
	v_add_f32_e32 v76, 1.0, v76
	v_add_f32_e32 v77, 1.0, v77
	v_add_f32_e32 v78, 1.0, v78
	v_add_f32_e32 v79, 1.0, v79
	v_add_f32_e32 v80, 1.0, v80
	v_add_f32_e32 v81, 1.0, v81
	v_rcp_f32_e32 v74, v74
	v_rcp_f32_e32 v75, v75
	v_rcp_f32_e32 v76, v76
	v_rcp_f32_e32 v77, v77
	v_rcp_f32_e32 v78, v78
	v_rcp_f32_e32 v79, v79
	v_rcp_f32_e32 v80, v80
	v_rcp_f32_e32 v81, v81
	v_cvt_pk_bf16_f32 v74, v74, v75
	v_cvt_pk_bf16_f32 v75, v76, v77
	v_cvt_pk_bf16_f32 v76, v78, v79
	v_cvt_pk_bf16_f32 v77, v80, v81
	global_store_dwordx4 v240, v[74:77], s[10:11] offset:1024 sc1
	v_mul_f32_e32 v82, s12, v82
	v_mul_f32_e32 v83, s12, v83
	v_mul_f32_e32 v84, s12, v84
	v_mul_f32_e32 v85, s12, v85
	v_mul_f32_e32 v86, s12, v86
	v_mul_f32_e32 v87, s12, v87
	v_mul_f32_e32 v88, s12, v88
	v_mul_f32_e32 v89, s12, v89
	v_exp_f32_e32 v82, v82
	v_exp_f32_e32 v83, v83
	v_exp_f32_e32 v84, v84
	v_exp_f32_e32 v85, v85
	v_exp_f32_e32 v86, v86
	v_exp_f32_e32 v87, v87
	v_exp_f32_e32 v88, v88
	v_exp_f32_e32 v89, v89
	v_add_f32_e32 v82, 1.0, v82
	v_add_f32_e32 v83, 1.0, v83
	v_add_f32_e32 v84, 1.0, v84
	v_add_f32_e32 v85, 1.0, v85
	v_add_f32_e32 v86, 1.0, v86
	v_add_f32_e32 v87, 1.0, v87
	v_add_f32_e32 v88, 1.0, v88
	v_add_f32_e32 v89, 1.0, v89
	v_rcp_f32_e32 v82, v82
	v_rcp_f32_e32 v83, v83
	v_rcp_f32_e32 v84, v84
	v_rcp_f32_e32 v85, v85
	v_rcp_f32_e32 v86, v86
	v_rcp_f32_e32 v87, v87
	v_rcp_f32_e32 v88, v88
	v_rcp_f32_e32 v89, v89
	v_cvt_pk_bf16_f32 v82, v82, v83
	v_cvt_pk_bf16_f32 v83, v84, v85
	v_cvt_pk_bf16_f32 v84, v86, v87
	v_cvt_pk_bf16_f32 v85, v88, v89
	global_store_dwordx4 v240, v[82:85], s[10:11] offset:2048 sc1
	v_mul_f32_e32 v90, s12, v90
	v_mul_f32_e32 v91, s12, v91
	v_mul_f32_e32 v92, s12, v92
	v_mul_f32_e32 v93, s12, v93
	v_mul_f32_e32 v94, s12, v94
	v_mul_f32_e32 v95, s12, v95
	v_mul_f32_e32 v96, s12, v96
	v_mul_f32_e32 v97, s12, v97
	v_exp_f32_e32 v90, v90
	v_exp_f32_e32 v91, v91
	v_exp_f32_e32 v92, v92
	v_exp_f32_e32 v93, v93
	v_exp_f32_e32 v94, v94
	v_exp_f32_e32 v95, v95
	v_exp_f32_e32 v96, v96
	v_exp_f32_e32 v97, v97
	v_add_f32_e32 v90, 1.0, v90
	v_add_f32_e32 v91, 1.0, v91
	v_add_f32_e32 v92, 1.0, v92
	v_add_f32_e32 v93, 1.0, v93
	v_add_f32_e32 v94, 1.0, v94
	v_add_f32_e32 v95, 1.0, v95
	v_add_f32_e32 v96, 1.0, v96
	v_add_f32_e32 v97, 1.0, v97
	v_rcp_f32_e32 v90, v90
	v_rcp_f32_e32 v91, v91
	v_rcp_f32_e32 v92, v92
	v_rcp_f32_e32 v93, v93
	v_rcp_f32_e32 v94, v94
	v_rcp_f32_e32 v95, v95
	v_rcp_f32_e32 v96, v96
	v_rcp_f32_e32 v97, v97
	v_cvt_pk_bf16_f32 v90, v90, v91
	v_cvt_pk_bf16_f32 v91, v92, v93
	v_cvt_pk_bf16_f32 v92, v94, v95
	v_cvt_pk_bf16_f32 v93, v96, v97
	global_store_dwordx4 v240, v[90:93], s[10:11] offset:3072 sc1
	v_mul_f32_e32 v98, s12, v98
	v_mul_f32_e32 v99, s12, v99
	v_mul_f32_e32 v100, s12, v100
	v_mul_f32_e32 v101, s12, v101
	v_mul_f32_e32 v102, s12, v102
	v_mul_f32_e32 v103, s12, v103
	v_mul_f32_e32 v104, s12, v104
	v_mul_f32_e32 v105, s12, v105
	v_exp_f32_e32 v98, v98
	v_exp_f32_e32 v99, v99
	v_exp_f32_e32 v100, v100
	v_exp_f32_e32 v101, v101
	v_exp_f32_e32 v102, v102
	v_exp_f32_e32 v103, v103
	v_exp_f32_e32 v104, v104
	v_exp_f32_e32 v105, v105
	v_add_f32_e32 v98, 1.0, v98
	v_add_f32_e32 v99, 1.0, v99
	v_add_f32_e32 v100, 1.0, v100
	v_add_f32_e32 v101, 1.0, v101
	v_add_f32_e32 v102, 1.0, v102
	v_add_f32_e32 v103, 1.0, v103
	v_add_f32_e32 v104, 1.0, v104
	v_add_f32_e32 v105, 1.0, v105
	v_rcp_f32_e32 v98, v98
	v_rcp_f32_e32 v99, v99
	v_rcp_f32_e32 v100, v100
	v_rcp_f32_e32 v101, v101
	v_rcp_f32_e32 v102, v102
	v_rcp_f32_e32 v103, v103
	v_rcp_f32_e32 v104, v104
	v_rcp_f32_e32 v105, v105
	v_cvt_pk_bf16_f32 v98, v98, v99
	v_cvt_pk_bf16_f32 v99, v100, v101
	v_cvt_pk_bf16_f32 v100, v102, v103
	v_cvt_pk_bf16_f32 v101, v104, v105
	global_store_dwordx4 v241, v[98:101], s[10:11] offset:0 sc1
	v_mul_f32_e32 v106, s12, v106
	v_mul_f32_e32 v107, s12, v107
	v_mul_f32_e32 v108, s12, v108
	v_mul_f32_e32 v109, s12, v109
	v_mul_f32_e32 v110, s12, v110
	v_mul_f32_e32 v111, s12, v111
	v_mul_f32_e32 v112, s12, v112
	v_mul_f32_e32 v113, s12, v113
	v_exp_f32_e32 v106, v106
	v_exp_f32_e32 v107, v107
	v_exp_f32_e32 v108, v108
	v_exp_f32_e32 v109, v109
	v_exp_f32_e32 v110, v110
	v_exp_f32_e32 v111, v111
	v_exp_f32_e32 v112, v112
	v_exp_f32_e32 v113, v113
	v_add_f32_e32 v106, 1.0, v106
	v_add_f32_e32 v107, 1.0, v107
	v_add_f32_e32 v108, 1.0, v108
	v_add_f32_e32 v109, 1.0, v109
	v_add_f32_e32 v110, 1.0, v110
	v_add_f32_e32 v111, 1.0, v111
	v_add_f32_e32 v112, 1.0, v112
	v_add_f32_e32 v113, 1.0, v113
	v_rcp_f32_e32 v106, v106
	v_rcp_f32_e32 v107, v107
	v_rcp_f32_e32 v108, v108
	v_rcp_f32_e32 v109, v109
	v_rcp_f32_e32 v110, v110
	v_rcp_f32_e32 v111, v111
	v_rcp_f32_e32 v112, v112
	v_rcp_f32_e32 v113, v113
	v_cvt_pk_bf16_f32 v106, v106, v107
	v_cvt_pk_bf16_f32 v107, v108, v109
	v_cvt_pk_bf16_f32 v108, v110, v111
	v_cvt_pk_bf16_f32 v109, v112, v113
	global_store_dwordx4 v241, v[106:109], s[10:11] offset:1024 sc1
	v_mul_f32_e32 v114, s12, v114
	v_mul_f32_e32 v115, s12, v115
	v_mul_f32_e32 v116, s12, v116
	v_mul_f32_e32 v117, s12, v117
	v_mul_f32_e32 v118, s12, v118
	v_mul_f32_e32 v119, s12, v119
	v_mul_f32_e32 v120, s12, v120
	v_mul_f32_e32 v121, s12, v121
	v_exp_f32_e32 v114, v114
	v_exp_f32_e32 v115, v115
	v_exp_f32_e32 v116, v116
	v_exp_f32_e32 v117, v117
	v_exp_f32_e32 v118, v118
	v_exp_f32_e32 v119, v119
	v_exp_f32_e32 v120, v120
	v_exp_f32_e32 v121, v121
	v_add_f32_e32 v114, 1.0, v114
	v_add_f32_e32 v115, 1.0, v115
	v_add_f32_e32 v116, 1.0, v116
	v_add_f32_e32 v117, 1.0, v117
	v_add_f32_e32 v118, 1.0, v118
	v_add_f32_e32 v119, 1.0, v119
	v_add_f32_e32 v120, 1.0, v120
	v_add_f32_e32 v121, 1.0, v121
	v_rcp_f32_e32 v114, v114
	v_rcp_f32_e32 v115, v115
	v_rcp_f32_e32 v116, v116
	v_rcp_f32_e32 v117, v117
	v_rcp_f32_e32 v118, v118
	v_rcp_f32_e32 v119, v119
	v_rcp_f32_e32 v120, v120
	v_rcp_f32_e32 v121, v121
	v_cvt_pk_bf16_f32 v114, v114, v115
	v_cvt_pk_bf16_f32 v115, v116, v117
	v_cvt_pk_bf16_f32 v116, v118, v119
	v_cvt_pk_bf16_f32 v117, v120, v121
	global_store_dwordx4 v241, v[114:117], s[10:11] offset:2048 sc1
	v_mul_f32_e32 v122, s12, v122
	v_mul_f32_e32 v123, s12, v123
	v_mul_f32_e32 v124, s12, v124
	v_mul_f32_e32 v125, s12, v125
	v_mul_f32_e32 v126, s12, v126
	v_mul_f32_e32 v127, s12, v127
	v_mul_f32_e32 v128, s12, v128
	v_mul_f32_e32 v129, s12, v129
	v_exp_f32_e32 v122, v122
	v_exp_f32_e32 v123, v123
	v_exp_f32_e32 v124, v124
	v_exp_f32_e32 v125, v125
	v_exp_f32_e32 v126, v126
	v_exp_f32_e32 v127, v127
	v_exp_f32_e32 v128, v128
	v_exp_f32_e32 v129, v129
	v_add_f32_e32 v122, 1.0, v122
	v_add_f32_e32 v123, 1.0, v123
	v_add_f32_e32 v124, 1.0, v124
	v_add_f32_e32 v125, 1.0, v125
	v_add_f32_e32 v126, 1.0, v126
	v_add_f32_e32 v127, 1.0, v127
	v_add_f32_e32 v128, 1.0, v128
	v_add_f32_e32 v129, 1.0, v129
	v_rcp_f32_e32 v122, v122
	v_rcp_f32_e32 v123, v123
	v_rcp_f32_e32 v124, v124
	v_rcp_f32_e32 v125, v125
	v_rcp_f32_e32 v126, v126
	v_rcp_f32_e32 v127, v127
	v_rcp_f32_e32 v128, v128
	v_rcp_f32_e32 v129, v129
	v_cvt_pk_bf16_f32 v122, v122, v123
	v_cvt_pk_bf16_f32 v123, v124, v125
	v_cvt_pk_bf16_f32 v124, v126, v127
	v_cvt_pk_bf16_f32 v125, v128, v129
	global_store_dwordx4 v241, v[122:125], s[10:11] offset:3072 sc1
	s_waitcnt vmcnt(0)
	s_barrier
	s_and_b32 s0, s2, 7
	s_lshl_b32 s0, s0, 2
	s_lshr_b32 s1, s2, 3
	s_and_b32 s1, s1, 3
	s_add_u32 s0, s0, s1
	s_lshl_b32 s1, s80, 5
	s_add_u32 s0, s0, s1
	s_add_u32 s0, s0, 64
	s_lshl_b32 s0, s0, 2
	v_readlane_b32 s22, v253, 2
	v_readlane_b32 s23, v253, 3
	s_nop 0
	s_add_u32 s22, s22, s0
	s_addc_u32 s23, s23, 0
	v_cmp_eq_u32_e32 vcc, 0, v0
	s_and_saveexec_b64 s[24:25], vcc
	v_mov_b32_e32 v1, 1
	global_atomic_add v131, v1, s[22:23]
	s_or_b64 exec, exec, s[24:25]
	v_mov_b32_e32 v236, s20
	v_mov_b32_e32 v237, s21
	v_mov_b32_e32 v238, 0x200f0
	ds_write_b64 v238, v[236:237]
	s_waitcnt vmcnt(0)
	v_readlane_b32 s60, v254, 32
	v_readlane_b32 s58, v254, 46
	s_mov_b32 s64, s44
	s_mov_b32 s72, s67
	s_cmpk_gt_u32 s50, 0xff
	v_readlane_b32 s61, v254, 33
	v_readlane_b32 s59, v254, 47
	s_movk_i32 s73, 0xf0
	v_readlane_b32 s79, v254, 50

.LBB0_826:
	s_waitcnt vmcnt(0) lgkmcnt(0)
	s_barrier
	s_waitcnt vmcnt(0)
	s_barrier
	s_mov_b64 s[0:1], exec
	v_readlane_b32 s4, v253, 0
	v_readlane_b32 s5, v253, 1
	s_and_b64 s[4:5], s[0:1], s[4:5]
	s_mov_b64 s[50:51], 0x10000
	s_mov_b64 exec, s[4:5]
	s_branch .LBB0_878
	s_getreg_b32 s4, hwreg(HW_REG_XCC_ID, 0, 4)
	s_and_b32 s10, s4, 15
	v_readlane_b32 s4, v254, 25
	s_waitcnt vmcnt(0) expcnt(0) lgkmcnt(0)
	s_nop 0
	v_mov_b32_e32 v1, s4
	ds_read_b32 v3, v1
	v_readlane_b32 s4, v254, 23
	s_waitcnt lgkmcnt(0)
	v_cmp_ne_u32_e32 vcc, 0, v3
	v_mov_b32_e32 v1, s4
	ds_read_b32 v2, v1
	s_cbranch_vccnz .LBB0_842
	v_readlane_b32 s6, v253, 5
	v_readlane_b32 s7, v253, 6
	s_load_dwordx2 s[4:5], s[6:7], 0x4
	s_mov_b32 s12, 1
	s_waitcnt lgkmcnt(0)
	s_mul_i32 s11, s4, s65
	s_mul_i32 s11, s11, s5
	s_branch .LBB0_830

.LBB0_880:
	s_andn2_b64 vcc, exec, s[0:1]
	s_cbranch_vccnz .LBB0_891
	s_lshl_b32 s96, s80, 20
	s_mov_b64 s[4:5], s[96:97]
	s_mov_b32 s13, s2
	v_mov_b32_e32 v205, 0x200f0
	ds_read_b64 v[250:251], v205
	v_and_b32_e32 v198, 63, v0
	v_lshrrev_b32_e32 v199, 6, v0
	v_lshrrev_b32_e32 v200, 3, v198
	v_lshrrev_b32_e32 v201, 4, v198
	s_nop 0
	v_readfirstlane_b32 s0, v199
	v_add_u32_e32 v132, 0, v201
	v_xor_b32_e32 v132, v132, v198
	v_and_b32_e32 v132, 7, v132
	v_lshlrev_b32_e32 v132, 4, v132
	v_lshl_add_u32 v130, v199, 5, v200
	v_add_u32_e32 v130, 0, v130
	v_mul_u32_u24_e32 v130, 0x800, v130
	v_add_u32_e32 v132, v132, v130
	v_add_u32_e32 v133, 4, v201
	v_xor_b32_e32 v133, v133, v198
	v_and_b32_e32 v133, 7, v133
	v_lshlrev_b32_e32 v133, 4, v133
	v_lshl_add_u32 v130, v199, 5, v200
	v_add_u32_e32 v130, 8, v130
	v_mul_u32_u24_e32 v130, 0x800, v130
	v_add_u32_e32 v133, v133, v130
	v_add_u32_e32 v134, 8, v201
	v_xor_b32_e32 v134, v134, v198
	v_and_b32_e32 v134, 7, v134
	v_lshlrev_b32_e32 v134, 4, v134
	v_lshl_add_u32 v130, v199, 5, v200
	v_add_u32_e32 v130, 16, v130
	v_mul_u32_u24_e32 v130, 0x800, v130
	v_add_u32_e32 v134, v134, v130
	v_add_u32_e32 v135, 12, v201
	v_xor_b32_e32 v135, v135, v198
	v_and_b32_e32 v135, 7, v135
	v_lshlrev_b32_e32 v135, 4, v135
	v_lshl_add_u32 v130, v199, 5, v200
	v_add_u32_e32 v130, 24, v130
	v_mul_u32_u24_e32 v130, 0x800, v130
	v_add_u32_e32 v135, v135, v130
	v_add_u32_e32 v136, 0, v201
	v_xor_b32_e32 v136, v136, v198
	v_and_b32_e32 v136, 7, v136
	v_lshlrev_b32_e32 v136, 4, v136
	v_lshl_add_u32 v130, v199, 4, v200
	v_add_u32_e32 v130, 0, v130
	v_mul_u32_u24_e32 v130, 0x200, v130
	v_add_u32_e32 v136, v136, v130
	v_add_u32_e32 v137, 4, v201
	v_xor_b32_e32 v137, v137, v198
	v_and_b32_e32 v137, 7, v137
	v_lshlrev_b32_e32 v137, 4, v137
	v_lshl_add_u32 v130, v199, 4, v200
	v_add_u32_e32 v130, 8, v130
	v_mul_u32_u24_e32 v130, 0x200, v130
	v_add_u32_e32 v137, v137, v130
	v_and_b32_e32 v200, 15, v198
	v_lshrrev_b32_e32 v130, 1, v200
	v_xor_b32_e32 v130, v130, v201
	v_lshlrev_b32_e32 v130, 4, v130
	v_lshrrev_b32_e32 v198, 1, v199
	v_lshl_add_u32 v198, v198, 6, v200
	v_lshl_add_u32 v198, v198, 7, v130
	v_and_b32_e32 v199, 1, v199
	v_lshl_add_u32 v199, v199, 6, v200
	v_lshl_add_u32 v199, v199, 7, v130
	v_add_u32_e32 v138, 0x100, v198
	v_xor_b32_e32 v141, 64, v138
	v_add_u32_e32 v144, 0x8100, v199
	v_xor_b32_e32 v147, 64, v144
	v_add_u32_e32 v139, 0xc100, v198
	v_xor_b32_e32 v142, 64, v139
	v_add_u32_e32 v145, 0x14100, v199
	v_xor_b32_e32 v196, 64, v145
	v_add_u32_e32 v140, 0x18100, v198
	v_xor_b32_e32 v143, 64, v140
	v_add_u32_e32 v146, 0x20100, v199
	v_xor_b32_e32 v197, 64, v146
	s_lshl_b32 s1, s0, 12
	s_add_u32 s10, s1, 0x100
	s_lshl_b32 s1, s0, 11
	s_add_u32 s11, s1, 0x8100
	v_mov_b32_e32 v2, 0
	v_mov_b32_e32 v3, 0
	v_mov_b32_e32 v4, 0
	v_mov_b32_e32 v5, 0
	v_mov_b32_e32 v6, 0
	v_mov_b32_e32 v7, 0
	v_mov_b32_e32 v8, 0
	v_mov_b32_e32 v9, 0
	v_mov_b32_e32 v10, 0
	v_mov_b32_e32 v11, 0
	v_mov_b32_e32 v12, 0
	v_mov_b32_e32 v13, 0
	v_mov_b32_e32 v14, 0
	v_mov_b32_e32 v15, 0
	v_mov_b32_e32 v16, 0
	v_mov_b32_e32 v17, 0
	v_mov_b32_e32 v18, 0
	v_mov_b32_e32 v19, 0
	v_mov_b32_e32 v20, 0
	v_mov_b32_e32 v21, 0
	v_mov_b32_e32 v22, 0
	v_mov_b32_e32 v23, 0
	v_mov_b32_e32 v24, 0
	v_mov_b32_e32 v25, 0
	v_mov_b32_e32 v26, 0
	v_mov_b32_e32 v27, 0
	v_mov_b32_e32 v28, 0
	v_mov_b32_e32 v29, 0
	v_mov_b32_e32 v30, 0
	v_mov_b32_e32 v31, 0
	v_mov_b32_e32 v32, 0
	v_mov_b32_e32 v33, 0
	v_mov_b32_e32 v34, 0
	v_mov_b32_e32 v35, 0
	v_mov_b32_e32 v36, 0
	v_mov_b32_e32 v37, 0
	v_mov_b32_e32 v38, 0
	v_mov_b32_e32 v39, 0
	v_mov_b32_e32 v40, 0
	v_mov_b32_e32 v41, 0
	v_mov_b32_e32 v42, 0
	v_mov_b32_e32 v43, 0
	v_mov_b32_e32 v44, 0
	v_mov_b32_e32 v45, 0
	v_mov_b32_e32 v46, 0
	v_mov_b32_e32 v47, 0
	v_mov_b32_e32 v48, 0
	v_mov_b32_e32 v49, 0
	v_mov_b32_e32 v50, 0
	v_mov_b32_e32 v51, 0
	v_mov_b32_e32 v52, 0
	v_mov_b32_e32 v53, 0
	v_mov_b32_e32 v54, 0
	v_mov_b32_e32 v55, 0
	v_mov_b32_e32 v56, 0
	v_mov_b32_e32 v57, 0
	v_mov_b32_e32 v58, 0
	v_mov_b32_e32 v59, 0
	v_mov_b32_e32 v60, 0
	v_mov_b32_e32 v61, 0
	v_mov_b32_e32 v62, 0
	v_mov_b32_e32 v63, 0
	v_mov_b32_e32 v64, 0
	v_mov_b32_e32 v65, 0
	v_readfirstlane_b32 s0, v0
	s_cmp_lt_u32 s0, 64
	s_cbranch_scc0 .Lc2_go
	v_readlane_b32 s6, v253, 2
	v_readlane_b32 s7, v253, 3
	s_lshl_b32 s1, s80, 2
	s_add_u32 s1, s1, 24
	s_add_u32 s8, s6, s1
	s_addc_u32 s9, s7, 0
	s_and_b32 s0, s2, 31
	s_lshl_b32 s1, s80, 5
	s_add_u32 s0, s0, s1
	s_add_u32 s0, s0, 64
	s_lshl_b32 s0, s0, 2
	s_add_u32 s6, s6, s0
	s_addc_u32 s7, s7, 0
	s_mov_b32 s14, 0
.Lc2_poll:
	global_load_dword v198, v131, s[8:9] sc1
	global_load_dword v199, v131, s[6:7] sc1
	s_waitcnt vmcnt(0)
	v_readfirstlane_b32 s0, v198
	v_readfirstlane_b32 s1, v199
	s_cmpk_ge_u32 s0, 0x100
	s_cselect_b32 s0, 1, 0
	s_cmpk_ge_u32 s1, 8
	s_cselect_b32 s1, 1, 0
	s_and_b32 s0, s0, s1
	s_cmp_eq_u32 s0, 1
	s_cbranch_scc1 .Lc2_polled
	s_sleep 16
	s_add_u32 s14, s14, 1
	s_cmp_lt_u32 s14, 0x1388
	s_cbranch_scc1 .Lc2_poll

.Lc2_go:
	s_waitcnt lgkmcnt(0)
	s_barrier
	v_and_b32_e32 v198, 63, v0
	v_lshrrev_b32_e32 v199, 6, v0
	v_and_b32_e32 v200, 15, v198
	v_lshrrev_b32_e32 v201, 4, v198
	v_lshlrev_b32_e32 v202, 13, v199
	v_lshl_add_u32 v245, v198, 5, v202
	v_lshl_add_u32 v202, v198, 4, v202
	v_add_u32_e32 v203, 0x1000, v202
	v_lshrrev_b32_e32 v130, 1, v199
	v_lshl_add_u32 v130, v130, 6, v200
	v_lshlrev_b32_e32 v204, 11, v130
	v_and_b32_e32 v130, 1, v199
	v_lshl_add_u32 v204, v130, 7, v204
	v_lshl_add_u32 v204, v201, 3, v204
	v_add_u32_e32 v199, 0x1000, v245
